# replace unit-scale v_mfma_scale_*_f8f6f4 with non-scaled v_mfma_*_f8f6f4 (same fp8 operands, same results)
# speedup vs baseline: 1.0205x; 1.0205x over previous
.LBB0_250:
	s_waitcnt lgkmcnt(0)
	s_barrier
	s_setprio 1
	s_waitcnt lgkmcnt(0)
	v_mfma_f32_16x16x128_f8f6f4 v[126:129], v[26:33], v[58:65], v[126:129]
	v_mfma_f32_16x16x128_f8f6f4 v[122:125], v[18:25], v[58:65], v[122:125]
	v_mfma_f32_16x16x128_f8f6f4 v[110:113], v[26:33], v[50:57], v[110:113]
	v_mfma_f32_16x16x128_f8f6f4 v[106:109], v[18:25], v[50:57], v[106:109]
	v_mfma_f32_16x16x128_f8f6f4 v[94:97], v[26:33], v[42:49], v[94:97]
	v_mfma_f32_16x16x128_f8f6f4 v[90:93], v[18:25], v[42:49], v[90:93]
	v_mfma_f32_16x16x128_f8f6f4 v[78:81], v[26:33], v[34:41], v[78:81]
	v_mfma_f32_16x16x128_f8f6f4 v[74:77], v[18:25], v[34:41], v[74:77]
	s_setprio 0
	s_setprio 1
	v_mfma_f32_16x16x128_f8f6f4 v[118:121], v[10:17], v[58:65], v[118:121]
	v_mfma_f32_16x16x128_f8f6f4 v[114:117], v[2:9], v[58:65], v[114:117]
	v_mfma_f32_16x16x128_f8f6f4 v[102:105], v[10:17], v[50:57], v[102:105]
	v_mfma_f32_16x16x128_f8f6f4 v[98:101], v[2:9], v[50:57], v[98:101]
	v_mfma_f32_16x16x128_f8f6f4 v[86:89], v[10:17], v[42:49], v[86:89]
	v_mfma_f32_16x16x128_f8f6f4 v[82:85], v[2:9], v[42:49], v[82:85]
	v_mfma_f32_16x16x128_f8f6f4 v[70:73], v[10:17], v[34:41], v[70:73]
	v_mfma_f32_16x16x128_f8f6f4 v[66:69], v[2:9], v[34:41], v[66:69]
	s_setprio 0
	s_barrier
	v_add_u32_e32 v14, s53, v205
	v_add_u32_e32 v30, s58, v205
	ds_read_b128 v[2:5], v14
	ds_read_b128 v[6:9], v14 offset:1024
	ds_read_b128 v[10:13], v14 offset:2048
	ds_read_b128 v[14:17], v14 offset:3072
	ds_read_b128 v[18:21], v30
	ds_read_b128 v[22:25], v30 offset:1024
	ds_read_b128 v[26:29], v30 offset:2048
	ds_read_b128 v[30:33], v30 offset:3072
	s_add_u32 s36, s36, 0x530000
	s_addc_u32 s37, s37, 0
	s_mov_b32 m0, s51
	v_lshl_add_u64 v[242:243], s[36:37], 0, v[194:195]
	ds_read_b128 v[34:37], v234 offset:32768
	ds_read_b128 v[38:41], v234 offset:33792
	ds_read_b128 v[42:45], v234 offset:34816
	ds_read_b128 v[46:49], v234 offset:35840
	ds_read_b128 v[50:53], v234 offset:36864
	ds_read_b128 v[54:57], v234 offset:37888
	ds_read_b128 v[58:61], v234 offset:38912
	ds_read_b128 v[62:65], v234 offset:39936
	global_load_lds_dwordx4 v[242:243], off
	v_lshl_add_u64 v[242:243], s[36:37], 0, v[198:199]
	s_mov_b32 m0, s52
	s_nop 0
	global_load_lds_dwordx4 v[242:243], off
	s_waitcnt vmcnt(8)
	s_waitcnt lgkmcnt(0)
	s_barrier
	s_setprio 1
	s_waitcnt lgkmcnt(0)
	v_mfma_f32_16x16x128_f8f6f4 v[190:193], v[2:9], v[34:41], v[190:193]
	v_mfma_f32_16x16x128_f8f6f4 v[186:189], v[10:17], v[34:41], v[186:189]
	v_mfma_f32_16x16x128_f8f6f4 v[174:177], v[2:9], v[42:49], v[174:177]
	v_mfma_f32_16x16x128_f8f6f4 v[170:173], v[10:17], v[42:49], v[170:173]
	v_mfma_f32_16x16x128_f8f6f4 v[158:161], v[2:9], v[50:57], v[158:161]
	v_mfma_f32_16x16x128_f8f6f4 v[154:157], v[10:17], v[50:57], v[154:157]
	v_mfma_f32_16x16x128_f8f6f4 v[142:145], v[2:9], v[58:65], v[142:145]
	v_mfma_f32_16x16x128_f8f6f4 v[138:141], v[10:17], v[58:65], v[138:141]
	s_setprio 0
	s_setprio 1
	v_mfma_f32_16x16x128_f8f6f4 v[182:185], v[18:25], v[34:41], v[182:185]
	v_mfma_f32_16x16x128_f8f6f4 v[178:181], v[26:33], v[34:41], v[178:181]
	v_mfma_f32_16x16x128_f8f6f4 v[166:169], v[18:25], v[42:49], v[166:169]
	v_mfma_f32_16x16x128_f8f6f4 v[162:165], v[26:33], v[42:49], v[162:165]
	v_mfma_f32_16x16x128_f8f6f4 v[150:153], v[18:25], v[50:57], v[150:153]
	v_mfma_f32_16x16x128_f8f6f4 v[146:149], v[26:33], v[50:57], v[146:149]
	v_mfma_f32_16x16x128_f8f6f4 v[134:137], v[18:25], v[58:65], v[134:137]
	v_mfma_f32_16x16x128_f8f6f4 v[130:133], v[26:33], v[58:65], v[130:133]
	s_setprio 0
	s_barrier
	s_mov_b32 m0, s54
	v_lshl_add_u64 v[222:223], v[222:223], 0, s[12:13]
	s_add_u32 s34, s34, 0x40080
	ds_read_b128 v[34:37], v234 offset:49152
	ds_read_b128 v[38:41], v234 offset:50176
	ds_read_b128 v[42:45], v234 offset:51200
	ds_read_b128 v[46:49], v234 offset:52224
	ds_read_b128 v[50:53], v234 offset:53248
	ds_read_b128 v[54:57], v234 offset:54272
	ds_read_b128 v[58:61], v234 offset:55296
	ds_read_b128 v[62:65], v234 offset:56320
	global_load_lds_dwordx4 v[222:223], off
	v_lshl_add_u64 v[222:223], v[224:225], 0, s[12:13]
	s_mov_b32 m0, s55
	s_addc_u32 s35, s35, 0
	global_load_lds_dwordx4 v[222:223], off
	v_lshl_add_u64 v[222:223], s[34:35], 0, v[196:197]
	s_mov_b32 m0, s59
	s_nop 0
	global_load_lds_dwordx4 v[222:223], off
	v_lshl_add_u64 v[222:223], s[34:35], 0, v[200:201]
	s_mov_b32 m0, s60
	s_nop 0
	global_load_lds_dwordx4 v[222:223], off
	v_lshl_add_u64 v[222:223], v[226:227], 0, s[12:13]
	s_mov_b32 m0, s56
	s_nop 0
	global_load_lds_dwordx4 v[222:223], off
	v_lshl_add_u64 v[222:223], v[228:229], 0, s[12:13]
	s_mov_b32 m0, s57
	s_nop 0
	global_load_lds_dwordx4 v[222:223], off
	s_waitcnt vmcnt(8)
	s_waitcnt lgkmcnt(0)
	s_barrier
	s_setprio 1
	s_waitcnt lgkmcnt(0)
	v_mfma_f32_16x16x128_f8f6f4 v[126:129], v[2:9], v[34:41], v[126:129]
	v_mfma_f32_16x16x128_f8f6f4 v[122:125], v[10:17], v[34:41], v[122:125]
	v_mfma_f32_16x16x128_f8f6f4 v[110:113], v[2:9], v[42:49], v[110:113]
	v_mfma_f32_16x16x128_f8f6f4 v[106:109], v[10:17], v[42:49], v[106:109]
	v_mfma_f32_16x16x128_f8f6f4 v[94:97], v[2:9], v[50:57], v[94:97]
	v_mfma_f32_16x16x128_f8f6f4 v[90:93], v[10:17], v[50:57], v[90:93]
	v_mfma_f32_16x16x128_f8f6f4 v[78:81], v[2:9], v[58:65], v[78:81]
	v_mfma_f32_16x16x128_f8f6f4 v[74:77], v[10:17], v[58:65], v[74:77]
	s_setprio 0
	s_setprio 1
	v_mfma_f32_16x16x128_f8f6f4 v[118:121], v[18:25], v[34:41], v[118:121]
	v_mfma_f32_16x16x128_f8f6f4 v[114:117], v[26:33], v[34:41], v[114:117]
	v_mfma_f32_16x16x128_f8f6f4 v[102:105], v[18:25], v[42:49], v[102:105]
	v_mfma_f32_16x16x128_f8f6f4 v[98:101], v[26:33], v[42:49], v[98:101]
	v_mfma_f32_16x16x128_f8f6f4 v[86:89], v[18:25], v[50:57], v[86:89]
	v_mfma_f32_16x16x128_f8f6f4 v[82:85], v[26:33], v[50:57], v[82:85]
	v_mfma_f32_16x16x128_f8f6f4 v[70:73], v[18:25], v[58:65], v[70:73]
	v_mfma_f32_16x16x128_f8f6f4 v[66:69], v[26:33], v[58:65], v[66:69]
	s_setprio 0
	s_barrier
	s_add_i32 s80, s80, 2
	s_add_u32 s30, s30, 0x100
	s_addc_u32 s31, s31, 0
	s_cmp_gt_u32 s80, 13
	s_cbranch_scc1 .LBB0_258

.LBB0_254:
	s_add_u32 s34, s6, s30
	s_addc_u32 s35, s7, s31
	s_add_u32 s34, s34, 0x100
	s_addc_u32 s35, s35, 0
	s_add_u32 s81, s78, s30
	s_addc_u32 s82, s79, s31
	s_waitcnt lgkmcnt(0)
	s_cmpk_eq_i32 s30, 0x700
	s_cselect_b32 s37, s27, s35
	s_cselect_b32 s36, s26, s34
	s_cselect_b32 s35, s5, s82
	s_cselect_b32 s34, s25, s81
	s_barrier
	s_setprio 1
	s_waitcnt lgkmcnt(0)
	v_mfma_f32_16x16x128_f8f6f4 v[190:193], v[26:33], v[58:65], v[190:193]
	v_mfma_f32_16x16x128_f8f6f4 v[186:189], v[18:25], v[58:65], v[186:189]
	v_mfma_f32_16x16x128_f8f6f4 v[174:177], v[26:33], v[50:57], v[174:177]
	v_mfma_f32_16x16x128_f8f6f4 v[170:173], v[18:25], v[50:57], v[170:173]
	v_mfma_f32_16x16x128_f8f6f4 v[158:161], v[26:33], v[42:49], v[158:161]
	v_mfma_f32_16x16x128_f8f6f4 v[154:157], v[18:25], v[42:49], v[154:157]
	v_mfma_f32_16x16x128_f8f6f4 v[142:145], v[26:33], v[34:41], v[142:145]
	v_mfma_f32_16x16x128_f8f6f4 v[138:141], v[18:25], v[34:41], v[138:141]
	s_setprio 0
	s_setprio 1
	v_mfma_f32_16x16x128_f8f6f4 v[182:185], v[10:17], v[58:65], v[182:185]
	v_mfma_f32_16x16x128_f8f6f4 v[178:181], v[2:9], v[58:65], v[178:181]
	v_mfma_f32_16x16x128_f8f6f4 v[166:169], v[10:17], v[50:57], v[166:169]
	v_mfma_f32_16x16x128_f8f6f4 v[162:165], v[2:9], v[50:57], v[162:165]
	v_mfma_f32_16x16x128_f8f6f4 v[150:153], v[10:17], v[42:49], v[150:153]
	v_mfma_f32_16x16x128_f8f6f4 v[146:149], v[2:9], v[42:49], v[146:149]
	v_mfma_f32_16x16x128_f8f6f4 v[134:137], v[10:17], v[34:41], v[134:137]
	v_mfma_f32_16x16x128_f8f6f4 v[130:133], v[2:9], v[34:41], v[130:133]
	s_setprio 0
	s_barrier
	s_mov_b32 m0, s45
	v_lshl_add_u64 v[222:223], s[34:35], 0, v[196:197]
	s_add_u32 s82, s34, 0x40000
	ds_read_b128 v[58:61], v234 offset:16384
	ds_read_b128 v[62:65], v234 offset:17408
	ds_read_b128 v[50:53], v234 offset:18432
	ds_read_b128 v[54:57], v234 offset:19456
	ds_read_b128 v[42:45], v234 offset:20480
	ds_read_b128 v[46:49], v234 offset:21504
	ds_read_b128 v[34:37], v234 offset:22528
	ds_read_b128 v[38:41], v234 offset:23552
	global_load_lds_dwordx4 v[222:223], off
	v_lshl_add_u64 v[224:225], s[34:35], 0, v[200:201]
	s_mov_b32 m0, s46
	s_addc_u32 s83, s35, 0
	global_load_lds_dwordx4 v[224:225], off
	v_lshl_add_u64 v[226:227], s[82:83], 0, v[196:197]
	s_mov_b32 m0, s47
	v_lshl_add_u64 v[228:229], s[36:37], 0, v[198:199]
	global_load_lds_dwordx4 v[226:227], off
	v_lshl_add_u64 v[226:227], s[82:83], 0, v[200:201]
	s_mov_b32 m0, s48
	s_andn2_b64 vcc, exec, s[38:39]
	global_load_lds_dwordx4 v[226:227], off
	v_lshl_add_u64 v[226:227], s[36:37], 0, v[194:195]
	s_mov_b32 m0, s49
	s_nop 0
	global_load_lds_dwordx4 v[226:227], off
	s_mov_b32 m0, s50
	s_nop 0
	global_load_lds_dwordx4 v[228:229], off
	s_cbranch_vccnz .LBB0_257
	s_waitcnt vmcnt(16)
	s_cbranch_execnz .LBB0_250
	s_branch .LBB0_249

.LBB0_419:
	s_waitcnt lgkmcnt(0)
	s_barrier
	s_setprio 1
	v_mov_b64_e32 v[68:69], s[6:7]
	v_mov_b64_e32 v[172:173], s[6:7]
	v_mov_b64_e32 v[176:177], s[6:7]
	v_mov_b64_e32 v[156:157], s[6:7]
	v_mov_b64_e32 v[160:161], s[6:7]
	v_mov_b64_e32 v[140:141], s[6:7]
	v_mov_b64_e32 v[144:145], s[6:7]
	v_mov_b64_e32 v[132:133], s[6:7]
	v_mov_b64_e32 v[136:137], s[6:7]
	v_mov_b64_e32 v[66:67], s[4:5]
	v_mov_b64_e32 v[170:171], s[4:5]
	v_mov_b64_e32 v[174:175], s[4:5]
	v_mov_b64_e32 v[154:155], s[4:5]
	v_mov_b64_e32 v[158:159], s[4:5]
	v_mov_b64_e32 v[138:139], s[4:5]
	v_mov_b64_e32 v[142:143], s[4:5]
	v_mov_b64_e32 v[130:131], s[4:5]
	v_mov_b64_e32 v[134:135], s[4:5]
	s_waitcnt lgkmcnt(0)
	v_mfma_f32_16x16x128_f8f6f4 v[170:173], v[26:33], v[58:65], v[170:173]
	v_mfma_f32_16x16x128_f8f6f4 v[174:177], v[18:25], v[58:65], v[174:177]
	v_mfma_f32_16x16x128_f8f6f4 v[154:157], v[26:33], v[50:57], v[154:157]
	v_mfma_f32_16x16x128_f8f6f4 v[158:161], v[18:25], v[50:57], v[158:161]
	v_mfma_f32_16x16x128_f8f6f4 v[138:141], v[26:33], v[42:49], v[138:141]
	v_mfma_f32_16x16x128_f8f6f4 v[142:145], v[18:25], v[42:49], v[142:145]
	v_mfma_f32_16x16x128_f8f6f4 v[130:133], v[26:33], v[34:41], v[130:133]
	v_mfma_f32_16x16x128_f8f6f4 v[134:137], v[18:25], v[34:41], v[134:137]
	s_setprio 0
	s_setprio 1
	v_mov_b64_e32 v[100:101], s[6:7]
	v_mov_b64_e32 v[104:105], s[6:7]
	v_mov_b64_e32 v[88:89], s[6:7]
	v_mov_b64_e32 v[92:93], s[6:7]
	v_mov_b64_e32 v[80:81], s[6:7]
	v_mov_b64_e32 v[84:85], s[6:7]
	v_mov_b64_e32 v[76:77], s[6:7]
	v_mov_b64_e32 v[98:99], s[4:5]
	v_mov_b64_e32 v[102:103], s[4:5]
	v_mov_b64_e32 v[86:87], s[4:5]
	v_mov_b64_e32 v[90:91], s[4:5]
	v_mov_b64_e32 v[78:79], s[4:5]
	v_mov_b64_e32 v[82:83], s[4:5]
	v_mov_b64_e32 v[74:75], s[4:5]
	v_mfma_f32_16x16x128_f8f6f4 v[98:101], v[10:17], v[58:65], v[98:101]
	v_mfma_f32_16x16x128_f8f6f4 v[102:105], v[2:9], v[58:65], v[102:105]
	v_mfma_f32_16x16x128_f8f6f4 v[86:89], v[10:17], v[50:57], v[86:89]
	v_mfma_f32_16x16x128_f8f6f4 v[90:93], v[2:9], v[50:57], v[90:93]
	v_mfma_f32_16x16x128_f8f6f4 v[78:81], v[10:17], v[42:49], v[78:81]
	v_mfma_f32_16x16x128_f8f6f4 v[82:85], v[2:9], v[42:49], v[82:85]
	v_mfma_f32_16x16x128_f8f6f4 v[74:77], v[10:17], v[34:41], v[74:77]
	v_mfma_f32_16x16x128_f8f6f4 v[66:69], v[2:9], v[34:41], v[66:69]
	s_setprio 0
	s_barrier
	v_lshl_add_u64 v[206:207], s[36:37], 0, v[198:199]
	s_mov_b32 m0, s35
	v_lshl_add_u64 v[70:71], v[206:207], 0, s[18:19]
	v_lshl_add_u64 v[208:209], s[36:37], 0, v[194:195]
	s_add_u32 s42, s36, 0x10100
	ds_read_b128 v[58:61], v218 offset:16384
	ds_read_b128 v[62:65], v218 offset:17408
	ds_read_b128 v[50:53], v218 offset:18432
	ds_read_b128 v[54:57], v218 offset:19456
	ds_read_b128 v[42:45], v218 offset:20480
	ds_read_b128 v[46:49], v218 offset:21504
	ds_read_b128 v[34:37], v218 offset:22528
	ds_read_b128 v[38:41], v218 offset:23552
	global_load_lds_dwordx4 v[70:71], off
	v_lshl_add_u64 v[70:71], v[208:209], 0, s[18:19]
	s_mov_b32 m0, s51
	s_addc_u32 s43, s37, 0
	global_load_lds_dwordx4 v[70:71], off
	v_lshl_add_u64 v[70:71], s[42:43], 0, v[198:199]
	s_mov_b32 m0, s52
	v_lshl_add_u64 v[210:211], s[40:41], 0, v[200:201]
	global_load_lds_dwordx4 v[70:71], off
	v_lshl_add_u64 v[70:71], s[42:43], 0, v[194:195]
	s_mov_b32 m0, s53
	v_lshl_add_u64 v[212:213], s[40:41], 0, v[196:197]
	global_load_lds_dwordx4 v[70:71], off
	v_lshl_add_u64 v[70:71], v[210:211], 0, s[18:19]
	s_mov_b32 m0, s54
	s_andn2_b64 vcc, exec, s[38:39]
	global_load_lds_dwordx4 v[70:71], off
	v_lshl_add_u64 v[70:71], v[212:213], 0, s[18:19]
	s_mov_b32 m0, s55
	s_nop 0
	global_load_lds_dwordx4 v[70:71], off
	s_cbranch_vccnz .LBB0_435
	s_waitcnt vmcnt(16)
	s_cbranch_execnz .LBB0_422

.LBB0_422:
	s_waitcnt lgkmcnt(0)
	s_barrier
	s_setprio 1
	v_mov_b64_e32 v[72:73], s[6:7]
	v_mov_b64_e32 v[188:189], s[6:7]
	v_mov_b64_e32 v[192:193], s[6:7]
	v_mov_b64_e32 v[180:181], s[6:7]
	v_mov_b64_e32 v[184:185], s[6:7]
	v_mov_b64_e32 v[164:165], s[6:7]
	v_mov_b64_e32 v[168:169], s[6:7]
	v_mov_b64_e32 v[148:149], s[6:7]
	v_mov_b64_e32 v[152:153], s[6:7]
	v_mov_b64_e32 v[70:71], s[4:5]
	v_mov_b64_e32 v[186:187], s[4:5]
	v_mov_b64_e32 v[190:191], s[4:5]
	v_mov_b64_e32 v[178:179], s[4:5]
	v_mov_b64_e32 v[182:183], s[4:5]
	v_mov_b64_e32 v[162:163], s[4:5]
	v_mov_b64_e32 v[166:167], s[4:5]
	v_mov_b64_e32 v[146:147], s[4:5]
	v_mov_b64_e32 v[150:151], s[4:5]
	s_waitcnt lgkmcnt(0)
	v_mfma_f32_16x16x128_f8f6f4 v[186:189], v[26:33], v[58:65], v[186:189]
	v_mfma_f32_16x16x128_f8f6f4 v[190:193], v[18:25], v[58:65], v[190:193]
	v_mfma_f32_16x16x128_f8f6f4 v[178:181], v[26:33], v[50:57], v[178:181]
	v_mfma_f32_16x16x128_f8f6f4 v[182:185], v[18:25], v[50:57], v[182:185]
	v_mfma_f32_16x16x128_f8f6f4 v[162:165], v[26:33], v[42:49], v[162:165]
	v_mfma_f32_16x16x128_f8f6f4 v[166:169], v[18:25], v[42:49], v[166:169]
	v_mfma_f32_16x16x128_f8f6f4 v[146:149], v[26:33], v[34:41], v[146:149]
	v_mfma_f32_16x16x128_f8f6f4 v[150:153], v[18:25], v[34:41], v[150:153]
	s_setprio 0
	s_setprio 1
	v_mov_b64_e32 v[124:125], s[6:7]
	v_mov_b64_e32 v[128:129], s[6:7]
	v_mov_b64_e32 v[116:117], s[6:7]
	v_mov_b64_e32 v[120:121], s[6:7]
	v_mov_b64_e32 v[108:109], s[6:7]
	v_mov_b64_e32 v[112:113], s[6:7]
	v_mov_b64_e32 v[96:97], s[6:7]
	v_mov_b64_e32 v[122:123], s[4:5]
	v_mov_b64_e32 v[126:127], s[4:5]
	v_mov_b64_e32 v[114:115], s[4:5]
	v_mov_b64_e32 v[118:119], s[4:5]
	v_mov_b64_e32 v[106:107], s[4:5]
	v_mov_b64_e32 v[110:111], s[4:5]
	v_mov_b64_e32 v[94:95], s[4:5]
	v_mfma_f32_16x16x128_f8f6f4 v[122:125], v[10:17], v[58:65], v[122:125]
	v_mfma_f32_16x16x128_f8f6f4 v[126:129], v[2:9], v[58:65], v[126:129]
	v_mfma_f32_16x16x128_f8f6f4 v[114:117], v[10:17], v[50:57], v[114:117]
	v_mfma_f32_16x16x128_f8f6f4 v[118:121], v[2:9], v[50:57], v[118:121]
	v_mfma_f32_16x16x128_f8f6f4 v[106:109], v[10:17], v[42:49], v[106:109]
	v_mfma_f32_16x16x128_f8f6f4 v[110:113], v[2:9], v[42:49], v[110:113]
	v_mfma_f32_16x16x128_f8f6f4 v[94:97], v[10:17], v[34:41], v[94:97]
	v_mfma_f32_16x16x128_f8f6f4 v[70:73], v[2:9], v[34:41], v[70:73]
	s_setprio 0
	s_barrier
	v_add_u32_e32 v221, s58, v1
	v_add_u32_e32 v222, s63, v1
	ds_read_b128 v[2:5], v221
	ds_read_b128 v[6:9], v221 offset:1024
	ds_read_b128 v[10:13], v221 offset:2048
	ds_read_b128 v[14:17], v221 offset:3072
	ds_read_b128 v[18:21], v222
	ds_read_b128 v[22:25], v222 offset:1024
	ds_read_b128 v[26:29], v222 offset:2048
	ds_read_b128 v[30:33], v222 offset:3072
	s_add_u32 s38, s40, 0x10100
	s_addc_u32 s39, s41, 0
	s_mov_b32 m0, s56
	v_lshl_add_u64 v[224:225], s[38:39], 0, v[200:201]
	ds_read_b128 v[34:37], v218 offset:32768
	ds_read_b128 v[38:41], v218 offset:33792
	ds_read_b128 v[42:45], v218 offset:34816
	ds_read_b128 v[46:49], v218 offset:35840
	ds_read_b128 v[50:53], v218 offset:36864
	ds_read_b128 v[54:57], v218 offset:37888
	ds_read_b128 v[58:61], v218 offset:38912
	ds_read_b128 v[62:65], v218 offset:39936
	global_load_lds_dwordx4 v[224:225], off
	v_lshl_add_u64 v[224:225], s[38:39], 0, v[196:197]
	s_mov_b32 m0, s57
	s_nop 0
	global_load_lds_dwordx4 v[224:225], off
	s_waitcnt vmcnt(8)
	s_waitcnt lgkmcnt(0)
	s_barrier
	s_setprio 1
	s_waitcnt lgkmcnt(0)
	v_mfma_f32_16x16x128_f8f6f4 v[170:173], v[2:9], v[34:41], v[170:173]
	v_mfma_f32_16x16x128_f8f6f4 v[174:177], v[10:17], v[34:41], v[174:177]
	v_mfma_f32_16x16x128_f8f6f4 v[154:157], v[2:9], v[42:49], v[154:157]
	v_mfma_f32_16x16x128_f8f6f4 v[158:161], v[10:17], v[42:49], v[158:161]
	v_mfma_f32_16x16x128_f8f6f4 v[138:141], v[2:9], v[50:57], v[138:141]
	v_mfma_f32_16x16x128_f8f6f4 v[142:145], v[10:17], v[50:57], v[142:145]
	v_mfma_f32_16x16x128_f8f6f4 v[130:133], v[2:9], v[58:65], v[130:133]
	v_mfma_f32_16x16x128_f8f6f4 v[134:137], v[10:17], v[58:65], v[134:137]
	s_setprio 0
	s_setprio 1
	v_mfma_f32_16x16x128_f8f6f4 v[98:101], v[18:25], v[34:41], v[98:101]
	v_mfma_f32_16x16x128_f8f6f4 v[102:105], v[26:33], v[34:41], v[102:105]
	v_mfma_f32_16x16x128_f8f6f4 v[86:89], v[18:25], v[42:49], v[86:89]
	v_mfma_f32_16x16x128_f8f6f4 v[90:93], v[26:33], v[42:49], v[90:93]
	v_mfma_f32_16x16x128_f8f6f4 v[78:81], v[18:25], v[50:57], v[78:81]
	v_mfma_f32_16x16x128_f8f6f4 v[82:85], v[26:33], v[50:57], v[82:85]
	v_mfma_f32_16x16x128_f8f6f4 v[74:77], v[18:25], v[58:65], v[74:77]
	v_mfma_f32_16x16x128_f8f6f4 v[66:69], v[26:33], v[58:65], v[66:69]
	s_setprio 0
	s_barrier
	s_mov_b32 m0, s59
	v_lshl_add_u64 v[206:207], v[206:207], 0, s[20:21]
	s_add_u32 s38, s36, 0x10180
	ds_read_b128 v[34:37], v218 offset:49152
	ds_read_b128 v[38:41], v218 offset:50176
	ds_read_b128 v[42:45], v218 offset:51200
	ds_read_b128 v[46:49], v218 offset:52224
	ds_read_b128 v[50:53], v218 offset:53248
	ds_read_b128 v[54:57], v218 offset:54272
	ds_read_b128 v[58:61], v218 offset:55296
	ds_read_b128 v[62:65], v218 offset:56320
	global_load_lds_dwordx4 v[206:207], off
	v_lshl_add_u64 v[206:207], v[208:209], 0, s[20:21]
	s_mov_b32 m0, s60
	s_addc_u32 s39, s37, 0
	global_load_lds_dwordx4 v[206:207], off
	v_lshl_add_u64 v[206:207], s[38:39], 0, v[198:199]
	s_mov_b32 m0, s64
	s_nop 0
	global_load_lds_dwordx4 v[206:207], off
	v_lshl_add_u64 v[206:207], s[38:39], 0, v[194:195]
	s_mov_b32 m0, s65
	s_nop 0
	global_load_lds_dwordx4 v[206:207], off
	v_lshl_add_u64 v[206:207], v[210:211], 0, s[20:21]
	s_mov_b32 m0, s61
	s_nop 0
	global_load_lds_dwordx4 v[206:207], off
	v_lshl_add_u64 v[206:207], v[212:213], 0, s[20:21]
	s_mov_b32 m0, s62
	s_nop 0
	global_load_lds_dwordx4 v[206:207], off
	s_waitcnt vmcnt(8)
	s_waitcnt lgkmcnt(0)
	s_barrier
	s_setprio 1
	s_waitcnt lgkmcnt(0)
	v_mfma_f32_16x16x128_f8f6f4 v[186:189], v[2:9], v[34:41], v[186:189]
	v_mfma_f32_16x16x128_f8f6f4 v[190:193], v[10:17], v[34:41], v[190:193]
	v_mfma_f32_16x16x128_f8f6f4 v[178:181], v[2:9], v[42:49], v[178:181]
	v_mfma_f32_16x16x128_f8f6f4 v[182:185], v[10:17], v[42:49], v[182:185]
	v_mfma_f32_16x16x128_f8f6f4 v[162:165], v[2:9], v[50:57], v[162:165]
	v_mfma_f32_16x16x128_f8f6f4 v[166:169], v[10:17], v[50:57], v[166:169]
	v_mfma_f32_16x16x128_f8f6f4 v[146:149], v[2:9], v[58:65], v[146:149]
	v_mfma_f32_16x16x128_f8f6f4 v[150:153], v[10:17], v[58:65], v[150:153]
	s_setprio 0
	s_setprio 1
	v_mfma_f32_16x16x128_f8f6f4 v[122:125], v[18:25], v[34:41], v[122:125]
	v_mfma_f32_16x16x128_f8f6f4 v[126:129], v[26:33], v[34:41], v[126:129]
	v_mfma_f32_16x16x128_f8f6f4 v[114:117], v[18:25], v[42:49], v[114:117]
	v_mfma_f32_16x16x128_f8f6f4 v[118:121], v[26:33], v[42:49], v[118:121]
	v_mfma_f32_16x16x128_f8f6f4 v[106:109], v[18:25], v[50:57], v[106:109]
	v_mfma_f32_16x16x128_f8f6f4 v[110:113], v[26:33], v[50:57], v[110:113]
	v_mfma_f32_16x16x128_f8f6f4 v[94:97], v[18:25], v[58:65], v[94:97]
	v_mfma_f32_16x16x128_f8f6f4 v[70:73], v[26:33], v[58:65], v[70:73]
	s_setprio 0
	s_barrier
	s_mov_b32 s42, 0
	ds_read_b128 v[26:29], v216
	ds_read_b128 v[30:33], v216 offset:1024
	ds_read_b128 v[18:21], v216 offset:2048
	ds_read_b128 v[22:25], v216 offset:3072
	ds_read_b128 v[10:13], v217
	ds_read_b128 v[14:17], v217 offset:1024
	ds_read_b128 v[2:5], v217 offset:2048
	ds_read_b128 v[6:9], v217 offset:3072
	s_add_u32 s38, s40, 0x10180
	s_addc_u32 s39, s41, 0
	s_mov_b32 m0, s31
	v_lshl_add_u64 v[206:207], s[38:39], 0, v[200:201]
	ds_read_b128 v[58:61], v218
	ds_read_b128 v[62:65], v218 offset:1024
	ds_read_b128 v[50:53], v218 offset:2048
	ds_read_b128 v[54:57], v218 offset:3072
	ds_read_b128 v[42:45], v218 offset:4096
	ds_read_b128 v[46:49], v218 offset:5120
	ds_read_b128 v[34:37], v218 offset:6144
	ds_read_b128 v[38:41], v218 offset:7168
	global_load_lds_dwordx4 v[206:207], off
	v_lshl_add_u64 v[206:207], s[38:39], 0, v[196:197]
	s_mov_b32 m0, s29
	s_cmp_lg_u32 s42, 0
	global_load_lds_dwordx4 v[206:207], off
	s_cselect_b64 s[44:45], -1, 0
	s_cmp_eq_u32 s42, 0
	s_cbranch_scc1 .LBB0_436
	s_waitcnt vmcnt(16)
	s_cbranch_execnz .LBB0_425

.LBB0_425:
	s_ashr_i32 s29, s28, 31
	s_lshl_b64 s[38:39], s[28:29], 17
	s_add_u32 s38, s46, s38
	s_addc_u32 s39, s47, s39
	s_and_b64 s[42:43], s[2:3], exec
	s_cselect_b32 s43, s39, s41
	s_cselect_b32 s42, s38, s40
	s_ashr_i32 s31, s30, 31
	s_lshl_b64 s[40:41], s[30:31], 17
	s_add_u32 s40, s48, s40
	s_addc_u32 s41, s49, s41
	s_waitcnt lgkmcnt(0)
	s_and_b64 s[68:69], s[2:3], exec
	s_cselect_b32 s37, s41, s37
	s_cselect_b32 s36, s40, s36
	s_barrier
	s_setprio 1
	s_waitcnt lgkmcnt(0)
	v_mfma_f32_16x16x128_f8f6f4 v[170:173], v[26:33], v[58:65], v[170:173]
	v_mfma_f32_16x16x128_f8f6f4 v[174:177], v[18:25], v[58:65], v[174:177]
	v_mfma_f32_16x16x128_f8f6f4 v[154:157], v[26:33], v[50:57], v[154:157]
	v_mfma_f32_16x16x128_f8f6f4 v[158:161], v[18:25], v[50:57], v[158:161]
	v_mfma_f32_16x16x128_f8f6f4 v[138:141], v[26:33], v[42:49], v[138:141]
	v_mfma_f32_16x16x128_f8f6f4 v[142:145], v[18:25], v[42:49], v[142:145]
	v_mfma_f32_16x16x128_f8f6f4 v[130:133], v[26:33], v[34:41], v[130:133]
	v_mfma_f32_16x16x128_f8f6f4 v[134:137], v[18:25], v[34:41], v[134:137]
	s_setprio 0
	s_setprio 1
	v_mfma_f32_16x16x128_f8f6f4 v[98:101], v[10:17], v[58:65], v[98:101]
	v_mfma_f32_16x16x128_f8f6f4 v[102:105], v[2:9], v[58:65], v[102:105]
	v_mfma_f32_16x16x128_f8f6f4 v[86:89], v[10:17], v[50:57], v[86:89]
	v_mfma_f32_16x16x128_f8f6f4 v[90:93], v[2:9], v[50:57], v[90:93]
	v_mfma_f32_16x16x128_f8f6f4 v[78:81], v[10:17], v[42:49], v[78:81]
	v_mfma_f32_16x16x128_f8f6f4 v[82:85], v[2:9], v[42:49], v[82:85]
	v_mfma_f32_16x16x128_f8f6f4 v[74:77], v[10:17], v[34:41], v[74:77]
	v_mfma_f32_16x16x128_f8f6f4 v[66:69], v[2:9], v[34:41], v[66:69]
	s_setprio 0
	s_barrier
	s_mov_b32 m0, s35
	v_lshl_add_u64 v[206:207], s[36:37], 0, v[198:199]
	s_add_u32 s68, s36, 0x10000
	ds_read_b128 v[58:61], v218 offset:16384
	ds_read_b128 v[62:65], v218 offset:17408
	ds_read_b128 v[50:53], v218 offset:18432
	ds_read_b128 v[54:57], v218 offset:19456
	ds_read_b128 v[42:45], v218 offset:20480
	ds_read_b128 v[46:49], v218 offset:21504
	ds_read_b128 v[34:37], v218 offset:22528
	ds_read_b128 v[38:41], v218 offset:23552
	global_load_lds_dwordx4 v[206:207], off
	v_lshl_add_u64 v[208:209], s[36:37], 0, v[194:195]
	s_mov_b32 m0, s51
	s_addc_u32 s69, s37, 0
	global_load_lds_dwordx4 v[208:209], off
	v_lshl_add_u64 v[210:211], s[68:69], 0, v[198:199]
	s_mov_b32 m0, s52
	v_lshl_add_u64 v[212:213], s[42:43], 0, v[196:197]
	global_load_lds_dwordx4 v[210:211], off
	v_lshl_add_u64 v[210:211], s[68:69], 0, v[194:195]
	s_mov_b32 m0, s53
	s_andn2_b64 vcc, exec, s[44:45]
	global_load_lds_dwordx4 v[210:211], off
	v_lshl_add_u64 v[210:211], s[42:43], 0, v[200:201]
	s_mov_b32 m0, s54
	s_nop 0
	global_load_lds_dwordx4 v[210:211], off
	s_mov_b32 m0, s55
	s_nop 0
	global_load_lds_dwordx4 v[212:213], off
	s_cbranch_vccnz .LBB0_437
	s_waitcnt vmcnt(16)
	s_cbranch_execnz .LBB0_428

.LBB0_428:
	s_waitcnt lgkmcnt(0)
	s_barrier
	s_setprio 1
	s_waitcnt lgkmcnt(0)
	v_mfma_f32_16x16x128_f8f6f4 v[186:189], v[26:33], v[58:65], v[186:189]
	v_mfma_f32_16x16x128_f8f6f4 v[190:193], v[18:25], v[58:65], v[190:193]
	v_mfma_f32_16x16x128_f8f6f4 v[178:181], v[26:33], v[50:57], v[178:181]
	v_mfma_f32_16x16x128_f8f6f4 v[182:185], v[18:25], v[50:57], v[182:185]
	v_mfma_f32_16x16x128_f8f6f4 v[162:165], v[26:33], v[42:49], v[162:165]
	v_mfma_f32_16x16x128_f8f6f4 v[166:169], v[18:25], v[42:49], v[166:169]
	v_mfma_f32_16x16x128_f8f6f4 v[146:149], v[26:33], v[34:41], v[146:149]
	v_mfma_f32_16x16x128_f8f6f4 v[150:153], v[18:25], v[34:41], v[150:153]
	s_setprio 0
	s_setprio 1
	v_mfma_f32_16x16x128_f8f6f4 v[122:125], v[10:17], v[58:65], v[122:125]
	v_mfma_f32_16x16x128_f8f6f4 v[126:129], v[2:9], v[58:65], v[126:129]
	v_mfma_f32_16x16x128_f8f6f4 v[114:117], v[10:17], v[50:57], v[114:117]
	v_mfma_f32_16x16x128_f8f6f4 v[118:121], v[2:9], v[50:57], v[118:121]
	v_mfma_f32_16x16x128_f8f6f4 v[106:109], v[10:17], v[42:49], v[106:109]
	v_mfma_f32_16x16x128_f8f6f4 v[110:113], v[2:9], v[42:49], v[110:113]
	v_mfma_f32_16x16x128_f8f6f4 v[94:97], v[10:17], v[34:41], v[94:97]
	v_mfma_f32_16x16x128_f8f6f4 v[70:73], v[2:9], v[34:41], v[70:73]
	s_setprio 0
	s_barrier
	ds_read_b128 v[2:5], v221
	ds_read_b128 v[6:9], v221 offset:1024
	ds_read_b128 v[10:13], v221 offset:2048
	ds_read_b128 v[14:17], v221 offset:3072
	ds_read_b128 v[18:21], v222
	ds_read_b128 v[22:25], v222 offset:1024
	ds_read_b128 v[26:29], v222 offset:2048
	ds_read_b128 v[30:33], v222 offset:3072
	s_add_u32 s42, s42, 0x10000
	s_addc_u32 s43, s43, 0
	s_mov_b32 m0, s56
	v_lshl_add_u64 v[222:223], s[42:43], 0, v[200:201]
	ds_read_b128 v[34:37], v218 offset:32768
	ds_read_b128 v[38:41], v218 offset:33792
	ds_read_b128 v[42:45], v218 offset:34816
	ds_read_b128 v[46:49], v218 offset:35840
	ds_read_b128 v[50:53], v218 offset:36864
	ds_read_b128 v[54:57], v218 offset:37888
	ds_read_b128 v[58:61], v218 offset:38912
	ds_read_b128 v[62:65], v218 offset:39936
	global_load_lds_dwordx4 v[222:223], off
	v_lshl_add_u64 v[222:223], s[42:43], 0, v[196:197]
	s_mov_b32 m0, s57
	s_nop 0
	global_load_lds_dwordx4 v[222:223], off
	s_waitcnt vmcnt(8)
	s_waitcnt lgkmcnt(0)
	s_barrier
	s_setprio 1
	s_waitcnt lgkmcnt(0)
	v_mfma_f32_16x16x128_f8f6f4 v[170:173], v[2:9], v[34:41], v[170:173]
	v_mfma_f32_16x16x128_f8f6f4 v[174:177], v[10:17], v[34:41], v[174:177]
	v_mfma_f32_16x16x128_f8f6f4 v[154:157], v[2:9], v[42:49], v[154:157]
	v_mfma_f32_16x16x128_f8f6f4 v[158:161], v[10:17], v[42:49], v[158:161]
	v_mfma_f32_16x16x128_f8f6f4 v[138:141], v[2:9], v[50:57], v[138:141]
	v_mfma_f32_16x16x128_f8f6f4 v[142:145], v[10:17], v[50:57], v[142:145]
	v_mfma_f32_16x16x128_f8f6f4 v[130:133], v[2:9], v[58:65], v[130:133]
	v_mfma_f32_16x16x128_f8f6f4 v[134:137], v[10:17], v[58:65], v[134:137]
	s_setprio 0
	s_setprio 1
	v_mfma_f32_16x16x128_f8f6f4 v[98:101], v[18:25], v[34:41], v[98:101]
	v_mfma_f32_16x16x128_f8f6f4 v[102:105], v[26:33], v[34:41], v[102:105]
	v_mfma_f32_16x16x128_f8f6f4 v[86:89], v[18:25], v[42:49], v[86:89]
	v_mfma_f32_16x16x128_f8f6f4 v[90:93], v[26:33], v[42:49], v[90:93]
	v_mfma_f32_16x16x128_f8f6f4 v[78:81], v[18:25], v[50:57], v[78:81]
	v_mfma_f32_16x16x128_f8f6f4 v[82:85], v[26:33], v[50:57], v[82:85]
	v_mfma_f32_16x16x128_f8f6f4 v[74:77], v[18:25], v[58:65], v[74:77]
	v_mfma_f32_16x16x128_f8f6f4 v[66:69], v[26:33], v[58:65], v[66:69]
	s_setprio 0
	s_barrier
	s_mov_b32 m0, s59
	v_lshl_add_u64 v[206:207], v[206:207], 0, s[12:13]
	s_add_u32 s36, s36, 0x10080
	ds_read_b128 v[34:37], v218 offset:49152
	ds_read_b128 v[38:41], v218 offset:50176
	ds_read_b128 v[42:45], v218 offset:51200
	ds_read_b128 v[46:49], v218 offset:52224
	ds_read_b128 v[50:53], v218 offset:53248
	ds_read_b128 v[54:57], v218 offset:54272
	ds_read_b128 v[58:61], v218 offset:55296
	ds_read_b128 v[62:65], v218 offset:56320
	global_load_lds_dwordx4 v[206:207], off
	v_lshl_add_u64 v[206:207], v[208:209], 0, s[12:13]
	s_mov_b32 m0, s60
	s_addc_u32 s37, s37, 0
	global_load_lds_dwordx4 v[206:207], off
	v_lshl_add_u64 v[206:207], s[36:37], 0, v[198:199]
	s_mov_b32 m0, s64
	s_nop 0
	global_load_lds_dwordx4 v[206:207], off
	v_lshl_add_u64 v[206:207], s[36:37], 0, v[194:195]
	s_mov_b32 m0, s65
	s_nop 0
	global_load_lds_dwordx4 v[206:207], off
	v_lshl_add_u64 v[206:207], v[210:211], 0, s[12:13]
	s_mov_b32 m0, s61
	s_nop 0
	global_load_lds_dwordx4 v[206:207], off
	v_lshl_add_u64 v[206:207], v[212:213], 0, s[12:13]
	s_mov_b32 m0, s62
	s_nop 0
	global_load_lds_dwordx4 v[206:207], off
	s_waitcnt vmcnt(8)
	s_waitcnt lgkmcnt(0)
	s_barrier
	s_setprio 1
	s_waitcnt lgkmcnt(0)
	v_mfma_f32_16x16x128_f8f6f4 v[186:189], v[2:9], v[34:41], v[186:189]
	v_mfma_f32_16x16x128_f8f6f4 v[190:193], v[10:17], v[34:41], v[190:193]
	v_mfma_f32_16x16x128_f8f6f4 v[178:181], v[2:9], v[42:49], v[178:181]
	v_mfma_f32_16x16x128_f8f6f4 v[182:185], v[10:17], v[42:49], v[182:185]
	v_mfma_f32_16x16x128_f8f6f4 v[162:165], v[2:9], v[50:57], v[162:165]
	v_mfma_f32_16x16x128_f8f6f4 v[166:169], v[10:17], v[50:57], v[166:169]
	v_mfma_f32_16x16x128_f8f6f4 v[146:149], v[2:9], v[58:65], v[146:149]
	v_mfma_f32_16x16x128_f8f6f4 v[150:153], v[10:17], v[58:65], v[150:153]
	s_setprio 0
	s_setprio 1
	v_mfma_f32_16x16x128_f8f6f4 v[122:125], v[18:25], v[34:41], v[122:125]
	v_mfma_f32_16x16x128_f8f6f4 v[126:129], v[26:33], v[34:41], v[126:129]
	v_mfma_f32_16x16x128_f8f6f4 v[114:117], v[18:25], v[42:49], v[114:117]
	v_mfma_f32_16x16x128_f8f6f4 v[118:121], v[26:33], v[42:49], v[118:121]
	v_mfma_f32_16x16x128_f8f6f4 v[106:109], v[18:25], v[50:57], v[106:109]
	v_mfma_f32_16x16x128_f8f6f4 v[110:113], v[26:33], v[50:57], v[110:113]
	v_mfma_f32_16x16x128_f8f6f4 v[94:97], v[18:25], v[58:65], v[94:97]
	v_mfma_f32_16x16x128_f8f6f4 v[70:73], v[26:33], v[58:65], v[70:73]
	s_setprio 0
	s_barrier
	s_andn2_b64 vcc, exec, s[14:15]
	s_cbranch_vccnz .LBB0_430
	s_barrier

.LBB0_506:
	s_waitcnt vmcnt(0)
	v_lshlrev_b32_e32 v58, 16, v46
	v_and_b32_e32 v46, 0xffff0000, v46
	v_mov_b32_e32 v146, v171
	v_cvt_pk_fp8_f32 v146, v58, v46
	v_lshlrev_b32_e32 v58, 16, v48
	v_and_b32_e32 v48, 0xffff0000, v48
	v_mov_b32_e32 v147, v171
	v_cvt_pk_fp8_f32 v147, v58, v48
	v_lshlrev_b32_e32 v46, 16, v47
	v_and_b32_e32 v47, 0xffff0000, v47
	v_cvt_pk_fp8_f32 v146, v46, v47 op_sel:[0,0,1]
	v_lshlrev_b32_e32 v46, 16, v49
	v_and_b32_e32 v47, 0xffff0000, v49
	v_cvt_pk_fp8_f32 v147, v46, v47 op_sel:[0,0,1]
	v_lshlrev_b32_e32 v46, 16, v42
	v_and_b32_e32 v42, 0xffff0000, v42
	v_mov_b32_e32 v148, v171
	v_cvt_pk_fp8_f32 v148, v46, v42
	v_lshlrev_b32_e32 v46, 16, v44
	v_and_b32_e32 v44, 0xffff0000, v44
	v_mov_b32_e32 v149, v171
	v_cvt_pk_fp8_f32 v149, v46, v44
	v_lshlrev_b32_e32 v42, 16, v43
	v_and_b32_e32 v43, 0xffff0000, v43
	v_cvt_pk_fp8_f32 v148, v42, v43 op_sel:[0,0,1]
	v_lshlrev_b32_e32 v42, 16, v45
	v_and_b32_e32 v43, 0xffff0000, v45
	v_cvt_pk_fp8_f32 v149, v42, v43 op_sel:[0,0,1]
	v_lshlrev_b32_e32 v42, 16, v38
	v_and_b32_e32 v38, 0xffff0000, v38
	v_mov_b32_e32 v150, v171
	v_cvt_pk_fp8_f32 v150, v42, v38
	v_lshlrev_b32_e32 v42, 16, v40
	v_and_b32_e32 v40, 0xffff0000, v40
	v_mov_b32_e32 v151, v171
	v_cvt_pk_fp8_f32 v151, v42, v40
	v_lshlrev_b32_e32 v38, 16, v39
	v_and_b32_e32 v39, 0xffff0000, v39
	v_cvt_pk_fp8_f32 v150, v38, v39 op_sel:[0,0,1]
	v_lshlrev_b32_e32 v38, 16, v41
	v_and_b32_e32 v39, 0xffff0000, v41
	v_cvt_pk_fp8_f32 v151, v38, v39 op_sel:[0,0,1]
	v_lshlrev_b32_e32 v38, 16, v34
	v_and_b32_e32 v34, 0xffff0000, v34
	v_mov_b32_e32 v152, v171
	v_cvt_pk_fp8_f32 v152, v38, v34
	v_lshlrev_b32_e32 v38, 16, v36
	v_and_b32_e32 v36, 0xffff0000, v36
	v_mov_b32_e32 v153, v171
	v_cvt_pk_fp8_f32 v153, v38, v36
	v_lshlrev_b32_e32 v34, 16, v35
	v_and_b32_e32 v35, 0xffff0000, v35
	v_cvt_pk_fp8_f32 v152, v34, v35 op_sel:[0,0,1]
	v_lshlrev_b32_e32 v34, 16, v37
	v_and_b32_e32 v35, 0xffff0000, v37
	v_cvt_pk_fp8_f32 v153, v34, v35 op_sel:[0,0,1]
	v_lshlrev_b32_e32 v34, 16, v30
	v_and_b32_e32 v30, 0xffff0000, v30
	v_mov_b32_e32 v154, v171
	v_cvt_pk_fp8_f32 v154, v34, v30
	v_lshlrev_b32_e32 v34, 16, v32
	v_and_b32_e32 v32, 0xffff0000, v32
	v_mov_b32_e32 v155, v171
	v_cvt_pk_fp8_f32 v155, v34, v32
	v_lshlrev_b32_e32 v30, 16, v31
	v_and_b32_e32 v31, 0xffff0000, v31
	v_cvt_pk_fp8_f32 v154, v30, v31 op_sel:[0,0,1]
	v_lshlrev_b32_e32 v30, 16, v33
	v_and_b32_e32 v31, 0xffff0000, v33
	v_cvt_pk_fp8_f32 v155, v30, v31 op_sel:[0,0,1]
	v_lshlrev_b32_e32 v30, 16, v26
	v_and_b32_e32 v26, 0xffff0000, v26
	v_mov_b32_e32 v156, v171
	v_cvt_pk_fp8_f32 v156, v30, v26
	v_lshlrev_b32_e32 v30, 16, v28
	v_and_b32_e32 v28, 0xffff0000, v28
	v_mov_b32_e32 v157, v171
	v_cvt_pk_fp8_f32 v157, v30, v28
	v_lshlrev_b32_e32 v26, 16, v27
	v_and_b32_e32 v27, 0xffff0000, v27
	v_cvt_pk_fp8_f32 v156, v26, v27 op_sel:[0,0,1]
	v_lshlrev_b32_e32 v26, 16, v29
	v_and_b32_e32 v27, 0xffff0000, v29
	v_cvt_pk_fp8_f32 v157, v26, v27 op_sel:[0,0,1]
	v_lshlrev_b32_e32 v26, 16, v22
	v_and_b32_e32 v22, 0xffff0000, v22
	v_mov_b32_e32 v158, v171
	v_cvt_pk_fp8_f32 v158, v26, v22
	v_lshlrev_b32_e32 v26, 16, v24
	v_and_b32_e32 v24, 0xffff0000, v24
	v_mov_b32_e32 v159, v171
	v_cvt_pk_fp8_f32 v159, v26, v24
	v_lshlrev_b32_e32 v22, 16, v23
	v_and_b32_e32 v23, 0xffff0000, v23
	v_cvt_pk_fp8_f32 v158, v22, v23 op_sel:[0,0,1]
	v_lshlrev_b32_e32 v22, 16, v25
	v_and_b32_e32 v23, 0xffff0000, v25
	v_cvt_pk_fp8_f32 v159, v22, v23 op_sel:[0,0,1]
	v_lshlrev_b32_e32 v22, 16, v18
	v_and_b32_e32 v18, 0xffff0000, v18
	v_mov_b32_e32 v160, v171
	v_cvt_pk_fp8_f32 v160, v22, v18
	v_lshlrev_b32_e32 v22, 16, v20
	v_and_b32_e32 v20, 0xffff0000, v20
	v_mov_b32_e32 v161, v171
	v_cvt_pk_fp8_f32 v161, v22, v20
	v_lshlrev_b32_e32 v18, 16, v19
	v_and_b32_e32 v19, 0xffff0000, v19
	v_cvt_pk_fp8_f32 v160, v18, v19 op_sel:[0,0,1]
	v_lshlrev_b32_e32 v18, 16, v21
	v_and_b32_e32 v19, 0xffff0000, v21
	v_cvt_pk_fp8_f32 v161, v18, v19 op_sel:[0,0,1]
	v_lshlrev_b32_e32 v18, 16, v14
	v_and_b32_e32 v14, 0xffff0000, v14
	v_mov_b32_e32 v162, v171
	v_cvt_pk_fp8_f32 v162, v18, v14
	v_lshlrev_b32_e32 v18, 16, v16
	v_and_b32_e32 v16, 0xffff0000, v16
	v_mov_b32_e32 v163, v171
	v_cvt_pk_fp8_f32 v163, v18, v16
	v_lshlrev_b32_e32 v14, 16, v15
	v_and_b32_e32 v15, 0xffff0000, v15
	v_cvt_pk_fp8_f32 v162, v14, v15 op_sel:[0,0,1]
	v_lshlrev_b32_e32 v14, 16, v17
	v_and_b32_e32 v15, 0xffff0000, v17
	v_cvt_pk_fp8_f32 v163, v14, v15 op_sel:[0,0,1]
	v_lshlrev_b32_e32 v14, 16, v10
	v_and_b32_e32 v10, 0xffff0000, v10
	v_mov_b32_e32 v164, v171
	v_cvt_pk_fp8_f32 v164, v14, v10
	v_lshlrev_b32_e32 v14, 16, v12
	v_and_b32_e32 v12, 0xffff0000, v12
	v_mov_b32_e32 v165, v171
	v_cvt_pk_fp8_f32 v165, v14, v12
	v_lshlrev_b32_e32 v10, 16, v11
	v_and_b32_e32 v11, 0xffff0000, v11
	v_cvt_pk_fp8_f32 v164, v10, v11 op_sel:[0,0,1]
	v_lshlrev_b32_e32 v10, 16, v13
	v_and_b32_e32 v11, 0xffff0000, v13
	v_cvt_pk_fp8_f32 v165, v10, v11 op_sel:[0,0,1]
	v_lshlrev_b32_e32 v10, 16, v6
	v_and_b32_e32 v6, 0xffff0000, v6
	v_mov_b32_e32 v166, v171
	v_cvt_pk_fp8_f32 v166, v10, v6
	v_lshlrev_b32_e32 v10, 16, v8
	v_and_b32_e32 v8, 0xffff0000, v8
	v_mov_b32_e32 v167, v171
	v_cvt_pk_fp8_f32 v167, v10, v8
	v_lshlrev_b32_e32 v6, 16, v7
	v_and_b32_e32 v7, 0xffff0000, v7
	v_cvt_pk_fp8_f32 v166, v6, v7 op_sel:[0,0,1]
	v_lshlrev_b32_e32 v6, 16, v9
	v_and_b32_e32 v7, 0xffff0000, v9
	v_cvt_pk_fp8_f32 v167, v6, v7 op_sel:[0,0,1]
	v_lshlrev_b32_e32 v6, 16, v2
	v_and_b32_e32 v2, 0xffff0000, v2
	v_mov_b32_e32 v168, v171
	v_cvt_pk_fp8_f32 v168, v6, v2
	v_lshlrev_b32_e32 v6, 16, v4
	v_and_b32_e32 v4, 0xffff0000, v4
	v_mov_b32_e32 v169, v171
	v_cvt_pk_fp8_f32 v169, v6, v4
	v_lshlrev_b32_e32 v2, 16, v3
	v_and_b32_e32 v3, 0xffff0000, v3
	v_cvt_pk_fp8_f32 v168, v2, v3 op_sel:[0,0,1]
	v_lshlrev_b32_e32 v2, 16, v5
	v_and_b32_e32 v3, 0xffff0000, v5
	v_cvt_pk_fp8_f32 v169, v2, v3 op_sel:[0,0,1]
	v_lshrrev_b32_e32 v2, 1, v55
	v_and_b32_e32 v3, 8, v55
	v_and_or_b32 v2, v2, 3, v3
	v_bfe_u32 v58, v55, 5, 1
	v_lshlrev_b32_e32 v2, 7, v2
	v_lshl_or_b32 v10, v58, 9, v2
	v_lshlrev_b32_e32 v2, 3, v55
	v_lshlrev_b32_e32 v42, 3, v52
	v_or_b32_e32 v61, 32, v52
	v_and_b32_e32 v11, 8, v2
	s_waitcnt lgkmcnt(0)
	v_bitop3_b32 v12, v42, v56, s45 bitop3:0x6c
	v_lshl_add_u32 v43, v52, 7, s63
	v_or_b32_e32 v2, 16, v56
	v_lshl_add_u32 v44, v61, 7, s63
	s_barrier
	v_add_u32_e32 v213, v43, v12
	v_bitop3_b32 v13, v42, v2, s45 bitop3:0x6c
	v_add_u32_e32 v215, v44, v12
	v_add_u32_e32 v214, v43, v13
	ds_read_b128 v[2:5], v213 offset:32768
	ds_read_b128 v[6:9], v214 offset:32768
	v_add_u32_e32 v216, v44, v13
	ds_read_b128 v[34:37], v215 offset:32768
	ds_read_b128 v[38:41], v216 offset:32768
	v_bfe_u32 v59, v55, 1, 3
	v_add3_u32 v62, v11, s63, v10
	v_bitop3_b32 v10, v57, v59, 1 bitop3:0x6c
	v_lshl_add_u32 v208, v10, 4, v62
	s_waitcnt lgkmcnt(0)
	v_mfma_f32_32x32x64_f8f6f4 v[18:33], v[2:9], v[146:153], 0
	v_mfma_f32_32x32x64_f8f6f4 v[2:17], v[34:41], v[146:153], 0
	v_or_b32_e32 v34, 64, v56
	v_bitop3_b32 v45, v42, v34, s45 bitop3:0x6c
	v_or_b32_e32 v34, 0x50, v56
	v_add_u32_e32 v217, v43, v45
	v_bitop3_b32 v42, v42, v34, s45 bitop3:0x6c
	v_add_u32_e32 v218, v43, v42
	ds_read_b128 v[34:37], v217 offset:32768
	ds_read_b128 v[38:41], v218 offset:32768
	v_add_u32_e32 v211, v44, v45
	v_add_u32_e32 v212, v44, v42
	ds_read_b128 v[42:45], v211 offset:32768
	ds_read_b128 v[46:49], v212 offset:32768
	s_waitcnt lgkmcnt(2)
	v_mfma_f32_32x32x64_f8f6f4 v[18:33], v[34:41], v[154:161], v[18:33]
	v_lshlrev_b32_e32 v34, 1, v58
	v_lshrrev_b32_e32 v35, 2, v55
	v_and_b32_e32 v199, 63, v55
	v_and_b32_e32 v60, 1, v57
	v_lshlrev_b32_e32 v57, 6, v52
	v_bfe_u32 v36, v55, 2, 2
	v_bitop3_b32 v35, v34, v35, 3 bitop3:0x78
	v_lshlrev_b32_e32 v55, 6, v61
	s_waitcnt lgkmcnt(0)
	v_mfma_f32_32x32x64_f8f6f4 v[2:17], v[42:49], v[154:161], v[2:17]
	v_lshlrev_b32_e32 v219, 4, v35
	v_add_u32_e32 v35, s37, v57
	v_bitop3_b32 v34, v34, v36, 1 bitop3:0x36
	v_add_u32_e32 v42, s37, v55
	v_add_u32_e32 v220, v35, v219
	v_lshlrev_b32_e32 v221, 4, v34
	v_add_u32_e32 v223, v42, v219
	v_add_u32_e32 v222, v35, v221
	ds_read_b128 v[34:37], v220
	ds_read_b128 v[38:41], v222
	v_add_u32_e32 v224, v42, v221
	ds_read_b128 v[42:45], v223
	ds_read_b128 v[46:49], v224
	s_waitcnt lgkmcnt(2)
	v_mfma_f32_32x32x64_f8f6f4 v[18:33], v[34:41], v[162:169], v[18:33]
	s_waitcnt lgkmcnt(0)
	v_mfma_f32_32x32x64_f8f6f4 v[2:17], v[42:49], v[162:169], v[2:17]
	s_nop 0
	s_nop 15
	s_nop 7
	s_and_b32 s2, s54, 0x3fffffc0
	v_max_f32_e32 v34, v19, v19
	v_max_f32_e32 v35, v18, v18
	v_max_f32_e32 v34, v35, v34
	v_max3_f32 v34, v34, v20, v21
	v_max3_f32 v34, v34, v22, v23
	v_max3_f32 v34, v34, v24, v25
	v_max3_f32 v34, v34, v26, v27
	v_max3_f32 v34, v34, v28, v29
	v_max3_f32 v34, v34, v30, v31
	v_max3_f32 v34, v34, v32, v33
	v_max3_f32 v34, v34, v2, v3
	v_max3_f32 v34, v34, v4, v5
	v_max3_f32 v34, v34, v6, v7
	v_max3_f32 v34, v34, v8, v9
	v_max3_f32 v34, v34, v10, v11
	v_max3_f32 v34, v34, v12, v13
	v_max3_f32 v34, v34, v14, v15
	v_max3_f32 v34, v34, v16, v17
	v_mov_b32_e32 v35, v34
	s_nop 1
	v_permlane32_swap_b32_e32 v34, v35
	v_max_f32_e32 v35, v35, v35
	v_max_f32_e32 v34, v34, v34
	v_max_f32_e32 v34, v34, v35
	s_lshl_b32 s2, s2, 2
	v_add_f32_e32 v35, 0x7149f2ca, v34
	s_add_i32 s54, s36, s2
	v_cmp_ge_f32_e32 vcc, s46, v35
	s_cmp_eq_u64 vcc, exec
	v_max_f32_e32 v34, 0xf149f2ca, v34
	s_cselect_b64 vcc, -1, 0
	v_cndmask_b32_e32 v233, v34, v198, vcc
	v_sub_f32_e32 v36, 0xf149f2ca, v34
	v_fma_f32 v34, v233, s47, 4.0
	v_mov_b32_e32 v35, v34
	s_add_u32 s2, s26, s28
	v_fmac_f32_e32 v35, 0x3dd53b94, v33
	s_addc_u32 s3, s27, s29
	s_add_i32 s55, s63, s55
	v_pk_fma_f32 v[66:67], v[2:3], s[6:7], v[34:35] op_sel_hi:[1,0,0]
	v_lshl_add_u64 v[2:3], s[2:3], 0, v[174:175]
	s_add_i32 s58, s55, 0x4000
	v_lshl_add_u64 v[2:3], v[2:3], 0, s[8:9]
	s_mov_b32 m0, s58
	v_lshl_add_u64 v[176:177], s[24:25], 0, v[172:173]
	global_load_lds_dwordx4 v[2:3], off
	s_add_u32 s24, s40, s53
	s_addc_u32 s25, s41, 0
	s_add_u32 s24, s24, s28
	v_mul_f32_e32 v36, 0x3dd53b94, v36
	s_addc_u32 s25, s25, s29
	v_bitop3_b32 v56, v60, v59, 2 bitop3:0x36
	v_exp_f32_e32 v36, v36
	v_fmamk_f32 v18, v18, 0x3dd53b94, v34
	v_fmamk_f32 v19, v19, 0x3dd53b94, v34
	v_fmamk_f32 v20, v20, 0x3dd53b94, v34
	v_fmamk_f32 v21, v21, 0x3dd53b94, v34
	v_fmamk_f32 v22, v22, 0x3dd53b94, v34
	v_fmamk_f32 v23, v23, 0x3dd53b94, v34
	v_fmamk_f32 v24, v24, 0x3dd53b94, v34
	v_fmamk_f32 v25, v25, 0x3dd53b94, v34
	v_fmamk_f32 v26, v26, 0x3dd53b94, v34
	v_fmamk_f32 v27, v27, 0x3dd53b94, v34
	v_fmamk_f32 v28, v28, 0x3dd53b94, v34
	v_fmamk_f32 v29, v29, 0x3dd53b94, v34
	v_fmamk_f32 v30, v30, 0x3dd53b94, v34
	v_fmamk_f32 v31, v31, 0x3dd53b94, v34
	v_fmamk_f32 v32, v32, 0x3dd53b94, v34
	v_lshl_add_u64 v[184:185], s[24:25], 0, v[174:175]
	s_add_u32 s24, s28, s53
	v_lshl_add_u32 v210, v56, 4, v62
	v_bitop3_b32 v56, v60, v59, 4 bitop3:0x36
	v_exp_f32_e32 v82, v18
	v_exp_f32_e32 v83, v19
	v_exp_f32_e32 v84, v20
	v_exp_f32_e32 v85, v21
	v_exp_f32_e32 v190, v22
	v_exp_f32_e32 v191, v23
	v_exp_f32_e32 v188, v24
	v_exp_f32_e32 v189, v25
	v_exp_f32_e32 v144, v26
	v_exp_f32_e32 v145, v27
	v_exp_f32_e32 v138, v28
	v_exp_f32_e32 v139, v29
	v_exp_f32_e32 v142, v30
	v_exp_f32_e32 v143, v31
	v_exp_f32_e32 v140, v32
	v_exp_f32_e32 v141, v35
	s_waitcnt vmcnt(1)
	v_lshl_add_u64 v[2:3], s[4:5], 0, v[50:51]
	s_addc_u32 s25, s29, 0
	v_lshl_add_u32 v209, v56, 4, v62
	v_bitop3_b32 v56, v60, v59, 6 bitop3:0x36
	s_barrier
	v_lshl_add_u64 v[182:183], v[2:3], 0, v[170:171]
	v_add_u32_e32 v2, v54, v53
	s_add_u32 s24, s42, s24
	v_lshl_add_u32 v206, v56, 4, v62
	v_ashrrev_i32_e32 v3, 31, v2
	s_addc_u32 s25, s43, s25
	v_mov_b32_e32 v200, 0
	s_mov_b32 s23, 2
	v_cndmask_b32_e64 v225, v36, 1.0, vcc
	v_pk_fma_f32 v[80:81], v[16:17], s[6:7], v[34:35] op_sel_hi:[1,0,0]
	v_pk_fma_f32 v[78:79], v[14:15], s[6:7], v[34:35] op_sel_hi:[1,0,0]
	v_pk_fma_f32 v[76:77], v[12:13], s[6:7], v[34:35] op_sel_hi:[1,0,0]
	v_pk_fma_f32 v[74:75], v[10:11], s[6:7], v[34:35] op_sel_hi:[1,0,0]
	v_pk_fma_f32 v[72:73], v[8:9], s[6:7], v[34:35] op_sel_hi:[1,0,0]
	v_pk_fma_f32 v[70:71], v[6:7], s[6:7], v[34:35] op_sel_hi:[1,0,0]
	v_pk_fma_f32 v[68:69], v[4:5], s[6:7], v[34:35] op_sel_hi:[1,0,0]
	v_add_u32_e32 v226, s38, v57
	v_add_u32_e32 v227, s38, v55
	v_cmp_gt_u32_e64 s[2:3], 32, v199
	v_lshl_add_u32 v207, v52, 2, s54
	v_lshl_add_u32 v205, v58, 4, s54
	v_add_u32_e32 v204, 0x4000, v208
	v_add_u32_e32 v203, 0x4000, v210
	v_add_u32_e32 v202, 0x4000, v209
	v_add_u32_e32 v201, 0x4000, v206
	v_lshl_add_u64 v[178:179], s[0:1], 0, v[170:171]
	v_lshl_add_u64 v[180:181], s[26:27], 0, v[174:175]
	v_lshl_add_u64 v[186:187], s[24:25], 0, v[2:3]
	s_movk_i32 s28, 0xc0
	v_mov_b32_e32 v2, 0
	v_mov_b32_e32 v3, v200
	v_mov_b32_e32 v4, v200
	v_mov_b32_e32 v5, v200
	v_mov_b32_e32 v6, v200
	v_mov_b32_e32 v7, v200
	v_mov_b32_e32 v8, v200
	v_mov_b32_e32 v9, v200
	v_mov_b32_e32 v10, v200
	v_mov_b32_e32 v11, v200
	v_mov_b32_e32 v12, v200
	v_mov_b32_e32 v13, v200
	v_mov_b32_e32 v14, v200
	v_mov_b32_e32 v15, v200
	v_mov_b32_e32 v16, v200
	v_mov_b32_e32 v17, v200
	v_mov_b32_e32 v18, 0
	v_mov_b32_e32 v19, v200
	v_mov_b32_e32 v20, v200
	v_mov_b32_e32 v21, v200
	v_mov_b32_e32 v22, v200
	v_mov_b32_e32 v23, v200
	v_mov_b32_e32 v24, v200
	v_mov_b32_e32 v25, v200
	v_mov_b32_e32 v26, v200
	v_mov_b32_e32 v27, v200
	v_mov_b32_e32 v28, v200
	v_mov_b32_e32 v29, v200
	v_mov_b32_e32 v30, v200
	v_mov_b32_e32 v31, v200
	v_mov_b32_e32 v32, v200
	v_mov_b32_e32 v33, v200
	v_mov_b32_e32 v34, 0
	v_mov_b32_e32 v35, v200
	v_mov_b32_e32 v36, v200
	v_mov_b32_e32 v37, v200
	v_mov_b32_e32 v38, v200
	v_mov_b32_e32 v39, v200
	v_mov_b32_e32 v40, v200
	v_mov_b32_e32 v41, v200
	v_mov_b32_e32 v42, v200
	v_mov_b32_e32 v43, v200
	v_mov_b32_e32 v44, v200
	v_mov_b32_e32 v45, v200
	v_mov_b32_e32 v46, v200
	v_mov_b32_e32 v47, v200
	v_mov_b32_e32 v48, v200
	v_mov_b32_e32 v49, v200
	v_mov_b32_e32 v50, 0
	v_mov_b32_e32 v51, v200
	v_mov_b32_e32 v52, v200
	v_mov_b32_e32 v53, v200
	v_mov_b32_e32 v54, v200
	v_mov_b32_e32 v55, v200
	v_mov_b32_e32 v56, v200
	v_mov_b32_e32 v57, v200
	v_mov_b32_e32 v58, v200
	v_mov_b32_e32 v59, v200
	v_mov_b32_e32 v60, v200
	v_mov_b32_e32 v61, v200
	v_mov_b32_e32 v62, v200
	v_mov_b32_e32 v63, v200
	v_mov_b32_e32 v64, v200
	v_mov_b32_e32 v65, v200
.LBB0_507:
	s_add_i32 s27, s55, 0x8000
	s_mov_b32 m0, s27
	s_add_i32 s26, s37, s57
	global_load_lds_dwordx4 v[186:187], off
	s_mov_b32 m0, s26
	s_nop 0
	global_load_lds_dwordx4 v[182:183], off
	ds_read_b128 v[102:105], v213 offset:49152
	ds_read_b128 v[106:109], v214 offset:49152
	ds_read_b128 v[130:133], v215 offset:49152
	ds_read_b128 v[134:137], v216 offset:49152
	v_add_u32_e32 v228, v226, v219
	v_add_u32_e32 v229, v226, v221
	s_waitcnt lgkmcnt(0)
	v_mfma_f32_32x32x64_f8f6f4 v[86:101], v[102:109], v[146:153], 0
	ds_read_b128 v[102:105], v217 offset:49152
	ds_read_b128 v[106:109], v218 offset:49152
	v_exp_f32_e32 v66, v66
	v_exp_f32_e32 v67, v67
	v_exp_f32_e32 v68, v68
	v_mfma_f32_32x32x64_f8f6f4 v[114:129], v[130:137], v[146:153], 0
	ds_read_b128 v[234:237], v211 offset:49152
	ds_read_b128 v[238:241], v212 offset:49152
	v_exp_f32_e32 v69, v69
	v_exp_f32_e32 v70, v70
	v_exp_f32_e32 v71, v71
	s_waitcnt lgkmcnt(0)
	v_mfma_f32_32x32x64_f8f6f4 v[86:101], v[102:109], v[154:161], v[86:101]
	ds_read_b128 v[102:105], v228
	ds_read_b128 v[106:109], v229
	v_exp_f32_e32 v72, v72
	v_exp_f32_e32 v73, v73
	v_exp_f32_e32 v74, v74
	v_add_u32_e32 v231, v227, v219
	v_mfma_f32_32x32x64_f8f6f4 v[114:129], v[234:241], v[154:161], v[114:129]
	v_add_u32_e32 v232, v227, v221
	ds_read_b128 v[234:237], v231
	ds_read_b128 v[238:241], v232
	v_exp_f32_e32 v75, v75
	v_exp_f32_e32 v76, v76
	v_exp_f32_e32 v77, v77
	s_waitcnt lgkmcnt(0)
	v_mfma_f32_32x32x64_f8f6f4 v[86:101], v[102:109], v[162:169], v[86:101]
	v_mov_b32_e32 v130, 0
	v_exp_f32_e32 v78, v78
	v_exp_f32_e32 v79, v79
	v_mfma_f32_32x32x64_f8f6f4 v[114:129], v[234:241], v[162:169], v[114:129]
	ds_read_b64_tr_b8 v[102:103], v208 offset:0
	ds_read_b64_tr_b8 v[104:105], v208 offset:0x800
	ds_read_b64_tr_b8 v[106:107], v208 offset:0x1000
	v_mov_b32_e32 v134, 0
	v_mov_b32_e32 v131, 0
	v_mov_b32_e32 v135, 0
	v_mov_b32_e32 v132, 0
	v_mov_b32_e32 v136, 0
	v_mov_b32_e32 v133, 0
	v_mov_b32_e32 v137, 0
	ds_read_b64_tr_b8 v[108:109], v208 offset:0x1800
	v_cvt_pk_fp8_f32 v130, v82, v83
	v_cvt_pk_fp8_f32 v131, v190, v191
	v_cvt_pk_fp8_f32 v132, v144, v145
	v_cvt_pk_fp8_f32 v134, v66, v67
	v_cvt_pk_fp8_f32 v135, v70, v71
	v_exp_f32_e32 v80, v80
	v_exp_f32_e32 v81, v81
	v_cvt_pk_fp8_f32 v136, v74, v75
	v_cvt_pk_fp8_f32 v133, v142, v143
	v_cvt_pk_fp8_f32 v137, v78, v79
	ds_read_b64_tr_b8 v[236:237], v210 offset:0
	ds_read_b64_tr_b8 v[238:239], v210 offset:0x800
	ds_read_b64_tr_b8 v[240:241], v210 offset:0x1000
	ds_read_b64_tr_b8 v[242:243], v210 offset:0x1800
	v_cvt_pk_fp8_f32 v130, v84, v85 op_sel:[0,0,1]
	v_cvt_pk_fp8_f32 v131, v188, v189 op_sel:[0,0,1]
	v_cvt_pk_fp8_f32 v134, v68, v69 op_sel:[0,0,1]
	v_cvt_pk_fp8_f32 v135, v72, v73 op_sel:[0,0,1]
	v_cvt_pk_fp8_f32 v132, v138, v139 op_sel:[0,0,1]
	v_cvt_pk_fp8_f32 v136, v76, v77 op_sel:[0,0,1]
	v_cvt_pk_fp8_f32 v133, v140, v141 op_sel:[0,0,1]
	v_cvt_pk_fp8_f32 v137, v80, v81 op_sel:[0,0,1]
	s_waitcnt lgkmcnt(4)
	s_mov_b32 m0, s55
	v_mfma_f32_32x32x64_f8f6f4 v[2:17], v[130:137], v[102:109], v[2:17]
	ds_read_b64_tr_b8 v[244:245], v209 offset:0
	ds_read_b64_tr_b8 v[246:247], v209 offset:0x800
	ds_read_b64_tr_b8 v[248:249], v209 offset:0x1000
	ds_read_b64_tr_b8 v[250:251], v209 offset:0x1800
	s_waitcnt lgkmcnt(4)
	s_nop 0
	v_max_f32_e32 v102, v87, v87
	v_max_f32_e32 v103, v86, v86
	v_max_f32_e32 v102, v103, v102
	v_max3_f32 v102, v102, v88, v89
	v_max3_f32 v102, v102, v90, v91
	v_max3_f32 v102, v102, v92, v93
	v_max3_f32 v102, v102, v94, v95
	v_max3_f32 v102, v102, v96, v97
	v_max3_f32 v102, v102, v98, v99
	v_max3_f32 v102, v102, v100, v101
	v_max3_f32 v102, v102, v114, v115
	v_max3_f32 v102, v102, v116, v117
	v_max3_f32 v102, v102, v118, v119
	v_max3_f32 v102, v102, v120, v121
	v_max3_f32 v102, v102, v122, v123
	v_max3_f32 v102, v102, v124, v125
	v_max3_f32 v102, v102, v126, v127
	v_max3_f32 v102, v102, v128, v129
	v_mov_b32_e32 v103, v102
	s_nop 1
	v_permlane32_swap_b32_e32 v102, v103
	v_max_f32_e32 v103, v103, v103
	v_max_f32_e32 v102, v102, v102
	v_max_f32_e32 v102, v102, v103
	v_sub_f32_e32 v103, v102, v233
	v_cmp_ge_f32_e32 vcc, s46, v103
	s_cmp_eq_u64 vcc, exec
	v_max_f32_e32 v103, v233, v233
	v_max_f32_e32 v193, v103, v102
	s_cselect_b64 vcc, -1, 0
	v_cndmask_b32_e32 v235, v193, v233, vcc
	v_fma_f32 v192, v235, s47, 4.0
	v_mfma_f32_32x32x64_f8f6f4 v[18:33], v[130:137], v[236:243], v[18:33]
	v_pk_add_f32 v[82:83], v[82:83], v[84:85]
	v_pk_fma_f32 v[110:111], v[98:99], s[6:7], v[192:193] op_sel_hi:[1,0,0]
	v_pk_fma_f32 v[98:99], v[86:87], s[6:7], v[192:193] op_sel_hi:[1,0,0]
	ds_read_b64_tr_b8 v[86:87], v206 offset:0
	v_pk_fma_f32 v[112:113], v[100:101], s[6:7], v[192:193] op_sel_hi:[1,0,0]
	v_pk_fma_f32 v[100:101], v[88:89], s[6:7], v[192:193] op_sel_hi:[1,0,0]
	ds_read_b64_tr_b8 v[88:89], v206 offset:0x800
	v_pk_fma_f32 v[102:103], v[90:91], s[6:7], v[192:193] op_sel_hi:[1,0,0]
	ds_read_b64_tr_b8 v[90:91], v206 offset:0x1000
	v_pk_fma_f32 v[108:109], v[96:97], s[6:7], v[192:193] op_sel_hi:[1,0,0]
	v_pk_fma_f32 v[106:107], v[94:95], s[6:7], v[192:193] op_sel_hi:[1,0,0]
	v_pk_fma_f32 v[104:105], v[92:93], s[6:7], v[192:193] op_sel_hi:[1,0,0]
	v_pk_fma_f32 v[128:129], v[128:129], s[6:7], v[192:193] op_sel_hi:[1,0,0]
	v_pk_fma_f32 v[126:127], v[126:127], s[6:7], v[192:193] op_sel_hi:[1,0,0]
	v_pk_fma_f32 v[124:125], v[124:125], s[6:7], v[192:193] op_sel_hi:[1,0,0]
	v_pk_fma_f32 v[122:123], v[122:123], s[6:7], v[192:193] op_sel_hi:[1,0,0]
	v_pk_fma_f32 v[120:121], v[120:121], s[6:7], v[192:193] op_sel_hi:[1,0,0]
	v_pk_fma_f32 v[118:119], v[118:119], s[6:7], v[192:193] op_sel_hi:[1,0,0]
	v_pk_fma_f32 v[116:117], v[116:117], s[6:7], v[192:193] op_sel_hi:[1,0,0]
	v_pk_fma_f32 v[114:115], v[114:115], s[6:7], v[192:193] op_sel_hi:[1,0,0]
	ds_read_b64_tr_b8 v[92:93], v206 offset:0x1800
	s_waitcnt lgkmcnt(4)
	v_pk_add_f32 v[82:83], v[190:191], v[82:83]
	v_mfma_f32_32x32x64_f8f6f4 v[34:49], v[130:137], v[244:251], v[34:49]
	s_waitcnt lgkmcnt(0)
	s_nop 0
	v_exp_f32_e32 v98, v98
	v_exp_f32_e32 v99, v99
	v_exp_f32_e32 v100, v100
	v_exp_f32_e32 v101, v101
	v_mfma_f32_32x32x64_f8f6f4 v[50:65], v[130:137], v[86:93], v[50:65]
	s_barrier
	global_load_lds_dwordx4 v[184:185], off
	v_pk_add_f32 v[82:83], v[188:189], v[82:83]
	s_nop 0
	v_pk_add_f32 v[82:83], v[144:145], v[82:83]
	s_nop 0
	v_pk_add_f32 v[82:83], v[138:139], v[82:83]
	s_nop 0
	v_pk_add_f32 v[82:83], v[142:143], v[82:83]
	s_nop 0
	v_pk_add_f32 v[82:83], v[140:141], v[82:83]
	s_nop 0
	v_pk_add_f32 v[66:67], v[82:83], v[66:67]
	s_nop 0
	v_pk_add_f32 v[66:67], v[68:69], v[66:67]
	s_nop 0
	v_pk_add_f32 v[66:67], v[70:71], v[66:67]
	s_nop 0
	v_pk_add_f32 v[66:67], v[72:73], v[66:67]
	s_nop 0
	v_pk_add_f32 v[66:67], v[74:75], v[66:67]
	s_nop 0
	v_pk_add_f32 v[66:67], v[76:77], v[66:67]
	s_nop 0
	v_pk_add_f32 v[66:67], v[78:79], v[66:67]
	s_nop 0
	v_pk_add_f32 v[66:67], v[80:81], v[66:67]
	s_nop 0
	v_pk_add_f32 v[188:189], v[66:67], v[66:67] op_sel:[0,1] op_sel_hi:[1,0]
	v_sub_f32_e32 v66, v233, v193
	v_mul_f32_e32 v66, 0x3dd53b94, v66
	v_exp_f32_e32 v66, v66
	v_mov_b32_e32 v234, v188
	s_nop 1
	v_permlane32_swap_b32_e32 v188, v234
	v_cndmask_b32_e64 v189, v66, 1.0, vcc
	v_cmp_gt_f32_e32 vcc, 1.0, v189
	s_cbranch_vccz .LBB0_511
	s_and_saveexec_b64 s[24:25], s[2:3]
	ds_write_b32 v207, v189 offset:128
	s_or_b64 exec, exec, s[24:25]
	s_waitcnt lgkmcnt(0)
	s_nop 15
	s_nop 7
	ds_read2_b32 v[66:67], v205 offset0:32 offset1:33
	ds_read2_b32 v[68:69], v205 offset0:34 offset1:35
	ds_read2_b32 v[70:71], v205 offset0:40 offset1:41
	ds_read2_b32 v[72:73], v205 offset0:42 offset1:43
	s_waitcnt lgkmcnt(0)
	v_pk_mul_f32 v[2:3], v[66:67], v[2:3]
	v_pk_mul_f32 v[18:19], v[66:67], v[18:19]
	v_pk_mul_f32 v[34:35], v[66:67], v[34:35]
	v_pk_mul_f32 v[50:51], v[66:67], v[50:51]
	v_pk_mul_f32 v[4:5], v[4:5], v[68:69]
	v_pk_mul_f32 v[20:21], v[20:21], v[68:69]
	v_pk_mul_f32 v[36:37], v[36:37], v[68:69]
	v_pk_mul_f32 v[52:53], v[52:53], v[68:69]
	v_pk_mul_f32 v[6:7], v[6:7], v[70:71]
	v_pk_mul_f32 v[22:23], v[22:23], v[70:71]
	v_pk_mul_f32 v[38:39], v[38:39], v[70:71]
	v_pk_mul_f32 v[54:55], v[54:55], v[70:71]
	v_pk_mul_f32 v[8:9], v[8:9], v[72:73]
	v_pk_mul_f32 v[24:25], v[24:25], v[72:73]
	v_pk_mul_f32 v[40:41], v[40:41], v[72:73]
	ds_read2_b32 v[66:67], v205 offset0:48 offset1:49
	v_pk_mul_f32 v[56:57], v[56:57], v[72:73]
	ds_read2_b32 v[68:69], v205 offset0:50 offset1:51
	ds_read2_b32 v[70:71], v205 offset0:56 offset1:57
	ds_read2_b32 v[72:73], v205 offset0:58 offset1:59
	s_waitcnt lgkmcnt(0)
	v_pk_mul_f32 v[10:11], v[10:11], v[66:67]
	v_pk_mul_f32 v[26:27], v[26:27], v[66:67]
	v_pk_mul_f32 v[42:43], v[42:43], v[66:67]
	v_pk_mul_f32 v[58:59], v[58:59], v[66:67]
	v_pk_mul_f32 v[12:13], v[12:13], v[68:69]
	v_pk_mul_f32 v[28:29], v[28:29], v[68:69]
	v_pk_mul_f32 v[44:45], v[44:45], v[68:69]
	v_pk_mul_f32 v[60:61], v[60:61], v[68:69]
	v_pk_mul_f32 v[14:15], v[14:15], v[70:71]
	v_pk_mul_f32 v[30:31], v[30:31], v[70:71]
	v_pk_mul_f32 v[46:47], v[46:47], v[70:71]
	v_pk_mul_f32 v[62:63], v[62:63], v[70:71]
	v_pk_mul_f32 v[16:17], v[16:17], v[72:73]
	v_pk_mul_f32 v[32:33], v[32:33], v[72:73]
	v_pk_mul_f32 v[48:49], v[48:49], v[72:73]
	v_pk_mul_f32 v[64:65], v[64:65], v[72:73]
.LBB0_511:
	s_add_i32 s24, s23, 1
	s_cmp_lt_u32 s24, s56
	s_cselect_b32 s24, 0, s56
	s_cselect_b32 s25, s22, 0
	s_lshl_b32 s24, s24, 6
	s_ashr_i32 s29, s25, 31
	s_sub_i32 s24, s28, s24
	s_add_u32 s60, s24, s25
	s_addc_u32 s61, 0, s29
	s_waitcnt vmcnt(1)
	s_lshl_b64 s[24:25], s[60:61], 11
	s_add_i32 s59, s55, 0xc000
	s_barrier
	v_lshl_add_u64 v[66:67], v[176:177], 0, s[24:25]
	s_mov_b32 m0, s59
	s_lshl_b64 s[60:61], s[60:61], 6
	s_add_i32 s29, s38, s57
	global_load_lds_dwordx4 v[66:67], off
	v_lshl_add_u64 v[66:67], v[178:179], 0, s[60:61]
	s_mov_b32 m0, s29
	v_exp_f32_e32 v190, v102
	global_load_lds_dwordx4 v[66:67], off
	v_exp_f32_e32 v191, v103
	v_exp_f32_e32 v192, v104
	v_exp_f32_e32 v193, v105
	v_exp_f32_e32 v194, v106
	v_exp_f32_e32 v195, v107
	v_exp_f32_e32 v196, v108
	v_exp_f32_e32 v197, v109
	v_exp_f32_e32 v110, v110
	v_exp_f32_e32 v111, v111
	v_exp_f32_e32 v112, v112
	v_exp_f32_e32 v113, v113
	ds_read_b128 v[82:85], v213 offset:32768
	ds_read_b128 v[86:89], v214 offset:32768
	ds_read_b128 v[90:93], v215 offset:32768
	ds_read_b128 v[94:97], v216 offset:32768
	v_mov_b32_e32 v102, 0
	v_mov_b32_e32 v103, 0
	s_waitcnt lgkmcnt(0)
	v_mfma_f32_32x32x64_f8f6f4 v[66:81], v[82:89], v[146:153], 0
	ds_read_b128 v[82:85], v217 offset:32768
	ds_read_b128 v[86:89], v218 offset:32768
	v_exp_f32_e32 v114, v114
	v_exp_f32_e32 v115, v115
	v_exp_f32_e32 v116, v116
	v_mfma_f32_32x32x64_f8f6f4 v[130:145], v[90:97], v[146:153], 0
	ds_read_b128 v[90:93], v211 offset:32768
	ds_read_b128 v[94:97], v212 offset:32768
	v_exp_f32_e32 v117, v117
	v_exp_f32_e32 v118, v118
	v_exp_f32_e32 v119, v119
	s_waitcnt lgkmcnt(0)
	v_mfma_f32_32x32x64_f8f6f4 v[66:81], v[82:89], v[154:161], v[66:81]
	ds_read_b128 v[82:85], v220
	ds_read_b128 v[86:89], v222
	v_exp_f32_e32 v120, v120
	v_exp_f32_e32 v121, v121
	v_exp_f32_e32 v122, v122
	v_mfma_f32_32x32x64_f8f6f4 v[130:145], v[90:97], v[154:161], v[130:145]
	ds_read_b128 v[90:93], v223
	ds_read_b128 v[94:97], v224
	v_exp_f32_e32 v123, v123
	v_exp_f32_e32 v124, v124
	v_exp_f32_e32 v125, v125
	s_waitcnt lgkmcnt(0)
	v_mfma_f32_32x32x64_f8f6f4 v[66:81], v[82:89], v[162:169], v[66:81]
	v_mov_b32_e32 v106, 0
	v_exp_f32_e32 v126, v126
	v_exp_f32_e32 v127, v127
	v_mfma_f32_32x32x64_f8f6f4 v[130:145], v[90:97], v[162:169], v[130:145]
	ds_read_b64_tr_b8 v[82:83], v204 offset:0
	ds_read_b64_tr_b8 v[84:85], v204 offset:0x800
	ds_read_b64_tr_b8 v[86:87], v204 offset:0x1000
	v_mov_b32_e32 v107, 0
	v_mov_b32_e32 v104, 0
	v_mov_b32_e32 v108, 0
	v_mov_b32_e32 v105, 0
	v_mov_b32_e32 v109, 0
	ds_read_b64_tr_b8 v[88:89], v204 offset:0x1800
	v_cvt_pk_fp8_f32 v102, v98, v99
	v_cvt_pk_fp8_f32 v103, v190, v191
	v_cvt_pk_fp8_f32 v104, v194, v195
	v_cvt_pk_fp8_f32 v105, v110, v111
	v_exp_f32_e32 v128, v128
	v_cvt_pk_fp8_f32 v106, v114, v115
	v_cvt_pk_fp8_f32 v107, v118, v119
	v_exp_f32_e32 v129, v129
	v_cvt_pk_fp8_f32 v108, v122, v123
	v_cvt_pk_fp8_f32 v109, v126, v127
	ds_read_b64_tr_b8 v[90:91], v203 offset:0
	ds_read_b64_tr_b8 v[92:93], v203 offset:0x800
	ds_read_b64_tr_b8 v[94:95], v203 offset:0x1000
	ds_read_b64_tr_b8 v[96:97], v203 offset:0x1800
	v_cvt_pk_fp8_f32 v102, v100, v101 op_sel:[0,0,1]
	v_cvt_pk_fp8_f32 v103, v192, v193 op_sel:[0,0,1]
	v_cvt_pk_fp8_f32 v106, v116, v117 op_sel:[0,0,1]
	v_cvt_pk_fp8_f32 v107, v120, v121 op_sel:[0,0,1]
	v_cvt_pk_fp8_f32 v104, v196, v197 op_sel:[0,0,1]
	v_cvt_pk_fp8_f32 v108, v124, v125 op_sel:[0,0,1]
	v_cvt_pk_fp8_f32 v105, v112, v113 op_sel:[0,0,1]
	v_cvt_pk_fp8_f32 v109, v128, v129 op_sel:[0,0,1]
	s_waitcnt lgkmcnt(4)
	s_mov_b32 m0, s58
	v_mfma_f32_32x32x64_f8f6f4 v[2:17], v[102:109], v[82:89], v[2:17]
	ds_read_b64_tr_b8 v[236:237], v202 offset:0
	ds_read_b64_tr_b8 v[238:239], v202 offset:0x800
	ds_read_b64_tr_b8 v[240:241], v202 offset:0x1000
	ds_read_b64_tr_b8 v[242:243], v202 offset:0x1800
	s_waitcnt lgkmcnt(4)
	s_nop 0
	v_max_f32_e32 v82, v67, v67
	v_max_f32_e32 v83, v66, v66
	v_max_f32_e32 v82, v83, v82
	v_max3_f32 v82, v82, v68, v69
	v_max3_f32 v82, v82, v70, v71
	v_max3_f32 v82, v82, v72, v73
	v_max3_f32 v82, v82, v74, v75
	v_max3_f32 v82, v82, v76, v77
	v_max3_f32 v82, v82, v78, v79
	v_max3_f32 v82, v82, v80, v81
	v_max3_f32 v82, v82, v130, v131
	v_max3_f32 v82, v82, v132, v133
	v_max3_f32 v82, v82, v134, v135
	v_max3_f32 v82, v82, v136, v137
	v_max3_f32 v82, v82, v138, v139
	v_max3_f32 v82, v82, v140, v141
	v_max3_f32 v82, v82, v142, v143
	v_max3_f32 v82, v82, v144, v145
	v_mov_b32_e32 v83, v82
	s_nop 1
	v_permlane32_swap_b32_e32 v82, v83
	v_max_f32_e32 v83, v83, v83
	v_max_f32_e32 v82, v82, v82
	v_max_f32_e32 v82, v82, v83
	v_sub_f32_e32 v83, v82, v235
	v_cmp_ge_f32_e32 vcc, s46, v83
	s_cmp_eq_u64 vcc, exec
	v_max_f32_e32 v83, v235, v235
	v_max_f32_e32 v245, v83, v82
	s_cselect_b64 vcc, -1, 0
	v_cndmask_b32_e32 v233, v245, v235, vcc
	v_fma_f32 v244, v233, s47, 4.0
	v_mfma_f32_32x32x64_f8f6f4 v[18:33], v[102:109], v[90:97], v[18:33]
	v_pk_add_f32 v[98:99], v[98:99], v[100:101]
	v_pk_fma_f32 v[82:83], v[66:67], s[6:7], v[244:245] op_sel_hi:[1,0,0]
	v_pk_fma_f32 v[66:67], v[130:131], s[6:7], v[244:245] op_sel_hi:[1,0,0]
	ds_read_b64_tr_b8 v[130:131], v201 offset:0
	v_pk_fma_f32 v[84:85], v[68:69], s[6:7], v[244:245] op_sel_hi:[1,0,0]
	v_pk_fma_f32 v[68:69], v[132:133], s[6:7], v[244:245] op_sel_hi:[1,0,0]
	ds_read_b64_tr_b8 v[132:133], v201 offset:0x800
	v_pk_fma_f32 v[86:87], v[70:71], s[6:7], v[244:245] op_sel_hi:[1,0,0]
	v_pk_fma_f32 v[70:71], v[134:135], s[6:7], v[244:245] op_sel_hi:[1,0,0]
	ds_read_b64_tr_b8 v[134:135], v201 offset:0x1000
	v_pk_fma_f32 v[96:97], v[80:81], s[6:7], v[244:245] op_sel_hi:[1,0,0]
	v_pk_fma_f32 v[94:95], v[78:79], s[6:7], v[244:245] op_sel_hi:[1,0,0]
	v_pk_fma_f32 v[92:93], v[76:77], s[6:7], v[244:245] op_sel_hi:[1,0,0]
	v_pk_fma_f32 v[90:91], v[74:75], s[6:7], v[244:245] op_sel_hi:[1,0,0]
	v_pk_fma_f32 v[88:89], v[72:73], s[6:7], v[244:245] op_sel_hi:[1,0,0]
	v_pk_fma_f32 v[80:81], v[144:145], s[6:7], v[244:245] op_sel_hi:[1,0,0]
	v_pk_fma_f32 v[78:79], v[142:143], s[6:7], v[244:245] op_sel_hi:[1,0,0]
	v_pk_fma_f32 v[76:77], v[140:141], s[6:7], v[244:245] op_sel_hi:[1,0,0]
	v_pk_fma_f32 v[74:75], v[138:139], s[6:7], v[244:245] op_sel_hi:[1,0,0]
	v_pk_fma_f32 v[72:73], v[136:137], s[6:7], v[244:245] op_sel_hi:[1,0,0]
	ds_read_b64_tr_b8 v[136:137], v201 offset:0x1800
	s_waitcnt lgkmcnt(4)
	v_pk_add_f32 v[98:99], v[98:99], v[190:191]
	v_mfma_f32_32x32x64_f8f6f4 v[34:49], v[102:109], v[236:243], v[34:49]
	s_waitcnt lgkmcnt(0)
	s_nop 0
	v_exp_f32_e32 v82, v82
	v_exp_f32_e32 v83, v83
	v_exp_f32_e32 v84, v84
	v_exp_f32_e32 v85, v85
	v_mfma_f32_32x32x64_f8f6f4 v[50:65], v[102:109], v[130:137], v[50:65]
	s_barrier
	v_lshl_add_u64 v[102:103], v[180:181], 0, s[24:25]
	global_load_lds_dwordx4 v[102:103], off
	v_pk_add_f32 v[98:99], v[192:193], v[98:99]
	s_nop 0
	v_pk_add_f32 v[98:99], v[194:195], v[98:99]
	s_nop 0
	v_pk_add_f32 v[98:99], v[196:197], v[98:99]
	s_nop 0
	v_pk_add_f32 v[98:99], v[110:111], v[98:99]
	s_nop 0
	v_pk_add_f32 v[98:99], v[112:113], v[98:99]
	s_nop 0
	v_pk_add_f32 v[98:99], v[98:99], v[114:115]
	s_nop 0
	v_pk_add_f32 v[98:99], v[116:117], v[98:99]
	s_nop 0
	v_pk_add_f32 v[98:99], v[118:119], v[98:99]
	s_nop 0
	v_pk_add_f32 v[98:99], v[120:121], v[98:99]
	s_nop 0
	v_pk_add_f32 v[98:99], v[122:123], v[98:99]
	s_nop 0
	v_pk_add_f32 v[98:99], v[124:125], v[98:99]
	s_nop 0
	v_pk_add_f32 v[98:99], v[126:127], v[98:99]
	s_nop 0
	v_pk_add_f32 v[98:99], v[128:129], v[98:99]
	s_nop 0
	v_pk_add_f32 v[98:99], v[98:99], v[98:99] op_sel:[0,1] op_sel_hi:[1,0]
	s_nop 0
	v_sub_f32_e32 v99, v235, v245
	v_mul_f32_e32 v99, 0x3dd53b94, v99
	v_exp_f32_e32 v100, v99
	v_mov_b32_e32 v99, v98
	s_nop 1
	v_permlane32_swap_b32_e32 v98, v99
	v_cndmask_b32_e64 v128, v100, 1.0, vcc
	v_cmp_gt_f32_e32 vcc, 1.0, v128
	s_cbranch_vccz .LBB0_515
	s_and_saveexec_b64 s[24:25], s[2:3]
	ds_write_b32 v207, v128 offset:128
	s_or_b64 exec, exec, s[24:25]
	s_waitcnt lgkmcnt(0)
	s_nop 15
	s_nop 7
	ds_read2_b32 v[100:101], v205 offset0:32 offset1:33
	ds_read2_b32 v[102:103], v205 offset0:34 offset1:35
	ds_read2_b32 v[104:105], v205 offset0:40 offset1:41
	ds_read2_b32 v[106:107], v205 offset0:42 offset1:43
	s_waitcnt lgkmcnt(0)
	v_pk_mul_f32 v[2:3], v[100:101], v[2:3]
	v_pk_mul_f32 v[18:19], v[100:101], v[18:19]
	v_pk_mul_f32 v[34:35], v[100:101], v[34:35]
	v_pk_mul_f32 v[50:51], v[100:101], v[50:51]
	v_pk_mul_f32 v[4:5], v[4:5], v[102:103]
	v_pk_mul_f32 v[20:21], v[20:21], v[102:103]
	v_pk_mul_f32 v[36:37], v[36:37], v[102:103]
	v_pk_mul_f32 v[52:53], v[52:53], v[102:103]
	v_pk_mul_f32 v[6:7], v[6:7], v[104:105]
	v_pk_mul_f32 v[22:23], v[22:23], v[104:105]
	v_pk_mul_f32 v[38:39], v[38:39], v[104:105]
	v_pk_mul_f32 v[54:55], v[54:55], v[104:105]
	v_pk_mul_f32 v[8:9], v[8:9], v[106:107]
	v_pk_mul_f32 v[24:25], v[24:25], v[106:107]
	v_pk_mul_f32 v[40:41], v[40:41], v[106:107]
	ds_read2_b32 v[100:101], v205 offset0:48 offset1:49
	v_pk_mul_f32 v[56:57], v[56:57], v[106:107]
	ds_read2_b32 v[102:103], v205 offset0:50 offset1:51
	ds_read2_b32 v[104:105], v205 offset0:56 offset1:57
	ds_read2_b32 v[106:107], v205 offset0:58 offset1:59
	s_waitcnt lgkmcnt(0)
	v_pk_mul_f32 v[10:11], v[10:11], v[100:101]
	v_pk_mul_f32 v[26:27], v[26:27], v[100:101]
	v_pk_mul_f32 v[42:43], v[42:43], v[100:101]
	v_pk_mul_f32 v[58:59], v[58:59], v[100:101]
	v_pk_mul_f32 v[12:13], v[12:13], v[102:103]
	v_pk_mul_f32 v[28:29], v[28:29], v[102:103]
	v_pk_mul_f32 v[44:45], v[44:45], v[102:103]
	v_pk_mul_f32 v[60:61], v[60:61], v[102:103]
	v_pk_mul_f32 v[14:15], v[14:15], v[104:105]
	v_pk_mul_f32 v[30:31], v[30:31], v[104:105]
	v_pk_mul_f32 v[46:47], v[46:47], v[104:105]
	v_pk_mul_f32 v[62:63], v[62:63], v[104:105]
	v_pk_mul_f32 v[16:17], v[16:17], v[106:107]
	v_pk_mul_f32 v[32:33], v[32:33], v[106:107]
	v_pk_mul_f32 v[48:49], v[48:49], v[106:107]
	v_pk_mul_f32 v[64:65], v[64:65], v[106:107]

.LBB0_517:
	ds_read_b128 v[102:105], v213 offset:49152
	ds_read_b128 v[106:109], v214 offset:49152
	ds_read_b128 v[120:123], v215 offset:49152
	ds_read_b128 v[124:127], v216 offset:49152
	v_mov_b32_e32 v118, v171
	v_cvt_pk_fp8_f32 v118, v82, v83
	s_waitcnt lgkmcnt(0)
	v_mfma_f32_32x32x64_f8f6f4 v[86:101], v[102:109], v[146:153], 0
	ds_read_b128 v[130:133], v217 offset:49152
	ds_read_b128 v[134:137], v218 offset:49152
	v_exp_f32_e32 v66, v66
	v_exp_f32_e32 v67, v67
	v_exp_f32_e32 v68, v68
	v_pk_add_f32 v[102:103], v[82:83], v[84:85]
	v_mov_b32_e32 v119, v171
	v_pk_add_f32 v[176:177], v[102:103], v[190:191]
	v_mfma_f32_32x32x64_f8f6f4 v[102:117], v[120:127], v[146:153], 0
	ds_read_b128 v[120:123], v211 offset:49152
	ds_read_b128 v[124:127], v212 offset:49152
	v_exp_f32_e32 v69, v69
	v_exp_f32_e32 v70, v70
	v_exp_f32_e32 v71, v71
	s_waitcnt lgkmcnt(0)
	v_mfma_f32_32x32x64_f8f6f4 v[86:101], v[130:137], v[154:161], v[86:101]
	ds_read_b128 v[130:133], v228
	ds_read_b128 v[134:137], v229
	v_exp_f32_e32 v72, v72
	v_exp_f32_e32 v73, v73
	v_exp_f32_e32 v74, v74
	v_mfma_f32_32x32x64_f8f6f4 v[102:117], v[120:127], v[154:161], v[102:117]
	v_pk_add_f32 v[82:83], v[176:177], v[188:189]
	ds_read_b128 v[146:149], v231
	ds_read_b128 v[150:153], v232
	v_pk_add_f32 v[82:83], v[82:83], v[144:145]
	v_exp_f32_e32 v75, v75
	v_exp_f32_e32 v76, v76
	v_exp_f32_e32 v77, v77
	v_pk_add_f32 v[82:83], v[82:83], v[138:139]
	s_waitcnt lgkmcnt(0)
	v_mfma_f32_32x32x64_f8f6f4 v[86:101], v[130:137], v[162:169], v[86:101]
	v_mov_b32_e32 v122, v171
	v_pk_add_f32 v[82:83], v[82:83], v[142:143]
	v_exp_f32_e32 v78, v78
	v_exp_f32_e32 v79, v79
	v_pk_add_f32 v[82:83], v[82:83], v[140:141]
	v_mfma_f32_32x32x64_f8f6f4 v[102:117], v[146:153], v[162:169], v[102:117]
	v_mov_b32_e32 v123, v171
	v_pk_add_f32 v[82:83], v[82:83], v[66:67]
	v_cvt_pk_fp8_f32 v122, v66, v67
	v_pk_add_f32 v[66:67], v[68:69], v[82:83]
	v_exp_f32_e32 v80, v80
	v_pk_add_f32 v[66:67], v[70:71], v[66:67]
	v_exp_f32_e32 v81, v81
	v_pk_add_f32 v[66:67], v[72:73], v[66:67]
	v_cvt_pk_fp8_f32 v123, v70, v71
	v_pk_add_f32 v[66:67], v[74:75], v[66:67]
	v_mov_b32_e32 v124, v171
	v_pk_add_f32 v[66:67], v[76:77], v[66:67]
	v_cvt_pk_fp8_f32 v122, v68, v69 op_sel:[0,0,1]
	v_pk_add_f32 v[66:67], v[78:79], v[66:67]
	v_cvt_pk_fp8_f32 v124, v74, v75
	v_pk_add_f32 v[66:67], v[80:81], v[66:67]
	v_mov_b32_e32 v125, v171
	v_pk_add_f32 v[126:127], v[66:67], v[66:67] op_sel:[0,1] op_sel_hi:[1,0]
	ds_read_b64_tr_b8 v[66:67], v208 offset:0
	ds_read_b64_tr_b8 v[68:69], v208 offset:0x800
	ds_read_b64_tr_b8 v[70:71], v208 offset:0x1000
	v_cvt_pk_fp8_f32 v123, v72, v73 op_sel:[0,0,1]
	v_mov_b32_e32 v120, v171
	v_mov_b32_e32 v121, v171
	v_cvt_pk_fp8_f32 v125, v78, v79
	ds_read_b64_tr_b8 v[72:73], v208 offset:0x1800
	v_cvt_pk_fp8_f32 v119, v190, v191
	v_cvt_pk_fp8_f32 v120, v144, v145
	v_cvt_pk_fp8_f32 v121, v142, v143
	ds_read_b64_tr_b8 v[74:75], v210 offset:0
	v_cvt_pk_fp8_f32 v124, v76, v77 op_sel:[0,0,1]
	ds_read_b64_tr_b8 v[76:77], v210 offset:0x800
	ds_read_b64_tr_b8 v[78:79], v210 offset:0x1000
	v_cvt_pk_fp8_f32 v125, v80, v81 op_sel:[0,0,1]
	ds_read_b64_tr_b8 v[80:81], v210 offset:0x1800
	v_cvt_pk_fp8_f32 v118, v84, v85 op_sel:[0,0,1]
	v_cvt_pk_fp8_f32 v119, v188, v189 op_sel:[0,0,1]
	v_cvt_pk_fp8_f32 v120, v138, v139 op_sel:[0,0,1]
	v_cvt_pk_fp8_f32 v121, v140, v141 op_sel:[0,0,1]
	s_waitcnt lgkmcnt(4)
	v_mov_b32_e32 v127, v126
	v_mfma_f32_32x32x64_f8f6f4 v[2:17], v[118:125], v[66:73], v[2:17]
	ds_read_b64_tr_b8 v[130:131], v209 offset:0
	ds_read_b64_tr_b8 v[132:133], v209 offset:0x800
	ds_read_b64_tr_b8 v[134:135], v209 offset:0x1000
	ds_read_b64_tr_b8 v[136:137], v209 offset:0x1800
	s_waitcnt lgkmcnt(4)
	s_nop 0
	v_max_f32_e32 v66, v87, v87
	v_max_f32_e32 v67, v86, v86
	v_max_f32_e32 v66, v67, v66
	v_max3_f32 v66, v66, v88, v89
	v_max3_f32 v66, v66, v90, v91
	v_max3_f32 v66, v66, v92, v93
	v_max3_f32 v66, v66, v94, v95
	v_max3_f32 v66, v66, v96, v97
	v_max3_f32 v66, v66, v98, v99
	v_max3_f32 v66, v66, v100, v101
	v_max3_f32 v66, v66, v102, v103
	v_max3_f32 v66, v66, v104, v105
	v_max3_f32 v66, v66, v106, v107
	v_max3_f32 v66, v66, v108, v109
	v_max3_f32 v66, v66, v110, v111
	v_max3_f32 v66, v66, v112, v113
	v_max3_f32 v66, v66, v114, v115
	v_max3_f32 v66, v66, v116, v117
	v_mov_b32_e32 v67, v66
	s_nop 1
	v_permlane32_swap_b32_e32 v66, v67
	v_max_f32_e32 v67, v67, v67
	v_max_f32_e32 v66, v66, v66
	v_max_f32_e32 v66, v66, v67
	v_sub_f32_e32 v67, v66, v233
	v_cmp_ge_f32_e32 vcc, s46, v67
	s_cmp_eq_u64 vcc, exec
	v_max_f32_e32 v67, v233, v233
	v_max_f32_e32 v66, v67, v66
	s_cselect_b64 vcc, -1, 0
	v_sub_f32_e32 v67, v233, v66
	v_cndmask_b32_e32 v66, v66, v233, vcc
	v_mul_f32_e32 v83, 0x3dd53b94, v67
	v_fma_f32 v82, v66, s47, 4.0
	v_mfma_f32_32x32x64_f8f6f4 v[18:33], v[118:125], v[74:81], v[18:33]
	v_permlane32_swap_b32_e32 v126, v127
	v_pk_fma_f32 v[80:81], v[100:101], s[6:7], v[82:83] op_sel_hi:[1,0,0]
	ds_read_b64_tr_b8 v[100:101], v206 offset:0
	v_pk_fma_f32 v[78:79], v[98:99], s[6:7], v[82:83] op_sel_hi:[1,0,0]
	v_pk_fma_f32 v[76:77], v[96:97], s[6:7], v[82:83] op_sel_hi:[1,0,0]
	v_pk_fma_f32 v[74:75], v[94:95], s[6:7], v[82:83] op_sel_hi:[1,0,0]
	v_pk_fma_f32 v[72:73], v[92:93], s[6:7], v[82:83] op_sel_hi:[1,0,0]
	v_pk_fma_f32 v[70:71], v[90:91], s[6:7], v[82:83] op_sel_hi:[1,0,0]
	v_pk_fma_f32 v[68:69], v[88:89], s[6:7], v[82:83] op_sel_hi:[1,0,0]
	v_pk_fma_f32 v[66:67], v[86:87], s[6:7], v[82:83] op_sel_hi:[1,0,0]
	v_exp_f32_e32 v98, v83
	v_pk_fma_f32 v[96:97], v[116:117], s[6:7], v[82:83] op_sel_hi:[1,0,0]
	v_pk_fma_f32 v[94:95], v[114:115], s[6:7], v[82:83] op_sel_hi:[1,0,0]
	v_pk_fma_f32 v[92:93], v[112:113], s[6:7], v[82:83] op_sel_hi:[1,0,0]
	v_pk_fma_f32 v[90:91], v[110:111], s[6:7], v[82:83] op_sel_hi:[1,0,0]
	v_pk_fma_f32 v[88:89], v[108:109], s[6:7], v[82:83] op_sel_hi:[1,0,0]
	v_pk_fma_f32 v[86:87], v[106:107], s[6:7], v[82:83] op_sel_hi:[1,0,0]
	v_pk_fma_f32 v[84:85], v[104:105], s[6:7], v[82:83] op_sel_hi:[1,0,0]
	v_pk_fma_f32 v[82:83], v[102:103], s[6:7], v[82:83] op_sel_hi:[1,0,0]
	ds_read_b64_tr_b8 v[102:103], v206 offset:0x800
	ds_read_b64_tr_b8 v[104:105], v206 offset:0x1000
	ds_read_b64_tr_b8 v[106:107], v206 offset:0x1800
	s_waitcnt lgkmcnt(4)
	v_cndmask_b32_e64 v98, v98, 1.0, vcc
	v_mfma_f32_32x32x64_f8f6f4 v[34:49], v[118:125], v[130:137], v[34:49]
	s_waitcnt lgkmcnt(0)
	v_cmp_gt_f32_e32 vcc, 1.0, v98
	v_exp_f32_e32 v66, v66
	v_exp_f32_e32 v67, v67
	v_exp_f32_e32 v68, v68
	v_exp_f32_e32 v69, v69
	v_mfma_f32_32x32x64_f8f6f4 v[50:65], v[118:125], v[100:107], v[50:65]
	s_cbranch_vccz .LBB0_521
	s_and_saveexec_b64 s[22:23], s[2:3]
	ds_write_b32 v207, v98 offset:128
	s_or_b64 exec, exec, s[22:23]
	s_waitcnt lgkmcnt(0)
	s_nop 15
	s_nop 7
	ds_read2_b32 v[100:101], v205 offset0:32 offset1:33
	ds_read2_b32 v[102:103], v205 offset0:34 offset1:35
	ds_read2_b32 v[104:105], v205 offset0:40 offset1:41
	ds_read2_b32 v[106:107], v205 offset0:42 offset1:43
	s_waitcnt lgkmcnt(0)
	v_pk_mul_f32 v[2:3], v[100:101], v[2:3]
	v_pk_mul_f32 v[18:19], v[100:101], v[18:19]
	v_pk_mul_f32 v[34:35], v[100:101], v[34:35]
	v_pk_mul_f32 v[50:51], v[100:101], v[50:51]
	v_pk_mul_f32 v[4:5], v[4:5], v[102:103]
	v_pk_mul_f32 v[20:21], v[20:21], v[102:103]
	v_pk_mul_f32 v[36:37], v[36:37], v[102:103]
	v_pk_mul_f32 v[52:53], v[52:53], v[102:103]
	v_pk_mul_f32 v[6:7], v[6:7], v[104:105]
	v_pk_mul_f32 v[22:23], v[22:23], v[104:105]
	v_pk_mul_f32 v[38:39], v[38:39], v[104:105]
	v_pk_mul_f32 v[54:55], v[54:55], v[104:105]
	v_pk_mul_f32 v[8:9], v[8:9], v[106:107]
	v_pk_mul_f32 v[24:25], v[24:25], v[106:107]
	v_pk_mul_f32 v[40:41], v[40:41], v[106:107]
	ds_read2_b32 v[100:101], v205 offset0:48 offset1:49
	v_pk_mul_f32 v[56:57], v[56:57], v[106:107]
	ds_read2_b32 v[102:103], v205 offset0:50 offset1:51
	ds_read2_b32 v[104:105], v205 offset0:56 offset1:57
	ds_read2_b32 v[106:107], v205 offset0:58 offset1:59
	s_waitcnt lgkmcnt(0)
	v_pk_mul_f32 v[10:11], v[10:11], v[100:101]
	v_pk_mul_f32 v[26:27], v[26:27], v[100:101]
	v_pk_mul_f32 v[42:43], v[42:43], v[100:101]
	v_pk_mul_f32 v[58:59], v[58:59], v[100:101]
	v_pk_mul_f32 v[12:13], v[12:13], v[102:103]
	v_pk_mul_f32 v[28:29], v[28:29], v[102:103]
	v_pk_mul_f32 v[44:45], v[44:45], v[102:103]
	v_pk_mul_f32 v[60:61], v[60:61], v[102:103]
	v_pk_mul_f32 v[14:15], v[14:15], v[104:105]
	v_pk_mul_f32 v[30:31], v[30:31], v[104:105]
	v_pk_mul_f32 v[46:47], v[46:47], v[104:105]
	v_pk_mul_f32 v[62:63], v[62:63], v[104:105]
	v_pk_mul_f32 v[16:17], v[16:17], v[106:107]
	v_pk_mul_f32 v[32:33], v[32:33], v[106:107]
	v_pk_mul_f32 v[48:49], v[48:49], v[106:107]
	v_pk_mul_f32 v[64:65], v[64:65], v[106:107]

.LBB0_523:
	v_exp_f32_e32 v99, v70
	v_add_f32_e32 v70, 0, v66
	v_exp_f32_e32 v71, v71
	v_add_f32_e32 v70, v67, v70
	v_exp_f32_e32 v100, v72
	v_add_f32_e32 v70, v68, v70
	v_exp_f32_e32 v101, v73
	v_add_f32_e32 v70, v69, v70
	v_exp_f32_e32 v102, v74
	v_add_f32_e32 v70, v99, v70
	v_exp_f32_e32 v75, v75
	v_add_f32_e32 v70, v71, v70
	v_exp_f32_e32 v103, v76
	v_add_f32_e32 v70, v100, v70
	v_exp_f32_e32 v104, v77
	v_add_f32_e32 v70, v101, v70
	v_exp_f32_e32 v105, v78
	v_add_f32_e32 v70, v102, v70
	v_exp_f32_e32 v79, v79
	v_add_f32_e32 v70, v75, v70
	v_exp_f32_e32 v80, v80
	v_add_f32_e32 v70, v103, v70
	v_exp_f32_e32 v81, v81
	v_add_f32_e32 v70, v104, v70
	v_exp_f32_e32 v73, v82
	v_add_f32_e32 v70, v105, v70
	v_exp_f32_e32 v74, v83
	v_add_f32_e32 v70, v79, v70
	v_exp_f32_e32 v78, v84
	v_add_f32_e32 v70, v80, v70
	v_exp_f32_e32 v82, v85
	v_add_f32_e32 v70, v81, v70
	v_exp_f32_e32 v83, v86
	v_add_f32_e32 v70, v73, v70
	v_exp_f32_e32 v84, v87
	v_add_f32_e32 v70, v74, v70
	v_exp_f32_e32 v85, v88
	v_add_f32_e32 v70, v78, v70
	v_exp_f32_e32 v86, v89
	v_add_f32_e32 v70, v82, v70
	v_exp_f32_e32 v87, v90
	v_add_f32_e32 v70, v83, v70
	v_exp_f32_e32 v88, v91
	v_add_f32_e32 v70, v84, v70
	v_exp_f32_e32 v89, v92
	v_add_f32_e32 v70, v85, v70
	v_exp_f32_e32 v90, v93
	v_add_f32_e32 v70, v86, v70
	v_exp_f32_e32 v91, v94
	v_add_f32_e32 v70, v87, v70
	v_mov_b32_e32 v76, v171
	v_exp_f32_e32 v92, v95
	v_add_f32_e32 v70, v88, v70
	v_cvt_pk_fp8_f32 v76, v73, v74
	v_exp_f32_e32 v93, v96
	v_add_f32_e32 v70, v89, v70
	v_exp_f32_e32 v94, v97
	v_add_f32_e32 v70, v90, v70
	v_mov_b32_e32 v74, v171
	v_add_f32_e32 v70, v91, v70
	v_cvt_pk_fp8_f32 v74, v102, v75
	v_mov_b32_e32 v75, v171
	v_add_f32_e32 v70, v92, v70
	v_mov_b32_e32 v72, v171
	v_mov_b32_e32 v73, v171
	v_mov_b32_e32 v77, v171
	v_cvt_pk_fp8_f32 v76, v78, v82 op_sel:[0,0,1]
	v_mov_b32_e32 v78, v171
	v_cvt_pk_fp8_f32 v75, v105, v79
	v_mov_b32_e32 v79, v171
	v_add_f32_e32 v70, v93, v70
	v_cvt_pk_fp8_f32 v72, v66, v67
	v_cvt_pk_fp8_f32 v73, v99, v71
	v_cvt_pk_fp8_f32 v77, v83, v84
	v_cvt_pk_fp8_f32 v78, v87, v88
	v_cvt_pk_fp8_f32 v79, v91, v92
	v_add_f32_e32 v70, v94, v70
	v_mov_b32_e32 v66, v70
	s_nop 1
	v_permlane32_swap_b32_e32 v70, v66
	v_cvt_pk_fp8_f32 v72, v68, v69 op_sel:[0,0,1]
	v_cvt_pk_fp8_f32 v73, v100, v101 op_sel:[0,0,1]
	v_cvt_pk_fp8_f32 v77, v85, v86 op_sel:[0,0,1]
	v_cvt_pk_fp8_f32 v74, v103, v104 op_sel:[0,0,1]
	v_cvt_pk_fp8_f32 v78, v89, v90 op_sel:[0,0,1]
	v_cvt_pk_fp8_f32 v75, v80, v81 op_sel:[0,0,1]
	v_cvt_pk_fp8_f32 v79, v93, v94 op_sel:[0,0,1]
	ds_read_b64_tr_b8 v[80:81], v204 offset:0
	ds_read_b64_tr_b8 v[82:83], v204 offset:0x800
	ds_read_b64_tr_b8 v[84:85], v204 offset:0x1000
	ds_read_b64_tr_b8 v[86:87], v204 offset:0x1800
	s_waitcnt lgkmcnt(0)
	s_nop 0
	v_mfma_f32_32x32x64_f8f6f4 v[2:17], v[72:79], v[80:87], v[2:17]
	ds_read_b64_tr_b8 v[80:81], v203 offset:0
	ds_read_b64_tr_b8 v[82:83], v203 offset:0x800
	ds_read_b64_tr_b8 v[84:85], v203 offset:0x1000
	ds_read_b64_tr_b8 v[86:87], v203 offset:0x1800
	s_waitcnt lgkmcnt(0)
	s_nop 0
	v_mfma_f32_32x32x64_f8f6f4 v[18:33], v[72:79], v[80:87], v[18:33]
	ds_read_b64_tr_b8 v[80:81], v202 offset:0
	ds_read_b64_tr_b8 v[82:83], v202 offset:0x800
	ds_read_b64_tr_b8 v[84:85], v202 offset:0x1000
	ds_read_b64_tr_b8 v[86:87], v202 offset:0x1800
	s_waitcnt lgkmcnt(0)
	s_nop 0
	v_mfma_f32_32x32x64_f8f6f4 v[34:49], v[72:79], v[80:87], v[34:49]
	ds_read_b64_tr_b8 v[80:81], v201 offset:0
	ds_read_b64_tr_b8 v[82:83], v201 offset:0x800
	ds_read_b64_tr_b8 v[84:85], v201 offset:0x1000
	ds_read_b64_tr_b8 v[86:87], v201 offset:0x1800
	s_waitcnt lgkmcnt(0)
	s_nop 0
	v_mfma_f32_32x32x64_f8f6f4 v[50:65], v[72:79], v[80:87], v[50:65]
	s_nop 0
	s_nop 15
	s_nop 7
	s_nop 0
	v_and_b32_e32 v67, 31, v199
	v_cmp_gt_u32_e32 vcc, 32, v199
	s_and_saveexec_b64 s[2:3], vcc
	s_cbranch_execz .LBB0_493
	v_add_f32_e32 v68, v126, v127
	v_fmac_f32_e32 v68, v200, v128
	v_add_f32_e32 v66, v70, v66
	v_fmac_f32_e32 v66, v68, v98
	v_lshl_add_u32 v68, v67, 2, s54
	ds_write_b32 v68, v66
	s_branch .LBB0_493

.LBB0_550:
	v_lshrrev_b32_e32 v4, 3, v39
	v_and_b32_e32 v3, 8, v39
	v_and_b32_e32 v58, 4, v4
	v_bfe_u32 v4, v39, 1, 2
	v_or3_b32 v3, v4, v3, v58
	v_lshlrev_b32_e32 v4, 3, v39
	v_bfe_u32 v56, v39, 1, 3
	v_lshlrev_b32_e32 v3, 7, v3
	v_and_b32_e32 v4, 8, v4
	v_and_b32_e32 v57, 1, v2
	v_add3_u32 v59, v4, s63, v3
	v_bitop3_b32 v2, v2, v56, 1 bitop3:0x6c
	v_lshlrev_b32_e32 v48, 3, v38
	v_lshl_add_u32 v195, v2, 4, v59
	v_bitop3_b32 v2, v48, v162, s28 bitop3:0x6c
	v_lshl_add_u32 v49, v38, 7, s63
	s_waitcnt lgkmcnt(0)
	v_add_u32_e32 v199, v49, v2
	v_or_b32_e32 v2, 16, v162
	s_barrier
	v_bitop3_b32 v2, v48, v2, s28 bitop3:0x6c
	v_add_u32_e32 v200, v49, v2
	ds_read_b128 v[2:5], v199 offset:32768
	ds_read_b128 v[40:43], v199 offset:36864
	ds_read_b128 v[6:9], v200 offset:32768
	ds_read_b128 v[44:47], v200 offset:36864
	v_bitop3_b32 v10, v57, v56, 2 bitop3:0x36
	v_lshl_add_u32 v196, v10, 4, v59
	v_bitop3_b32 v10, v57, v56, 4 bitop3:0x36
	v_lshl_add_u32 v194, v10, 4, v59
	s_waitcnt vmcnt(0) lgkmcnt(0)
	v_mfma_f32_32x32x64_f8f6f4 v[18:33], v[2:9], v[154:161], 0
	v_mfma_f32_32x32x64_f8f6f4 v[2:17], v[40:47], v[154:161], 0
	v_or_b32_e32 v40, 64, v162
	v_bitop3_b32 v40, v48, v40, s28 bitop3:0x6c
	v_add_u32_e32 v197, v49, v40
	v_or_b32_e32 v40, 0x50, v162
	v_bitop3_b32 v40, v48, v40, s28 bitop3:0x6c
	v_add_u32_e32 v198, v49, v40
	ds_read_b128 v[40:43], v197 offset:32768
	ds_read_b128 v[48:51], v197 offset:36864
	ds_read_b128 v[44:47], v198 offset:32768
	ds_read_b128 v[52:55], v198 offset:36864
	s_waitcnt lgkmcnt(1)
	v_mfma_f32_32x32x64_f8f6f4 v[18:33], v[40:47], v[146:153], v[18:33]
	s_waitcnt lgkmcnt(0)
	v_mfma_f32_32x32x64_f8f6f4 v[2:17], v[48:55], v[146:153], v[2:17]
	v_and_b32_e32 v183, 63, v39
	s_nop 15
	s_nop 7
	s_and_b32 s24, s42, 0x3fffffc0
	v_max_f32_e32 v39, v19, v19
	v_max_f32_e32 v40, v18, v18
	v_max_f32_e32 v39, v40, v39
	v_max3_f32 v39, v39, v20, v21
	v_max3_f32 v39, v39, v22, v23
	v_max3_f32 v39, v39, v24, v25
	v_max3_f32 v39, v39, v26, v27
	v_max3_f32 v39, v39, v28, v29
	v_max3_f32 v39, v39, v30, v31
	v_max3_f32 v39, v39, v32, v33
	v_max3_f32 v39, v39, v2, v3
	v_max3_f32 v39, v39, v4, v5
	v_max3_f32 v39, v39, v6, v7
	v_max3_f32 v39, v39, v8, v9
	v_max3_f32 v39, v39, v10, v11
	v_max3_f32 v39, v39, v12, v13
	v_max3_f32 v39, v39, v14, v15
	v_max3_f32 v39, v39, v16, v17
	v_mov_b32_e32 v40, v39
	s_nop 1
	v_permlane32_swap_b32_e32 v39, v40
	v_max_f32_e32 v40, v40, v40
	v_max_f32_e32 v39, v39, v39
	v_max_f32_e32 v39, v39, v40
	v_add_f32_e32 v40, 0x7149f2ca, v39
	v_max_f32_e32 v39, 0xf149f2ca, v39
	s_lshl_b32 s24, s24, 2
	v_sub_f32_e32 v41, 0xf149f2ca, v39
	s_add_i32 s24, s5, s24
	v_mul_f32_e32 v41, 0x3e0293ee, v41
	v_cmp_ge_f32_e32 vcc, s29, v40
	v_exp_f32_e32 v41, v41
	s_cmp_eq_u64 vcc, exec
	s_cselect_b64 vcc, -1, 0
	s_add_u32 s2, s22, s2
	v_cndmask_b32_e32 v202, v39, v182, vcc
	s_addc_u32 s3, s23, s3
	s_add_i32 s25, s63, s43
	v_fma_f32 v40, v202, s33, 4.0
	s_add_i32 s43, s25, 0x4000
	v_pk_fma_f32 v[66:67], v[2:3], s[4:5], v[40:41] op_sel_hi:[1,0,0]
	v_lshl_add_u64 v[2:3], s[2:3], 0, v[36:37]
	s_mov_b32 m0, s43
	v_lshl_add_u64 v[168:169], v[36:37], 0, s[16:17]
	global_load_lds_dwordx4 v[2:3], off
	s_add_u32 s16, s39, 0x80
	s_addc_u32 s17, s45, 0
	v_mov_b32_e32 v39, v40
	v_lshl_add_u64 v[164:165], s[20:21], 0, v[34:35]
	s_mul_i32 s17, s41, s17
	s_mul_hi_u32 s20, s41, s16
	v_fmamk_f32 v18, v18, 0x3e0293ee, v40
	v_fmamk_f32 v19, v19, 0x3e0293ee, v40
	v_fmamk_f32 v20, v20, 0x3e0293ee, v40
	v_fmamk_f32 v21, v21, 0x3e0293ee, v40
	v_fmamk_f32 v22, v22, 0x3e0293ee, v40
	v_fmamk_f32 v23, v23, 0x3e0293ee, v40
	v_fmamk_f32 v24, v24, 0x3e0293ee, v40
	v_fmamk_f32 v25, v25, 0x3e0293ee, v40
	v_fmamk_f32 v26, v26, 0x3e0293ee, v40
	v_fmamk_f32 v27, v27, 0x3e0293ee, v40
	v_fmamk_f32 v28, v28, 0x3e0293ee, v40
	v_fmamk_f32 v29, v29, 0x3e0293ee, v40
	v_fmamk_f32 v30, v30, 0x3e0293ee, v40
	v_fmamk_f32 v31, v31, 0x3e0293ee, v40
	v_fmamk_f32 v32, v32, 0x3e0293ee, v40
	v_fmac_f32_e32 v39, 0x3e0293ee, v33
	s_add_i32 s20, s20, s17
	s_mul_i32 s16, s41, s16
	v_exp_f32_e32 v82, v18
	v_exp_f32_e32 v83, v19
	v_exp_f32_e32 v84, v20
	v_exp_f32_e32 v85, v21
	v_exp_f32_e32 v176, v22
	v_exp_f32_e32 v177, v23
	v_exp_f32_e32 v174, v24
	v_exp_f32_e32 v175, v25
	v_exp_f32_e32 v172, v26
	v_exp_f32_e32 v173, v27
	v_exp_f32_e32 v140, v28
	v_exp_f32_e32 v141, v29
	v_exp_f32_e32 v144, v30
	v_exp_f32_e32 v145, v31
	v_exp_f32_e32 v142, v32
	v_exp_f32_e32 v143, v39
	s_waitcnt vmcnt(1)
	s_add_u32 s16, s16, s44
	v_bitop3_b32 v56, v57, v56, 6 bitop3:0x36
	s_barrier
	s_addc_u32 s17, s20, 0
	v_lshl_add_u32 v192, v56, 4, v59
	s_add_u32 s16, s30, s16
	v_mov_b32_e32 v162, 0
	s_mov_b32 s42, 2
	v_cndmask_b32_e64 v201, v41, 1.0, vcc
	v_pk_fma_f32 v[80:81], v[16:17], s[4:5], v[40:41] op_sel_hi:[1,0,0]
	v_pk_fma_f32 v[78:79], v[14:15], s[4:5], v[40:41] op_sel_hi:[1,0,0]
	v_pk_fma_f32 v[76:77], v[12:13], s[4:5], v[40:41] op_sel_hi:[1,0,0]
	v_pk_fma_f32 v[74:75], v[10:11], s[4:5], v[40:41] op_sel_hi:[1,0,0]
	v_pk_fma_f32 v[72:73], v[8:9], s[4:5], v[40:41] op_sel_hi:[1,0,0]
	v_pk_fma_f32 v[70:71], v[6:7], s[4:5], v[40:41] op_sel_hi:[1,0,0]
	v_pk_fma_f32 v[68:69], v[4:5], s[4:5], v[40:41] op_sel_hi:[1,0,0]
	v_cmp_gt_u32_e64 s[2:3], 32, v183
	v_lshl_add_u32 v193, v38, 2, s24
	v_lshl_add_u32 v191, v58, 2, s24
	v_add_u32_e32 v190, 0x4000, v195
	v_add_u32_e32 v189, 0x4000, v196
	v_add_u32_e32 v188, 0x4000, v194
	v_add_u32_e32 v187, 0x4000, v192
	v_lshl_add_u64 v[166:167], s[22:23], 0, v[36:37]
	s_addc_u32 s17, s31, s17
	s_lshl_b32 s21, s41, 7
	v_lshl_add_u64 v[170:171], v[34:35], 0, s[18:19]
	s_movk_i32 s22, 0xc0
	v_mov_b32_e32 v2, 0
	v_mov_b32_e32 v3, v162
	v_mov_b32_e32 v4, v162
	v_mov_b32_e32 v5, v162
	v_mov_b32_e32 v6, v162
	v_mov_b32_e32 v7, v162
	v_mov_b32_e32 v8, v162
	v_mov_b32_e32 v9, v162
	v_mov_b32_e32 v10, v162
	v_mov_b32_e32 v11, v162
	v_mov_b32_e32 v12, v162
	v_mov_b32_e32 v13, v162
	v_mov_b32_e32 v14, v162
	v_mov_b32_e32 v15, v162
	v_mov_b32_e32 v16, v162
	v_mov_b32_e32 v17, v162
	v_mov_b32_e32 v18, 0
	v_mov_b32_e32 v19, v162
	v_mov_b32_e32 v20, v162
	v_mov_b32_e32 v21, v162
	v_mov_b32_e32 v22, v162
	v_mov_b32_e32 v23, v162
	v_mov_b32_e32 v24, v162
	v_mov_b32_e32 v25, v162
	v_mov_b32_e32 v26, v162
	v_mov_b32_e32 v27, v162
	v_mov_b32_e32 v28, v162
	v_mov_b32_e32 v29, v162
	v_mov_b32_e32 v30, v162
	v_mov_b32_e32 v31, v162
	v_mov_b32_e32 v32, v162
	v_mov_b32_e32 v33, v162
	v_mov_b32_e32 v34, 0
	v_mov_b32_e32 v35, v162
	v_mov_b32_e32 v36, v162
	v_mov_b32_e32 v37, v162
	v_mov_b32_e32 v38, v162
	v_mov_b32_e32 v39, v162
	v_mov_b32_e32 v40, v162
	v_mov_b32_e32 v41, v162
	v_mov_b32_e32 v42, v162
	v_mov_b32_e32 v43, v162
	v_mov_b32_e32 v44, v162
	v_mov_b32_e32 v45, v162
	v_mov_b32_e32 v46, v162
	v_mov_b32_e32 v47, v162
	v_mov_b32_e32 v48, v162
	v_mov_b32_e32 v49, v162
	v_mov_b32_e32 v50, 0
	v_mov_b32_e32 v51, v162
	v_mov_b32_e32 v52, v162
	v_mov_b32_e32 v53, v162
	v_mov_b32_e32 v54, v162
	v_mov_b32_e32 v55, v162
	v_mov_b32_e32 v56, v162
	v_mov_b32_e32 v57, v162
	v_mov_b32_e32 v58, v162
	v_mov_b32_e32 v59, v162
	v_mov_b32_e32 v60, v162
	v_mov_b32_e32 v61, v162
	v_mov_b32_e32 v62, v162
	v_mov_b32_e32 v63, v162
	v_mov_b32_e32 v64, v162
	v_mov_b32_e32 v65, v162
.LBB0_551:
	s_add_i32 s20, s25, 0x8000
	v_lshl_add_u64 v[86:87], s[16:17], 0, v[170:171]
	s_mov_b32 m0, s20
	s_nop 0
	global_load_lds_dwordx4 v[86:87], off
	ds_read_b128 v[106:109], v200 offset:49152
	ds_read_b128 v[102:105], v199 offset:49152
	ds_read_b128 v[130:133], v199 offset:53248
	ds_read_b128 v[134:137], v200 offset:53248
	s_mov_b32 m0, s25
	s_waitcnt lgkmcnt(0)
	v_mfma_f32_32x32x64_f8f6f4 v[86:101], v[102:109], v[154:161], 0
	s_nop 0
	v_exp_f32_e32 v66, v66
	v_exp_f32_e32 v67, v67
	v_exp_f32_e32 v68, v68
	v_exp_f32_e32 v69, v69
	ds_read_b128 v[102:105], v197 offset:49152
	ds_read_b128 v[106:109], v198 offset:49152
	v_mfma_f32_32x32x64_f8f6f4 v[114:129], v[130:137], v[154:161], 0
	ds_read_b128 v[204:207], v197 offset:53248
	ds_read_b128 v[208:211], v198 offset:53248
	v_exp_f32_e32 v70, v70
	v_exp_f32_e32 v71, v71
	v_exp_f32_e32 v72, v72
	v_exp_f32_e32 v73, v73
	s_waitcnt lgkmcnt(0)
	v_mfma_f32_32x32x64_f8f6f4 v[86:101], v[102:109], v[146:153], v[86:101]
	v_mov_b32_e32 v130, 0
	v_exp_f32_e32 v74, v74
	v_exp_f32_e32 v75, v75
	v_exp_f32_e32 v76, v76
	v_exp_f32_e32 v77, v77
	v_mfma_f32_32x32x64_f8f6f4 v[114:129], v[204:211], v[146:153], v[114:129]
	ds_read_b64_tr_b8 v[102:103], v195 offset:0
	ds_read_b64_tr_b8 v[104:105], v195 offset:0x800
	ds_read_b64_tr_b8 v[106:107], v195 offset:0x1000
	v_mov_b32_e32 v134, 0
	v_exp_f32_e32 v78, v78
	v_exp_f32_e32 v79, v79
	v_mov_b32_e32 v131, 0
	v_mov_b32_e32 v135, 0
	v_mov_b32_e32 v132, 0
	v_mov_b32_e32 v136, 0
	v_mov_b32_e32 v133, 0
	v_mov_b32_e32 v137, 0
	ds_read_b64_tr_b8 v[108:109], v195 offset:0x1800
	v_cvt_pk_fp8_f32 v130, v82, v83
	v_exp_f32_e32 v80, v80
	v_exp_f32_e32 v81, v81
	v_cvt_pk_fp8_f32 v134, v66, v67
	v_cvt_pk_fp8_f32 v131, v176, v177
	v_cvt_pk_fp8_f32 v135, v70, v71
	v_cvt_pk_fp8_f32 v132, v172, v173
	v_cvt_pk_fp8_f32 v136, v74, v75
	v_cvt_pk_fp8_f32 v133, v144, v145
	v_cvt_pk_fp8_f32 v137, v78, v79
	ds_read_b64_tr_b8 v[206:207], v196 offset:0
	ds_read_b64_tr_b8 v[208:209], v196 offset:0x800
	ds_read_b64_tr_b8 v[210:211], v196 offset:0x1000
	ds_read_b64_tr_b8 v[212:213], v196 offset:0x1800
	v_cvt_pk_fp8_f32 v130, v84, v85 op_sel:[0,0,1]
	v_cvt_pk_fp8_f32 v134, v68, v69 op_sel:[0,0,1]
	v_cvt_pk_fp8_f32 v131, v174, v175 op_sel:[0,0,1]
	v_cvt_pk_fp8_f32 v135, v72, v73 op_sel:[0,0,1]
	v_cvt_pk_fp8_f32 v132, v140, v141 op_sel:[0,0,1]
	v_cvt_pk_fp8_f32 v136, v76, v77 op_sel:[0,0,1]
	v_cvt_pk_fp8_f32 v133, v142, v143 op_sel:[0,0,1]
	v_cvt_pk_fp8_f32 v137, v80, v81 op_sel:[0,0,1]
	s_waitcnt lgkmcnt(4)
	v_pk_add_f32 v[82:83], v[82:83], v[84:85]
	v_mfma_f32_32x32x64_f8f6f4 v[2:17], v[130:137], v[102:109], v[2:17]
	ds_read_b64_tr_b8 v[214:215], v194 offset:0
	ds_read_b64_tr_b8 v[216:217], v194 offset:0x800
	ds_read_b64_tr_b8 v[218:219], v194 offset:0x1000
	ds_read_b64_tr_b8 v[220:221], v194 offset:0x1800
	s_waitcnt lgkmcnt(4)
	s_nop 0
	v_max_f32_e32 v102, v87, v87
	v_max_f32_e32 v103, v86, v86
	v_max_f32_e32 v102, v103, v102
	v_max3_f32 v102, v102, v88, v89
	v_max3_f32 v102, v102, v90, v91
	v_max3_f32 v102, v102, v92, v93
	v_max3_f32 v102, v102, v94, v95
	v_max3_f32 v102, v102, v96, v97
	v_max3_f32 v102, v102, v98, v99
	v_max3_f32 v102, v102, v100, v101
	v_max3_f32 v102, v102, v114, v115
	v_max3_f32 v102, v102, v116, v117
	v_max3_f32 v102, v102, v118, v119
	v_max3_f32 v102, v102, v120, v121
	v_max3_f32 v102, v102, v122, v123
	v_max3_f32 v102, v102, v124, v125
	v_max3_f32 v102, v102, v126, v127
	v_max3_f32 v102, v102, v128, v129
	v_mov_b32_e32 v103, v102
	s_nop 1
	v_permlane32_swap_b32_e32 v102, v103
	v_max_f32_e32 v103, v103, v103
	v_max_f32_e32 v102, v102, v102
	v_max_f32_e32 v102, v102, v103
	v_sub_f32_e32 v103, v102, v202
	v_cmp_ge_f32_e32 vcc, s29, v103
	s_cmp_eq_u64 vcc, exec
	v_max_f32_e32 v103, v202, v202
	v_max_f32_e32 v139, v103, v102
	s_cselect_b64 vcc, -1, 0
	v_cndmask_b32_e32 v204, v139, v202, vcc
	v_fma_f32 v138, v204, s33, 4.0
	v_mfma_f32_32x32x64_f8f6f4 v[18:33], v[130:137], v[206:213], v[18:33]
	v_pk_add_f32 v[82:83], v[176:177], v[82:83]
	v_pk_fma_f32 v[110:111], v[98:99], s[4:5], v[138:139] op_sel_hi:[1,0,0]
	v_pk_fma_f32 v[98:99], v[86:87], s[4:5], v[138:139] op_sel_hi:[1,0,0]
	ds_read_b64_tr_b8 v[86:87], v192 offset:0
	v_pk_fma_f32 v[112:113], v[100:101], s[4:5], v[138:139] op_sel_hi:[1,0,0]
	v_pk_fma_f32 v[100:101], v[88:89], s[4:5], v[138:139] op_sel_hi:[1,0,0]
	ds_read_b64_tr_b8 v[88:89], v192 offset:0x800
	v_pk_fma_f32 v[102:103], v[90:91], s[4:5], v[138:139] op_sel_hi:[1,0,0]
	ds_read_b64_tr_b8 v[90:91], v192 offset:0x1000
	v_pk_fma_f32 v[108:109], v[96:97], s[4:5], v[138:139] op_sel_hi:[1,0,0]
	v_pk_fma_f32 v[106:107], v[94:95], s[4:5], v[138:139] op_sel_hi:[1,0,0]
	v_pk_fma_f32 v[104:105], v[92:93], s[4:5], v[138:139] op_sel_hi:[1,0,0]
	v_pk_fma_f32 v[128:129], v[128:129], s[4:5], v[138:139] op_sel_hi:[1,0,0]
	v_pk_fma_f32 v[126:127], v[126:127], s[4:5], v[138:139] op_sel_hi:[1,0,0]
	v_pk_fma_f32 v[124:125], v[124:125], s[4:5], v[138:139] op_sel_hi:[1,0,0]
	v_pk_fma_f32 v[122:123], v[122:123], s[4:5], v[138:139] op_sel_hi:[1,0,0]
	v_pk_fma_f32 v[120:121], v[120:121], s[4:5], v[138:139] op_sel_hi:[1,0,0]
	v_pk_fma_f32 v[118:119], v[118:119], s[4:5], v[138:139] op_sel_hi:[1,0,0]
	v_pk_fma_f32 v[116:117], v[116:117], s[4:5], v[138:139] op_sel_hi:[1,0,0]
	v_pk_fma_f32 v[114:115], v[114:115], s[4:5], v[138:139] op_sel_hi:[1,0,0]
	ds_read_b64_tr_b8 v[92:93], v192 offset:0x1800
	s_waitcnt lgkmcnt(4)
	v_pk_add_f32 v[82:83], v[174:175], v[82:83]
	v_mfma_f32_32x32x64_f8f6f4 v[34:49], v[130:137], v[214:221], v[34:49]
	s_waitcnt lgkmcnt(0)
	s_nop 0
	v_exp_f32_e32 v98, v98
	v_exp_f32_e32 v99, v99
	v_exp_f32_e32 v100, v100
	v_exp_f32_e32 v101, v101
	v_mfma_f32_32x32x64_f8f6f4 v[50:65], v[130:137], v[86:93], v[50:65]
	s_barrier
	v_lshl_add_u64 v[86:87], s[16:17], 0, v[168:169]
	global_load_lds_dwordx4 v[86:87], off
	v_pk_add_f32 v[82:83], v[172:173], v[82:83]
	s_nop 0
	v_pk_add_f32 v[82:83], v[140:141], v[82:83]
	s_nop 0
	v_pk_add_f32 v[82:83], v[144:145], v[82:83]
	s_nop 0
	v_pk_add_f32 v[82:83], v[142:143], v[82:83]
	s_nop 0
	v_pk_add_f32 v[66:67], v[82:83], v[66:67]
	s_nop 0
	v_pk_add_f32 v[66:67], v[68:69], v[66:67]
	s_nop 0
	v_pk_add_f32 v[66:67], v[70:71], v[66:67]
	s_nop 0
	v_pk_add_f32 v[66:67], v[72:73], v[66:67]
	s_nop 0
	v_pk_add_f32 v[66:67], v[74:75], v[66:67]
	s_nop 0
	v_pk_add_f32 v[66:67], v[76:77], v[66:67]
	s_nop 0
	v_pk_add_f32 v[66:67], v[78:79], v[66:67]
	s_nop 0
	v_pk_add_f32 v[66:67], v[80:81], v[66:67]
	s_nop 0
	v_pk_add_f32 v[172:173], v[66:67], v[66:67] op_sel:[0,1] op_sel_hi:[1,0]
	v_sub_f32_e32 v66, v202, v139
	v_mul_f32_e32 v66, 0x3e0293ee, v66
	v_exp_f32_e32 v66, v66
	v_mov_b32_e32 v203, v172
	s_nop 1
	v_permlane32_swap_b32_e32 v172, v203
	v_cndmask_b32_e64 v173, v66, 1.0, vcc
	v_cmp_gt_f32_e32 vcc, 1.0, v173
	s_cbranch_vccz .LBB0_555
	s_and_saveexec_b64 s[18:19], s[2:3]
	ds_write_b32 v193, v173 offset:128
	s_or_b64 exec, exec, s[18:19]
	s_waitcnt lgkmcnt(0)
	s_nop 15
	s_nop 7
	ds_read2_b32 v[66:67], v191 offset0:32 offset1:33
	ds_read2_b32 v[68:69], v191 offset0:34 offset1:35
	ds_read2_b32 v[70:71], v191 offset0:40 offset1:41
	ds_read2_b32 v[72:73], v191 offset0:42 offset1:43
	s_waitcnt lgkmcnt(0)
	v_pk_mul_f32 v[2:3], v[66:67], v[2:3]
	v_pk_mul_f32 v[18:19], v[66:67], v[18:19]
	v_pk_mul_f32 v[34:35], v[66:67], v[34:35]
	v_pk_mul_f32 v[50:51], v[66:67], v[50:51]
	v_pk_mul_f32 v[4:5], v[4:5], v[68:69]
	v_pk_mul_f32 v[20:21], v[20:21], v[68:69]
	v_pk_mul_f32 v[36:37], v[36:37], v[68:69]
	v_pk_mul_f32 v[52:53], v[52:53], v[68:69]
	v_pk_mul_f32 v[6:7], v[6:7], v[70:71]
	v_pk_mul_f32 v[22:23], v[22:23], v[70:71]
	v_pk_mul_f32 v[38:39], v[38:39], v[70:71]
	v_pk_mul_f32 v[54:55], v[54:55], v[70:71]
	v_pk_mul_f32 v[8:9], v[8:9], v[72:73]
	v_pk_mul_f32 v[24:25], v[24:25], v[72:73]
	v_pk_mul_f32 v[40:41], v[40:41], v[72:73]
	ds_read2_b32 v[66:67], v191 offset0:48 offset1:49
	v_pk_mul_f32 v[56:57], v[56:57], v[72:73]
	ds_read2_b32 v[68:69], v191 offset0:50 offset1:51
	ds_read2_b32 v[70:71], v191 offset0:56 offset1:57
	ds_read2_b32 v[72:73], v191 offset0:58 offset1:59
	s_waitcnt lgkmcnt(0)
	v_pk_mul_f32 v[10:11], v[10:11], v[66:67]
	v_pk_mul_f32 v[26:27], v[26:27], v[66:67]
	v_pk_mul_f32 v[42:43], v[42:43], v[66:67]
	v_pk_mul_f32 v[58:59], v[58:59], v[66:67]
	v_pk_mul_f32 v[12:13], v[12:13], v[68:69]
	v_pk_mul_f32 v[28:29], v[28:29], v[68:69]
	v_pk_mul_f32 v[44:45], v[44:45], v[68:69]
	v_pk_mul_f32 v[60:61], v[60:61], v[68:69]
	v_pk_mul_f32 v[14:15], v[14:15], v[70:71]
	v_pk_mul_f32 v[30:31], v[30:31], v[70:71]
	v_pk_mul_f32 v[46:47], v[46:47], v[70:71]
	v_pk_mul_f32 v[62:63], v[62:63], v[70:71]
	v_pk_mul_f32 v[16:17], v[16:17], v[72:73]
	v_pk_mul_f32 v[32:33], v[32:33], v[72:73]
	v_pk_mul_f32 v[48:49], v[48:49], v[72:73]
	v_pk_mul_f32 v[64:65], v[64:65], v[72:73]
.LBB0_555:
	s_add_i32 s18, s42, 1
	s_cmp_lt_u32 s18, s40
	s_cselect_b32 s18, 0, s40
	s_cselect_b32 s19, s39, 0
	s_lshl_b32 s18, s18, 6
	s_ashr_i32 s23, s19, 31
	s_sub_i32 s18, s22, s18
	s_add_u32 s18, s18, s19
	s_addc_u32 s19, 0, s23
	v_mov_b32_e32 v205, s41
	s_waitcnt vmcnt(1)
	v_mad_u64_u32 v[66:67], s[44:45], s18, v205, v[164:165]
	s_mul_i32 s19, s19, s41
	s_add_i32 s23, s25, 0xc000
	s_barrier
	v_add_u32_e32 v67, s19, v67
	s_mov_b32 m0, s23
	v_exp_f32_e32 v178, v106
	global_load_lds_dwordx4 v[66:67], off
	v_exp_f32_e32 v174, v102
	v_exp_f32_e32 v175, v103
	v_exp_f32_e32 v176, v104
	v_exp_f32_e32 v177, v105
	v_exp_f32_e32 v179, v107
	v_exp_f32_e32 v180, v108
	v_exp_f32_e32 v181, v109
	v_exp_f32_e32 v110, v110
	v_exp_f32_e32 v111, v111
	v_exp_f32_e32 v112, v112
	v_exp_f32_e32 v113, v113
	ds_read_b128 v[86:89], v200 offset:32768
	ds_read_b128 v[82:85], v199 offset:32768
	ds_read_b128 v[90:93], v199 offset:36864
	ds_read_b128 v[94:97], v200 offset:36864
	v_mov_b32_e32 v102, 0
	v_mov_b32_e32 v106, 0
	s_waitcnt lgkmcnt(0)
	v_mfma_f32_32x32x64_f8f6f4 v[66:81], v[82:89], v[154:161], 0
	ds_read_b128 v[82:85], v197 offset:32768
	ds_read_b128 v[86:89], v198 offset:32768
	v_exp_f32_e32 v114, v114
	v_exp_f32_e32 v115, v115
	v_exp_f32_e32 v116, v116
	v_exp_f32_e32 v117, v117
	v_mfma_f32_32x32x64_f8f6f4 v[130:145], v[90:97], v[154:161], 0
	ds_read_b128 v[90:93], v197 offset:36864
	ds_read_b128 v[94:97], v198 offset:36864
	v_exp_f32_e32 v118, v118
	v_exp_f32_e32 v119, v119
	v_exp_f32_e32 v120, v120
	v_exp_f32_e32 v121, v121
	s_waitcnt lgkmcnt(0)
	v_mfma_f32_32x32x64_f8f6f4 v[66:81], v[82:89], v[146:153], v[66:81]
	v_mov_b32_e32 v103, 0
	v_exp_f32_e32 v122, v122
	v_exp_f32_e32 v123, v123
	v_exp_f32_e32 v124, v124
	v_exp_f32_e32 v125, v125
	v_mfma_f32_32x32x64_f8f6f4 v[130:145], v[90:97], v[146:153], v[130:145]
	ds_read_b64_tr_b8 v[82:83], v190 offset:0
	ds_read_b64_tr_b8 v[84:85], v190 offset:0x800
	ds_read_b64_tr_b8 v[86:87], v190 offset:0x1000
	v_mov_b32_e32 v107, 0
	v_exp_f32_e32 v126, v126
	v_exp_f32_e32 v127, v127
	v_mov_b32_e32 v104, 0
	v_mov_b32_e32 v108, 0
	v_mov_b32_e32 v105, 0
	v_mov_b32_e32 v109, 0
	ds_read_b64_tr_b8 v[88:89], v190 offset:0x1800
	v_cvt_pk_fp8_f32 v102, v98, v99
	v_exp_f32_e32 v128, v128
	v_exp_f32_e32 v129, v129
	v_cvt_pk_fp8_f32 v106, v114, v115
	v_cvt_pk_fp8_f32 v103, v174, v175
	v_cvt_pk_fp8_f32 v107, v118, v119
	v_cvt_pk_fp8_f32 v104, v178, v179
	v_cvt_pk_fp8_f32 v108, v122, v123
	v_cvt_pk_fp8_f32 v105, v110, v111
	v_cvt_pk_fp8_f32 v109, v126, v127
	ds_read_b64_tr_b8 v[90:91], v189 offset:0
	ds_read_b64_tr_b8 v[92:93], v189 offset:0x800
	ds_read_b64_tr_b8 v[94:95], v189 offset:0x1000
	ds_read_b64_tr_b8 v[96:97], v189 offset:0x1800
	v_cvt_pk_fp8_f32 v102, v100, v101 op_sel:[0,0,1]
	v_cvt_pk_fp8_f32 v106, v116, v117 op_sel:[0,0,1]
	v_cvt_pk_fp8_f32 v103, v176, v177 op_sel:[0,0,1]
	v_cvt_pk_fp8_f32 v107, v120, v121 op_sel:[0,0,1]
	v_cvt_pk_fp8_f32 v104, v180, v181 op_sel:[0,0,1]
	v_cvt_pk_fp8_f32 v108, v124, v125 op_sel:[0,0,1]
	v_cvt_pk_fp8_f32 v105, v112, v113 op_sel:[0,0,1]
	v_cvt_pk_fp8_f32 v109, v128, v129 op_sel:[0,0,1]
	s_waitcnt lgkmcnt(4)
	s_mov_b32 m0, s43
	v_mfma_f32_32x32x64_f8f6f4 v[2:17], v[102:109], v[82:89], v[2:17]
	ds_read_b64_tr_b8 v[206:207], v188 offset:0
	ds_read_b64_tr_b8 v[208:209], v188 offset:0x800
	ds_read_b64_tr_b8 v[210:211], v188 offset:0x1000
	ds_read_b64_tr_b8 v[212:213], v188 offset:0x1800
	s_waitcnt lgkmcnt(4)
	s_nop 0
	v_max_f32_e32 v82, v67, v67
	v_max_f32_e32 v83, v66, v66
	v_max_f32_e32 v82, v83, v82
	v_max3_f32 v82, v82, v68, v69
	v_max3_f32 v82, v82, v70, v71
	v_max3_f32 v82, v82, v72, v73
	v_max3_f32 v82, v82, v74, v75
	v_max3_f32 v82, v82, v76, v77
	v_max3_f32 v82, v82, v78, v79
	v_max3_f32 v82, v82, v80, v81
	v_max3_f32 v82, v82, v130, v131
	v_max3_f32 v82, v82, v132, v133
	v_max3_f32 v82, v82, v134, v135
	v_max3_f32 v82, v82, v136, v137
	v_max3_f32 v82, v82, v138, v139
	v_max3_f32 v82, v82, v140, v141
	v_max3_f32 v82, v82, v142, v143
	v_max3_f32 v82, v82, v144, v145
	v_mov_b32_e32 v83, v82
	s_nop 1
	v_permlane32_swap_b32_e32 v82, v83
	v_max_f32_e32 v83, v83, v83
	v_max_f32_e32 v82, v82, v82
	v_max_f32_e32 v82, v82, v83
	v_sub_f32_e32 v83, v82, v204
	v_cmp_ge_f32_e32 vcc, s29, v83
	s_cmp_eq_u64 vcc, exec
	v_max_f32_e32 v83, v204, v204
	v_max_f32_e32 v215, v83, v82
	s_cselect_b64 vcc, -1, 0
	v_cndmask_b32_e32 v202, v215, v204, vcc
	v_fma_f32 v214, v202, s33, 4.0
	v_mfma_f32_32x32x64_f8f6f4 v[18:33], v[102:109], v[90:97], v[18:33]
	v_pk_add_f32 v[98:99], v[98:99], v[100:101]
	v_pk_fma_f32 v[82:83], v[66:67], s[4:5], v[214:215] op_sel_hi:[1,0,0]
	v_pk_fma_f32 v[66:67], v[130:131], s[4:5], v[214:215] op_sel_hi:[1,0,0]
	ds_read_b64_tr_b8 v[130:131], v187 offset:0
	v_pk_fma_f32 v[84:85], v[68:69], s[4:5], v[214:215] op_sel_hi:[1,0,0]
	v_pk_fma_f32 v[68:69], v[132:133], s[4:5], v[214:215] op_sel_hi:[1,0,0]
	ds_read_b64_tr_b8 v[132:133], v187 offset:0x800
	v_pk_fma_f32 v[86:87], v[70:71], s[4:5], v[214:215] op_sel_hi:[1,0,0]
	v_pk_fma_f32 v[70:71], v[134:135], s[4:5], v[214:215] op_sel_hi:[1,0,0]
	ds_read_b64_tr_b8 v[134:135], v187 offset:0x1000
	v_pk_fma_f32 v[96:97], v[80:81], s[4:5], v[214:215] op_sel_hi:[1,0,0]
	v_pk_fma_f32 v[94:95], v[78:79], s[4:5], v[214:215] op_sel_hi:[1,0,0]
	v_pk_fma_f32 v[92:93], v[76:77], s[4:5], v[214:215] op_sel_hi:[1,0,0]
	v_pk_fma_f32 v[90:91], v[74:75], s[4:5], v[214:215] op_sel_hi:[1,0,0]
	v_pk_fma_f32 v[88:89], v[72:73], s[4:5], v[214:215] op_sel_hi:[1,0,0]
	v_pk_fma_f32 v[80:81], v[144:145], s[4:5], v[214:215] op_sel_hi:[1,0,0]
	v_pk_fma_f32 v[78:79], v[142:143], s[4:5], v[214:215] op_sel_hi:[1,0,0]
	v_pk_fma_f32 v[76:77], v[140:141], s[4:5], v[214:215] op_sel_hi:[1,0,0]
	v_pk_fma_f32 v[74:75], v[138:139], s[4:5], v[214:215] op_sel_hi:[1,0,0]
	v_pk_fma_f32 v[72:73], v[136:137], s[4:5], v[214:215] op_sel_hi:[1,0,0]
	ds_read_b64_tr_b8 v[136:137], v187 offset:0x1800
	s_waitcnt lgkmcnt(4)
	v_pk_add_f32 v[98:99], v[98:99], v[174:175]
	v_mfma_f32_32x32x64_f8f6f4 v[34:49], v[102:109], v[206:213], v[34:49]
	s_waitcnt lgkmcnt(0)
	s_nop 0
	v_exp_f32_e32 v82, v82
	v_exp_f32_e32 v83, v83
	v_exp_f32_e32 v84, v84
	v_exp_f32_e32 v85, v85
	v_mfma_f32_32x32x64_f8f6f4 v[50:65], v[102:109], v[130:137], v[50:65]
	v_mad_u64_u32 v[102:103], s[44:45], s18, v205, v[166:167]
	s_barrier
	v_add_u32_e32 v103, s19, v103
	global_load_lds_dwordx4 v[102:103], off
	v_pk_add_f32 v[98:99], v[176:177], v[98:99]
	s_nop 0
	v_pk_add_f32 v[98:99], v[178:179], v[98:99]
	s_nop 0
	v_pk_add_f32 v[98:99], v[180:181], v[98:99]
	s_nop 0
	v_pk_add_f32 v[98:99], v[110:111], v[98:99]
	s_nop 0
	v_pk_add_f32 v[98:99], v[112:113], v[98:99]
	s_nop 0
	v_pk_add_f32 v[98:99], v[98:99], v[114:115]
	s_nop 0
	v_pk_add_f32 v[98:99], v[116:117], v[98:99]
	s_nop 0
	v_pk_add_f32 v[98:99], v[118:119], v[98:99]
	s_nop 0
	v_pk_add_f32 v[98:99], v[120:121], v[98:99]
	s_nop 0
	v_pk_add_f32 v[98:99], v[122:123], v[98:99]
	s_nop 0
	v_pk_add_f32 v[98:99], v[124:125], v[98:99]
	s_nop 0
	v_pk_add_f32 v[98:99], v[126:127], v[98:99]
	s_nop 0
	v_pk_add_f32 v[98:99], v[128:129], v[98:99]
	s_nop 0
	v_pk_add_f32 v[98:99], v[98:99], v[98:99] op_sel:[0,1] op_sel_hi:[1,0]
	s_nop 0
	v_sub_f32_e32 v99, v204, v215
	v_mul_f32_e32 v99, 0x3e0293ee, v99
	v_exp_f32_e32 v100, v99
	v_mov_b32_e32 v99, v98
	s_nop 1
	v_permlane32_swap_b32_e32 v98, v99
	v_cndmask_b32_e64 v178, v100, 1.0, vcc
	v_cmp_gt_f32_e32 vcc, 1.0, v178
	s_cbranch_vccz .LBB0_559
	s_and_saveexec_b64 s[18:19], s[2:3]
	ds_write_b32 v193, v178 offset:128
	s_or_b64 exec, exec, s[18:19]
	s_waitcnt lgkmcnt(0)
	s_nop 15
	s_nop 7
	ds_read2_b32 v[100:101], v191 offset0:32 offset1:33
	ds_read2_b32 v[102:103], v191 offset0:34 offset1:35
	ds_read2_b32 v[104:105], v191 offset0:40 offset1:41
	ds_read2_b32 v[106:107], v191 offset0:42 offset1:43
	s_waitcnt lgkmcnt(0)
	v_pk_mul_f32 v[2:3], v[100:101], v[2:3]
	v_pk_mul_f32 v[18:19], v[100:101], v[18:19]
	v_pk_mul_f32 v[34:35], v[100:101], v[34:35]
	v_pk_mul_f32 v[50:51], v[100:101], v[50:51]
	v_pk_mul_f32 v[4:5], v[4:5], v[102:103]
	v_pk_mul_f32 v[20:21], v[20:21], v[102:103]
	v_pk_mul_f32 v[36:37], v[36:37], v[102:103]
	v_pk_mul_f32 v[52:53], v[52:53], v[102:103]
	v_pk_mul_f32 v[6:7], v[6:7], v[104:105]
	v_pk_mul_f32 v[22:23], v[22:23], v[104:105]
	v_pk_mul_f32 v[38:39], v[38:39], v[104:105]
	v_pk_mul_f32 v[54:55], v[54:55], v[104:105]
	v_pk_mul_f32 v[8:9], v[8:9], v[106:107]
	v_pk_mul_f32 v[24:25], v[24:25], v[106:107]
	v_pk_mul_f32 v[40:41], v[40:41], v[106:107]
	ds_read2_b32 v[100:101], v191 offset0:48 offset1:49
	v_pk_mul_f32 v[56:57], v[56:57], v[106:107]
	ds_read2_b32 v[102:103], v191 offset0:50 offset1:51
	ds_read2_b32 v[104:105], v191 offset0:56 offset1:57
	ds_read2_b32 v[106:107], v191 offset0:58 offset1:59
	s_waitcnt lgkmcnt(0)
	v_pk_mul_f32 v[10:11], v[10:11], v[100:101]
	v_pk_mul_f32 v[26:27], v[26:27], v[100:101]
	v_pk_mul_f32 v[42:43], v[42:43], v[100:101]
	v_pk_mul_f32 v[58:59], v[58:59], v[100:101]
	v_pk_mul_f32 v[12:13], v[12:13], v[102:103]
	v_pk_mul_f32 v[28:29], v[28:29], v[102:103]
	v_pk_mul_f32 v[44:45], v[44:45], v[102:103]
	v_pk_mul_f32 v[60:61], v[60:61], v[102:103]
	v_pk_mul_f32 v[14:15], v[14:15], v[104:105]
	v_pk_mul_f32 v[30:31], v[30:31], v[104:105]
	v_pk_mul_f32 v[46:47], v[46:47], v[104:105]
	v_pk_mul_f32 v[62:63], v[62:63], v[104:105]
	v_pk_mul_f32 v[16:17], v[16:17], v[106:107]
	v_pk_mul_f32 v[32:33], v[32:33], v[106:107]
	v_pk_mul_f32 v[48:49], v[48:49], v[106:107]
	v_pk_mul_f32 v[64:65], v[64:65], v[106:107]

.LBB0_561:
	ds_read_b128 v[90:93], v200 offset:49152
	ds_read_b128 v[86:89], v199 offset:49152
	ds_read_b128 v[130:133], v199 offset:53248
	ds_read_b128 v[134:137], v200 offset:53248
	v_pk_add_f32 v[94:95], v[82:83], v[84:85]
	s_waitcnt lgkmcnt(0)
	v_mfma_f32_32x32x64_f8f6f4 v[114:129], v[86:93], v[154:161], 0
	s_nop 0
	v_exp_f32_e32 v66, v66
	v_exp_f32_e32 v67, v67
	v_exp_f32_e32 v68, v68
	v_exp_f32_e32 v69, v69
	ds_read_b128 v[86:89], v197 offset:49152
	ds_read_b128 v[90:93], v198 offset:49152
	v_mfma_f32_32x32x64_f8f6f4 v[98:113], v[130:137], v[154:161], 0
	ds_read_b128 v[130:133], v197 offset:53248
	ds_read_b128 v[134:137], v198 offset:53248
	v_exp_f32_e32 v70, v70
	v_exp_f32_e32 v71, v71
	v_exp_f32_e32 v72, v72
	v_exp_f32_e32 v73, v73
	v_pk_add_f32 v[94:95], v[94:95], v[176:177]
	s_waitcnt lgkmcnt(0)
	v_mfma_f32_32x32x64_f8f6f4 v[114:129], v[86:93], v[146:153], v[114:129]
	v_pk_add_f32 v[94:95], v[94:95], v[174:175]
	v_exp_f32_e32 v74, v74
	v_exp_f32_e32 v75, v75
	v_exp_f32_e32 v76, v76
	v_exp_f32_e32 v77, v77
	v_pk_add_f32 v[86:87], v[94:95], v[172:173]
	v_mfma_f32_32x32x64_f8f6f4 v[98:113], v[130:137], v[146:153], v[98:113]
	v_mov_b32_e32 v134, v163
	v_pk_add_f32 v[86:87], v[86:87], v[140:141]
	v_cvt_pk_fp8_f32 v134, v66, v67
	v_pk_add_f32 v[86:87], v[86:87], v[144:145]
	v_mov_b32_e32 v135, v163
	v_exp_f32_e32 v78, v78
	v_exp_f32_e32 v79, v79
	v_pk_add_f32 v[86:87], v[86:87], v[142:143]
	v_cvt_pk_fp8_f32 v135, v70, v71
	v_pk_add_f32 v[86:87], v[86:87], v[66:67]
	v_mov_b32_e32 v136, v163
	ds_read_b64_tr_b8 v[66:67], v195 offset:0
	v_pk_add_f32 v[86:87], v[68:69], v[86:87]
	v_cvt_pk_fp8_f32 v134, v68, v69 op_sel:[0,0,1]
	v_cvt_pk_fp8_f32 v136, v74, v75
	ds_read_b64_tr_b8 v[68:69], v195 offset:0x800
	v_pk_add_f32 v[86:87], v[70:71], v[86:87]
	v_mov_b32_e32 v137, v163
	ds_read_b64_tr_b8 v[70:71], v195 offset:0x1000
	v_exp_f32_e32 v80, v80
	v_exp_f32_e32 v81, v81
	v_pk_add_f32 v[86:87], v[72:73], v[86:87]
	v_mov_b32_e32 v130, v163
	v_mov_b32_e32 v131, v163
	v_cvt_pk_fp8_f32 v135, v72, v73 op_sel:[0,0,1]
	v_mov_b32_e32 v132, v163
	v_mov_b32_e32 v133, v163
	v_cvt_pk_fp8_f32 v137, v78, v79
	ds_read_b64_tr_b8 v[72:73], v195 offset:0x1800
	v_pk_add_f32 v[86:87], v[74:75], v[86:87]
	v_cvt_pk_fp8_f32 v130, v82, v83
	v_cvt_pk_fp8_f32 v131, v176, v177
	v_cvt_pk_fp8_f32 v132, v172, v173
	v_cvt_pk_fp8_f32 v133, v144, v145
	ds_read_b64_tr_b8 v[74:75], v196 offset:0
	v_pk_add_f32 v[86:87], v[76:77], v[86:87]
	v_cvt_pk_fp8_f32 v136, v76, v77 op_sel:[0,0,1]
	ds_read_b64_tr_b8 v[76:77], v196 offset:0x800
	v_pk_add_f32 v[86:87], v[78:79], v[86:87]
	ds_read_b64_tr_b8 v[78:79], v196 offset:0x1000
	v_cvt_pk_fp8_f32 v137, v80, v81 op_sel:[0,0,1]
	v_pk_add_f32 v[86:87], v[80:81], v[86:87]
	ds_read_b64_tr_b8 v[80:81], v196 offset:0x1800
	v_cvt_pk_fp8_f32 v130, v84, v85 op_sel:[0,0,1]
	v_cvt_pk_fp8_f32 v131, v174, v175 op_sel:[0,0,1]
	v_cvt_pk_fp8_f32 v132, v140, v141 op_sel:[0,0,1]
	v_cvt_pk_fp8_f32 v133, v142, v143 op_sel:[0,0,1]
	s_waitcnt lgkmcnt(4)
	v_pk_add_f32 v[138:139], v[86:87], v[86:87] op_sel:[0,1] op_sel_hi:[1,0]
	v_mfma_f32_32x32x64_f8f6f4 v[2:17], v[130:137], v[66:73], v[2:17]
	ds_read_b64_tr_b8 v[140:141], v194 offset:0
	ds_read_b64_tr_b8 v[142:143], v194 offset:0x800
	ds_read_b64_tr_b8 v[144:145], v194 offset:0x1000
	ds_read_b64_tr_b8 v[146:147], v194 offset:0x1800
	s_waitcnt lgkmcnt(4)
	s_nop 0
	v_max_f32_e32 v66, v115, v115
	v_max_f32_e32 v67, v114, v114
	v_max_f32_e32 v66, v67, v66
	v_max3_f32 v66, v66, v116, v117
	v_max3_f32 v66, v66, v118, v119
	v_max3_f32 v66, v66, v120, v121
	v_max3_f32 v66, v66, v122, v123
	v_max3_f32 v66, v66, v124, v125
	v_max3_f32 v66, v66, v126, v127
	v_max3_f32 v66, v66, v128, v129
	v_max3_f32 v66, v66, v98, v99
	v_max3_f32 v66, v66, v100, v101
	v_max3_f32 v66, v66, v102, v103
	v_max3_f32 v66, v66, v104, v105
	v_max3_f32 v66, v66, v106, v107
	v_max3_f32 v66, v66, v108, v109
	v_max3_f32 v66, v66, v110, v111
	v_max3_f32 v66, v66, v112, v113
	v_mov_b32_e32 v67, v66
	s_nop 1
	v_permlane32_swap_b32_e32 v66, v67
	v_max_f32_e32 v67, v67, v67
	v_max_f32_e32 v66, v66, v66
	v_max_f32_e32 v66, v66, v67
	v_sub_f32_e32 v67, v66, v202
	v_cmp_ge_f32_e32 vcc, s29, v67
	s_cmp_eq_u64 vcc, exec
	v_max_f32_e32 v67, v202, v202
	v_max_f32_e32 v66, v67, v66
	s_cselect_b64 vcc, -1, 0
	v_sub_f32_e32 v67, v202, v66
	v_cndmask_b32_e32 v66, v66, v202, vcc
	v_mul_f32_e32 v83, 0x3e0293ee, v67
	v_fma_f32 v82, v66, s33, 4.0
	v_mfma_f32_32x32x64_f8f6f4 v[18:33], v[130:137], v[74:81], v[18:33]
	v_mov_b32_e32 v139, v138
	v_pk_fma_f32 v[84:85], v[100:101], s[4:5], v[82:83] op_sel_hi:[1,0,0]
	ds_read_b64_tr_b8 v[100:101], v192 offset:0
	v_pk_fma_f32 v[66:67], v[114:115], s[4:5], v[82:83] op_sel_hi:[1,0,0]
	v_exp_f32_e32 v114, v83
	v_pk_fma_f32 v[86:87], v[102:103], s[4:5], v[82:83] op_sel_hi:[1,0,0]
	ds_read_b64_tr_b8 v[102:103], v192 offset:0x800
	v_pk_fma_f32 v[88:89], v[104:105], s[4:5], v[82:83] op_sel_hi:[1,0,0]
	ds_read_b64_tr_b8 v[104:105], v192 offset:0x1000
	v_pk_fma_f32 v[80:81], v[128:129], s[4:5], v[82:83] op_sel_hi:[1,0,0]
	v_pk_fma_f32 v[78:79], v[126:127], s[4:5], v[82:83] op_sel_hi:[1,0,0]
	v_pk_fma_f32 v[76:77], v[124:125], s[4:5], v[82:83] op_sel_hi:[1,0,0]
	v_pk_fma_f32 v[74:75], v[122:123], s[4:5], v[82:83] op_sel_hi:[1,0,0]
	v_pk_fma_f32 v[72:73], v[120:121], s[4:5], v[82:83] op_sel_hi:[1,0,0]
	v_pk_fma_f32 v[70:71], v[118:119], s[4:5], v[82:83] op_sel_hi:[1,0,0]
	v_pk_fma_f32 v[68:69], v[116:117], s[4:5], v[82:83] op_sel_hi:[1,0,0]
	v_pk_fma_f32 v[96:97], v[112:113], s[4:5], v[82:83] op_sel_hi:[1,0,0]
	v_pk_fma_f32 v[94:95], v[110:111], s[4:5], v[82:83] op_sel_hi:[1,0,0]
	v_pk_fma_f32 v[92:93], v[108:109], s[4:5], v[82:83] op_sel_hi:[1,0,0]
	v_pk_fma_f32 v[90:91], v[106:107], s[4:5], v[82:83] op_sel_hi:[1,0,0]
	v_pk_fma_f32 v[82:83], v[98:99], s[4:5], v[82:83] op_sel_hi:[1,0,0]
	ds_read_b64_tr_b8 v[106:107], v192 offset:0x1800
	s_waitcnt lgkmcnt(4)
	v_cndmask_b32_e64 v98, v114, 1.0, vcc
	v_mfma_f32_32x32x64_f8f6f4 v[34:49], v[130:137], v[140:147], v[34:49]
	s_waitcnt lgkmcnt(0)
	v_permlane32_swap_b32_e32 v138, v139
	v_exp_f32_e32 v66, v66
	v_exp_f32_e32 v67, v67
	v_exp_f32_e32 v68, v68
	v_exp_f32_e32 v69, v69
	v_cmp_gt_f32_e32 vcc, 1.0, v98
	v_mfma_f32_32x32x64_f8f6f4 v[50:65], v[130:137], v[100:107], v[50:65]
	s_cbranch_vccz .LBB0_565
	s_and_saveexec_b64 s[16:17], s[2:3]
	ds_write_b32 v193, v98 offset:128
	s_or_b64 exec, exec, s[16:17]
	s_waitcnt lgkmcnt(0)
	s_nop 15
	s_nop 7
	ds_read2_b32 v[100:101], v191 offset0:32 offset1:33
	ds_read2_b32 v[102:103], v191 offset0:34 offset1:35
	ds_read2_b32 v[104:105], v191 offset0:40 offset1:41
	ds_read2_b32 v[106:107], v191 offset0:42 offset1:43
	s_waitcnt lgkmcnt(0)
	v_pk_mul_f32 v[2:3], v[100:101], v[2:3]
	v_pk_mul_f32 v[18:19], v[100:101], v[18:19]
	v_pk_mul_f32 v[34:35], v[100:101], v[34:35]
	v_pk_mul_f32 v[50:51], v[100:101], v[50:51]
	v_pk_mul_f32 v[4:5], v[4:5], v[102:103]
	v_pk_mul_f32 v[20:21], v[20:21], v[102:103]
	v_pk_mul_f32 v[36:37], v[36:37], v[102:103]
	v_pk_mul_f32 v[52:53], v[52:53], v[102:103]
	v_pk_mul_f32 v[6:7], v[6:7], v[104:105]
	v_pk_mul_f32 v[22:23], v[22:23], v[104:105]
	v_pk_mul_f32 v[38:39], v[38:39], v[104:105]
	v_pk_mul_f32 v[54:55], v[54:55], v[104:105]
	v_pk_mul_f32 v[8:9], v[8:9], v[106:107]
	v_pk_mul_f32 v[24:25], v[24:25], v[106:107]
	v_pk_mul_f32 v[40:41], v[40:41], v[106:107]
	ds_read2_b32 v[100:101], v191 offset0:48 offset1:49
	v_pk_mul_f32 v[56:57], v[56:57], v[106:107]
	ds_read2_b32 v[102:103], v191 offset0:50 offset1:51
	ds_read2_b32 v[104:105], v191 offset0:56 offset1:57
	ds_read2_b32 v[106:107], v191 offset0:58 offset1:59
	s_waitcnt lgkmcnt(0)
	v_pk_mul_f32 v[10:11], v[10:11], v[100:101]
	v_pk_mul_f32 v[26:27], v[26:27], v[100:101]
	v_pk_mul_f32 v[42:43], v[42:43], v[100:101]
	v_pk_mul_f32 v[58:59], v[58:59], v[100:101]
	v_pk_mul_f32 v[12:13], v[12:13], v[102:103]
	v_pk_mul_f32 v[28:29], v[28:29], v[102:103]
	v_pk_mul_f32 v[44:45], v[44:45], v[102:103]
	v_pk_mul_f32 v[60:61], v[60:61], v[102:103]
	v_pk_mul_f32 v[14:15], v[14:15], v[104:105]
	v_pk_mul_f32 v[30:31], v[30:31], v[104:105]
	v_pk_mul_f32 v[46:47], v[46:47], v[104:105]
	v_pk_mul_f32 v[62:63], v[62:63], v[104:105]
	v_pk_mul_f32 v[16:17], v[16:17], v[106:107]
	v_pk_mul_f32 v[32:33], v[32:33], v[106:107]
	v_pk_mul_f32 v[48:49], v[48:49], v[106:107]
	v_pk_mul_f32 v[64:65], v[64:65], v[106:107]

.LBB0_567:
	v_exp_f32_e32 v99, v70
	v_add_f32_e32 v70, 0, v66
	v_exp_f32_e32 v71, v71
	v_add_f32_e32 v70, v67, v70
	v_exp_f32_e32 v100, v72
	v_add_f32_e32 v70, v68, v70
	v_exp_f32_e32 v101, v73
	v_add_f32_e32 v70, v69, v70
	v_exp_f32_e32 v102, v74
	v_add_f32_e32 v70, v99, v70
	v_exp_f32_e32 v75, v75
	v_add_f32_e32 v70, v71, v70
	v_exp_f32_e32 v103, v76
	v_add_f32_e32 v70, v100, v70
	v_exp_f32_e32 v104, v77
	v_add_f32_e32 v70, v101, v70
	v_exp_f32_e32 v105, v78
	v_add_f32_e32 v70, v102, v70
	v_exp_f32_e32 v79, v79
	v_add_f32_e32 v70, v75, v70
	v_exp_f32_e32 v80, v80
	v_add_f32_e32 v70, v103, v70
	v_exp_f32_e32 v81, v81
	v_add_f32_e32 v70, v104, v70
	v_exp_f32_e32 v73, v82
	v_add_f32_e32 v70, v105, v70
	v_exp_f32_e32 v74, v83
	v_add_f32_e32 v70, v79, v70
	v_exp_f32_e32 v78, v84
	v_add_f32_e32 v70, v80, v70
	v_exp_f32_e32 v82, v85
	v_add_f32_e32 v70, v81, v70
	v_exp_f32_e32 v83, v86
	v_add_f32_e32 v70, v73, v70
	v_exp_f32_e32 v84, v87
	v_add_f32_e32 v70, v74, v70
	v_exp_f32_e32 v85, v88
	v_add_f32_e32 v70, v78, v70
	v_exp_f32_e32 v86, v89
	v_add_f32_e32 v70, v82, v70
	v_exp_f32_e32 v87, v90
	v_add_f32_e32 v70, v83, v70
	v_exp_f32_e32 v88, v91
	v_add_f32_e32 v70, v84, v70
	v_exp_f32_e32 v89, v92
	v_add_f32_e32 v70, v85, v70
	v_exp_f32_e32 v90, v93
	v_add_f32_e32 v70, v86, v70
	v_exp_f32_e32 v91, v94
	v_add_f32_e32 v70, v87, v70
	v_mov_b32_e32 v76, v163
	v_exp_f32_e32 v92, v95
	v_add_f32_e32 v70, v88, v70
	v_cvt_pk_fp8_f32 v76, v73, v74
	v_exp_f32_e32 v93, v96
	v_add_f32_e32 v70, v89, v70
	v_exp_f32_e32 v94, v97
	v_add_f32_e32 v70, v90, v70
	v_mov_b32_e32 v74, v163
	v_add_f32_e32 v70, v91, v70
	v_cvt_pk_fp8_f32 v74, v102, v75
	v_mov_b32_e32 v75, v163
	v_add_f32_e32 v70, v92, v70
	v_mov_b32_e32 v72, v163
	v_mov_b32_e32 v73, v163
	v_mov_b32_e32 v77, v163
	v_cvt_pk_fp8_f32 v76, v78, v82 op_sel:[0,0,1]
	v_mov_b32_e32 v78, v163
	v_cvt_pk_fp8_f32 v75, v105, v79
	v_mov_b32_e32 v79, v163
	v_add_f32_e32 v70, v93, v70
	v_cvt_pk_fp8_f32 v72, v66, v67
	v_cvt_pk_fp8_f32 v73, v99, v71
	v_cvt_pk_fp8_f32 v77, v83, v84
	v_cvt_pk_fp8_f32 v78, v87, v88
	v_cvt_pk_fp8_f32 v79, v91, v92
	v_add_f32_e32 v70, v94, v70
	v_mov_b32_e32 v66, v70
	s_nop 1
	v_permlane32_swap_b32_e32 v70, v66
	v_cvt_pk_fp8_f32 v72, v68, v69 op_sel:[0,0,1]
	v_cvt_pk_fp8_f32 v73, v100, v101 op_sel:[0,0,1]
	v_cvt_pk_fp8_f32 v77, v85, v86 op_sel:[0,0,1]
	v_cvt_pk_fp8_f32 v74, v103, v104 op_sel:[0,0,1]
	v_cvt_pk_fp8_f32 v78, v89, v90 op_sel:[0,0,1]
	v_cvt_pk_fp8_f32 v75, v80, v81 op_sel:[0,0,1]
	v_cvt_pk_fp8_f32 v79, v93, v94 op_sel:[0,0,1]
	ds_read_b64_tr_b8 v[80:81], v190 offset:0
	ds_read_b64_tr_b8 v[82:83], v190 offset:0x800
	ds_read_b64_tr_b8 v[84:85], v190 offset:0x1000
	ds_read_b64_tr_b8 v[86:87], v190 offset:0x1800
	s_waitcnt lgkmcnt(0)
	s_nop 0
	v_mfma_f32_32x32x64_f8f6f4 v[2:17], v[72:79], v[80:87], v[2:17]
	ds_read_b64_tr_b8 v[80:81], v189 offset:0
	ds_read_b64_tr_b8 v[82:83], v189 offset:0x800
	ds_read_b64_tr_b8 v[84:85], v189 offset:0x1000
	ds_read_b64_tr_b8 v[86:87], v189 offset:0x1800
	s_waitcnt lgkmcnt(0)
	s_nop 0
	v_mfma_f32_32x32x64_f8f6f4 v[18:33], v[72:79], v[80:87], v[18:33]
	ds_read_b64_tr_b8 v[80:81], v188 offset:0
	ds_read_b64_tr_b8 v[82:83], v188 offset:0x800
	ds_read_b64_tr_b8 v[84:85], v188 offset:0x1000
	ds_read_b64_tr_b8 v[86:87], v188 offset:0x1800
	s_waitcnt lgkmcnt(0)
	s_nop 0
	v_mfma_f32_32x32x64_f8f6f4 v[34:49], v[72:79], v[80:87], v[34:49]
	ds_read_b64_tr_b8 v[80:81], v187 offset:0
	ds_read_b64_tr_b8 v[82:83], v187 offset:0x800
	ds_read_b64_tr_b8 v[84:85], v187 offset:0x1000
	ds_read_b64_tr_b8 v[86:87], v187 offset:0x1800
	s_waitcnt lgkmcnt(0)
	s_nop 0
	v_mfma_f32_32x32x64_f8f6f4 v[50:65], v[72:79], v[80:87], v[50:65]
	s_nop 0
	s_nop 15
	s_nop 7
	s_nop 0
	v_and_b32_e32 v67, 31, v183
	v_cmp_gt_u32_e32 vcc, 32, v183
	s_and_saveexec_b64 s[2:3], vcc
	s_cbranch_execz .LBB0_527
	v_add_f32_e32 v68, v138, v139
	v_fmac_f32_e32 v68, v162, v178
	v_add_f32_e32 v66, v70, v66
	v_fmac_f32_e32 v66, v68, v98
	v_lshl_add_u32 v68, v67, 2, s24
	ds_write_b32 v68, v66
	s_branch .LBB0_527

.LBB0_582:
	v_lshrrev_b32_e32 v4, 3, v39
	v_and_b32_e32 v37, 4, v4
	v_and_or_b32 v4, s16, 32, v38
	v_med3_i32 v5, v4, 8, 56
	v_sub_u32_e32 v56, v5, v37
	v_xad_u32 v198, v4, 63, v37
	v_and_b32_e32 v4, 8, v39
	v_bfe_u32 v5, v39, 1, 2
	v_or3_b32 v4, v5, v4, v37
	v_lshlrev_b32_e32 v5, 3, v39
	v_lshlrev_b32_e32 v4, 7, v4
	v_and_b32_e32 v5, 8, v5
	v_lshlrev_b32_e32 v48, 3, v38
	s_lshl_b32 s1, s14, 2
	s_ashr_i32 s70, s15, 7
	v_bfe_u32 v57, v39, 1, 3
	v_add3_u32 v59, v5, s63, v4
	v_bitop3_b32 v4, v48, v36, s68 bitop3:0x6c
	v_lshl_add_u32 v49, v38, 7, s63
	s_add_i32 s7, s70, s1
	v_and_b32_e32 v58, 1, v2
	v_bitop3_b32 v2, v2, v57, 1 bitop3:0x6c
	s_waitcnt lgkmcnt(0)
	v_add_u32_e32 v203, v49, v4
	v_or_b32_e32 v4, 16, v36
	v_med3_i32 v6, s7, 4, 28
	v_lshl_add_u32 v200, v2, 4, v59
	v_bitop3_b32 v2, v58, v57, 2 bitop3:0x36
	s_barrier
	v_bitop3_b32 v4, v48, v4, s68 bitop3:0x6c
	v_readfirstlane_b32 s96, v6
	v_add_u32_e32 v204, v49, v4
	ds_read_b128 v[4:7], v203 offset:32768
	ds_read_b128 v[40:43], v203 offset:36864
	ds_read_b128 v[8:11], v204 offset:32768
	ds_read_b128 v[44:47], v204 offset:36864
	v_lshl_add_u32 v202, v2, 4, v59
	v_bitop3_b32 v2, v58, v57, 4 bitop3:0x36
	v_lshl_add_u32 v199, v2, 4, v59
	v_or_b32_e32 v2, 64, v36
	v_bitop3_b32 v2, v48, v2, s68 bitop3:0x6c
	v_add_u32_e32 v205, v49, v2
	v_or_b32_e32 v2, 0x50, v36
	v_bitop3_b32 v2, v48, v2, s68 bitop3:0x6c
	s_waitcnt vmcnt(0) lgkmcnt(0)
	v_mfma_f32_32x32x64_f8f6f4 v[20:35], v[4:11], v[172:179], 0
	v_mfma_f32_32x32x64_f8f6f4 v[4:19], v[40:47], v[172:179], 0
	v_add_u32_e32 v206, v49, v2
	ds_read_b128 v[40:43], v205 offset:32768
	ds_read_b128 v[48:51], v205 offset:36864
	ds_read_b128 v[44:47], v206 offset:32768
	ds_read_b128 v[52:55], v206 offset:36864
	v_bitop3_b32 v2, v58, v57, 6 bitop3:0x36
	s_waitcnt lgkmcnt(1)
	v_mfma_f32_32x32x64_f8f6f4 v[20:35], v[40:47], v[164:171], v[20:35]
	s_waitcnt lgkmcnt(0)
	v_mfma_f32_32x32x64_f8f6f4 v[4:19], v[48:55], v[164:171], v[4:19]
	v_lshl_add_u32 v201, v2, 4, v59
	s_nop 15
	s_nop 7
	v_writelane_b32 v252, s16, 24
	v_max_f32_e32 v2, v21, v21
	v_max_f32_e32 v36, v20, v20
	v_max_f32_e32 v2, v36, v2
	v_max3_f32 v2, v2, v22, v23
	v_max3_f32 v2, v2, v24, v25
	v_max3_f32 v2, v2, v26, v27
	v_max3_f32 v2, v2, v28, v29
	v_max3_f32 v2, v2, v30, v31
	v_max3_f32 v2, v2, v32, v33
	v_max3_f32 v2, v2, v34, v35
	v_max3_f32 v2, v2, v4, v5
	v_writelane_b32 v252, s7, 25
	s_and_b32 s7, s74, 7
	v_max3_f32 v2, v2, v6, v7
	s_add_i32 s94, s96, -4
	s_lshl_b32 s71, s7, 2
	s_add_i32 s1, s1, -4
	v_max3_f32 v2, v2, v8, v9
	s_cmp_eq_u32 s14, 0
	v_max3_f32 v2, v2, v10, v11
	s_cselect_b64 s[8:9], -1, 0
	v_max3_f32 v2, v2, v12, v13
	s_and_b64 s[16:17], s[8:9], exec
	v_max3_f32 v2, v2, v14, v15
	s_cselect_b32 s1, 0, s1
	s_cmp_eq_u32 s14, 7
	v_max3_f32 v2, v2, v16, v17
	s_cselect_b64 s[16:17], -1, 0
	v_max3_f32 v2, v2, v18, v19
	s_or_b64 s[8:9], s[8:9], s[16:17]
	v_mov_b32_e32 v36, v2
	s_and_b64 s[8:9], s[8:9], exec
	s_nop 0
	v_permlane32_swap_b32_e32 v2, v36
	s_cselect_b32 s78, 12, 16
	s_lshl_b32 s79, s1, 6
	v_max_f32_e32 v36, v36, v36
	v_max_f32_e32 v2, v2, v2
	s_add_i32 s79, s79, s6
	s_and_b32 s6, s15, 0x3fffffc0
	v_max_f32_e32 v2, v2, v36
	s_lshl_b32 s6, s6, 2
	v_readlane_b32 s7, v252, 13
	v_add_f32_e32 v36, 0x7149f2ca, v2
	s_add_i32 s6, s7, s6
	v_cmp_ge_f32_e32 vcc, s76, v36
	s_cmp_eq_u64 vcc, exec
	v_max_f32_e32 v2, 0xf149f2ca, v2
	s_cselect_b64 vcc, -1, 0
	v_cndmask_b32_e32 v196, v2, v188, vcc
	s_add_u32 s2, s12, s2
	v_and_b32_e32 v189, 63, v39
	v_sub_f32_e32 v39, 0xf149f2ca, v2
	v_fma_f32 v2, v196, s33, 4.0
	s_addc_u32 s3, s13, s3
	s_add_i32 s92, s63, s10
	v_pk_fma_f32 v[114:115], v[18:19], s[80:81], v[2:3] op_sel_hi:[1,0,0]
	v_pk_fma_f32 v[112:113], v[16:17], s[80:81], v[2:3] op_sel_hi:[1,0,0]
	v_pk_fma_f32 v[110:111], v[14:15], s[80:81], v[2:3] op_sel_hi:[1,0,0]
	v_pk_fma_f32 v[108:109], v[12:13], s[80:81], v[2:3] op_sel_hi:[1,0,0]
	v_pk_fma_f32 v[106:107], v[10:11], s[80:81], v[2:3] op_sel_hi:[1,0,0]
	v_pk_fma_f32 v[104:105], v[8:9], s[80:81], v[2:3] op_sel_hi:[1,0,0]
	v_pk_fma_f32 v[102:103], v[6:7], s[80:81], v[2:3] op_sel_hi:[1,0,0]
	v_pk_fma_f32 v[100:101], v[4:5], s[80:81], v[2:3] op_sel_hi:[1,0,0]
	v_lshl_add_u64 v[4:5], s[2:3], 0, v[180:181]
	s_mov_b64 s[2:3], 0x420000
	s_add_i32 s81, s92, 0x4000
	v_lshl_add_u64 v[4:5], v[4:5], 0, s[2:3]
	s_mov_b32 m0, s81
	v_fmamk_f32 v20, v20, 0x3e0293ee, v2
	global_load_lds_dwordx4 v[4:5], off
	v_fmamk_f32 v21, v21, 0x3e0293ee, v2
	v_fmamk_f32 v22, v22, 0x3e0293ee, v2
	v_fmamk_f32 v23, v23, 0x3e0293ee, v2
	v_fmamk_f32 v24, v24, 0x3e0293ee, v2
	v_fmamk_f32 v25, v25, 0x3e0293ee, v2
	v_fmamk_f32 v26, v26, 0x3e0293ee, v2
	v_fmamk_f32 v27, v27, 0x3e0293ee, v2
	v_fmamk_f32 v28, v28, 0x3e0293ee, v2
	v_fmamk_f32 v29, v29, 0x3e0293ee, v2
	v_fmamk_f32 v30, v30, 0x3e0293ee, v2
	v_fmamk_f32 v31, v31, 0x3e0293ee, v2
	v_fmamk_f32 v32, v32, 0x3e0293ee, v2
	v_fmamk_f32 v33, v33, 0x3e0293ee, v2
	v_fmamk_f32 v34, v34, 0x3e0293ee, v2
	v_mov_b32_e32 v36, v2
	v_subrev_co_u32_e64 v2, s[68:69], 9, v56
	v_subrev_u32_e32 v7, 28, v56
	v_cmp_gt_u32_e64 s[36:37], 16, v2
	v_subrev_u32_e32 v2, 41, v56
	v_cmp_gt_u32_e64 s[54:55], 16, v7
	v_add_u32_e32 v7, -1, v56
	v_cmp_gt_u32_e64 s[34:35], 16, v2
	v_subrev_u32_e32 v2, 42, v56
	v_cmp_gt_u32_e64 s[52:53], 16, v7
	v_subrev_u32_e32 v7, 33, v56
	v_cmp_gt_u32_e64 s[28:29], 16, v2
	v_subrev_u32_e32 v2, 43, v56
	v_cmp_gt_u32_e64 s[50:51], 16, v7
	v_add_u32_e32 v7, -2, v56
	v_cmp_gt_u32_e64 s[24:25], 16, v2
	v_subrev_u32_e32 v2, 44, v56
	v_mul_f32_e32 v39, 0x3e0293ee, v39
	v_cmp_gt_u32_e64 s[48:49], 16, v7
	v_subrev_u32_e32 v7, 34, v56
	v_cmp_gt_u32_e64 s[20:21], 16, v2
	v_subrev_u32_e32 v2, 17, v56
	v_exp_f32_e32 v39, v39
	v_cmp_gt_u32_e64 s[46:47], 16, v7
	v_add_u32_e32 v7, -3, v56
	v_cmp_gt_u32_e64 s[18:19], 16, v2
	v_subrev_u32_e32 v2, 18, v56
	v_cmp_gt_u32_e64 s[44:45], 16, v7
	v_subrev_u32_e32 v7, 35, v56
	v_cmp_gt_u32_e64 s[14:15], 16, v2
	v_subrev_u32_e32 v2, 19, v56
	v_lshl_add_u64 v[184:185], s[4:5], 0, v[182:183]
	v_cmp_lt_u32_e64 s[4:5], 50, v56
	v_fmac_f32_e32 v36, 0x3e0293ee, v35
	v_subrev_u32_e32 v4, 25, v56
	v_subrev_u32_e32 v5, 26, v56
	v_subrev_u32_e32 v6, 27, v56
	v_cmp_gt_u32_e64 s[42:43], 16, v7
	v_add_u32_e32 v7, -4, v56
	v_cmp_gt_u32_e64 s[8:9], 16, v2
	v_writelane_b32 v252, s4, 26
	v_subrev_u32_e32 v2, 20, v56
	v_exp_f32_e32 v116, v20
	v_exp_f32_e32 v117, v21
	v_exp_f32_e32 v118, v22
	v_exp_f32_e32 v119, v23
	v_exp_f32_e32 v120, v24
	v_exp_f32_e32 v121, v25
	v_exp_f32_e32 v122, v26
	v_exp_f32_e32 v123, v27
	v_exp_f32_e32 v124, v28
	v_exp_f32_e32 v125, v29
	v_exp_f32_e32 v126, v30
	v_exp_f32_e32 v127, v31
	v_exp_f32_e32 v128, v32
	v_exp_f32_e32 v129, v33
	v_exp_f32_e32 v130, v34
	v_exp_f32_e32 v131, v36
	s_waitcnt vmcnt(1)
	v_cmp_gt_u32_e64 s[66:67], 16, v4
	v_subrev_co_u32_e64 v4, s[64:65], 10, v56
	v_cmp_gt_u32_e64 s[62:63], 16, v5
	v_subrev_co_u32_e64 v5, s[60:61], 11, v56
	v_cmp_gt_u32_e64 s[58:59], 16, v6
	v_subrev_co_u32_e64 v6, s[56:57], 12, v56
	v_cmp_gt_u32_e64 s[40:41], 16, v7
	v_subrev_u32_e32 v7, 36, v56
	v_writelane_b32 v252, s5, 27
	v_cmp_gt_u32_e64 s[4:5], 16, v2
	v_mov_b32_e32 v16, v3
	v_mov_b32_e32 v17, v3
	v_cndmask_b32_e64 v132, v39, 1.0, vcc
	s_barrier
	v_lshl_add_u32 v195, v38, 2, s6
	v_cmp_gt_u32_e64 s[38:39], 16, v7
	v_cmp_gt_u32_e64 s[30:31], 16, v4
	v_cmp_gt_u32_e64 s[26:27], 16, v5
	v_cmp_gt_u32_e64 s[22:23], 16, v6
	v_cmp_lt_u32_e64 s[16:17], 48, v56
	v_cmp_lt_u32_e64 s[10:11], 49, v56
	v_lshl_add_u64 v[186:187], s[12:13], 0, v[180:181]
	v_writelane_b32 v252, s4, 28
	v_lshl_add_u32 v194, v37, 2, s6
	v_mov_b32_e32 v2, v3
	v_mov_b32_e32 v4, v3
	v_mov_b32_e32 v5, v3
	v_mov_b32_e32 v6, v3
	v_mov_b32_e32 v7, v3
	v_mov_b32_e32 v8, v3
	v_mov_b32_e32 v9, v3
	v_mov_b32_e32 v10, v3
	v_mov_b32_e32 v11, v3
	v_mov_b32_e32 v12, v3
	v_mov_b32_e32 v13, v3
	v_mov_b32_e32 v14, v3
	v_mov_b32_e32 v15, v3
	v_mov_b64_e32 v[34:35], v[16:17]
	v_cmp_lt_u32_e64 s[12:13], 51, v56
	v_mov_b64_e32 v[66:67], v[16:17]
	v_mov_b64_e32 v[50:51], v[16:17]
	v_writelane_b32 v252, s5, 29
	s_sub_i32 s4, s1, s70
	v_mov_b64_e32 v[32:33], v[14:15]
	v_mov_b64_e32 v[30:31], v[12:13]
	v_mov_b64_e32 v[28:29], v[10:11]
	v_mov_b64_e32 v[26:27], v[8:9]
	v_mov_b64_e32 v[24:25], v[6:7]
	v_mov_b64_e32 v[22:23], v[4:5]
	v_mov_b64_e32 v[20:21], v[2:3]
	v_mov_b64_e32 v[64:65], v[14:15]
	v_mov_b64_e32 v[62:63], v[12:13]
	v_mov_b64_e32 v[60:61], v[10:11]
	v_mov_b64_e32 v[58:59], v[8:9]
	v_mov_b64_e32 v[56:57], v[6:7]
	v_mov_b64_e32 v[54:55], v[4:5]
	v_mov_b64_e32 v[52:53], v[2:3]
	v_mov_b64_e32 v[48:49], v[14:15]
	v_mov_b64_e32 v[46:47], v[12:13]
	v_mov_b64_e32 v[44:45], v[10:11]
	v_mov_b64_e32 v[42:43], v[8:9]
	v_mov_b64_e32 v[40:41], v[6:7]
	v_mov_b64_e32 v[38:39], v[4:5]
	v_mov_b64_e32 v[36:37], v[2:3]
	v_mov_b64_e32 v[18:19], v[16:17]
	s_mov_b32 s97, 2
	s_add_i32 s96, s96, 4
	v_cmp_gt_u32_e64 s[2:3], 32, v189
	v_add_u32_e32 v193, 0x4000, v200
	v_add_u32_e32 v192, 0x4000, v202
	v_add_u32_e32 v191, 0x4000, v199
	v_add_u32_e32 v190, 0x4000, v201
	v_lshl_add_u32 v207, v198, 2, s72
	s_sub_i32 s75, s4, s71
	v_mov_b32_e32 v197, 0
	s_movk_i32 s93, 0x80
	v_mov_b64_e32 v[16:17], v[14:15]
	v_mov_b64_e32 v[14:15], v[12:13]
	v_mov_b64_e32 v[12:13], v[10:11]
	v_mov_b64_e32 v[10:11], v[8:9]
	v_mov_b64_e32 v[8:9], v[6:7]
	v_mov_b64_e32 v[6:7], v[4:5]
	v_mov_b64_e32 v[4:5], v[2:3]
	v_writelane_b32 v252, s6, 30
	s_branch .LBB0_585

.LBB0_585:
	s_cmp_gt_u32 s97, 3
	s_cselect_b64 s[84:85], -1, 0
	s_add_i32 s4, s93, 0xffffff00
	s_cmp_lt_u32 s97, 4
	s_cselect_b64 s[72:73], -1, 0
	s_and_b64 s[70:71], s[72:73], exec
	s_cselect_b32 s5, s0, s79
	s_cselect_b32 s4, s93, s4
	s_ashr_i32 s6, s5, 31
	s_add_u32 s70, s4, s5
	s_addc_u32 s71, 0, s6
	s_lshl_b64 s[86:87], s[70:71], 11
	s_add_i32 s95, s92, 0x8000
	v_lshl_add_u64 v[134:135], v[184:185], 0, s[86:87]
	s_mov_b32 m0, s95
	s_add_i32 s82, s97, -1
	global_load_lds_dwordx4 v[134:135], off
	s_cmp_gt_u32 s82, 3
	s_cselect_b64 s[90:91], -1, 0
	s_cmp_lt_u32 s82, 4
	s_cselect_b64 s[70:71], -1, 0
	s_add_i32 s77, s1, s97
	s_add_i32 s4, s77, -5
	s_cmp_ge_i32 s4, s94
	s_cselect_b64 s[88:89], -1, 0
	s_cmp_lt_i32 s4, s96
	s_cselect_b64 vcc, -1, 0
	s_and_b64 s[88:89], s[88:89], vcc
	s_or_b64 vcc, s[70:71], s[88:89]
	v_cndmask_b32_e64 v2, 0, 1, vcc
	v_cmp_ne_u32_e64 s[70:71], 1, v2
	s_andn2_b64 vcc, exec, vcc
	s_cbranch_vccnz .LBB0_587
	ds_read_b128 v[68:71], v203 offset:49152
	ds_read_b128 v[134:137], v203 offset:53248
	ds_read_b128 v[72:75], v204 offset:49152
	ds_read_b128 v[138:141], v204 offset:53248
	s_waitcnt lgkmcnt(0)
	v_mfma_f32_32x32x64_f8f6f4 v[84:99], v[68:75], v[172:179], 0
	v_mfma_f32_32x32x64_f8f6f4 v[68:83], v[134:141], v[172:179], 0
	ds_read_b128 v[134:137], v205 offset:49152
	ds_read_b128 v[142:145], v205 offset:53248
	ds_read_b128 v[138:141], v206 offset:49152
	ds_read_b128 v[146:149], v206 offset:53248
	s_waitcnt lgkmcnt(0)
	v_mfma_f32_32x32x64_f8f6f4 v[84:99], v[134:141], v[164:171], v[84:99]
	v_mfma_f32_32x32x64_f8f6f4 v[68:83], v[142:149], v[164:171], v[68:83]
	s_nop 0
	s_nop 15
	s_nop 7
.LBB0_587:
	s_cmp_lt_u32 s82, 5
	s_cselect_b64 vcc, -1, 0
	s_add_i32 s6, s77, -6
	s_cmp_ge_i32 s6, s94
	s_cselect_b64 s[4:5], -1, 0
	s_cmp_lt_i32 s6, s96
	s_cselect_b64 s[6:7], -1, 0
	s_and_b64 s[4:5], s[4:5], s[6:7]
	s_or_b64 s[4:5], vcc, s[4:5]
	s_andn2_b64 vcc, exec, s[4:5]
	s_cbranch_vccnz .LBB0_589
	v_add_f32_e32 v2, 0, v116
	v_add_f32_e32 v2, v117, v2
	v_add_f32_e32 v2, v118, v2
	v_add_f32_e32 v2, v119, v2
	v_add_f32_e32 v2, v120, v2
	v_add_f32_e32 v2, v121, v2
	v_add_f32_e32 v2, v122, v2
	v_add_f32_e32 v2, v123, v2
	v_add_f32_e32 v2, v124, v2
	v_add_f32_e32 v2, v125, v2
	v_add_f32_e32 v2, v126, v2
	v_add_f32_e32 v2, v127, v2
	v_exp_f32_e32 v100, v100
	v_add_f32_e32 v2, v128, v2
	v_exp_f32_e32 v101, v101
	v_add_f32_e32 v2, v129, v2
	v_exp_f32_e32 v102, v102
	v_add_f32_e32 v2, v130, v2
	v_exp_f32_e32 v103, v103
	v_add_f32_e32 v2, v131, v2
	v_exp_f32_e32 v104, v104
	v_add_f32_e32 v2, v100, v2
	v_exp_f32_e32 v105, v105
	v_add_f32_e32 v2, v101, v2
	v_exp_f32_e32 v106, v106
	v_add_f32_e32 v2, v102, v2
	v_exp_f32_e32 v107, v107
	v_add_f32_e32 v2, v103, v2
	v_exp_f32_e32 v108, v108
	v_add_f32_e32 v2, v104, v2
	v_exp_f32_e32 v109, v109
	v_add_f32_e32 v2, v105, v2
	v_exp_f32_e32 v110, v110
	v_add_f32_e32 v2, v106, v2
	v_exp_f32_e32 v111, v111
	v_add_f32_e32 v2, v107, v2
	v_exp_f32_e32 v112, v112
	v_add_f32_e32 v2, v108, v2
	v_exp_f32_e32 v113, v113
	v_add_f32_e32 v2, v109, v2
	v_exp_f32_e32 v114, v114
	v_add_f32_e32 v2, v110, v2
	v_exp_f32_e32 v115, v115
	v_add_f32_e32 v2, v111, v2
	v_add_f32_e32 v2, v112, v2
	v_add_f32_e32 v2, v113, v2
	v_add_f32_e32 v2, v114, v2
	v_add_f32_e32 v2, v115, v2
	v_mov_b32_e32 v133, v2
	s_nop 1
	v_permlane32_swap_b32_e32 v2, v133
	v_add_f32_e32 v2, v2, v133
	v_fmac_f32_e32 v2, v197, v132
	v_mov_b32_e32 v132, 0
	v_mov_b32_e32 v136, 0
	v_mov_b32_e32 v133, 0
	v_mov_b32_e32 v137, 0
	v_mov_b32_e32 v134, 0
	v_mov_b32_e32 v138, 0
	v_mov_b32_e32 v135, 0
	v_mov_b32_e32 v139, 0
	v_cvt_pk_fp8_f32 v132, v116, v117
	v_cvt_pk_fp8_f32 v136, v100, v101
	v_cvt_pk_fp8_f32 v133, v120, v121
	v_cvt_pk_fp8_f32 v137, v104, v105
	v_cvt_pk_fp8_f32 v134, v124, v125
	v_cvt_pk_fp8_f32 v138, v108, v109
	v_cvt_pk_fp8_f32 v135, v128, v129
	v_cvt_pk_fp8_f32 v139, v112, v113
	v_cvt_pk_fp8_f32 v132, v118, v119 op_sel:[0,0,1]
	v_cvt_pk_fp8_f32 v136, v102, v103 op_sel:[0,0,1]
	v_cvt_pk_fp8_f32 v133, v122, v123 op_sel:[0,0,1]
	v_cvt_pk_fp8_f32 v137, v106, v107 op_sel:[0,0,1]
	v_cvt_pk_fp8_f32 v134, v126, v127 op_sel:[0,0,1]
	v_cvt_pk_fp8_f32 v138, v110, v111 op_sel:[0,0,1]
	v_cvt_pk_fp8_f32 v135, v130, v131 op_sel:[0,0,1]
	v_cvt_pk_fp8_f32 v139, v114, v115 op_sel:[0,0,1]
	ds_read_b64_tr_b8 v[140:141], v200 offset:0
	ds_read_b64_tr_b8 v[142:143], v200 offset:0x800
	ds_read_b64_tr_b8 v[144:145], v200 offset:0x1000
	ds_read_b64_tr_b8 v[146:147], v200 offset:0x1800
	s_waitcnt lgkmcnt(0)
	s_nop 0
	v_mfma_f32_32x32x64_f8f6f4 v[20:35], v[132:139], v[140:147], v[20:35]
	ds_read_b64_tr_b8 v[140:141], v202 offset:0
	ds_read_b64_tr_b8 v[142:143], v202 offset:0x800
	ds_read_b64_tr_b8 v[144:145], v202 offset:0x1000
	ds_read_b64_tr_b8 v[146:147], v202 offset:0x1800
	s_waitcnt lgkmcnt(0)
	s_nop 0
	v_mfma_f32_32x32x64_f8f6f4 v[52:67], v[132:139], v[140:147], v[52:67]
	ds_read_b64_tr_b8 v[140:141], v199 offset:0
	ds_read_b64_tr_b8 v[142:143], v199 offset:0x800
	ds_read_b64_tr_b8 v[144:145], v199 offset:0x1000
	ds_read_b64_tr_b8 v[146:147], v199 offset:0x1800
	s_waitcnt lgkmcnt(0)
	s_nop 0
	v_mfma_f32_32x32x64_f8f6f4 v[36:51], v[132:139], v[140:147], v[36:51]
	ds_read_b64_tr_b8 v[140:141], v201 offset:0
	ds_read_b64_tr_b8 v[142:143], v201 offset:0x800
	ds_read_b64_tr_b8 v[144:145], v201 offset:0x1000
	ds_read_b64_tr_b8 v[146:147], v201 offset:0x1800
	s_waitcnt lgkmcnt(0)
	s_nop 0
	v_mfma_f32_32x32x64_f8f6f4 v[4:19], v[132:139], v[140:147], v[4:19]
	v_mov_b32_e32 v197, v2
	s_nop 15
	s_nop 7

.LBB0_661:
	s_add_i32 s4, s82, 2
	s_add_i32 s83, s82, -2
	s_cmp_lt_u32 s82, 2
	s_cselect_b32 s4, s4, s83
	s_cselect_b32 s5, s0, s79
	s_ashr_i32 s6, s5, 31
	s_lshl_b32 s4, s4, 6
	s_add_u32 s4, s4, s5
	s_addc_u32 s5, 0, s6
	s_waitcnt vmcnt(1)
	s_lshl_b64 s[86:87], s[4:5], 11
	s_add_i32 s90, s92, 0xc000
	s_barrier
	v_lshl_add_u64 v[132:133], v[184:185], 0, s[86:87]
	s_mov_b32 m0, s90
	s_add_i32 s77, s77, -4
	global_load_lds_dwordx4 v[132:133], off
	s_cmp_ge_i32 s77, s94
	s_cselect_b64 s[4:5], -1, 0
	s_cmp_lt_i32 s77, s96
	s_cselect_b64 s[6:7], -1, 0
	s_and_b64 s[88:89], s[4:5], s[6:7]
	s_or_b64 s[4:5], s[72:73], s[88:89]
	v_cndmask_b32_e64 v132, 0, 1, s[4:5]
	v_cmp_ne_u32_e64 s[72:73], 1, v132
	s_andn2_b64 vcc, exec, s[4:5]
	s_cbranch_vccnz .LBB0_664
	ds_read_b128 v[100:103], v203 offset:32768
	ds_read_b128 v[132:135], v203 offset:36864
	ds_read_b128 v[104:107], v204 offset:32768
	ds_read_b128 v[136:139], v204 offset:36864
	s_waitcnt lgkmcnt(0)
	v_mfma_f32_32x32x64_f8f6f4 v[116:131], v[100:107], v[172:179], 0
	v_mfma_f32_32x32x64_f8f6f4 v[100:115], v[132:139], v[172:179], 0
	ds_read_b128 v[132:135], v205 offset:32768
	ds_read_b128 v[140:143], v205 offset:36864
	ds_read_b128 v[136:139], v206 offset:32768
	ds_read_b128 v[144:147], v206 offset:36864
	s_waitcnt lgkmcnt(0)
	v_mfma_f32_32x32x64_f8f6f4 v[116:131], v[132:139], v[164:171], v[116:131]
	v_mfma_f32_32x32x64_f8f6f4 v[100:115], v[140:147], v[164:171], v[100:115]
	s_nop 0
	s_nop 15
	s_nop 7
	s_and_b64 vcc, exec, s[70:71]
	s_cbranch_vccz .LBB0_665

.LBB0_665:
	v_add_f32_e32 v132, 0, v84
	v_add_f32_e32 v132, v85, v132
	v_add_f32_e32 v132, v86, v132
	v_add_f32_e32 v132, v87, v132
	v_add_f32_e32 v132, v88, v132
	v_add_f32_e32 v132, v89, v132
	v_add_f32_e32 v132, v90, v132
	v_add_f32_e32 v132, v91, v132
	v_add_f32_e32 v132, v92, v132
	v_add_f32_e32 v132, v93, v132
	v_add_f32_e32 v132, v94, v132
	v_add_f32_e32 v132, v95, v132
	v_exp_f32_e32 v68, v68
	v_add_f32_e32 v132, v96, v132
	v_exp_f32_e32 v69, v69
	v_add_f32_e32 v132, v97, v132
	v_exp_f32_e32 v70, v70
	v_add_f32_e32 v132, v98, v132
	v_exp_f32_e32 v71, v71
	v_add_f32_e32 v132, v99, v132
	v_exp_f32_e32 v72, v72
	v_add_f32_e32 v132, v68, v132
	v_exp_f32_e32 v73, v73
	v_add_f32_e32 v132, v69, v132
	v_exp_f32_e32 v74, v74
	v_add_f32_e32 v132, v70, v132
	v_exp_f32_e32 v75, v75
	v_add_f32_e32 v132, v71, v132
	v_exp_f32_e32 v76, v76
	v_add_f32_e32 v132, v72, v132
	v_exp_f32_e32 v77, v77
	v_add_f32_e32 v132, v73, v132
	v_exp_f32_e32 v78, v78
	v_add_f32_e32 v132, v74, v132
	v_exp_f32_e32 v79, v79
	v_add_f32_e32 v132, v75, v132
	v_exp_f32_e32 v80, v80
	v_add_f32_e32 v132, v76, v132
	v_exp_f32_e32 v81, v81
	v_add_f32_e32 v132, v77, v132
	v_exp_f32_e32 v82, v82
	v_add_f32_e32 v132, v78, v132
	v_exp_f32_e32 v83, v83
	v_add_f32_e32 v132, v79, v132
	v_add_f32_e32 v132, v80, v132
	v_add_f32_e32 v132, v81, v132
	v_add_f32_e32 v132, v82, v132
	v_add_f32_e32 v132, v83, v132
	v_mov_b32_e32 v133, v132
	s_nop 1
	v_permlane32_swap_b32_e32 v132, v133
	v_add_f32_e32 v148, v132, v133
	v_mov_b32_e32 v132, 0
	v_mov_b32_e32 v136, 0
	v_mov_b32_e32 v133, 0
	v_mov_b32_e32 v137, 0
	v_mov_b32_e32 v134, 0
	v_mov_b32_e32 v138, 0
	v_mov_b32_e32 v135, 0
	v_mov_b32_e32 v139, 0
	v_cvt_pk_fp8_f32 v132, v84, v85
	v_cvt_pk_fp8_f32 v136, v68, v69
	v_cvt_pk_fp8_f32 v133, v88, v89
	v_cvt_pk_fp8_f32 v137, v72, v73
	v_cvt_pk_fp8_f32 v134, v92, v93
	v_cvt_pk_fp8_f32 v138, v76, v77
	v_cvt_pk_fp8_f32 v135, v96, v97
	v_cvt_pk_fp8_f32 v139, v80, v81
	v_fmac_f32_e32 v148, v197, v2
	v_cvt_pk_fp8_f32 v132, v86, v87 op_sel:[0,0,1]
	v_cvt_pk_fp8_f32 v136, v70, v71 op_sel:[0,0,1]
	v_cvt_pk_fp8_f32 v133, v90, v91 op_sel:[0,0,1]
	v_cvt_pk_fp8_f32 v137, v74, v75 op_sel:[0,0,1]
	v_cvt_pk_fp8_f32 v134, v94, v95 op_sel:[0,0,1]
	v_cvt_pk_fp8_f32 v138, v78, v79 op_sel:[0,0,1]
	v_cvt_pk_fp8_f32 v135, v98, v99 op_sel:[0,0,1]
	v_cvt_pk_fp8_f32 v139, v82, v83 op_sel:[0,0,1]
	ds_read_b64_tr_b8 v[140:141], v193 offset:0
	ds_read_b64_tr_b8 v[142:143], v193 offset:0x800
	ds_read_b64_tr_b8 v[144:145], v193 offset:0x1000
	ds_read_b64_tr_b8 v[146:147], v193 offset:0x1800
	s_waitcnt lgkmcnt(0)
	s_nop 0
	v_mfma_f32_32x32x64_f8f6f4 v[20:35], v[132:139], v[140:147], v[20:35]
	ds_read_b64_tr_b8 v[140:141], v192 offset:0
	ds_read_b64_tr_b8 v[142:143], v192 offset:0x800
	ds_read_b64_tr_b8 v[144:145], v192 offset:0x1000
	ds_read_b64_tr_b8 v[146:147], v192 offset:0x1800
	s_waitcnt lgkmcnt(0)
	s_nop 0
	v_mfma_f32_32x32x64_f8f6f4 v[52:67], v[132:139], v[140:147], v[52:67]
	ds_read_b64_tr_b8 v[140:141], v191 offset:0
	ds_read_b64_tr_b8 v[142:143], v191 offset:0x800
	ds_read_b64_tr_b8 v[144:145], v191 offset:0x1000
	ds_read_b64_tr_b8 v[146:147], v191 offset:0x1800
	s_waitcnt lgkmcnt(0)
	s_nop 0
	v_mfma_f32_32x32x64_f8f6f4 v[36:51], v[132:139], v[140:147], v[36:51]
	ds_read_b64_tr_b8 v[140:141], v190 offset:0
	ds_read_b64_tr_b8 v[142:143], v190 offset:0x800
	ds_read_b64_tr_b8 v[144:145], v190 offset:0x1000
	ds_read_b64_tr_b8 v[146:147], v190 offset:0x1800
	s_waitcnt lgkmcnt(0)
	s_nop 0
	v_mfma_f32_32x32x64_f8f6f4 v[4:19], v[132:139], v[140:147], v[4:19]
	v_mov_b32_e32 v197, v148
	s_nop 15
	s_nop 7
	s_and_b64 vcc, exec, s[72:73]
	v_mov_b32_e32 v132, 1.0
	s_cbranch_vccnz .LBB0_733

.LBB0_736:
	s_add_i32 s70, s1, s78
	s_add_i32 s72, s70, -5
	s_cmp_ge_i32 s72, s94
	s_cselect_b64 s[0:1], -1, 0
	s_cmp_lt_i32 s72, s96
	s_cselect_b64 s[78:79], -1, 0
	s_and_b64 s[0:1], s[0:1], s[78:79]
	s_and_b64 vcc, exec, s[0:1]
	s_cbranch_vccz .LBB0_738
	ds_read_b128 v[68:71], v203 offset:49152
	ds_read_b128 v[134:137], v203 offset:53248
	ds_read_b128 v[72:75], v204 offset:49152
	ds_read_b128 v[138:141], v204 offset:53248
	s_waitcnt lgkmcnt(0)
	v_mfma_f32_32x32x64_f8f6f4 v[84:99], v[68:75], v[172:179], 0
	v_mfma_f32_32x32x64_f8f6f4 v[68:83], v[134:141], v[172:179], 0
	ds_read_b128 v[134:137], v205 offset:49152
	ds_read_b128 v[142:145], v205 offset:53248
	ds_read_b128 v[138:141], v206 offset:49152
	ds_read_b128 v[146:149], v206 offset:53248
	s_waitcnt lgkmcnt(0)
	v_mfma_f32_32x32x64_f8f6f4 v[84:99], v[134:141], v[164:171], v[84:99]
	v_mfma_f32_32x32x64_f8f6f4 v[68:83], v[142:149], v[164:171], v[68:83]
	s_nop 0
	s_nop 15
	s_nop 7
.LBB0_738:
	s_add_i32 s70, s70, -6
	s_cmp_ge_i32 s70, s94
	s_cselect_b64 s[4:5], -1, 0
	s_cmp_lt_i32 s70, s96
	s_cselect_b64 s[6:7], -1, 0
	s_and_b64 s[4:5], s[4:5], s[6:7]
	s_andn2_b64 vcc, exec, s[4:5]
	v_readlane_b32 s87, v252, 7
	v_readlane_b32 s88, v252, 8
	s_cbranch_vccnz .LBB0_740
	v_exp_f32_e32 v2, v100
	v_add_f32_e32 v100, 0, v116
	v_add_f32_e32 v100, v117, v100
	v_add_f32_e32 v100, v118, v100
	v_add_f32_e32 v100, v119, v100
	v_add_f32_e32 v100, v120, v100
	v_add_f32_e32 v100, v121, v100
	v_add_f32_e32 v100, v122, v100
	v_add_f32_e32 v100, v123, v100
	v_add_f32_e32 v100, v124, v100
	v_add_f32_e32 v100, v125, v100
	v_add_f32_e32 v100, v126, v100
	v_add_f32_e32 v100, v127, v100
	v_add_f32_e32 v100, v128, v100
	v_exp_f32_e32 v101, v101
	v_add_f32_e32 v100, v129, v100
	v_exp_f32_e32 v102, v102
	v_add_f32_e32 v100, v130, v100
	v_exp_f32_e32 v103, v103
	v_add_f32_e32 v100, v131, v100
	v_exp_f32_e32 v133, v104
	v_add_f32_e32 v100, v2, v100
	v_exp_f32_e32 v134, v105
	v_add_f32_e32 v100, v101, v100
	v_exp_f32_e32 v106, v106
	v_add_f32_e32 v100, v102, v100
	v_exp_f32_e32 v107, v107
	v_add_f32_e32 v100, v103, v100
	v_exp_f32_e32 v108, v108
	v_add_f32_e32 v100, v133, v100
	v_exp_f32_e32 v109, v109
	v_add_f32_e32 v100, v134, v100
	v_exp_f32_e32 v110, v110
	v_add_f32_e32 v100, v106, v100
	v_exp_f32_e32 v111, v111
	v_add_f32_e32 v100, v107, v100
	v_exp_f32_e32 v112, v112
	v_add_f32_e32 v100, v108, v100
	v_exp_f32_e32 v113, v113
	v_add_f32_e32 v100, v109, v100
	v_exp_f32_e32 v114, v114
	v_add_f32_e32 v100, v110, v100
	v_mov_b32_e32 v104, v3
	v_mov_b32_e32 v105, v3
	v_exp_f32_e32 v115, v115
	v_add_f32_e32 v100, v111, v100
	v_cvt_pk_fp8_f32 v104, v2, v101
	v_cvt_pk_fp8_f32 v105, v133, v134
	v_add_f32_e32 v100, v112, v100
	v_add_f32_e32 v100, v113, v100
	v_add_f32_e32 v100, v114, v100
	v_add_f32_e32 v135, v115, v100
	v_mov_b32_e32 v100, v3
	v_mov_b32_e32 v101, v3
	v_cvt_pk_fp8_f32 v104, v102, v103 op_sel:[0,0,1]
	v_cvt_pk_fp8_f32 v105, v106, v107 op_sel:[0,0,1]
	v_mov_b32_e32 v102, v3
	v_mov_b32_e32 v106, v3
	v_mov_b32_e32 v103, v3
	v_mov_b32_e32 v107, v3
	v_cvt_pk_fp8_f32 v100, v116, v117
	v_cvt_pk_fp8_f32 v101, v120, v121
	v_cvt_pk_fp8_f32 v102, v124, v125
	v_cvt_pk_fp8_f32 v106, v108, v109
	v_cvt_pk_fp8_f32 v103, v128, v129
	v_cvt_pk_fp8_f32 v107, v112, v113
	v_mov_b32_e32 v136, v135
	s_nop 1
	v_permlane32_swap_b32_e32 v135, v136
	v_add_f32_e32 v2, v135, v136
	v_cvt_pk_fp8_f32 v100, v118, v119 op_sel:[0,0,1]
	v_cvt_pk_fp8_f32 v101, v122, v123 op_sel:[0,0,1]
	v_cvt_pk_fp8_f32 v102, v126, v127 op_sel:[0,0,1]
	v_cvt_pk_fp8_f32 v106, v110, v111 op_sel:[0,0,1]
	v_cvt_pk_fp8_f32 v103, v130, v131 op_sel:[0,0,1]
	v_cvt_pk_fp8_f32 v107, v114, v115 op_sel:[0,0,1]
	v_fmac_f32_e32 v2, v197, v132
	ds_read_b64_tr_b8 v[108:109], v200 offset:0
	ds_read_b64_tr_b8 v[110:111], v200 offset:0x800
	ds_read_b64_tr_b8 v[112:113], v200 offset:0x1000
	ds_read_b64_tr_b8 v[114:115], v200 offset:0x1800
	s_waitcnt lgkmcnt(0)
	s_nop 0
	v_mfma_f32_32x32x64_f8f6f4 v[20:35], v[100:107], v[108:115], v[20:35]
	ds_read_b64_tr_b8 v[108:109], v202 offset:0
	ds_read_b64_tr_b8 v[110:111], v202 offset:0x800
	ds_read_b64_tr_b8 v[112:113], v202 offset:0x1000
	ds_read_b64_tr_b8 v[114:115], v202 offset:0x1800
	s_waitcnt lgkmcnt(0)
	s_nop 0
	v_mfma_f32_32x32x64_f8f6f4 v[52:67], v[100:107], v[108:115], v[52:67]
	ds_read_b64_tr_b8 v[108:109], v199 offset:0
	ds_read_b64_tr_b8 v[110:111], v199 offset:0x800
	ds_read_b64_tr_b8 v[112:113], v199 offset:0x1000
	ds_read_b64_tr_b8 v[114:115], v199 offset:0x1800
	s_waitcnt lgkmcnt(0)
	s_nop 0
	v_mfma_f32_32x32x64_f8f6f4 v[36:51], v[100:107], v[108:115], v[36:51]
	ds_read_b64_tr_b8 v[108:109], v201 offset:0
	ds_read_b64_tr_b8 v[110:111], v201 offset:0x800
	ds_read_b64_tr_b8 v[112:113], v201 offset:0x1000
	ds_read_b64_tr_b8 v[114:115], v201 offset:0x1800
	s_waitcnt lgkmcnt(0)
	s_nop 0
	v_mfma_f32_32x32x64_f8f6f4 v[4:19], v[100:107], v[108:115], v[4:19]
	v_mov_b32_e32 v197, v2
	s_nop 15
	s_nop 7

.LBB0_812:
	s_and_b64 vcc, exec, s[70:71]
	s_cbranch_vccnz .LBB0_814
	v_exp_f32_e32 v100, v68
	v_add_f32_e32 v68, 0, v84
	v_add_f32_e32 v68, v85, v68
	v_add_f32_e32 v68, v86, v68
	v_add_f32_e32 v68, v87, v68
	v_add_f32_e32 v68, v88, v68
	v_add_f32_e32 v68, v89, v68
	v_add_f32_e32 v68, v90, v68
	v_add_f32_e32 v68, v91, v68
	v_add_f32_e32 v68, v92, v68
	v_add_f32_e32 v68, v93, v68
	v_add_f32_e32 v68, v94, v68
	v_add_f32_e32 v68, v95, v68
	v_add_f32_e32 v68, v96, v68
	v_exp_f32_e32 v69, v69
	v_add_f32_e32 v68, v97, v68
	v_exp_f32_e32 v70, v70
	v_add_f32_e32 v68, v98, v68
	v_exp_f32_e32 v71, v71
	v_add_f32_e32 v68, v99, v68
	v_exp_f32_e32 v101, v72
	v_add_f32_e32 v68, v100, v68
	v_exp_f32_e32 v102, v73
	v_add_f32_e32 v68, v69, v68
	v_exp_f32_e32 v74, v74
	v_add_f32_e32 v68, v70, v68
	v_exp_f32_e32 v75, v75
	v_add_f32_e32 v68, v71, v68
	v_exp_f32_e32 v76, v76
	v_add_f32_e32 v68, v101, v68
	v_exp_f32_e32 v77, v77
	v_add_f32_e32 v68, v102, v68
	v_exp_f32_e32 v78, v78
	v_add_f32_e32 v68, v74, v68
	v_exp_f32_e32 v79, v79
	v_add_f32_e32 v68, v75, v68
	v_exp_f32_e32 v80, v80
	v_add_f32_e32 v68, v76, v68
	v_exp_f32_e32 v81, v81
	v_add_f32_e32 v68, v77, v68
	v_exp_f32_e32 v82, v82
	v_add_f32_e32 v68, v78, v68
	v_mov_b32_e32 v72, v3
	v_mov_b32_e32 v73, v3
	v_exp_f32_e32 v83, v83
	v_add_f32_e32 v68, v79, v68
	v_cvt_pk_fp8_f32 v72, v100, v69
	v_cvt_pk_fp8_f32 v73, v101, v102
	v_add_f32_e32 v68, v80, v68
	v_add_f32_e32 v68, v81, v68
	v_add_f32_e32 v68, v82, v68
	v_add_f32_e32 v103, v83, v68
	v_mov_b32_e32 v68, v3
	v_mov_b32_e32 v69, v3
	v_cvt_pk_fp8_f32 v72, v70, v71 op_sel:[0,0,1]
	v_cvt_pk_fp8_f32 v73, v74, v75 op_sel:[0,0,1]
	v_mov_b32_e32 v70, v3
	v_mov_b32_e32 v74, v3
	v_mov_b32_e32 v71, v3
	v_mov_b32_e32 v75, v3
	v_cvt_pk_fp8_f32 v68, v84, v85
	v_cvt_pk_fp8_f32 v69, v88, v89
	v_cvt_pk_fp8_f32 v70, v92, v93
	v_cvt_pk_fp8_f32 v74, v76, v77
	v_cvt_pk_fp8_f32 v71, v96, v97
	v_cvt_pk_fp8_f32 v75, v80, v81
	v_mov_b32_e32 v104, v103
	s_nop 1
	v_permlane32_swap_b32_e32 v103, v104
	v_add_f32_e32 v84, v103, v104
	v_cvt_pk_fp8_f32 v68, v86, v87 op_sel:[0,0,1]
	v_cvt_pk_fp8_f32 v69, v90, v91 op_sel:[0,0,1]
	v_cvt_pk_fp8_f32 v70, v94, v95 op_sel:[0,0,1]
	v_cvt_pk_fp8_f32 v74, v78, v79 op_sel:[0,0,1]
	v_cvt_pk_fp8_f32 v71, v98, v99 op_sel:[0,0,1]
	v_cvt_pk_fp8_f32 v75, v82, v83 op_sel:[0,0,1]
	v_fmac_f32_e32 v84, v197, v2
	ds_read_b64_tr_b8 v[76:77], v193 offset:0
	ds_read_b64_tr_b8 v[78:79], v193 offset:0x800
	ds_read_b64_tr_b8 v[80:81], v193 offset:0x1000
	ds_read_b64_tr_b8 v[82:83], v193 offset:0x1800
	s_waitcnt lgkmcnt(0)
	s_nop 0
	v_mfma_f32_32x32x64_f8f6f4 v[20:35], v[68:75], v[76:83], v[20:35]
	ds_read_b64_tr_b8 v[76:77], v192 offset:0
	ds_read_b64_tr_b8 v[78:79], v192 offset:0x800
	ds_read_b64_tr_b8 v[80:81], v192 offset:0x1000
	ds_read_b64_tr_b8 v[82:83], v192 offset:0x1800
	s_waitcnt lgkmcnt(0)
	s_nop 0
	v_mfma_f32_32x32x64_f8f6f4 v[52:67], v[68:75], v[76:83], v[52:67]
	ds_read_b64_tr_b8 v[76:77], v191 offset:0
	ds_read_b64_tr_b8 v[78:79], v191 offset:0x800
	ds_read_b64_tr_b8 v[80:81], v191 offset:0x1000
	ds_read_b64_tr_b8 v[82:83], v191 offset:0x1800
	s_waitcnt lgkmcnt(0)
	s_nop 0
	v_mfma_f32_32x32x64_f8f6f4 v[36:51], v[68:75], v[76:83], v[36:51]
	ds_read_b64_tr_b8 v[76:77], v190 offset:0
	ds_read_b64_tr_b8 v[78:79], v190 offset:0x800
	ds_read_b64_tr_b8 v[80:81], v190 offset:0x1000
	ds_read_b64_tr_b8 v[82:83], v190 offset:0x1800
	s_waitcnt lgkmcnt(0)
	s_nop 0
	v_mfma_f32_32x32x64_f8f6f4 v[4:19], v[68:75], v[76:83], v[4:19]
	v_mov_b32_e32 v197, v84
	s_nop 15
	s_nop 7

.LBB0_885:
	s_waitcnt lgkmcnt(0)
	s_barrier
	s_setprio 1
	s_waitcnt lgkmcnt(0)
	v_mfma_f32_16x16x128_f8f6f4 v[126:129], v[26:33], v[58:65], v[126:129]
	v_mfma_f32_16x16x128_f8f6f4 v[122:125], v[18:25], v[58:65], v[122:125]
	v_mfma_f32_16x16x128_f8f6f4 v[110:113], v[26:33], v[50:57], v[110:113]
	v_mfma_f32_16x16x128_f8f6f4 v[106:109], v[18:25], v[50:57], v[106:109]
	v_mfma_f32_16x16x128_f8f6f4 v[94:97], v[26:33], v[42:49], v[94:97]
	v_mfma_f32_16x16x128_f8f6f4 v[90:93], v[18:25], v[42:49], v[90:93]
	v_mfma_f32_16x16x128_f8f6f4 v[78:81], v[26:33], v[34:41], v[78:81]
	v_mfma_f32_16x16x128_f8f6f4 v[74:77], v[18:25], v[34:41], v[74:77]
	s_setprio 0
	s_setprio 1
	v_mfma_f32_16x16x128_f8f6f4 v[118:121], v[10:17], v[58:65], v[118:121]
	v_mfma_f32_16x16x128_f8f6f4 v[114:117], v[2:9], v[58:65], v[114:117]
	v_mfma_f32_16x16x128_f8f6f4 v[102:105], v[10:17], v[50:57], v[102:105]
	v_mfma_f32_16x16x128_f8f6f4 v[98:101], v[2:9], v[50:57], v[98:101]
	v_mfma_f32_16x16x128_f8f6f4 v[86:89], v[10:17], v[42:49], v[86:89]
	v_mfma_f32_16x16x128_f8f6f4 v[82:85], v[2:9], v[42:49], v[82:85]
	v_mfma_f32_16x16x128_f8f6f4 v[70:73], v[10:17], v[34:41], v[70:73]
	v_mfma_f32_16x16x128_f8f6f4 v[66:69], v[2:9], v[34:41], v[66:69]
	s_setprio 0
	s_barrier
	v_add_u32_e32 v14, s48, v222
	v_add_u32_e32 v30, s53, v222
	ds_read_b128 v[2:5], v14
	ds_read_b128 v[6:9], v14 offset:1024
	ds_read_b128 v[10:13], v14 offset:2048
	ds_read_b128 v[14:17], v14 offset:3072
	ds_read_b128 v[18:21], v30
	ds_read_b128 v[22:25], v30 offset:1024
	ds_read_b128 v[26:29], v30 offset:2048
	ds_read_b128 v[30:33], v30 offset:3072
	s_add_u32 s28, s28, 0x530000
	s_addc_u32 s29, s29, 0
	s_mov_b32 m0, s42
	v_lshl_add_u64 v[228:229], s[28:29], 0, v[194:195]
	ds_read_b128 v[34:37], v226 offset:32768
	ds_read_b128 v[38:41], v226 offset:33792
	ds_read_b128 v[42:45], v226 offset:34816
	ds_read_b128 v[46:49], v226 offset:35840
	ds_read_b128 v[50:53], v226 offset:36864
	ds_read_b128 v[54:57], v226 offset:37888
	ds_read_b128 v[58:61], v226 offset:38912
	ds_read_b128 v[62:65], v226 offset:39936
	global_load_lds_dwordx4 v[228:229], off
	v_lshl_add_u64 v[228:229], s[28:29], 0, v[198:199]
	s_mov_b32 m0, s43
	s_nop 0
	global_load_lds_dwordx4 v[228:229], off
	s_waitcnt vmcnt(8)
	s_waitcnt lgkmcnt(0)
	s_barrier
	s_setprio 1
	s_waitcnt lgkmcnt(0)
	v_mfma_f32_16x16x128_f8f6f4 v[190:193], v[2:9], v[34:41], v[190:193]
	v_mfma_f32_16x16x128_f8f6f4 v[186:189], v[10:17], v[34:41], v[186:189]
	v_mfma_f32_16x16x128_f8f6f4 v[174:177], v[2:9], v[42:49], v[174:177]
	v_mfma_f32_16x16x128_f8f6f4 v[170:173], v[10:17], v[42:49], v[170:173]
	v_mfma_f32_16x16x128_f8f6f4 v[158:161], v[2:9], v[50:57], v[158:161]
	v_mfma_f32_16x16x128_f8f6f4 v[154:157], v[10:17], v[50:57], v[154:157]
	v_mfma_f32_16x16x128_f8f6f4 v[142:145], v[2:9], v[58:65], v[142:145]
	v_mfma_f32_16x16x128_f8f6f4 v[138:141], v[10:17], v[58:65], v[138:141]
	s_setprio 0
	s_setprio 1
	v_mfma_f32_16x16x128_f8f6f4 v[182:185], v[18:25], v[34:41], v[182:185]
	v_mfma_f32_16x16x128_f8f6f4 v[178:181], v[26:33], v[34:41], v[178:181]
	v_mfma_f32_16x16x128_f8f6f4 v[166:169], v[18:25], v[42:49], v[166:169]
	v_mfma_f32_16x16x128_f8f6f4 v[162:165], v[26:33], v[42:49], v[162:165]
	v_mfma_f32_16x16x128_f8f6f4 v[150:153], v[18:25], v[50:57], v[150:153]
	v_mfma_f32_16x16x128_f8f6f4 v[146:149], v[26:33], v[50:57], v[146:149]
	v_mfma_f32_16x16x128_f8f6f4 v[134:137], v[18:25], v[58:65], v[134:137]
	v_mfma_f32_16x16x128_f8f6f4 v[130:133], v[26:33], v[58:65], v[130:133]
	s_setprio 0
	s_barrier
	s_mov_b32 m0, s49
	v_lshl_add_u64 v[214:215], v[214:215], 0, s[14:15]
	s_add_u32 s26, s26, 0x40080
	ds_read_b128 v[34:37], v226 offset:49152
	ds_read_b128 v[38:41], v226 offset:50176
	ds_read_b128 v[42:45], v226 offset:51200
	ds_read_b128 v[46:49], v226 offset:52224
	ds_read_b128 v[50:53], v226 offset:53248
	ds_read_b128 v[54:57], v226 offset:54272
	ds_read_b128 v[58:61], v226 offset:55296
	ds_read_b128 v[62:65], v226 offset:56320
	global_load_lds_dwordx4 v[214:215], off
	v_lshl_add_u64 v[214:215], v[216:217], 0, s[14:15]
	s_mov_b32 m0, s50
	s_addc_u32 s27, s27, 0
	global_load_lds_dwordx4 v[214:215], off
	v_lshl_add_u64 v[214:215], s[26:27], 0, v[196:197]
	s_mov_b32 m0, s54
	s_nop 0
	global_load_lds_dwordx4 v[214:215], off
	v_lshl_add_u64 v[214:215], s[26:27], 0, v[200:201]
	s_mov_b32 m0, s55
	s_nop 0
	global_load_lds_dwordx4 v[214:215], off
	v_lshl_add_u64 v[214:215], v[218:219], 0, s[16:17]
	s_mov_b32 m0, s51
	s_nop 0
	global_load_lds_dwordx4 v[214:215], off
	v_lshl_add_u64 v[214:215], v[220:221], 0, s[16:17]
	s_mov_b32 m0, s52
	s_nop 0
	global_load_lds_dwordx4 v[214:215], off
	s_waitcnt vmcnt(8)
	s_waitcnt lgkmcnt(0)
	s_barrier
	s_setprio 1
	s_waitcnt lgkmcnt(0)
	v_mfma_f32_16x16x128_f8f6f4 v[126:129], v[2:9], v[34:41], v[126:129]
	v_mfma_f32_16x16x128_f8f6f4 v[122:125], v[10:17], v[34:41], v[122:125]
	v_mfma_f32_16x16x128_f8f6f4 v[110:113], v[2:9], v[42:49], v[110:113]
	v_mfma_f32_16x16x128_f8f6f4 v[106:109], v[10:17], v[42:49], v[106:109]
	v_mfma_f32_16x16x128_f8f6f4 v[94:97], v[2:9], v[50:57], v[94:97]
	v_mfma_f32_16x16x128_f8f6f4 v[90:93], v[10:17], v[50:57], v[90:93]
	v_mfma_f32_16x16x128_f8f6f4 v[78:81], v[2:9], v[58:65], v[78:81]
	v_mfma_f32_16x16x128_f8f6f4 v[74:77], v[10:17], v[58:65], v[74:77]
	s_setprio 0
	s_setprio 1
	v_mfma_f32_16x16x128_f8f6f4 v[118:121], v[18:25], v[34:41], v[118:121]
	v_mfma_f32_16x16x128_f8f6f4 v[114:117], v[26:33], v[34:41], v[114:117]
	v_mfma_f32_16x16x128_f8f6f4 v[102:105], v[18:25], v[42:49], v[102:105]
	v_mfma_f32_16x16x128_f8f6f4 v[98:101], v[26:33], v[42:49], v[98:101]
	v_mfma_f32_16x16x128_f8f6f4 v[86:89], v[18:25], v[50:57], v[86:89]
	v_mfma_f32_16x16x128_f8f6f4 v[82:85], v[26:33], v[50:57], v[82:85]
	v_mfma_f32_16x16x128_f8f6f4 v[70:73], v[18:25], v[58:65], v[70:73]
	v_mfma_f32_16x16x128_f8f6f4 v[66:69], v[26:33], v[58:65], v[66:69]
	s_setprio 0
	s_barrier
	s_add_i32 s70, s70, 2
	s_add_u32 s6, s6, 0x200
	s_addc_u32 s7, s7, 0
	s_add_u32 s68, s68, 0x100
	s_addc_u32 s69, s69, 0
	s_cmp_gt_u32 s70, 13
	s_cbranch_scc1 .LBB0_893

.LBB0_889:
	s_add_u32 s26, s4, s6
	s_addc_u32 s27, s5, s7
	s_add_u32 s26, s26, 0x200
	s_addc_u32 s27, s27, 0
	s_waitcnt lgkmcnt(0)
	s_cmpk_eq_i32 s6, 0xe00
	s_cselect_b32 s29, s23, s27
	s_cselect_b32 s28, s22, s26
	s_cselect_b32 s27, s66, s69
	s_cselect_b32 s26, s67, s68
	s_barrier
	s_setprio 1
	s_waitcnt lgkmcnt(0)
	v_mfma_f32_16x16x128_f8f6f4 v[190:193], v[26:33], v[58:65], v[190:193]
	v_mfma_f32_16x16x128_f8f6f4 v[186:189], v[18:25], v[58:65], v[186:189]
	v_mfma_f32_16x16x128_f8f6f4 v[174:177], v[26:33], v[50:57], v[174:177]
	v_mfma_f32_16x16x128_f8f6f4 v[170:173], v[18:25], v[50:57], v[170:173]
	v_mfma_f32_16x16x128_f8f6f4 v[158:161], v[26:33], v[42:49], v[158:161]
	v_mfma_f32_16x16x128_f8f6f4 v[154:157], v[18:25], v[42:49], v[154:157]
	v_mfma_f32_16x16x128_f8f6f4 v[142:145], v[26:33], v[34:41], v[142:145]
	v_mfma_f32_16x16x128_f8f6f4 v[138:141], v[18:25], v[34:41], v[138:141]
	s_setprio 0
	s_setprio 1
	v_mfma_f32_16x16x128_f8f6f4 v[182:185], v[10:17], v[58:65], v[182:185]
	v_mfma_f32_16x16x128_f8f6f4 v[178:181], v[2:9], v[58:65], v[178:181]
	v_mfma_f32_16x16x128_f8f6f4 v[166:169], v[10:17], v[50:57], v[166:169]
	v_mfma_f32_16x16x128_f8f6f4 v[162:165], v[2:9], v[50:57], v[162:165]
	v_mfma_f32_16x16x128_f8f6f4 v[150:153], v[10:17], v[42:49], v[150:153]
	v_mfma_f32_16x16x128_f8f6f4 v[146:149], v[2:9], v[42:49], v[146:149]
	v_mfma_f32_16x16x128_f8f6f4 v[134:137], v[10:17], v[34:41], v[134:137]
	v_mfma_f32_16x16x128_f8f6f4 v[130:133], v[2:9], v[34:41], v[130:133]
	s_setprio 0
	s_barrier
	s_mov_b32 m0, s36
	v_lshl_add_u64 v[214:215], s[26:27], 0, v[196:197]
	s_add_u32 s72, s26, 0x40000
	ds_read_b128 v[58:61], v226 offset:16384
	ds_read_b128 v[62:65], v226 offset:17408
	ds_read_b128 v[50:53], v226 offset:18432
	ds_read_b128 v[54:57], v226 offset:19456
	ds_read_b128 v[42:45], v226 offset:20480
	ds_read_b128 v[46:49], v226 offset:21504
	ds_read_b128 v[34:37], v226 offset:22528
	ds_read_b128 v[38:41], v226 offset:23552
	global_load_lds_dwordx4 v[214:215], off
	v_lshl_add_u64 v[216:217], s[26:27], 0, v[200:201]
	s_mov_b32 m0, s37
	s_addc_u32 s73, s27, 0
	global_load_lds_dwordx4 v[216:217], off
	v_lshl_add_u64 v[218:219], s[72:73], 0, v[196:197]
	s_mov_b32 m0, s38
	v_lshl_add_u64 v[220:221], s[28:29], 0, v[198:199]
	global_load_lds_dwordx4 v[218:219], off
	v_lshl_add_u64 v[218:219], s[72:73], 0, v[200:201]
	s_mov_b32 m0, s39
	s_andn2_b64 vcc, exec, s[30:31]
	global_load_lds_dwordx4 v[218:219], off
	v_lshl_add_u64 v[218:219], s[28:29], 0, v[194:195]
	s_mov_b32 m0, s40
	s_nop 0
	global_load_lds_dwordx4 v[218:219], off
	s_mov_b32 m0, s41
	s_nop 0
	global_load_lds_dwordx4 v[220:221], off
	s_cbranch_vccnz .LBB0_892
	s_waitcnt vmcnt(24)
	s_cbranch_execnz .LBB0_885
	s_branch .LBB0_884

.LBB0_1062:
	s_waitcnt lgkmcnt(0)
	s_barrier
	s_setprio 1
	s_waitcnt lgkmcnt(0)
	v_mfma_f32_16x16x128_f8f6f4 v[126:129], v[26:33], v[58:65], v[126:129]
	v_mfma_f32_16x16x128_f8f6f4 v[122:125], v[18:25], v[58:65], v[122:125]
	v_mfma_f32_16x16x128_f8f6f4 v[114:117], v[26:33], v[50:57], v[114:117]
	v_mfma_f32_16x16x128_f8f6f4 v[106:109], v[18:25], v[50:57], v[106:109]
	v_mfma_f32_16x16x128_f8f6f4 v[98:101], v[26:33], v[42:49], v[98:101]
	v_mfma_f32_16x16x128_f8f6f4 v[90:93], v[18:25], v[42:49], v[90:93]
	v_mfma_f32_16x16x128_f8f6f4 v[82:85], v[26:33], v[34:41], v[82:85]
	v_mfma_f32_16x16x128_f8f6f4 v[74:77], v[18:25], v[34:41], v[74:77]
	s_setprio 0
	s_setprio 1
	v_mfma_f32_16x16x128_f8f6f4 v[118:121], v[10:17], v[58:65], v[118:121]
	v_mfma_f32_16x16x128_f8f6f4 v[110:113], v[2:9], v[58:65], v[110:113]
	v_mfma_f32_16x16x128_f8f6f4 v[102:105], v[10:17], v[50:57], v[102:105]
	v_mfma_f32_16x16x128_f8f6f4 v[94:97], v[2:9], v[50:57], v[94:97]
	v_mfma_f32_16x16x128_f8f6f4 v[86:89], v[10:17], v[42:49], v[86:89]
	v_mfma_f32_16x16x128_f8f6f4 v[78:81], v[2:9], v[42:49], v[78:81]
	v_mfma_f32_16x16x128_f8f6f4 v[70:73], v[10:17], v[34:41], v[70:73]
	v_mfma_f32_16x16x128_f8f6f4 v[66:69], v[2:9], v[34:41], v[66:69]
	s_setprio 0
	s_barrier
	v_add_u32_e32 v14, s58, v222
	v_add_u32_e32 v30, s63, v222
	ds_read_b128 v[2:5], v14
	ds_read_b128 v[6:9], v14 offset:1024
	ds_read_b128 v[10:13], v14 offset:2048
	ds_read_b128 v[14:17], v14 offset:3072
	ds_read_b128 v[18:21], v30
	ds_read_b128 v[22:25], v30 offset:1024
	ds_read_b128 v[26:29], v30 offset:2048
	ds_read_b128 v[30:33], v30 offset:3072
	s_add_u32 s40, s40, 0x40000
	s_addc_u32 s41, s41, 0
	s_mov_b32 m0, s56
	v_lshl_add_u64 v[228:229], s[40:41], 0, v[200:201]
	ds_read_b128 v[34:37], v226 offset:32768
	ds_read_b128 v[38:41], v226 offset:33792
	ds_read_b128 v[42:45], v226 offset:34816
	ds_read_b128 v[46:49], v226 offset:35840
	ds_read_b128 v[50:53], v226 offset:36864
	ds_read_b128 v[54:57], v226 offset:37888
	ds_read_b128 v[58:61], v226 offset:38912
	ds_read_b128 v[62:65], v226 offset:39936
	global_load_lds_dwordx4 v[228:229], off
	v_lshl_add_u64 v[228:229], s[40:41], 0, v[196:197]
	s_mov_b32 m0, s57
	s_nop 0
	global_load_lds_dwordx4 v[228:229], off
	s_waitcnt vmcnt(8)
	s_waitcnt lgkmcnt(0)
	s_barrier
	s_setprio 1
	s_waitcnt lgkmcnt(0)
	v_mfma_f32_16x16x128_f8f6f4 v[190:193], v[2:9], v[34:41], v[190:193]
	v_mfma_f32_16x16x128_f8f6f4 v[186:189], v[10:17], v[34:41], v[186:189]
	v_mfma_f32_16x16x128_f8f6f4 v[178:181], v[2:9], v[42:49], v[178:181]
	v_mfma_f32_16x16x128_f8f6f4 v[170:173], v[10:17], v[42:49], v[170:173]
	v_mfma_f32_16x16x128_f8f6f4 v[162:165], v[2:9], v[50:57], v[162:165]
	v_mfma_f32_16x16x128_f8f6f4 v[154:157], v[10:17], v[50:57], v[154:157]
	v_mfma_f32_16x16x128_f8f6f4 v[146:149], v[2:9], v[58:65], v[146:149]
	v_mfma_f32_16x16x128_f8f6f4 v[138:141], v[10:17], v[58:65], v[138:141]
	s_setprio 0
	s_setprio 1
	v_mfma_f32_16x16x128_f8f6f4 v[182:185], v[18:25], v[34:41], v[182:185]
	v_mfma_f32_16x16x128_f8f6f4 v[174:177], v[26:33], v[34:41], v[174:177]
	v_mfma_f32_16x16x128_f8f6f4 v[166:169], v[18:25], v[42:49], v[166:169]
	v_mfma_f32_16x16x128_f8f6f4 v[158:161], v[26:33], v[42:49], v[158:161]
	v_mfma_f32_16x16x128_f8f6f4 v[150:153], v[18:25], v[50:57], v[150:153]
	v_mfma_f32_16x16x128_f8f6f4 v[142:145], v[26:33], v[50:57], v[142:145]
	v_mfma_f32_16x16x128_f8f6f4 v[134:137], v[18:25], v[58:65], v[134:137]
	v_mfma_f32_16x16x128_f8f6f4 v[130:133], v[26:33], v[58:65], v[130:133]
	s_setprio 0
	s_barrier
	s_mov_b32 m0, s59
	v_lshl_add_u64 v[214:215], v[214:215], 0, s[6:7]
	s_add_u32 s38, s38, 0x40080
	ds_read_b128 v[34:37], v226 offset:49152
	ds_read_b128 v[38:41], v226 offset:50176
	ds_read_b128 v[42:45], v226 offset:51200
	ds_read_b128 v[46:49], v226 offset:52224
	ds_read_b128 v[50:53], v226 offset:53248
	ds_read_b128 v[54:57], v226 offset:54272
	ds_read_b128 v[58:61], v226 offset:55296
	ds_read_b128 v[62:65], v226 offset:56320
	global_load_lds_dwordx4 v[214:215], off
	v_lshl_add_u64 v[214:215], v[216:217], 0, s[6:7]
	s_mov_b32 m0, s60
	s_addc_u32 s39, s39, 0
	global_load_lds_dwordx4 v[214:215], off
	v_lshl_add_u64 v[214:215], s[38:39], 0, v[198:199]
	s_mov_b32 m0, s64
	s_nop 0
	global_load_lds_dwordx4 v[214:215], off
	v_lshl_add_u64 v[214:215], s[38:39], 0, v[194:195]
	s_mov_b32 m0, s65
	s_nop 0
	global_load_lds_dwordx4 v[214:215], off
	v_lshl_add_u64 v[214:215], v[218:219], 0, s[6:7]
	s_mov_b32 m0, s61
	s_nop 0
	global_load_lds_dwordx4 v[214:215], off
	v_lshl_add_u64 v[214:215], v[220:221], 0, s[6:7]
	s_mov_b32 m0, s62
	s_nop 0
	global_load_lds_dwordx4 v[214:215], off
	s_waitcnt vmcnt(8)
	s_waitcnt lgkmcnt(0)
	s_barrier
	s_setprio 1
	s_waitcnt lgkmcnt(0)
	v_mfma_f32_16x16x128_f8f6f4 v[126:129], v[2:9], v[34:41], v[126:129]
	v_mfma_f32_16x16x128_f8f6f4 v[122:125], v[10:17], v[34:41], v[122:125]
	v_mfma_f32_16x16x128_f8f6f4 v[114:117], v[2:9], v[42:49], v[114:117]
	v_mfma_f32_16x16x128_f8f6f4 v[106:109], v[10:17], v[42:49], v[106:109]
	v_mfma_f32_16x16x128_f8f6f4 v[98:101], v[2:9], v[50:57], v[98:101]
	v_mfma_f32_16x16x128_f8f6f4 v[90:93], v[10:17], v[50:57], v[90:93]
	v_mfma_f32_16x16x128_f8f6f4 v[82:85], v[2:9], v[58:65], v[82:85]
	v_mfma_f32_16x16x128_f8f6f4 v[74:77], v[10:17], v[58:65], v[74:77]
	s_setprio 0
	s_setprio 1
	v_mfma_f32_16x16x128_f8f6f4 v[118:121], v[18:25], v[34:41], v[118:121]
	v_mfma_f32_16x16x128_f8f6f4 v[110:113], v[26:33], v[34:41], v[110:113]
	v_mfma_f32_16x16x128_f8f6f4 v[102:105], v[18:25], v[42:49], v[102:105]
	v_mfma_f32_16x16x128_f8f6f4 v[94:97], v[26:33], v[42:49], v[94:97]
	v_mfma_f32_16x16x128_f8f6f4 v[86:89], v[18:25], v[50:57], v[86:89]
	v_mfma_f32_16x16x128_f8f6f4 v[78:81], v[26:33], v[50:57], v[78:81]
	v_mfma_f32_16x16x128_f8f6f4 v[70:73], v[18:25], v[58:65], v[70:73]
	v_mfma_f32_16x16x128_f8f6f4 v[66:69], v[26:33], v[58:65], v[66:69]
	s_setprio 0
	s_barrier
	s_add_i32 s77, s77, 2
	s_add_u32 s36, s36, 0x100
	s_addc_u32 s37, s37, 0
	s_cmp_gt_u32 s77, 13
	s_cbranch_scc1 .LBB0_1070

.LBB0_1066:
	s_add_u32 s38, s30, s36
	s_addc_u32 s39, s31, s37
	s_add_u32 s38, s38, 0x100
	s_addc_u32 s39, s39, 0
	s_add_u32 s78, s75, s36
	s_addc_u32 s79, s76, s37
	s_waitcnt lgkmcnt(0)
	s_cmpk_eq_i32 s36, 0x700
	s_cselect_b32 s41, s21, s39
	s_cselect_b32 s40, s73, s38
	s_cselect_b32 s39, s23, s79
	s_cselect_b32 s38, s74, s78
	s_barrier
	s_setprio 1
	s_waitcnt lgkmcnt(0)
	v_mfma_f32_16x16x128_f8f6f4 v[190:193], v[26:33], v[58:65], v[190:193]
	v_mfma_f32_16x16x128_f8f6f4 v[186:189], v[18:25], v[58:65], v[186:189]
	v_mfma_f32_16x16x128_f8f6f4 v[178:181], v[26:33], v[50:57], v[178:181]
	v_mfma_f32_16x16x128_f8f6f4 v[170:173], v[18:25], v[50:57], v[170:173]
	v_mfma_f32_16x16x128_f8f6f4 v[162:165], v[26:33], v[42:49], v[162:165]
	v_mfma_f32_16x16x128_f8f6f4 v[154:157], v[18:25], v[42:49], v[154:157]
	v_mfma_f32_16x16x128_f8f6f4 v[146:149], v[26:33], v[34:41], v[146:149]
	v_mfma_f32_16x16x128_f8f6f4 v[138:141], v[18:25], v[34:41], v[138:141]
	s_setprio 0
	s_setprio 1
	v_mfma_f32_16x16x128_f8f6f4 v[182:185], v[10:17], v[58:65], v[182:185]
	v_mfma_f32_16x16x128_f8f6f4 v[174:177], v[2:9], v[58:65], v[174:177]
	v_mfma_f32_16x16x128_f8f6f4 v[166:169], v[10:17], v[50:57], v[166:169]
	v_mfma_f32_16x16x128_f8f6f4 v[158:161], v[2:9], v[50:57], v[158:161]
	v_mfma_f32_16x16x128_f8f6f4 v[150:153], v[10:17], v[42:49], v[150:153]
	v_mfma_f32_16x16x128_f8f6f4 v[142:145], v[2:9], v[42:49], v[142:145]
	v_mfma_f32_16x16x128_f8f6f4 v[134:137], v[10:17], v[34:41], v[134:137]
	v_mfma_f32_16x16x128_f8f6f4 v[130:133], v[2:9], v[34:41], v[130:133]
	s_setprio 0
	s_barrier
	s_mov_b32 m0, s29
	v_lshl_add_u64 v[214:215], s[38:39], 0, v[198:199]
	s_add_u32 s78, s38, 0x40000
	ds_read_b128 v[58:61], v226 offset:16384
	ds_read_b128 v[62:65], v226 offset:17408
	ds_read_b128 v[50:53], v226 offset:18432
	ds_read_b128 v[54:57], v226 offset:19456
	ds_read_b128 v[42:45], v226 offset:20480
	ds_read_b128 v[46:49], v226 offset:21504
	ds_read_b128 v[34:37], v226 offset:22528
	ds_read_b128 v[38:41], v226 offset:23552
	global_load_lds_dwordx4 v[214:215], off
	v_lshl_add_u64 v[216:217], s[38:39], 0, v[194:195]
	s_mov_b32 m0, s51
	s_addc_u32 s79, s39, 0
	global_load_lds_dwordx4 v[216:217], off
	v_lshl_add_u64 v[218:219], s[78:79], 0, v[198:199]
	s_mov_b32 m0, s52
	v_lshl_add_u64 v[220:221], s[40:41], 0, v[196:197]
	global_load_lds_dwordx4 v[218:219], off
	v_lshl_add_u64 v[218:219], s[78:79], 0, v[194:195]
	s_mov_b32 m0, s53
	s_andn2_b64 vcc, exec, s[42:43]
	global_load_lds_dwordx4 v[218:219], off
	v_lshl_add_u64 v[218:219], s[40:41], 0, v[200:201]
	s_mov_b32 m0, s54
	s_nop 0
	global_load_lds_dwordx4 v[218:219], off
	s_mov_b32 m0, s55
	s_nop 0
	global_load_lds_dwordx4 v[220:221], off
	s_cbranch_vccnz .LBB0_1069
	s_waitcnt vmcnt(24)
	s_cbranch_execnz .LBB0_1062
	s_branch .LBB0_1061

.LBB0_1848:
	s_waitcnt vmcnt(0)
	v_lshlrev_b32_e32 v58, 16, v46
	v_and_b32_e32 v46, 0xffff0000, v46
	v_mov_b32_e32 v146, v171
	v_cvt_pk_fp8_f32 v146, v58, v46
	v_lshlrev_b32_e32 v58, 16, v48
	v_and_b32_e32 v48, 0xffff0000, v48
	v_mov_b32_e32 v147, v171
	v_cvt_pk_fp8_f32 v147, v58, v48
	v_lshlrev_b32_e32 v46, 16, v47
	v_and_b32_e32 v47, 0xffff0000, v47
	v_cvt_pk_fp8_f32 v146, v46, v47 op_sel:[0,0,1]
	v_lshlrev_b32_e32 v46, 16, v49
	v_and_b32_e32 v47, 0xffff0000, v49
	v_cvt_pk_fp8_f32 v147, v46, v47 op_sel:[0,0,1]
	v_lshlrev_b32_e32 v46, 16, v42
	v_and_b32_e32 v42, 0xffff0000, v42
	v_mov_b32_e32 v148, v171
	v_cvt_pk_fp8_f32 v148, v46, v42
	v_lshlrev_b32_e32 v46, 16, v44
	v_and_b32_e32 v44, 0xffff0000, v44
	v_mov_b32_e32 v149, v171
	v_cvt_pk_fp8_f32 v149, v46, v44
	v_lshlrev_b32_e32 v42, 16, v43
	v_and_b32_e32 v43, 0xffff0000, v43
	v_cvt_pk_fp8_f32 v148, v42, v43 op_sel:[0,0,1]
	v_lshlrev_b32_e32 v42, 16, v45
	v_and_b32_e32 v43, 0xffff0000, v45
	v_cvt_pk_fp8_f32 v149, v42, v43 op_sel:[0,0,1]
	v_lshlrev_b32_e32 v42, 16, v38
	v_and_b32_e32 v38, 0xffff0000, v38
	v_mov_b32_e32 v150, v171
	v_cvt_pk_fp8_f32 v150, v42, v38
	v_lshlrev_b32_e32 v42, 16, v40
	v_and_b32_e32 v40, 0xffff0000, v40
	v_mov_b32_e32 v151, v171
	v_cvt_pk_fp8_f32 v151, v42, v40
	v_lshlrev_b32_e32 v38, 16, v39
	v_and_b32_e32 v39, 0xffff0000, v39
	v_cvt_pk_fp8_f32 v150, v38, v39 op_sel:[0,0,1]
	v_lshlrev_b32_e32 v38, 16, v41
	v_and_b32_e32 v39, 0xffff0000, v41
	v_cvt_pk_fp8_f32 v151, v38, v39 op_sel:[0,0,1]
	v_lshlrev_b32_e32 v38, 16, v34
	v_and_b32_e32 v34, 0xffff0000, v34
	v_mov_b32_e32 v152, v171
	v_cvt_pk_fp8_f32 v152, v38, v34
	v_lshlrev_b32_e32 v38, 16, v36
	v_and_b32_e32 v36, 0xffff0000, v36
	v_mov_b32_e32 v153, v171
	v_cvt_pk_fp8_f32 v153, v38, v36
	v_lshlrev_b32_e32 v34, 16, v35
	v_and_b32_e32 v35, 0xffff0000, v35
	v_cvt_pk_fp8_f32 v152, v34, v35 op_sel:[0,0,1]
	v_lshlrev_b32_e32 v34, 16, v37
	v_and_b32_e32 v35, 0xffff0000, v37
	v_cvt_pk_fp8_f32 v153, v34, v35 op_sel:[0,0,1]
	v_lshlrev_b32_e32 v34, 16, v30
	v_and_b32_e32 v30, 0xffff0000, v30
	v_mov_b32_e32 v154, v171
	v_cvt_pk_fp8_f32 v154, v34, v30
	v_lshlrev_b32_e32 v34, 16, v32
	v_and_b32_e32 v32, 0xffff0000, v32
	v_mov_b32_e32 v155, v171
	v_cvt_pk_fp8_f32 v155, v34, v32
	v_lshlrev_b32_e32 v30, 16, v31
	v_and_b32_e32 v31, 0xffff0000, v31
	v_cvt_pk_fp8_f32 v154, v30, v31 op_sel:[0,0,1]
	v_lshlrev_b32_e32 v30, 16, v33
	v_and_b32_e32 v31, 0xffff0000, v33
	v_cvt_pk_fp8_f32 v155, v30, v31 op_sel:[0,0,1]
	v_lshlrev_b32_e32 v30, 16, v26
	v_and_b32_e32 v26, 0xffff0000, v26
	v_mov_b32_e32 v156, v171
	v_cvt_pk_fp8_f32 v156, v30, v26
	v_lshlrev_b32_e32 v30, 16, v28
	v_and_b32_e32 v28, 0xffff0000, v28
	v_mov_b32_e32 v157, v171
	v_cvt_pk_fp8_f32 v157, v30, v28
	v_lshlrev_b32_e32 v26, 16, v27
	v_and_b32_e32 v27, 0xffff0000, v27
	v_cvt_pk_fp8_f32 v156, v26, v27 op_sel:[0,0,1]
	v_lshlrev_b32_e32 v26, 16, v29
	v_and_b32_e32 v27, 0xffff0000, v29
	v_cvt_pk_fp8_f32 v157, v26, v27 op_sel:[0,0,1]
	v_lshlrev_b32_e32 v26, 16, v22
	v_and_b32_e32 v22, 0xffff0000, v22
	v_mov_b32_e32 v158, v171
	v_cvt_pk_fp8_f32 v158, v26, v22
	v_lshlrev_b32_e32 v26, 16, v24
	v_and_b32_e32 v24, 0xffff0000, v24
	v_mov_b32_e32 v159, v171
	v_cvt_pk_fp8_f32 v159, v26, v24
	v_lshlrev_b32_e32 v22, 16, v23
	v_and_b32_e32 v23, 0xffff0000, v23
	v_cvt_pk_fp8_f32 v158, v22, v23 op_sel:[0,0,1]
	v_lshlrev_b32_e32 v22, 16, v25
	v_and_b32_e32 v23, 0xffff0000, v25
	v_cvt_pk_fp8_f32 v159, v22, v23 op_sel:[0,0,1]
	v_lshlrev_b32_e32 v22, 16, v18
	v_and_b32_e32 v18, 0xffff0000, v18
	v_mov_b32_e32 v160, v171
	v_cvt_pk_fp8_f32 v160, v22, v18
	v_lshlrev_b32_e32 v22, 16, v20
	v_and_b32_e32 v20, 0xffff0000, v20
	v_mov_b32_e32 v161, v171
	v_cvt_pk_fp8_f32 v161, v22, v20
	v_lshlrev_b32_e32 v18, 16, v19
	v_and_b32_e32 v19, 0xffff0000, v19
	v_cvt_pk_fp8_f32 v160, v18, v19 op_sel:[0,0,1]
	v_lshlrev_b32_e32 v18, 16, v21
	v_and_b32_e32 v19, 0xffff0000, v21
	v_cvt_pk_fp8_f32 v161, v18, v19 op_sel:[0,0,1]
	v_lshlrev_b32_e32 v18, 16, v14
	v_and_b32_e32 v14, 0xffff0000, v14
	v_mov_b32_e32 v162, v171
	v_cvt_pk_fp8_f32 v162, v18, v14
	v_lshlrev_b32_e32 v18, 16, v16
	v_and_b32_e32 v16, 0xffff0000, v16
	v_mov_b32_e32 v163, v171
	v_cvt_pk_fp8_f32 v163, v18, v16
	v_lshlrev_b32_e32 v14, 16, v15
	v_and_b32_e32 v15, 0xffff0000, v15
	v_cvt_pk_fp8_f32 v162, v14, v15 op_sel:[0,0,1]
	v_lshlrev_b32_e32 v14, 16, v17
	v_and_b32_e32 v15, 0xffff0000, v17
	v_cvt_pk_fp8_f32 v163, v14, v15 op_sel:[0,0,1]
	v_lshlrev_b32_e32 v14, 16, v10
	v_and_b32_e32 v10, 0xffff0000, v10
	v_mov_b32_e32 v164, v171
	v_cvt_pk_fp8_f32 v164, v14, v10
	v_lshlrev_b32_e32 v14, 16, v12
	v_and_b32_e32 v12, 0xffff0000, v12
	v_mov_b32_e32 v165, v171
	v_cvt_pk_fp8_f32 v165, v14, v12
	v_lshlrev_b32_e32 v10, 16, v11
	v_and_b32_e32 v11, 0xffff0000, v11
	v_cvt_pk_fp8_f32 v164, v10, v11 op_sel:[0,0,1]
	v_lshlrev_b32_e32 v10, 16, v13
	v_and_b32_e32 v11, 0xffff0000, v13
	v_cvt_pk_fp8_f32 v165, v10, v11 op_sel:[0,0,1]
	v_lshlrev_b32_e32 v10, 16, v6
	v_and_b32_e32 v6, 0xffff0000, v6
	v_mov_b32_e32 v166, v171
	v_cvt_pk_fp8_f32 v166, v10, v6
	v_lshlrev_b32_e32 v10, 16, v8
	v_and_b32_e32 v8, 0xffff0000, v8
	v_mov_b32_e32 v167, v171
	v_cvt_pk_fp8_f32 v167, v10, v8
	v_lshlrev_b32_e32 v6, 16, v7
	v_and_b32_e32 v7, 0xffff0000, v7
	v_cvt_pk_fp8_f32 v166, v6, v7 op_sel:[0,0,1]
	v_lshlrev_b32_e32 v6, 16, v9
	v_and_b32_e32 v7, 0xffff0000, v9
	v_cvt_pk_fp8_f32 v167, v6, v7 op_sel:[0,0,1]
	v_lshlrev_b32_e32 v6, 16, v2
	v_and_b32_e32 v2, 0xffff0000, v2
	v_mov_b32_e32 v168, v171
	v_cvt_pk_fp8_f32 v168, v6, v2
	v_lshlrev_b32_e32 v6, 16, v4
	v_and_b32_e32 v4, 0xffff0000, v4
	v_mov_b32_e32 v169, v171
	v_cvt_pk_fp8_f32 v169, v6, v4
	v_lshlrev_b32_e32 v2, 16, v3
	v_and_b32_e32 v3, 0xffff0000, v3
	v_cvt_pk_fp8_f32 v168, v2, v3 op_sel:[0,0,1]
	v_lshlrev_b32_e32 v2, 16, v5
	v_and_b32_e32 v3, 0xffff0000, v5
	v_cvt_pk_fp8_f32 v169, v2, v3 op_sel:[0,0,1]
	v_lshrrev_b32_e32 v2, 1, v55
	v_and_b32_e32 v3, 8, v55
	v_and_or_b32 v2, v2, 3, v3
	v_bfe_u32 v58, v55, 5, 1
	v_bfe_u32 v59, v55, 1, 3
	v_lshlrev_b32_e32 v2, 7, v2
	v_lshlrev_b32_e32 v3, 3, v55
	v_and_b32_e32 v60, 1, v57
	v_lshl_or_b32 v2, v58, 9, v2
	v_and_b32_e32 v3, 8, v3
	v_bitop3_b32 v10, v57, v59, 1 bitop3:0x6c
	v_lshlrev_b32_e32 v42, 3, v52
	v_or_b32_e32 v57, 32, v52
	v_add3_u32 v61, v3, s67, v2
	s_waitcnt lgkmcnt(0)
	v_bitop3_b32 v11, v42, v56, s45 bitop3:0x6c
	v_lshl_add_u32 v43, v52, 7, s67
	v_or_b32_e32 v2, 16, v56
	v_lshl_add_u32 v44, v57, 7, s67
	s_barrier
	v_add_u32_e32 v209, v43, v11
	v_bitop3_b32 v12, v42, v2, s45 bitop3:0x6c
	v_add_u32_e32 v211, v44, v11
	v_add_u32_e32 v210, v43, v12
	ds_read_b128 v[2:5], v209 offset:32768
	ds_read_b128 v[6:9], v210 offset:32768
	v_add_u32_e32 v212, v44, v12
	ds_read_b128 v[34:37], v211 offset:32768
	ds_read_b128 v[38:41], v212 offset:32768
	v_lshl_add_u32 v206, v10, 4, v61
	v_bitop3_b32 v10, v60, v59, 2 bitop3:0x36
	v_lshl_add_u32 v205, v10, 4, v61
	s_waitcnt lgkmcnt(0)
	v_mfma_f32_32x32x64_f8f6f4 v[18:33], v[2:9], v[146:153], 0
	v_mfma_f32_32x32x64_f8f6f4 v[2:17], v[34:41], v[146:153], 0
	v_or_b32_e32 v34, 64, v56
	v_bitop3_b32 v45, v42, v34, s45 bitop3:0x6c
	v_or_b32_e32 v34, 0x50, v56
	v_add_u32_e32 v213, v43, v45
	v_bitop3_b32 v42, v42, v34, s45 bitop3:0x6c
	v_add_u32_e32 v214, v43, v42
	ds_read_b128 v[34:37], v213 offset:32768
	ds_read_b128 v[38:41], v214 offset:32768
	v_add_u32_e32 v207, v44, v45
	v_add_u32_e32 v208, v44, v42
	ds_read_b128 v[42:45], v207 offset:32768
	ds_read_b128 v[46:49], v208 offset:32768
	v_bitop3_b32 v56, v60, v59, 4 bitop3:0x36
	s_waitcnt lgkmcnt(2)
	v_mfma_f32_32x32x64_f8f6f4 v[18:33], v[34:41], v[154:161], v[18:33]
	v_lshlrev_b32_e32 v34, 1, v58
	v_lshrrev_b32_e32 v35, 2, v55
	v_and_b32_e32 v195, 63, v55
	v_lshl_add_u32 v203, v56, 4, v61
	v_bitop3_b32 v56, v60, v59, 6 bitop3:0x36
	v_lshlrev_b32_e32 v59, 6, v52
	v_bfe_u32 v36, v55, 2, 2
	v_bitop3_b32 v35, v34, v35, 3 bitop3:0x78
	v_lshlrev_b32_e32 v55, 6, v57
	s_waitcnt lgkmcnt(0)
	v_mfma_f32_32x32x64_f8f6f4 v[2:17], v[42:49], v[154:161], v[2:17]
	v_lshlrev_b32_e32 v215, 4, v35
	v_add_u32_e32 v35, s42, v59
	v_bitop3_b32 v34, v34, v36, 1 bitop3:0x36
	v_add_u32_e32 v42, s42, v55
	v_add_u32_e32 v216, v35, v215
	v_lshlrev_b32_e32 v217, 4, v34
	v_add_u32_e32 v219, v42, v215
	v_add_u32_e32 v218, v35, v217
	ds_read_b128 v[34:37], v216
	ds_read_b128 v[38:41], v218
	v_add_u32_e32 v220, v42, v217
	ds_read_b128 v[42:45], v219
	ds_read_b128 v[46:49], v220
	s_waitcnt lgkmcnt(2)
	v_mfma_f32_32x32x64_f8f6f4 v[18:33], v[34:41], v[162:169], v[18:33]
	s_waitcnt lgkmcnt(0)
	v_mfma_f32_32x32x64_f8f6f4 v[2:17], v[42:49], v[162:169], v[2:17]
	s_nop 0
	s_nop 15
	s_nop 7
	s_lshr_b32 s2, s58, 3
	v_max_f32_e32 v34, v19, v19
	v_max_f32_e32 v35, v18, v18
	v_max_f32_e32 v34, v35, v34
	v_max3_f32 v34, v34, v20, v21
	v_max3_f32 v34, v34, v22, v23
	v_max3_f32 v34, v34, v24, v25
	v_max3_f32 v34, v34, v26, v27
	v_max3_f32 v34, v34, v28, v29
	v_max3_f32 v34, v34, v30, v31
	v_max3_f32 v34, v34, v32, v33
	v_max3_f32 v34, v34, v2, v3
	v_max3_f32 v34, v34, v4, v5
	v_max3_f32 v34, v34, v6, v7
	v_max3_f32 v34, v34, v8, v9
	v_max3_f32 v34, v34, v10, v11
	v_max3_f32 v34, v34, v12, v13
	v_max3_f32 v34, v34, v14, v15
	v_max3_f32 v34, v34, v16, v17
	v_mov_b32_e32 v35, v34
	s_nop 1
	v_permlane32_swap_b32_e32 v34, v35
	v_max_f32_e32 v35, v35, v35
	v_max_f32_e32 v34, v34, v34
	s_and_b32 s3, s59, 0x3fffffc0
	v_max_f32_e32 v34, v34, v35
	s_lshl_b32 s3, s3, 2
	s_and_b32 s2, s2, 15
	v_add_f32_e32 v35, 0x7149f2ca, v34
	s_add_i32 s36, s71, s3
	s_lshl_b32 s58, s2, 7
	v_cmp_ge_f32_e32 vcc, s46, v35
	s_cmp_eq_u64 vcc, exec
	v_max_f32_e32 v34, 0xf149f2ca, v34
	s_cselect_b64 vcc, -1, 0
	v_cndmask_b32_e32 v228, v34, v194, vcc
	v_sub_f32_e32 v36, 0xf149f2ca, v34
	v_fma_f32 v34, v228, s47, 4.0
	v_mov_b32_e32 v35, v34
	s_add_u32 s2, s54, s34
	v_fmac_f32_e32 v35, 0x3dd53b94, v33
	s_addc_u32 s3, s55, s35
	s_add_i32 s37, s67, s57
	v_pk_fma_f32 v[66:67], v[2:3], s[4:5], v[34:35] op_sel_hi:[1,0,0]
	v_lshl_add_u64 v[2:3], s[2:3], 0, v[174:175]
	s_add_i32 s57, s37, 0x4000
	v_lshl_add_u64 v[2:3], v[2:3], 0, s[6:7]
	s_mov_b32 m0, s57
	v_mul_f32_e32 v36, 0x3dd53b94, v36
	global_load_lds_dwordx4 v[2:3], off
	v_exp_f32_e32 v36, v36
	v_fmamk_f32 v18, v18, 0x3dd53b94, v34
	v_fmamk_f32 v19, v19, 0x3dd53b94, v34
	v_fmamk_f32 v20, v20, 0x3dd53b94, v34
	v_fmamk_f32 v21, v21, 0x3dd53b94, v34
	v_fmamk_f32 v22, v22, 0x3dd53b94, v34
	v_fmamk_f32 v23, v23, 0x3dd53b94, v34
	v_fmamk_f32 v24, v24, 0x3dd53b94, v34
	v_fmamk_f32 v25, v25, 0x3dd53b94, v34
	v_fmamk_f32 v26, v26, 0x3dd53b94, v34
	v_fmamk_f32 v27, v27, 0x3dd53b94, v34
	v_fmamk_f32 v28, v28, 0x3dd53b94, v34
	v_fmamk_f32 v29, v29, 0x3dd53b94, v34
	v_fmamk_f32 v30, v30, 0x3dd53b94, v34
	v_fmamk_f32 v31, v31, 0x3dd53b94, v34
	v_fmamk_f32 v32, v32, 0x3dd53b94, v34
	v_exp_f32_e32 v82, v18
	v_exp_f32_e32 v83, v19
	v_exp_f32_e32 v84, v20
	v_exp_f32_e32 v85, v21
	v_exp_f32_e32 v184, v22
	v_exp_f32_e32 v185, v23
	v_exp_f32_e32 v182, v24
	v_exp_f32_e32 v183, v25
	v_exp_f32_e32 v144, v26
	v_exp_f32_e32 v145, v27
	v_exp_f32_e32 v138, v28
	v_exp_f32_e32 v139, v29
	v_exp_f32_e32 v142, v30
	v_exp_f32_e32 v143, v31
	v_exp_f32_e32 v140, v32
	v_exp_f32_e32 v141, v35
	s_waitcnt vmcnt(1)
	s_barrier
	s_add_u32 s34, s34, s58
	v_add_u32_e32 v2, v54, v53
	v_lshl_add_u32 v202, v56, 4, v61
	s_addc_u32 s35, s35, 0
	v_ashrrev_i32_e32 v3, 31, v2
	v_mov_b32_e32 v196, 0
	v_cndmask_b32_e64 v221, v36, 1.0, vcc
	v_pk_fma_f32 v[80:81], v[16:17], s[4:5], v[34:35] op_sel_hi:[1,0,0]
	v_pk_fma_f32 v[78:79], v[14:15], s[4:5], v[34:35] op_sel_hi:[1,0,0]
	v_pk_fma_f32 v[76:77], v[12:13], s[4:5], v[34:35] op_sel_hi:[1,0,0]
	v_pk_fma_f32 v[74:75], v[10:11], s[4:5], v[34:35] op_sel_hi:[1,0,0]
	v_pk_fma_f32 v[72:73], v[8:9], s[4:5], v[34:35] op_sel_hi:[1,0,0]
	v_pk_fma_f32 v[70:71], v[6:7], s[4:5], v[34:35] op_sel_hi:[1,0,0]
	v_pk_fma_f32 v[68:69], v[4:5], s[4:5], v[34:35] op_sel_hi:[1,0,0]
	v_add_u32_e32 v222, s43, v59
	v_add_u32_e32 v223, s43, v55
	v_cmp_gt_u32_e64 s[2:3], 32, v195
	v_lshl_add_u32 v204, v52, 2, s36
	v_lshl_add_u32 v201, v58, 4, s36
	v_add_u32_e32 v200, 0x4000, v206
	v_add_u32_e32 v199, 0x4000, v205
	v_add_u32_e32 v198, 0x4000, v203
	v_add_u32_e32 v197, 0x4000, v202
	v_lshl_add_u64 v[176:177], v[170:171], 0, v[50:51]
	v_lshl_add_u64 v[178:179], s[34:35], 0, v[174:175]
	v_lshl_add_u64 v[180:181], s[34:35], 0, v[2:3]
	s_mov_b32 s58, -1
	v_mov_b32_e32 v2, 0
	v_mov_b32_e32 v3, v196
	v_mov_b32_e32 v4, v196
	v_mov_b32_e32 v5, v196
	v_mov_b32_e32 v6, v196
	v_mov_b32_e32 v7, v196
	v_mov_b32_e32 v8, v196
	v_mov_b32_e32 v9, v196
	v_mov_b32_e32 v10, v196
	v_mov_b32_e32 v11, v196
	v_mov_b32_e32 v12, v196
	v_mov_b32_e32 v13, v196
	v_mov_b32_e32 v14, v196
	v_mov_b32_e32 v15, v196
	v_mov_b32_e32 v16, v196
	v_mov_b32_e32 v17, v196
	v_mov_b32_e32 v18, 0
	v_mov_b32_e32 v19, v196
	v_mov_b32_e32 v20, v196
	v_mov_b32_e32 v21, v196
	v_mov_b32_e32 v22, v196
	v_mov_b32_e32 v23, v196
	v_mov_b32_e32 v24, v196
	v_mov_b32_e32 v25, v196
	v_mov_b32_e32 v26, v196
	v_mov_b32_e32 v27, v196
	v_mov_b32_e32 v28, v196
	v_mov_b32_e32 v29, v196
	v_mov_b32_e32 v30, v196
	v_mov_b32_e32 v31, v196
	v_mov_b32_e32 v32, v196
	v_mov_b32_e32 v33, v196
	v_mov_b32_e32 v34, 0
	v_mov_b32_e32 v35, v196
	v_mov_b32_e32 v36, v196
	v_mov_b32_e32 v37, v196
	v_mov_b32_e32 v38, v196
	v_mov_b32_e32 v39, v196
	v_mov_b32_e32 v40, v196
	v_mov_b32_e32 v41, v196
	v_mov_b32_e32 v42, v196
	v_mov_b32_e32 v43, v196
	v_mov_b32_e32 v44, v196
	v_mov_b32_e32 v45, v196
	v_mov_b32_e32 v46, v196
	v_mov_b32_e32 v47, v196
	v_mov_b32_e32 v48, v196
	v_mov_b32_e32 v49, v196
	v_mov_b32_e32 v50, 0
	v_mov_b32_e32 v51, v196
	v_mov_b32_e32 v52, v196
	v_mov_b32_e32 v53, v196
	v_mov_b32_e32 v54, v196
	v_mov_b32_e32 v55, v196
	v_mov_b32_e32 v56, v196
	v_mov_b32_e32 v57, v196
	v_mov_b32_e32 v58, v196
	v_mov_b32_e32 v59, v196
	v_mov_b32_e32 v60, v196
	v_mov_b32_e32 v61, v196
	v_mov_b32_e32 v62, v196
	v_mov_b32_e32 v63, v196
	v_mov_b32_e32 v64, v196
	v_mov_b32_e32 v65, v196
.LBB0_1849:
	v_lshl_add_u64 v[186:187], s[0:1], 0, v[180:181]
	s_add_i32 s55, s37, 0x8000
	v_lshl_add_u64 v[86:87], v[186:187], 0, s[8:9]
	s_mov_b32 m0, s55
	v_lshl_add_u64 v[188:189], s[0:1], 0, v[176:177]
	s_add_i32 s54, s42, s56
	global_load_lds_dwordx4 v[86:87], off
	v_lshl_add_u64 v[86:87], v[188:189], 0, s[10:11]
	s_mov_b32 m0, s54
	s_nop 0
	global_load_lds_dwordx4 v[86:87], off
	ds_read_b128 v[102:105], v209 offset:49152
	ds_read_b128 v[106:109], v210 offset:49152
	ds_read_b128 v[130:133], v211 offset:49152
	ds_read_b128 v[134:137], v212 offset:49152
	v_add_u32_e32 v224, v222, v215
	v_add_u32_e32 v225, v222, v217
	s_waitcnt lgkmcnt(0)
	v_mfma_f32_32x32x64_f8f6f4 v[86:101], v[102:109], v[146:153], 0
	ds_read_b128 v[102:105], v213 offset:49152
	ds_read_b128 v[106:109], v214 offset:49152
	v_exp_f32_e32 v66, v66
	v_exp_f32_e32 v67, v67
	v_exp_f32_e32 v68, v68
	v_mfma_f32_32x32x64_f8f6f4 v[114:129], v[130:137], v[146:153], 0
	ds_read_b128 v[232:235], v207 offset:49152
	ds_read_b128 v[236:239], v208 offset:49152
	v_exp_f32_e32 v69, v69
	v_exp_f32_e32 v70, v70
	v_exp_f32_e32 v71, v71
	s_waitcnt lgkmcnt(0)
	v_mfma_f32_32x32x64_f8f6f4 v[86:101], v[102:109], v[154:161], v[86:101]
	ds_read_b128 v[102:105], v224
	ds_read_b128 v[106:109], v225
	v_exp_f32_e32 v72, v72
	v_exp_f32_e32 v73, v73
	v_exp_f32_e32 v74, v74
	v_add_u32_e32 v226, v223, v215
	v_mfma_f32_32x32x64_f8f6f4 v[114:129], v[232:239], v[154:161], v[114:129]
	v_add_u32_e32 v227, v223, v217
	ds_read_b128 v[232:235], v226
	ds_read_b128 v[236:239], v227
	v_exp_f32_e32 v75, v75
	v_exp_f32_e32 v76, v76
	v_exp_f32_e32 v77, v77
	s_waitcnt lgkmcnt(0)
	v_mfma_f32_32x32x64_f8f6f4 v[86:101], v[102:109], v[162:169], v[86:101]
	v_mov_b32_e32 v130, 0
	v_exp_f32_e32 v78, v78
	v_exp_f32_e32 v79, v79
	v_mfma_f32_32x32x64_f8f6f4 v[114:129], v[232:239], v[162:169], v[114:129]
	ds_read_b64_tr_b8 v[102:103], v206 offset:0
	ds_read_b64_tr_b8 v[104:105], v206 offset:0x800
	ds_read_b64_tr_b8 v[106:107], v206 offset:0x1000
	v_mov_b32_e32 v134, 0
	v_mov_b32_e32 v131, 0
	v_mov_b32_e32 v135, 0
	v_mov_b32_e32 v132, 0
	v_mov_b32_e32 v136, 0
	v_mov_b32_e32 v133, 0
	v_mov_b32_e32 v137, 0
	ds_read_b64_tr_b8 v[108:109], v206 offset:0x1800
	v_cvt_pk_fp8_f32 v130, v82, v83
	v_cvt_pk_fp8_f32 v131, v184, v185
	v_cvt_pk_fp8_f32 v132, v144, v145
	v_cvt_pk_fp8_f32 v134, v66, v67
	v_cvt_pk_fp8_f32 v135, v70, v71
	v_exp_f32_e32 v80, v80
	v_exp_f32_e32 v81, v81
	v_cvt_pk_fp8_f32 v136, v74, v75
	v_cvt_pk_fp8_f32 v133, v142, v143
	v_cvt_pk_fp8_f32 v137, v78, v79
	ds_read_b64_tr_b8 v[232:233], v205 offset:0
	ds_read_b64_tr_b8 v[234:235], v205 offset:0x800
	ds_read_b64_tr_b8 v[236:237], v205 offset:0x1000
	ds_read_b64_tr_b8 v[238:239], v205 offset:0x1800
	v_cvt_pk_fp8_f32 v130, v84, v85 op_sel:[0,0,1]
	v_cvt_pk_fp8_f32 v131, v182, v183 op_sel:[0,0,1]
	v_cvt_pk_fp8_f32 v134, v68, v69 op_sel:[0,0,1]
	v_cvt_pk_fp8_f32 v135, v72, v73 op_sel:[0,0,1]
	v_cvt_pk_fp8_f32 v132, v138, v139 op_sel:[0,0,1]
	v_cvt_pk_fp8_f32 v136, v76, v77 op_sel:[0,0,1]
	v_cvt_pk_fp8_f32 v133, v140, v141 op_sel:[0,0,1]
	v_cvt_pk_fp8_f32 v137, v80, v81 op_sel:[0,0,1]
	s_waitcnt lgkmcnt(4)
	s_mov_b32 m0, s37
	v_mfma_f32_32x32x64_f8f6f4 v[2:17], v[130:137], v[102:109], v[2:17]
	ds_read_b64_tr_b8 v[240:241], v203 offset:0
	ds_read_b64_tr_b8 v[242:243], v203 offset:0x800
	ds_read_b64_tr_b8 v[244:245], v203 offset:0x1000
	ds_read_b64_tr_b8 v[246:247], v203 offset:0x1800
	s_waitcnt lgkmcnt(4)
	s_nop 0
	v_max_f32_e32 v102, v87, v87
	v_max_f32_e32 v103, v86, v86
	v_max_f32_e32 v102, v103, v102
	v_max3_f32 v102, v102, v88, v89
	v_max3_f32 v102, v102, v90, v91
	v_max3_f32 v102, v102, v92, v93
	v_max3_f32 v102, v102, v94, v95
	v_max3_f32 v102, v102, v96, v97
	v_max3_f32 v102, v102, v98, v99
	v_max3_f32 v102, v102, v100, v101
	v_max3_f32 v102, v102, v114, v115
	v_max3_f32 v102, v102, v116, v117
	v_max3_f32 v102, v102, v118, v119
	v_max3_f32 v102, v102, v120, v121
	v_max3_f32 v102, v102, v122, v123
	v_max3_f32 v102, v102, v124, v125
	v_max3_f32 v102, v102, v126, v127
	v_max3_f32 v102, v102, v128, v129
	v_mov_b32_e32 v103, v102
	s_nop 1
	v_permlane32_swap_b32_e32 v102, v103
	v_max_f32_e32 v103, v103, v103
	v_max_f32_e32 v102, v102, v102
	v_max_f32_e32 v102, v102, v103
	v_sub_f32_e32 v103, v102, v228
	v_cmp_ge_f32_e32 vcc, s46, v103
	s_cmp_eq_u64 vcc, exec
	v_max_f32_e32 v103, v228, v228
	v_max_f32_e32 v192, v103, v102
	s_cselect_b64 vcc, -1, 0
	v_cndmask_b32_e32 v231, v192, v228, vcc
	v_fma_f32 v190, v231, s47, 4.0
	v_mfma_f32_32x32x64_f8f6f4 v[18:33], v[130:137], v[232:239], v[18:33]
	v_pk_add_f32 v[82:83], v[82:83], v[84:85]
	v_pk_fma_f32 v[110:111], v[98:99], s[4:5], v[190:191] op_sel_hi:[1,0,0]
	v_pk_fma_f32 v[98:99], v[86:87], s[4:5], v[190:191] op_sel_hi:[1,0,0]
	ds_read_b64_tr_b8 v[86:87], v202 offset:0
	v_pk_fma_f32 v[112:113], v[100:101], s[4:5], v[190:191] op_sel_hi:[1,0,0]
	v_pk_fma_f32 v[100:101], v[88:89], s[4:5], v[190:191] op_sel_hi:[1,0,0]
	ds_read_b64_tr_b8 v[88:89], v202 offset:0x800
	v_pk_fma_f32 v[102:103], v[90:91], s[4:5], v[190:191] op_sel_hi:[1,0,0]
	ds_read_b64_tr_b8 v[90:91], v202 offset:0x1000
	v_pk_fma_f32 v[108:109], v[96:97], s[4:5], v[190:191] op_sel_hi:[1,0,0]
	v_pk_fma_f32 v[106:107], v[94:95], s[4:5], v[190:191] op_sel_hi:[1,0,0]
	v_pk_fma_f32 v[104:105], v[92:93], s[4:5], v[190:191] op_sel_hi:[1,0,0]
	v_pk_fma_f32 v[128:129], v[128:129], s[4:5], v[190:191] op_sel_hi:[1,0,0]
	v_pk_fma_f32 v[126:127], v[126:127], s[4:5], v[190:191] op_sel_hi:[1,0,0]
	v_pk_fma_f32 v[124:125], v[124:125], s[4:5], v[190:191] op_sel_hi:[1,0,0]
	v_pk_fma_f32 v[122:123], v[122:123], s[4:5], v[190:191] op_sel_hi:[1,0,0]
	v_pk_fma_f32 v[120:121], v[120:121], s[4:5], v[190:191] op_sel_hi:[1,0,0]
	v_pk_fma_f32 v[118:119], v[118:119], s[4:5], v[190:191] op_sel_hi:[1,0,0]
	v_pk_fma_f32 v[116:117], v[116:117], s[4:5], v[190:191] op_sel_hi:[1,0,0]
	v_pk_fma_f32 v[114:115], v[114:115], s[4:5], v[190:191] op_sel_hi:[1,0,0]
	ds_read_b64_tr_b8 v[92:93], v202 offset:0x1800
	s_waitcnt lgkmcnt(4)
	v_lshl_add_u64 v[190:191], s[0:1], 0, v[178:179]
	v_mfma_f32_32x32x64_f8f6f4 v[34:49], v[130:137], v[240:247], v[34:49]
	s_waitcnt lgkmcnt(0)
	v_pk_add_f32 v[82:83], v[184:185], v[82:83]
	v_exp_f32_e32 v98, v98
	v_exp_f32_e32 v99, v99
	v_exp_f32_e32 v100, v100
	v_exp_f32_e32 v101, v101
	v_mfma_f32_32x32x64_f8f6f4 v[50:65], v[130:137], v[86:93], v[50:65]
	s_barrier
	v_lshl_add_u64 v[86:87], v[190:191], 0, s[12:13]
	global_load_lds_dwordx4 v[86:87], off
	v_pk_add_f32 v[82:83], v[182:183], v[82:83]
	s_nop 0
	v_pk_add_f32 v[82:83], v[144:145], v[82:83]
	s_nop 0
	v_pk_add_f32 v[82:83], v[138:139], v[82:83]
	s_nop 0
	v_pk_add_f32 v[82:83], v[142:143], v[82:83]
	s_nop 0
	v_pk_add_f32 v[82:83], v[140:141], v[82:83]
	s_nop 0
	v_pk_add_f32 v[66:67], v[82:83], v[66:67]
	s_nop 0
	v_pk_add_f32 v[66:67], v[68:69], v[66:67]
	s_nop 0
	v_pk_add_f32 v[66:67], v[70:71], v[66:67]
	s_nop 0
	v_pk_add_f32 v[66:67], v[72:73], v[66:67]
	s_nop 0
	v_pk_add_f32 v[66:67], v[74:75], v[66:67]
	s_nop 0
	v_pk_add_f32 v[66:67], v[76:77], v[66:67]
	s_nop 0
	v_pk_add_f32 v[66:67], v[78:79], v[66:67]
	s_nop 0
	v_pk_add_f32 v[66:67], v[80:81], v[66:67]
	s_nop 0
	v_pk_add_f32 v[182:183], v[66:67], v[66:67] op_sel:[0,1] op_sel_hi:[1,0]
	v_sub_f32_e32 v66, v228, v192
	v_mul_f32_e32 v66, 0x3dd53b94, v66
	v_exp_f32_e32 v66, v66
	v_mov_b32_e32 v229, v182
	s_nop 1
	v_permlane32_swap_b32_e32 v182, v229
	v_cndmask_b32_e64 v183, v66, 1.0, vcc
	v_cmp_gt_f32_e32 vcc, 1.0, v183
	s_cbranch_vccz .LBB0_1853
	s_and_saveexec_b64 s[34:35], s[2:3]
	ds_write_b32 v204, v183 offset:128
	s_or_b64 exec, exec, s[34:35]
	s_waitcnt lgkmcnt(0)
	s_nop 15
	s_nop 7
	ds_read2_b32 v[66:67], v201 offset0:32 offset1:33
	ds_read2_b32 v[68:69], v201 offset0:34 offset1:35
	ds_read2_b32 v[70:71], v201 offset0:40 offset1:41
	ds_read2_b32 v[72:73], v201 offset0:42 offset1:43
	s_waitcnt lgkmcnt(0)
	v_pk_mul_f32 v[2:3], v[66:67], v[2:3]
	v_pk_mul_f32 v[18:19], v[66:67], v[18:19]
	v_pk_mul_f32 v[34:35], v[66:67], v[34:35]
	v_pk_mul_f32 v[50:51], v[66:67], v[50:51]
	v_pk_mul_f32 v[4:5], v[4:5], v[68:69]
	v_pk_mul_f32 v[20:21], v[20:21], v[68:69]
	v_pk_mul_f32 v[36:37], v[36:37], v[68:69]
	v_pk_mul_f32 v[52:53], v[52:53], v[68:69]
	v_pk_mul_f32 v[6:7], v[6:7], v[70:71]
	v_pk_mul_f32 v[22:23], v[22:23], v[70:71]
	v_pk_mul_f32 v[38:39], v[38:39], v[70:71]
	v_pk_mul_f32 v[54:55], v[54:55], v[70:71]
	v_pk_mul_f32 v[8:9], v[8:9], v[72:73]
	v_pk_mul_f32 v[24:25], v[24:25], v[72:73]
	v_pk_mul_f32 v[40:41], v[40:41], v[72:73]
	ds_read2_b32 v[66:67], v201 offset0:48 offset1:49
	v_pk_mul_f32 v[56:57], v[56:57], v[72:73]
	ds_read2_b32 v[68:69], v201 offset0:50 offset1:51
	ds_read2_b32 v[70:71], v201 offset0:56 offset1:57
	ds_read2_b32 v[72:73], v201 offset0:58 offset1:59
	s_waitcnt lgkmcnt(0)
	v_pk_mul_f32 v[10:11], v[10:11], v[66:67]
	v_pk_mul_f32 v[26:27], v[26:27], v[66:67]
	v_pk_mul_f32 v[42:43], v[42:43], v[66:67]
	v_pk_mul_f32 v[58:59], v[58:59], v[66:67]
	v_pk_mul_f32 v[12:13], v[12:13], v[68:69]
	v_pk_mul_f32 v[28:29], v[28:29], v[68:69]
	v_pk_mul_f32 v[44:45], v[44:45], v[68:69]
	v_pk_mul_f32 v[60:61], v[60:61], v[68:69]
	v_pk_mul_f32 v[14:15], v[14:15], v[70:71]
	v_pk_mul_f32 v[30:31], v[30:31], v[70:71]
	v_pk_mul_f32 v[46:47], v[46:47], v[70:71]
	v_pk_mul_f32 v[62:63], v[62:63], v[70:71]
	v_pk_mul_f32 v[16:17], v[16:17], v[72:73]
	v_pk_mul_f32 v[32:33], v[32:33], v[72:73]
	v_pk_mul_f32 v[48:49], v[48:49], v[72:73]
	v_pk_mul_f32 v[64:65], v[64:65], v[72:73]
.LBB0_1853:
	s_waitcnt vmcnt(1)
	s_add_i32 s60, s37, 0xc000
	s_barrier
	v_lshl_add_u64 v[66:67], v[186:187], 0, s[14:15]
	s_mov_b32 m0, s60
	s_add_i32 s59, s43, s56
	global_load_lds_dwordx4 v[66:67], off
	v_lshl_add_u64 v[66:67], v[188:189], 0, s[16:17]
	s_mov_b32 m0, s59
	v_exp_f32_e32 v184, v102
	global_load_lds_dwordx4 v[66:67], off
	v_exp_f32_e32 v185, v103
	v_exp_f32_e32 v186, v104
	v_exp_f32_e32 v187, v105
	v_exp_f32_e32 v188, v106
	v_exp_f32_e32 v189, v107
	v_exp_f32_e32 v192, v108
	v_exp_f32_e32 v193, v109
	v_exp_f32_e32 v110, v110
	v_exp_f32_e32 v111, v111
	v_exp_f32_e32 v112, v112
	v_exp_f32_e32 v113, v113
	ds_read_b128 v[82:85], v209 offset:32768
	ds_read_b128 v[86:89], v210 offset:32768
	ds_read_b128 v[90:93], v211 offset:32768
	ds_read_b128 v[94:97], v212 offset:32768
	v_mov_b32_e32 v102, 0
	v_mov_b32_e32 v103, 0
	s_waitcnt lgkmcnt(0)
	v_mfma_f32_32x32x64_f8f6f4 v[66:81], v[82:89], v[146:153], 0
	ds_read_b128 v[82:85], v213 offset:32768
	ds_read_b128 v[86:89], v214 offset:32768
	v_exp_f32_e32 v114, v114
	v_exp_f32_e32 v115, v115
	v_exp_f32_e32 v116, v116
	v_mfma_f32_32x32x64_f8f6f4 v[130:145], v[90:97], v[146:153], 0
	ds_read_b128 v[90:93], v207 offset:32768
	ds_read_b128 v[94:97], v208 offset:32768
	v_exp_f32_e32 v117, v117
	v_exp_f32_e32 v118, v118
	v_exp_f32_e32 v119, v119
	s_waitcnt lgkmcnt(0)
	v_mfma_f32_32x32x64_f8f6f4 v[66:81], v[82:89], v[154:161], v[66:81]
	ds_read_b128 v[82:85], v216
	ds_read_b128 v[86:89], v218
	v_exp_f32_e32 v120, v120
	v_exp_f32_e32 v121, v121
	v_exp_f32_e32 v122, v122
	v_mfma_f32_32x32x64_f8f6f4 v[130:145], v[90:97], v[154:161], v[130:145]
	ds_read_b128 v[90:93], v219
	ds_read_b128 v[94:97], v220
	v_exp_f32_e32 v123, v123
	v_exp_f32_e32 v124, v124
	v_exp_f32_e32 v125, v125
	s_waitcnt lgkmcnt(0)
	v_mfma_f32_32x32x64_f8f6f4 v[66:81], v[82:89], v[162:169], v[66:81]
	v_mov_b32_e32 v106, 0
	v_exp_f32_e32 v126, v126
	v_exp_f32_e32 v127, v127
	v_mfma_f32_32x32x64_f8f6f4 v[130:145], v[90:97], v[162:169], v[130:145]
	ds_read_b64_tr_b8 v[82:83], v200 offset:0
	ds_read_b64_tr_b8 v[84:85], v200 offset:0x800
	ds_read_b64_tr_b8 v[86:87], v200 offset:0x1000
	v_mov_b32_e32 v107, 0
	v_mov_b32_e32 v104, 0
	v_mov_b32_e32 v108, 0
	v_mov_b32_e32 v105, 0
	v_mov_b32_e32 v109, 0
	ds_read_b64_tr_b8 v[88:89], v200 offset:0x1800
	v_cvt_pk_fp8_f32 v102, v98, v99
	v_cvt_pk_fp8_f32 v103, v184, v185
	v_cvt_pk_fp8_f32 v104, v188, v189
	v_cvt_pk_fp8_f32 v105, v110, v111
	v_exp_f32_e32 v128, v128
	v_cvt_pk_fp8_f32 v106, v114, v115
	v_cvt_pk_fp8_f32 v107, v118, v119
	v_exp_f32_e32 v129, v129
	v_cvt_pk_fp8_f32 v108, v122, v123
	v_cvt_pk_fp8_f32 v109, v126, v127
	ds_read_b64_tr_b8 v[90:91], v199 offset:0
	ds_read_b64_tr_b8 v[92:93], v199 offset:0x800
	ds_read_b64_tr_b8 v[94:95], v199 offset:0x1000
	ds_read_b64_tr_b8 v[96:97], v199 offset:0x1800
	v_cvt_pk_fp8_f32 v102, v100, v101 op_sel:[0,0,1]
	v_cvt_pk_fp8_f32 v103, v186, v187 op_sel:[0,0,1]
	v_cvt_pk_fp8_f32 v106, v116, v117 op_sel:[0,0,1]
	v_cvt_pk_fp8_f32 v107, v120, v121 op_sel:[0,0,1]
	v_cvt_pk_fp8_f32 v104, v192, v193 op_sel:[0,0,1]
	v_cvt_pk_fp8_f32 v108, v124, v125 op_sel:[0,0,1]
	v_cvt_pk_fp8_f32 v105, v112, v113 op_sel:[0,0,1]
	v_cvt_pk_fp8_f32 v109, v128, v129 op_sel:[0,0,1]
	s_waitcnt lgkmcnt(4)
	s_mov_b32 m0, s57
	v_mfma_f32_32x32x64_f8f6f4 v[2:17], v[102:109], v[82:89], v[2:17]
	ds_read_b64_tr_b8 v[232:233], v198 offset:0
	ds_read_b64_tr_b8 v[234:235], v198 offset:0x800
	ds_read_b64_tr_b8 v[236:237], v198 offset:0x1000
	ds_read_b64_tr_b8 v[238:239], v198 offset:0x1800
	s_waitcnt lgkmcnt(4)
	s_nop 0
	v_max_f32_e32 v82, v67, v67
	v_max_f32_e32 v83, v66, v66
	v_max_f32_e32 v82, v83, v82
	v_max3_f32 v82, v82, v68, v69
	v_max3_f32 v82, v82, v70, v71
	v_max3_f32 v82, v82, v72, v73
	v_max3_f32 v82, v82, v74, v75
	v_max3_f32 v82, v82, v76, v77
	v_max3_f32 v82, v82, v78, v79
	v_max3_f32 v82, v82, v80, v81
	v_max3_f32 v82, v82, v130, v131
	v_max3_f32 v82, v82, v132, v133
	v_max3_f32 v82, v82, v134, v135
	v_max3_f32 v82, v82, v136, v137
	v_max3_f32 v82, v82, v138, v139
	v_max3_f32 v82, v82, v140, v141
	v_max3_f32 v82, v82, v142, v143
	v_max3_f32 v82, v82, v144, v145
	v_mov_b32_e32 v83, v82
	s_nop 1
	v_permlane32_swap_b32_e32 v82, v83
	v_max_f32_e32 v83, v83, v83
	v_max_f32_e32 v82, v82, v82
	v_max_f32_e32 v82, v82, v83
	v_sub_f32_e32 v83, v82, v231
	v_cmp_ge_f32_e32 vcc, s46, v83
	s_cmp_eq_u64 vcc, exec
	v_max_f32_e32 v83, v231, v231
	v_max_f32_e32 v241, v83, v82
	s_cselect_b64 vcc, -1, 0
	v_cndmask_b32_e32 v228, v241, v231, vcc
	v_fma_f32 v240, v228, s47, 4.0
	v_mfma_f32_32x32x64_f8f6f4 v[18:33], v[102:109], v[90:97], v[18:33]
	v_pk_add_f32 v[98:99], v[98:99], v[100:101]
	v_pk_fma_f32 v[82:83], v[66:67], s[4:5], v[240:241] op_sel_hi:[1,0,0]
	v_pk_fma_f32 v[66:67], v[130:131], s[4:5], v[240:241] op_sel_hi:[1,0,0]
	ds_read_b64_tr_b8 v[130:131], v197 offset:0
	v_pk_fma_f32 v[84:85], v[68:69], s[4:5], v[240:241] op_sel_hi:[1,0,0]
	v_pk_fma_f32 v[68:69], v[132:133], s[4:5], v[240:241] op_sel_hi:[1,0,0]
	ds_read_b64_tr_b8 v[132:133], v197 offset:0x800
	v_pk_fma_f32 v[86:87], v[70:71], s[4:5], v[240:241] op_sel_hi:[1,0,0]
	v_pk_fma_f32 v[70:71], v[134:135], s[4:5], v[240:241] op_sel_hi:[1,0,0]
	ds_read_b64_tr_b8 v[134:135], v197 offset:0x1000
	v_pk_fma_f32 v[96:97], v[80:81], s[4:5], v[240:241] op_sel_hi:[1,0,0]
	v_pk_fma_f32 v[94:95], v[78:79], s[4:5], v[240:241] op_sel_hi:[1,0,0]
	v_pk_fma_f32 v[92:93], v[76:77], s[4:5], v[240:241] op_sel_hi:[1,0,0]
	v_pk_fma_f32 v[90:91], v[74:75], s[4:5], v[240:241] op_sel_hi:[1,0,0]
	v_pk_fma_f32 v[88:89], v[72:73], s[4:5], v[240:241] op_sel_hi:[1,0,0]
	v_pk_fma_f32 v[80:81], v[144:145], s[4:5], v[240:241] op_sel_hi:[1,0,0]
	v_pk_fma_f32 v[78:79], v[142:143], s[4:5], v[240:241] op_sel_hi:[1,0,0]
	v_pk_fma_f32 v[76:77], v[140:141], s[4:5], v[240:241] op_sel_hi:[1,0,0]
	v_pk_fma_f32 v[74:75], v[138:139], s[4:5], v[240:241] op_sel_hi:[1,0,0]
	v_pk_fma_f32 v[72:73], v[136:137], s[4:5], v[240:241] op_sel_hi:[1,0,0]
	ds_read_b64_tr_b8 v[136:137], v197 offset:0x1800
	s_waitcnt lgkmcnt(4)
	v_pk_add_f32 v[98:99], v[98:99], v[184:185]
	v_mfma_f32_32x32x64_f8f6f4 v[34:49], v[102:109], v[232:239], v[34:49]
	s_waitcnt lgkmcnt(0)
	s_nop 0
	v_exp_f32_e32 v82, v82
	v_exp_f32_e32 v83, v83
	v_exp_f32_e32 v84, v84
	v_exp_f32_e32 v85, v85
	v_mfma_f32_32x32x64_f8f6f4 v[50:65], v[102:109], v[130:137], v[50:65]
	s_barrier
	v_lshl_add_u64 v[102:103], v[190:191], 0, s[18:19]
	global_load_lds_dwordx4 v[102:103], off
	v_pk_add_f32 v[98:99], v[186:187], v[98:99]
	s_nop 0
	v_pk_add_f32 v[98:99], v[188:189], v[98:99]
	s_nop 0
	v_pk_add_f32 v[98:99], v[192:193], v[98:99]
	s_nop 0
	v_pk_add_f32 v[98:99], v[110:111], v[98:99]
	s_nop 0
	v_pk_add_f32 v[98:99], v[112:113], v[98:99]
	s_nop 0
	v_pk_add_f32 v[98:99], v[98:99], v[114:115]
	s_nop 0
	v_pk_add_f32 v[98:99], v[116:117], v[98:99]
	s_nop 0
	v_pk_add_f32 v[98:99], v[118:119], v[98:99]
	s_nop 0
	v_pk_add_f32 v[98:99], v[120:121], v[98:99]
	s_nop 0
	v_pk_add_f32 v[98:99], v[122:123], v[98:99]
	s_nop 0
	v_pk_add_f32 v[98:99], v[124:125], v[98:99]
	s_nop 0
	v_pk_add_f32 v[98:99], v[126:127], v[98:99]
	s_nop 0
	v_pk_add_f32 v[98:99], v[128:129], v[98:99]
	s_nop 0
	v_pk_add_f32 v[98:99], v[98:99], v[98:99] op_sel:[0,1] op_sel_hi:[1,0]
	s_nop 0
	v_sub_f32_e32 v99, v231, v241
	v_mul_f32_e32 v99, 0x3dd53b94, v99
	v_exp_f32_e32 v100, v99
	v_mov_b32_e32 v99, v98
	s_nop 1
	v_permlane32_swap_b32_e32 v98, v99
	v_cndmask_b32_e64 v128, v100, 1.0, vcc
	v_cmp_gt_f32_e32 vcc, 1.0, v128
	s_cbranch_vccz .LBB0_1857
	s_and_saveexec_b64 s[34:35], s[2:3]
	ds_write_b32 v204, v128 offset:128
	s_or_b64 exec, exec, s[34:35]
	s_waitcnt lgkmcnt(0)
	s_nop 15
	s_nop 7
	ds_read2_b32 v[100:101], v201 offset0:32 offset1:33
	ds_read2_b32 v[102:103], v201 offset0:34 offset1:35
	ds_read2_b32 v[104:105], v201 offset0:40 offset1:41
	ds_read2_b32 v[106:107], v201 offset0:42 offset1:43
	s_waitcnt lgkmcnt(0)
	v_pk_mul_f32 v[2:3], v[100:101], v[2:3]
	v_pk_mul_f32 v[18:19], v[100:101], v[18:19]
	v_pk_mul_f32 v[34:35], v[100:101], v[34:35]
	v_pk_mul_f32 v[50:51], v[100:101], v[50:51]
	v_pk_mul_f32 v[4:5], v[4:5], v[102:103]
	v_pk_mul_f32 v[20:21], v[20:21], v[102:103]
	v_pk_mul_f32 v[36:37], v[36:37], v[102:103]
	v_pk_mul_f32 v[52:53], v[52:53], v[102:103]
	v_pk_mul_f32 v[6:7], v[6:7], v[104:105]
	v_pk_mul_f32 v[22:23], v[22:23], v[104:105]
	v_pk_mul_f32 v[38:39], v[38:39], v[104:105]
	v_pk_mul_f32 v[54:55], v[54:55], v[104:105]
	v_pk_mul_f32 v[8:9], v[8:9], v[106:107]
	v_pk_mul_f32 v[24:25], v[24:25], v[106:107]
	v_pk_mul_f32 v[40:41], v[40:41], v[106:107]
	ds_read2_b32 v[100:101], v201 offset0:48 offset1:49
	v_pk_mul_f32 v[56:57], v[56:57], v[106:107]
	ds_read2_b32 v[102:103], v201 offset0:50 offset1:51
	ds_read2_b32 v[104:105], v201 offset0:56 offset1:57
	ds_read2_b32 v[106:107], v201 offset0:58 offset1:59
	s_waitcnt lgkmcnt(0)
	v_pk_mul_f32 v[10:11], v[10:11], v[100:101]
	v_pk_mul_f32 v[26:27], v[26:27], v[100:101]
	v_pk_mul_f32 v[42:43], v[42:43], v[100:101]
	v_pk_mul_f32 v[58:59], v[58:59], v[100:101]
	v_pk_mul_f32 v[12:13], v[12:13], v[102:103]
	v_pk_mul_f32 v[28:29], v[28:29], v[102:103]
	v_pk_mul_f32 v[44:45], v[44:45], v[102:103]
	v_pk_mul_f32 v[60:61], v[60:61], v[102:103]
	v_pk_mul_f32 v[14:15], v[14:15], v[104:105]
	v_pk_mul_f32 v[30:31], v[30:31], v[104:105]
	v_pk_mul_f32 v[46:47], v[46:47], v[104:105]
	v_pk_mul_f32 v[62:63], v[62:63], v[104:105]
	v_pk_mul_f32 v[16:17], v[16:17], v[106:107]
	v_pk_mul_f32 v[32:33], v[32:33], v[106:107]
	v_pk_mul_f32 v[48:49], v[48:49], v[106:107]
	v_pk_mul_f32 v[64:65], v[64:65], v[106:107]

.LBB0_1859:
	ds_read_b128 v[102:105], v209 offset:49152
	ds_read_b128 v[106:109], v210 offset:49152
	ds_read_b128 v[120:123], v211 offset:49152
	ds_read_b128 v[124:127], v212 offset:49152
	v_mov_b32_e32 v118, v171
	v_cvt_pk_fp8_f32 v118, v82, v83
	s_waitcnt lgkmcnt(0)
	v_mfma_f32_32x32x64_f8f6f4 v[86:101], v[102:109], v[146:153], 0
	ds_read_b128 v[130:133], v213 offset:49152
	ds_read_b128 v[134:137], v214 offset:49152
	v_exp_f32_e32 v66, v66
	v_exp_f32_e32 v67, v67
	v_exp_f32_e32 v68, v68
	v_pk_add_f32 v[102:103], v[82:83], v[84:85]
	v_mov_b32_e32 v119, v171
	v_pk_add_f32 v[176:177], v[102:103], v[184:185]
	v_mfma_f32_32x32x64_f8f6f4 v[102:117], v[120:127], v[146:153], 0
	ds_read_b128 v[120:123], v207 offset:49152
	ds_read_b128 v[124:127], v208 offset:49152
	v_exp_f32_e32 v69, v69
	v_exp_f32_e32 v70, v70
	v_exp_f32_e32 v71, v71
	s_waitcnt lgkmcnt(0)
	v_mfma_f32_32x32x64_f8f6f4 v[86:101], v[130:137], v[154:161], v[86:101]
	ds_read_b128 v[130:133], v224
	ds_read_b128 v[134:137], v225
	v_exp_f32_e32 v72, v72
	v_exp_f32_e32 v73, v73
	v_exp_f32_e32 v74, v74
	v_mfma_f32_32x32x64_f8f6f4 v[102:117], v[120:127], v[154:161], v[102:117]
	v_pk_add_f32 v[82:83], v[176:177], v[182:183]
	ds_read_b128 v[146:149], v226
	ds_read_b128 v[150:153], v227
	v_pk_add_f32 v[82:83], v[82:83], v[144:145]
	v_exp_f32_e32 v75, v75
	v_exp_f32_e32 v76, v76
	v_exp_f32_e32 v77, v77
	v_pk_add_f32 v[82:83], v[82:83], v[138:139]
	s_waitcnt lgkmcnt(0)
	v_mfma_f32_32x32x64_f8f6f4 v[86:101], v[130:137], v[162:169], v[86:101]
	v_mov_b32_e32 v122, v171
	v_pk_add_f32 v[82:83], v[82:83], v[142:143]
	v_exp_f32_e32 v78, v78
	v_exp_f32_e32 v79, v79
	v_pk_add_f32 v[82:83], v[82:83], v[140:141]
	v_mfma_f32_32x32x64_f8f6f4 v[102:117], v[146:153], v[162:169], v[102:117]
	v_mov_b32_e32 v123, v171
	v_pk_add_f32 v[82:83], v[82:83], v[66:67]
	v_cvt_pk_fp8_f32 v122, v66, v67
	v_pk_add_f32 v[66:67], v[68:69], v[82:83]
	v_exp_f32_e32 v80, v80
	v_pk_add_f32 v[66:67], v[70:71], v[66:67]
	v_exp_f32_e32 v81, v81
	v_pk_add_f32 v[66:67], v[72:73], v[66:67]
	v_cvt_pk_fp8_f32 v123, v70, v71
	v_pk_add_f32 v[66:67], v[74:75], v[66:67]
	v_mov_b32_e32 v124, v171
	v_pk_add_f32 v[66:67], v[76:77], v[66:67]
	v_cvt_pk_fp8_f32 v122, v68, v69 op_sel:[0,0,1]
	v_pk_add_f32 v[66:67], v[78:79], v[66:67]
	v_cvt_pk_fp8_f32 v124, v74, v75
	v_pk_add_f32 v[66:67], v[80:81], v[66:67]
	v_mov_b32_e32 v125, v171
	v_pk_add_f32 v[126:127], v[66:67], v[66:67] op_sel:[0,1] op_sel_hi:[1,0]
	ds_read_b64_tr_b8 v[66:67], v206 offset:0
	ds_read_b64_tr_b8 v[68:69], v206 offset:0x800
	ds_read_b64_tr_b8 v[70:71], v206 offset:0x1000
	v_cvt_pk_fp8_f32 v123, v72, v73 op_sel:[0,0,1]
	v_mov_b32_e32 v120, v171
	v_mov_b32_e32 v121, v171
	v_cvt_pk_fp8_f32 v125, v78, v79
	ds_read_b64_tr_b8 v[72:73], v206 offset:0x1800
	v_cvt_pk_fp8_f32 v119, v184, v185
	v_cvt_pk_fp8_f32 v120, v144, v145
	v_cvt_pk_fp8_f32 v121, v142, v143
	ds_read_b64_tr_b8 v[74:75], v205 offset:0
	v_cvt_pk_fp8_f32 v124, v76, v77 op_sel:[0,0,1]
	ds_read_b64_tr_b8 v[76:77], v205 offset:0x800
	ds_read_b64_tr_b8 v[78:79], v205 offset:0x1000
	v_cvt_pk_fp8_f32 v125, v80, v81 op_sel:[0,0,1]
	ds_read_b64_tr_b8 v[80:81], v205 offset:0x1800
	v_cvt_pk_fp8_f32 v118, v84, v85 op_sel:[0,0,1]
	v_cvt_pk_fp8_f32 v119, v182, v183 op_sel:[0,0,1]
	v_cvt_pk_fp8_f32 v120, v138, v139 op_sel:[0,0,1]
	v_cvt_pk_fp8_f32 v121, v140, v141 op_sel:[0,0,1]
	s_waitcnt lgkmcnt(4)
	v_mov_b32_e32 v127, v126
	v_mfma_f32_32x32x64_f8f6f4 v[2:17], v[118:125], v[66:73], v[2:17]
	ds_read_b64_tr_b8 v[130:131], v203 offset:0
	ds_read_b64_tr_b8 v[132:133], v203 offset:0x800
	ds_read_b64_tr_b8 v[134:135], v203 offset:0x1000
	ds_read_b64_tr_b8 v[136:137], v203 offset:0x1800
	s_waitcnt lgkmcnt(4)
	s_nop 0
	v_max_f32_e32 v66, v87, v87
	v_max_f32_e32 v67, v86, v86
	v_max_f32_e32 v66, v67, v66
	v_max3_f32 v66, v66, v88, v89
	v_max3_f32 v66, v66, v90, v91
	v_max3_f32 v66, v66, v92, v93
	v_max3_f32 v66, v66, v94, v95
	v_max3_f32 v66, v66, v96, v97
	v_max3_f32 v66, v66, v98, v99
	v_max3_f32 v66, v66, v100, v101
	v_max3_f32 v66, v66, v102, v103
	v_max3_f32 v66, v66, v104, v105
	v_max3_f32 v66, v66, v106, v107
	v_max3_f32 v66, v66, v108, v109
	v_max3_f32 v66, v66, v110, v111
	v_max3_f32 v66, v66, v112, v113
	v_max3_f32 v66, v66, v114, v115
	v_max3_f32 v66, v66, v116, v117
	v_mov_b32_e32 v67, v66
	s_nop 1
	v_permlane32_swap_b32_e32 v66, v67
	v_max_f32_e32 v67, v67, v67
	v_max_f32_e32 v66, v66, v66
	v_max_f32_e32 v66, v66, v67
	v_sub_f32_e32 v67, v66, v228
	v_cmp_ge_f32_e32 vcc, s46, v67
	s_cmp_eq_u64 vcc, exec
	v_max_f32_e32 v67, v228, v228
	v_max_f32_e32 v66, v67, v66
	s_cselect_b64 vcc, -1, 0
	v_sub_f32_e32 v67, v228, v66
	v_cndmask_b32_e32 v66, v66, v228, vcc
	v_mul_f32_e32 v83, 0x3dd53b94, v67
	v_fma_f32 v82, v66, s47, 4.0
	v_mfma_f32_32x32x64_f8f6f4 v[18:33], v[118:125], v[74:81], v[18:33]
	v_permlane32_swap_b32_e32 v126, v127
	v_pk_fma_f32 v[80:81], v[100:101], s[4:5], v[82:83] op_sel_hi:[1,0,0]
	ds_read_b64_tr_b8 v[100:101], v202 offset:0
	v_pk_fma_f32 v[78:79], v[98:99], s[4:5], v[82:83] op_sel_hi:[1,0,0]
	v_pk_fma_f32 v[76:77], v[96:97], s[4:5], v[82:83] op_sel_hi:[1,0,0]
	v_pk_fma_f32 v[74:75], v[94:95], s[4:5], v[82:83] op_sel_hi:[1,0,0]
	v_pk_fma_f32 v[72:73], v[92:93], s[4:5], v[82:83] op_sel_hi:[1,0,0]
	v_pk_fma_f32 v[70:71], v[90:91], s[4:5], v[82:83] op_sel_hi:[1,0,0]
	v_pk_fma_f32 v[68:69], v[88:89], s[4:5], v[82:83] op_sel_hi:[1,0,0]
	v_pk_fma_f32 v[66:67], v[86:87], s[4:5], v[82:83] op_sel_hi:[1,0,0]
	v_exp_f32_e32 v98, v83
	v_pk_fma_f32 v[96:97], v[116:117], s[4:5], v[82:83] op_sel_hi:[1,0,0]
	v_pk_fma_f32 v[94:95], v[114:115], s[4:5], v[82:83] op_sel_hi:[1,0,0]
	v_pk_fma_f32 v[92:93], v[112:113], s[4:5], v[82:83] op_sel_hi:[1,0,0]
	v_pk_fma_f32 v[90:91], v[110:111], s[4:5], v[82:83] op_sel_hi:[1,0,0]
	v_pk_fma_f32 v[88:89], v[108:109], s[4:5], v[82:83] op_sel_hi:[1,0,0]
	v_pk_fma_f32 v[86:87], v[106:107], s[4:5], v[82:83] op_sel_hi:[1,0,0]
	v_pk_fma_f32 v[84:85], v[104:105], s[4:5], v[82:83] op_sel_hi:[1,0,0]
	v_pk_fma_f32 v[82:83], v[102:103], s[4:5], v[82:83] op_sel_hi:[1,0,0]
	ds_read_b64_tr_b8 v[102:103], v202 offset:0x800
	ds_read_b64_tr_b8 v[104:105], v202 offset:0x1000
	ds_read_b64_tr_b8 v[106:107], v202 offset:0x1800
	s_waitcnt lgkmcnt(4)
	v_cndmask_b32_e64 v98, v98, 1.0, vcc
	v_mfma_f32_32x32x64_f8f6f4 v[34:49], v[118:125], v[130:137], v[34:49]
	s_waitcnt lgkmcnt(0)
	v_cmp_gt_f32_e32 vcc, 1.0, v98
	v_exp_f32_e32 v66, v66
	v_exp_f32_e32 v67, v67
	v_exp_f32_e32 v68, v68
	v_exp_f32_e32 v69, v69
	v_mfma_f32_32x32x64_f8f6f4 v[50:65], v[118:125], v[100:107], v[50:65]
	s_cbranch_vccz .LBB0_1863
	s_and_saveexec_b64 s[34:35], s[2:3]
	ds_write_b32 v204, v98 offset:128
	s_or_b64 exec, exec, s[34:35]
	s_waitcnt lgkmcnt(0)
	s_nop 15
	s_nop 7
	ds_read2_b32 v[100:101], v201 offset0:32 offset1:33
	ds_read2_b32 v[102:103], v201 offset0:34 offset1:35
	ds_read2_b32 v[104:105], v201 offset0:40 offset1:41
	ds_read2_b32 v[106:107], v201 offset0:42 offset1:43
	s_waitcnt lgkmcnt(0)
	v_pk_mul_f32 v[2:3], v[100:101], v[2:3]
	v_pk_mul_f32 v[18:19], v[100:101], v[18:19]
	v_pk_mul_f32 v[34:35], v[100:101], v[34:35]
	v_pk_mul_f32 v[50:51], v[100:101], v[50:51]
	v_pk_mul_f32 v[4:5], v[4:5], v[102:103]
	v_pk_mul_f32 v[20:21], v[20:21], v[102:103]
	v_pk_mul_f32 v[36:37], v[36:37], v[102:103]
	v_pk_mul_f32 v[52:53], v[52:53], v[102:103]
	v_pk_mul_f32 v[6:7], v[6:7], v[104:105]
	v_pk_mul_f32 v[22:23], v[22:23], v[104:105]
	v_pk_mul_f32 v[38:39], v[38:39], v[104:105]
	v_pk_mul_f32 v[54:55], v[54:55], v[104:105]
	v_pk_mul_f32 v[8:9], v[8:9], v[106:107]
	v_pk_mul_f32 v[24:25], v[24:25], v[106:107]
	v_pk_mul_f32 v[40:41], v[40:41], v[106:107]
	ds_read2_b32 v[100:101], v201 offset0:48 offset1:49
	v_pk_mul_f32 v[56:57], v[56:57], v[106:107]
	ds_read2_b32 v[102:103], v201 offset0:50 offset1:51
	ds_read2_b32 v[104:105], v201 offset0:56 offset1:57
	ds_read2_b32 v[106:107], v201 offset0:58 offset1:59
	s_waitcnt lgkmcnt(0)
	v_pk_mul_f32 v[10:11], v[10:11], v[100:101]
	v_pk_mul_f32 v[26:27], v[26:27], v[100:101]
	v_pk_mul_f32 v[42:43], v[42:43], v[100:101]
	v_pk_mul_f32 v[58:59], v[58:59], v[100:101]
	v_pk_mul_f32 v[12:13], v[12:13], v[102:103]
	v_pk_mul_f32 v[28:29], v[28:29], v[102:103]
	v_pk_mul_f32 v[44:45], v[44:45], v[102:103]
	v_pk_mul_f32 v[60:61], v[60:61], v[102:103]
	v_pk_mul_f32 v[14:15], v[14:15], v[104:105]
	v_pk_mul_f32 v[30:31], v[30:31], v[104:105]
	v_pk_mul_f32 v[46:47], v[46:47], v[104:105]
	v_pk_mul_f32 v[62:63], v[62:63], v[104:105]
	v_pk_mul_f32 v[16:17], v[16:17], v[106:107]
	v_pk_mul_f32 v[32:33], v[32:33], v[106:107]
	v_pk_mul_f32 v[48:49], v[48:49], v[106:107]
	v_pk_mul_f32 v[64:65], v[64:65], v[106:107]

.LBB0_1865:
	v_exp_f32_e32 v99, v70
	v_add_f32_e32 v70, 0, v66
	v_exp_f32_e32 v71, v71
	v_add_f32_e32 v70, v67, v70
	v_exp_f32_e32 v100, v72
	v_add_f32_e32 v70, v68, v70
	v_exp_f32_e32 v101, v73
	v_add_f32_e32 v70, v69, v70
	v_exp_f32_e32 v102, v74
	v_add_f32_e32 v70, v99, v70
	v_exp_f32_e32 v75, v75
	v_add_f32_e32 v70, v71, v70
	v_exp_f32_e32 v103, v76
	v_add_f32_e32 v70, v100, v70
	v_exp_f32_e32 v104, v77
	v_add_f32_e32 v70, v101, v70
	v_exp_f32_e32 v105, v78
	v_add_f32_e32 v70, v102, v70
	v_exp_f32_e32 v79, v79
	v_add_f32_e32 v70, v75, v70
	v_exp_f32_e32 v80, v80
	v_add_f32_e32 v70, v103, v70
	v_exp_f32_e32 v81, v81
	v_add_f32_e32 v70, v104, v70
	v_exp_f32_e32 v73, v82
	v_add_f32_e32 v70, v105, v70
	v_exp_f32_e32 v74, v83
	v_add_f32_e32 v70, v79, v70
	v_exp_f32_e32 v78, v84
	v_add_f32_e32 v70, v80, v70
	v_exp_f32_e32 v82, v85
	v_add_f32_e32 v70, v81, v70
	v_exp_f32_e32 v83, v86
	v_add_f32_e32 v70, v73, v70
	v_exp_f32_e32 v84, v87
	v_add_f32_e32 v70, v74, v70
	v_exp_f32_e32 v85, v88
	v_add_f32_e32 v70, v78, v70
	v_exp_f32_e32 v86, v89
	v_add_f32_e32 v70, v82, v70
	v_exp_f32_e32 v87, v90
	v_add_f32_e32 v70, v83, v70
	v_exp_f32_e32 v88, v91
	v_add_f32_e32 v70, v84, v70
	v_exp_f32_e32 v89, v92
	v_add_f32_e32 v70, v85, v70
	v_exp_f32_e32 v90, v93
	v_add_f32_e32 v70, v86, v70
	v_exp_f32_e32 v91, v94
	v_add_f32_e32 v70, v87, v70
	v_mov_b32_e32 v76, v171
	v_exp_f32_e32 v92, v95
	v_add_f32_e32 v70, v88, v70
	v_cvt_pk_fp8_f32 v76, v73, v74
	v_exp_f32_e32 v93, v96
	v_add_f32_e32 v70, v89, v70
	v_exp_f32_e32 v94, v97
	v_add_f32_e32 v70, v90, v70
	v_mov_b32_e32 v74, v171
	v_add_f32_e32 v70, v91, v70
	v_cvt_pk_fp8_f32 v74, v102, v75
	v_mov_b32_e32 v75, v171
	v_add_f32_e32 v70, v92, v70
	v_mov_b32_e32 v72, v171
	v_mov_b32_e32 v73, v171
	v_mov_b32_e32 v77, v171
	v_cvt_pk_fp8_f32 v76, v78, v82 op_sel:[0,0,1]
	v_mov_b32_e32 v78, v171
	v_cvt_pk_fp8_f32 v75, v105, v79
	v_mov_b32_e32 v79, v171
	v_add_f32_e32 v70, v93, v70
	v_cvt_pk_fp8_f32 v72, v66, v67
	v_cvt_pk_fp8_f32 v73, v99, v71
	v_cvt_pk_fp8_f32 v77, v83, v84
	v_cvt_pk_fp8_f32 v78, v87, v88
	v_cvt_pk_fp8_f32 v79, v91, v92
	v_add_f32_e32 v70, v94, v70
	v_mov_b32_e32 v66, v70
	s_nop 1
	v_permlane32_swap_b32_e32 v70, v66
	v_cvt_pk_fp8_f32 v72, v68, v69 op_sel:[0,0,1]
	v_cvt_pk_fp8_f32 v73, v100, v101 op_sel:[0,0,1]
	v_cvt_pk_fp8_f32 v77, v85, v86 op_sel:[0,0,1]
	v_cvt_pk_fp8_f32 v74, v103, v104 op_sel:[0,0,1]
	v_cvt_pk_fp8_f32 v78, v89, v90 op_sel:[0,0,1]
	v_cvt_pk_fp8_f32 v75, v80, v81 op_sel:[0,0,1]
	v_cvt_pk_fp8_f32 v79, v93, v94 op_sel:[0,0,1]
	ds_read_b64_tr_b8 v[80:81], v200 offset:0
	ds_read_b64_tr_b8 v[82:83], v200 offset:0x800
	ds_read_b64_tr_b8 v[84:85], v200 offset:0x1000
	ds_read_b64_tr_b8 v[86:87], v200 offset:0x1800
	s_waitcnt lgkmcnt(0)
	s_nop 0
	v_mfma_f32_32x32x64_f8f6f4 v[2:17], v[72:79], v[80:87], v[2:17]
	ds_read_b64_tr_b8 v[80:81], v199 offset:0
	ds_read_b64_tr_b8 v[82:83], v199 offset:0x800
	ds_read_b64_tr_b8 v[84:85], v199 offset:0x1000
	ds_read_b64_tr_b8 v[86:87], v199 offset:0x1800
	s_waitcnt lgkmcnt(0)
	s_nop 0
	v_mfma_f32_32x32x64_f8f6f4 v[18:33], v[72:79], v[80:87], v[18:33]
	ds_read_b64_tr_b8 v[80:81], v198 offset:0
	ds_read_b64_tr_b8 v[82:83], v198 offset:0x800
	ds_read_b64_tr_b8 v[84:85], v198 offset:0x1000
	ds_read_b64_tr_b8 v[86:87], v198 offset:0x1800
	s_waitcnt lgkmcnt(0)
	s_nop 0
	v_mfma_f32_32x32x64_f8f6f4 v[34:49], v[72:79], v[80:87], v[34:49]
	ds_read_b64_tr_b8 v[80:81], v197 offset:0
	ds_read_b64_tr_b8 v[82:83], v197 offset:0x800
	ds_read_b64_tr_b8 v[84:85], v197 offset:0x1000
	ds_read_b64_tr_b8 v[86:87], v197 offset:0x1800
	s_waitcnt lgkmcnt(0)
	s_nop 0
	v_mfma_f32_32x32x64_f8f6f4 v[50:65], v[72:79], v[80:87], v[50:65]
	s_nop 0
	s_nop 15
	s_nop 7
	s_nop 0
	v_and_b32_e32 v67, 31, v195
	v_cmp_gt_u32_e32 vcc, 32, v195
	s_and_saveexec_b64 s[2:3], vcc
	s_cbranch_execz .LBB0_1839
	v_add_f32_e32 v68, v126, v127
	v_fmac_f32_e32 v68, v196, v128
	v_add_f32_e32 v66, v70, v66
	v_fmac_f32_e32 v66, v68, v98
	v_lshl_add_u32 v68, v67, 2, s36
	ds_write_b32 v68, v66
	s_branch .LBB0_1839

.LBB0_1882:
	v_lshrrev_b32_e32 v4, 3, v39
	v_and_b32_e32 v3, 8, v39
	v_and_b32_e32 v56, 4, v4
	v_bfe_u32 v4, v39, 1, 2
	v_or3_b32 v3, v4, v3, v56
	v_lshlrev_b32_e32 v4, 3, v39
	v_bfe_u32 v10, v39, 1, 3
	v_lshlrev_b32_e32 v3, 7, v3
	v_and_b32_e32 v4, 8, v4
	v_and_b32_e32 v11, 1, v2
	v_add3_u32 v12, v4, s67, v3
	v_bitop3_b32 v2, v2, v10, 1 bitop3:0x6c
	v_lshl_add_u32 v194, v2, 4, v12
	v_bitop3_b32 v2, v11, v10, 2 bitop3:0x36
	v_lshlrev_b32_e32 v48, 3, v38
	v_lshl_add_u32 v193, v2, 4, v12
	v_bitop3_b32 v2, v48, v162, s37 bitop3:0x6c
	v_lshl_add_u32 v49, v38, 7, s67
	s_waitcnt lgkmcnt(0)
	v_add_u32_e32 v197, v49, v2
	v_or_b32_e32 v2, 16, v162
	s_barrier
	v_bitop3_b32 v2, v48, v2, s37 bitop3:0x6c
	v_add_u32_e32 v198, v49, v2
	ds_read_b128 v[2:5], v197 offset:32768
	ds_read_b128 v[40:43], v197 offset:36864
	ds_read_b128 v[6:9], v198 offset:32768
	ds_read_b128 v[44:47], v198 offset:36864
	v_bitop3_b32 v13, v11, v10, 4 bitop3:0x36
	v_bitop3_b32 v10, v11, v10, 6 bitop3:0x36
	v_lshl_add_u32 v192, v13, 4, v12
	v_lshl_add_u32 v190, v10, 4, v12
	s_waitcnt vmcnt(0) lgkmcnt(0)
	v_mfma_f32_32x32x64_f8f6f4 v[18:33], v[2:9], v[154:161], 0
	v_mfma_f32_32x32x64_f8f6f4 v[2:17], v[40:47], v[154:161], 0
	v_or_b32_e32 v40, 64, v162
	v_bitop3_b32 v40, v48, v40, s37 bitop3:0x6c
	v_add_u32_e32 v195, v49, v40
	v_or_b32_e32 v40, 0x50, v162
	v_bitop3_b32 v40, v48, v40, s37 bitop3:0x6c
	v_add_u32_e32 v196, v49, v40
	ds_read_b128 v[40:43], v195 offset:32768
	ds_read_b128 v[48:51], v195 offset:36864
	ds_read_b128 v[44:47], v196 offset:32768
	ds_read_b128 v[52:55], v196 offset:36864
	s_waitcnt lgkmcnt(1)
	v_mfma_f32_32x32x64_f8f6f4 v[18:33], v[40:47], v[146:153], v[18:33]
	s_waitcnt lgkmcnt(0)
	v_mfma_f32_32x32x64_f8f6f4 v[2:17], v[48:55], v[146:153], v[2:17]
	v_and_b32_e32 v181, 63, v39
	s_nop 15
	s_nop 7
	s_lshr_b32 s4, s4, 3
	v_max_f32_e32 v39, v19, v19
	v_max_f32_e32 v40, v18, v18
	v_max_f32_e32 v39, v40, v39
	v_max3_f32 v39, v39, v20, v21
	v_max3_f32 v39, v39, v22, v23
	v_max3_f32 v39, v39, v24, v25
	v_max3_f32 v39, v39, v26, v27
	v_max3_f32 v39, v39, v28, v29
	v_max3_f32 v39, v39, v30, v31
	v_max3_f32 v39, v39, v32, v33
	v_max3_f32 v39, v39, v2, v3
	v_max3_f32 v39, v39, v4, v5
	v_max3_f32 v39, v39, v6, v7
	v_max3_f32 v39, v39, v8, v9
	v_max3_f32 v39, v39, v10, v11
	v_max3_f32 v39, v39, v12, v13
	v_max3_f32 v39, v39, v14, v15
	v_max3_f32 v39, v39, v16, v17
	v_mov_b32_e32 v40, v39
	s_nop 1
	v_permlane32_swap_b32_e32 v39, v40
	v_max_f32_e32 v40, v40, v40
	v_max_f32_e32 v39, v39, v39
	v_max_f32_e32 v39, v39, v40
	s_and_b32 s30, s49, 0x3fffffc0
	v_add_f32_e32 v40, 0x7149f2ca, v39
	v_max_f32_e32 v39, 0xf149f2ca, v39
	s_lshl_b32 s30, s30, 2
	s_lshl_b32 s4, s4, 5
	v_sub_f32_e32 v41, 0xf149f2ca, v39
	s_add_i32 s30, s71, s30
	s_and_b32 s4, s4, 0x180
	v_mul_f32_e32 v41, 0x3e0293ee, v41
	v_cmp_ge_f32_e32 vcc, s38, v40
	v_exp_f32_e32 v41, v41
	s_cmp_eq_u64 vcc, exec
	s_cselect_b64 vcc, -1, 0
	s_add_u32 s2, s46, s2
	v_cndmask_b32_e32 v200, v39, v180, vcc
	s_addc_u32 s3, s47, s3
	s_add_i32 s31, s67, s48
	v_fma_f32 v40, v200, s39, 4.0
	s_add_i32 s47, s31, 0x4000
	v_pk_fma_f32 v[66:67], v[2:3], s[6:7], v[40:41] op_sel_hi:[1,0,0]
	v_lshl_add_u64 v[2:3], s[2:3], 0, v[36:37]
	s_mov_b32 m0, s47
	v_mov_b32_e32 v39, v40
	global_load_lds_dwordx4 v[2:3], off
	v_fmamk_f32 v18, v18, 0x3e0293ee, v40
	v_fmamk_f32 v19, v19, 0x3e0293ee, v40
	v_fmamk_f32 v20, v20, 0x3e0293ee, v40
	v_fmamk_f32 v21, v21, 0x3e0293ee, v40
	v_fmamk_f32 v22, v22, 0x3e0293ee, v40
	v_fmamk_f32 v23, v23, 0x3e0293ee, v40
	v_fmamk_f32 v24, v24, 0x3e0293ee, v40
	v_fmamk_f32 v25, v25, 0x3e0293ee, v40
	v_fmamk_f32 v26, v26, 0x3e0293ee, v40
	v_fmamk_f32 v27, v27, 0x3e0293ee, v40
	v_fmamk_f32 v28, v28, 0x3e0293ee, v40
	v_fmamk_f32 v29, v29, 0x3e0293ee, v40
	v_fmamk_f32 v30, v30, 0x3e0293ee, v40
	v_fmamk_f32 v31, v31, 0x3e0293ee, v40
	v_fmamk_f32 v32, v32, 0x3e0293ee, v40
	v_fmac_f32_e32 v39, 0x3e0293ee, v33
	v_exp_f32_e32 v82, v18
	v_exp_f32_e32 v83, v19
	v_exp_f32_e32 v84, v20
	v_exp_f32_e32 v85, v21
	v_exp_f32_e32 v172, v22
	v_exp_f32_e32 v173, v23
	v_exp_f32_e32 v170, v24
	v_exp_f32_e32 v171, v25
	v_exp_f32_e32 v168, v26
	v_exp_f32_e32 v169, v27
	v_exp_f32_e32 v140, v28
	v_exp_f32_e32 v141, v29
	v_exp_f32_e32 v144, v30
	v_exp_f32_e32 v145, v31
	v_exp_f32_e32 v142, v32
	v_exp_f32_e32 v143, v39
	s_waitcnt vmcnt(1)
	s_barrier
	s_add_u32 s28, s0, s28
	s_addc_u32 s29, s1, s29
	v_mov_b32_e32 v162, 0
	v_cndmask_b32_e64 v199, v41, 1.0, vcc
	v_pk_fma_f32 v[80:81], v[16:17], s[6:7], v[40:41] op_sel_hi:[1,0,0]
	v_pk_fma_f32 v[78:79], v[14:15], s[6:7], v[40:41] op_sel_hi:[1,0,0]
	v_pk_fma_f32 v[76:77], v[12:13], s[6:7], v[40:41] op_sel_hi:[1,0,0]
	v_pk_fma_f32 v[74:75], v[10:11], s[6:7], v[40:41] op_sel_hi:[1,0,0]
	v_pk_fma_f32 v[72:73], v[8:9], s[6:7], v[40:41] op_sel_hi:[1,0,0]
	v_pk_fma_f32 v[70:71], v[6:7], s[6:7], v[40:41] op_sel_hi:[1,0,0]
	v_pk_fma_f32 v[68:69], v[4:5], s[6:7], v[40:41] op_sel_hi:[1,0,0]
	v_cmp_gt_u32_e64 s[2:3], 32, v181
	v_lshl_add_u32 v191, v38, 2, s30
	v_lshl_add_u32 v189, v56, 2, s30
	v_add_u32_e32 v188, 0x4000, v194
	v_add_u32_e32 v187, 0x4000, v193
	v_add_u32_e32 v186, 0x4000, v192
	v_add_u32_e32 v185, 0x4000, v190
	v_lshl_add_u64 v[164:165], s[28:29], 0, v[36:37]
	v_lshl_add_u64 v[166:167], s[28:29], 0, v[34:35]
	s_mov_b32 s48, -1
	v_mov_b32_e32 v2, 0
	v_mov_b32_e32 v3, v162
	v_mov_b32_e32 v4, v162
	v_mov_b32_e32 v5, v162
	v_mov_b32_e32 v6, v162
	v_mov_b32_e32 v7, v162
	v_mov_b32_e32 v8, v162
	v_mov_b32_e32 v9, v162
	v_mov_b32_e32 v10, v162
	v_mov_b32_e32 v11, v162
	v_mov_b32_e32 v12, v162
	v_mov_b32_e32 v13, v162
	v_mov_b32_e32 v14, v162
	v_mov_b32_e32 v15, v162
	v_mov_b32_e32 v16, v162
	v_mov_b32_e32 v17, v162
	v_mov_b32_e32 v18, 0
	v_mov_b32_e32 v19, v162
	v_mov_b32_e32 v20, v162
	v_mov_b32_e32 v21, v162
	v_mov_b32_e32 v22, v162
	v_mov_b32_e32 v23, v162
	v_mov_b32_e32 v24, v162
	v_mov_b32_e32 v25, v162
	v_mov_b32_e32 v26, v162
	v_mov_b32_e32 v27, v162
	v_mov_b32_e32 v28, v162
	v_mov_b32_e32 v29, v162
	v_mov_b32_e32 v30, v162
	v_mov_b32_e32 v31, v162
	v_mov_b32_e32 v32, v162
	v_mov_b32_e32 v33, v162
	v_mov_b32_e32 v34, 0
	v_mov_b32_e32 v35, v162
	v_mov_b32_e32 v36, v162
	v_mov_b32_e32 v37, v162
	v_mov_b32_e32 v38, v162
	v_mov_b32_e32 v39, v162
	v_mov_b32_e32 v40, v162
	v_mov_b32_e32 v41, v162
	v_mov_b32_e32 v42, v162
	v_mov_b32_e32 v43, v162
	v_mov_b32_e32 v44, v162
	v_mov_b32_e32 v45, v162
	v_mov_b32_e32 v46, v162
	v_mov_b32_e32 v47, v162
	v_mov_b32_e32 v48, v162
	v_mov_b32_e32 v49, v162
	v_mov_b32_e32 v50, 0
	v_mov_b32_e32 v51, v162
	v_mov_b32_e32 v52, v162
	v_mov_b32_e32 v53, v162
	v_mov_b32_e32 v54, v162
	v_mov_b32_e32 v55, v162
	v_mov_b32_e32 v56, v162
	v_mov_b32_e32 v57, v162
	v_mov_b32_e32 v58, v162
	v_mov_b32_e32 v59, v162
	v_mov_b32_e32 v60, v162
	v_mov_b32_e32 v61, v162
	v_mov_b32_e32 v62, v162
	v_mov_b32_e32 v63, v162
	v_mov_b32_e32 v64, v162
	v_mov_b32_e32 v65, v162
.LBB0_1883:
	v_lshl_add_u64 v[138:139], v[166:167], 0, s[4:5]
	s_add_i32 s46, s31, 0x8000
	v_lshl_add_u64 v[86:87], v[138:139], 0, s[8:9]
	s_mov_b32 m0, s46
	s_nop 0
	global_load_lds_dwordx4 v[86:87], off
	ds_read_b128 v[106:109], v198 offset:49152
	ds_read_b128 v[102:105], v197 offset:49152
	ds_read_b128 v[130:133], v197 offset:53248
	ds_read_b128 v[134:137], v198 offset:53248
	s_mov_b32 m0, s31
	s_waitcnt lgkmcnt(0)
	v_mfma_f32_32x32x64_f8f6f4 v[86:101], v[102:109], v[154:161], 0
	s_nop 0
	v_exp_f32_e32 v66, v66
	v_exp_f32_e32 v67, v67
	v_exp_f32_e32 v68, v68
	v_exp_f32_e32 v69, v69
	ds_read_b128 v[102:105], v195 offset:49152
	ds_read_b128 v[106:109], v196 offset:49152
	v_mfma_f32_32x32x64_f8f6f4 v[114:129], v[130:137], v[154:161], 0
	ds_read_b128 v[202:205], v195 offset:53248
	ds_read_b128 v[206:209], v196 offset:53248
	v_exp_f32_e32 v70, v70
	v_exp_f32_e32 v71, v71
	v_exp_f32_e32 v72, v72
	v_exp_f32_e32 v73, v73
	s_waitcnt lgkmcnt(0)
	v_mfma_f32_32x32x64_f8f6f4 v[86:101], v[102:109], v[146:153], v[86:101]
	v_mov_b32_e32 v130, 0
	v_exp_f32_e32 v74, v74
	v_exp_f32_e32 v75, v75
	v_exp_f32_e32 v76, v76
	v_exp_f32_e32 v77, v77
	v_mfma_f32_32x32x64_f8f6f4 v[114:129], v[202:209], v[146:153], v[114:129]
	ds_read_b64_tr_b8 v[102:103], v194 offset:0
	ds_read_b64_tr_b8 v[104:105], v194 offset:0x800
	ds_read_b64_tr_b8 v[106:107], v194 offset:0x1000
	v_mov_b32_e32 v134, 0
	v_exp_f32_e32 v78, v78
	v_exp_f32_e32 v79, v79
	v_mov_b32_e32 v131, 0
	v_mov_b32_e32 v135, 0
	v_mov_b32_e32 v132, 0
	v_mov_b32_e32 v136, 0
	v_mov_b32_e32 v133, 0
	v_mov_b32_e32 v137, 0
	ds_read_b64_tr_b8 v[108:109], v194 offset:0x1800
	v_cvt_pk_fp8_f32 v130, v82, v83
	v_exp_f32_e32 v80, v80
	v_exp_f32_e32 v81, v81
	v_cvt_pk_fp8_f32 v134, v66, v67
	v_cvt_pk_fp8_f32 v131, v172, v173
	v_cvt_pk_fp8_f32 v135, v70, v71
	v_cvt_pk_fp8_f32 v132, v168, v169
	v_cvt_pk_fp8_f32 v136, v74, v75
	v_cvt_pk_fp8_f32 v133, v144, v145
	v_cvt_pk_fp8_f32 v137, v78, v79
	ds_read_b64_tr_b8 v[204:205], v193 offset:0
	ds_read_b64_tr_b8 v[206:207], v193 offset:0x800
	ds_read_b64_tr_b8 v[208:209], v193 offset:0x1000
	ds_read_b64_tr_b8 v[210:211], v193 offset:0x1800
	v_cvt_pk_fp8_f32 v130, v84, v85 op_sel:[0,0,1]
	v_cvt_pk_fp8_f32 v134, v68, v69 op_sel:[0,0,1]
	v_cvt_pk_fp8_f32 v131, v170, v171 op_sel:[0,0,1]
	v_cvt_pk_fp8_f32 v135, v72, v73 op_sel:[0,0,1]
	v_cvt_pk_fp8_f32 v132, v140, v141 op_sel:[0,0,1]
	v_cvt_pk_fp8_f32 v136, v76, v77 op_sel:[0,0,1]
	v_cvt_pk_fp8_f32 v133, v142, v143 op_sel:[0,0,1]
	v_cvt_pk_fp8_f32 v137, v80, v81 op_sel:[0,0,1]
	s_waitcnt lgkmcnt(4)
	v_pk_add_f32 v[82:83], v[82:83], v[84:85]
	v_mfma_f32_32x32x64_f8f6f4 v[2:17], v[130:137], v[102:109], v[2:17]
	ds_read_b64_tr_b8 v[212:213], v192 offset:0
	ds_read_b64_tr_b8 v[214:215], v192 offset:0x800
	ds_read_b64_tr_b8 v[216:217], v192 offset:0x1000
	ds_read_b64_tr_b8 v[218:219], v192 offset:0x1800
	s_waitcnt lgkmcnt(4)
	s_nop 0
	v_max_f32_e32 v102, v87, v87
	v_max_f32_e32 v103, v86, v86
	v_max_f32_e32 v102, v103, v102
	v_max3_f32 v102, v102, v88, v89
	v_max3_f32 v102, v102, v90, v91
	v_max3_f32 v102, v102, v92, v93
	v_max3_f32 v102, v102, v94, v95
	v_max3_f32 v102, v102, v96, v97
	v_max3_f32 v102, v102, v98, v99
	v_max3_f32 v102, v102, v100, v101
	v_max3_f32 v102, v102, v114, v115
	v_max3_f32 v102, v102, v116, v117
	v_max3_f32 v102, v102, v118, v119
	v_max3_f32 v102, v102, v120, v121
	v_max3_f32 v102, v102, v122, v123
	v_max3_f32 v102, v102, v124, v125
	v_max3_f32 v102, v102, v126, v127
	v_max3_f32 v102, v102, v128, v129
	v_mov_b32_e32 v103, v102
	s_nop 1
	v_permlane32_swap_b32_e32 v102, v103
	v_max_f32_e32 v103, v103, v103
	v_max_f32_e32 v102, v102, v102
	v_max_f32_e32 v102, v102, v103
	v_sub_f32_e32 v103, v102, v200
	v_cmp_ge_f32_e32 vcc, s38, v103
	s_cmp_eq_u64 vcc, exec
	v_max_f32_e32 v103, v200, v200
	v_max_f32_e32 v176, v103, v102
	s_cselect_b64 vcc, -1, 0
	v_cndmask_b32_e32 v202, v176, v200, vcc
	v_fma_f32 v174, v202, s39, 4.0
	v_mfma_f32_32x32x64_f8f6f4 v[18:33], v[130:137], v[204:211], v[18:33]
	v_pk_add_f32 v[82:83], v[172:173], v[82:83]
	v_pk_fma_f32 v[110:111], v[98:99], s[6:7], v[174:175] op_sel_hi:[1,0,0]
	v_pk_fma_f32 v[98:99], v[86:87], s[6:7], v[174:175] op_sel_hi:[1,0,0]
	ds_read_b64_tr_b8 v[86:87], v190 offset:0
	v_pk_fma_f32 v[112:113], v[100:101], s[6:7], v[174:175] op_sel_hi:[1,0,0]
	v_pk_fma_f32 v[100:101], v[88:89], s[6:7], v[174:175] op_sel_hi:[1,0,0]
	ds_read_b64_tr_b8 v[88:89], v190 offset:0x800
	v_pk_fma_f32 v[102:103], v[90:91], s[6:7], v[174:175] op_sel_hi:[1,0,0]
	ds_read_b64_tr_b8 v[90:91], v190 offset:0x1000
	v_pk_fma_f32 v[108:109], v[96:97], s[6:7], v[174:175] op_sel_hi:[1,0,0]
	v_pk_fma_f32 v[106:107], v[94:95], s[6:7], v[174:175] op_sel_hi:[1,0,0]
	v_pk_fma_f32 v[104:105], v[92:93], s[6:7], v[174:175] op_sel_hi:[1,0,0]
	v_pk_fma_f32 v[128:129], v[128:129], s[6:7], v[174:175] op_sel_hi:[1,0,0]
	v_pk_fma_f32 v[126:127], v[126:127], s[6:7], v[174:175] op_sel_hi:[1,0,0]
	v_pk_fma_f32 v[124:125], v[124:125], s[6:7], v[174:175] op_sel_hi:[1,0,0]
	v_pk_fma_f32 v[122:123], v[122:123], s[6:7], v[174:175] op_sel_hi:[1,0,0]
	v_pk_fma_f32 v[120:121], v[120:121], s[6:7], v[174:175] op_sel_hi:[1,0,0]
	v_pk_fma_f32 v[118:119], v[118:119], s[6:7], v[174:175] op_sel_hi:[1,0,0]
	v_pk_fma_f32 v[116:117], v[116:117], s[6:7], v[174:175] op_sel_hi:[1,0,0]
	v_pk_fma_f32 v[114:115], v[114:115], s[6:7], v[174:175] op_sel_hi:[1,0,0]
	ds_read_b64_tr_b8 v[92:93], v190 offset:0x1800
	s_waitcnt lgkmcnt(4)
	v_lshl_add_u64 v[174:175], v[164:165], 0, s[4:5]
	v_mfma_f32_32x32x64_f8f6f4 v[34:49], v[130:137], v[212:219], v[34:49]
	s_waitcnt lgkmcnt(0)
	v_pk_add_f32 v[82:83], v[170:171], v[82:83]
	v_exp_f32_e32 v98, v98
	v_exp_f32_e32 v99, v99
	v_exp_f32_e32 v100, v100
	v_exp_f32_e32 v101, v101
	v_mfma_f32_32x32x64_f8f6f4 v[50:65], v[130:137], v[86:93], v[50:65]
	s_barrier
	v_lshl_add_u64 v[86:87], v[174:175], 0, s[10:11]
	global_load_lds_dwordx4 v[86:87], off
	v_pk_add_f32 v[82:83], v[168:169], v[82:83]
	s_nop 0
	v_pk_add_f32 v[82:83], v[140:141], v[82:83]
	s_nop 0
	v_pk_add_f32 v[82:83], v[144:145], v[82:83]
	s_nop 0
	v_pk_add_f32 v[82:83], v[142:143], v[82:83]
	s_nop 0
	v_pk_add_f32 v[66:67], v[82:83], v[66:67]
	s_nop 0
	v_pk_add_f32 v[66:67], v[68:69], v[66:67]
	s_nop 0
	v_pk_add_f32 v[66:67], v[70:71], v[66:67]
	s_nop 0
	v_pk_add_f32 v[66:67], v[72:73], v[66:67]
	s_nop 0
	v_pk_add_f32 v[66:67], v[74:75], v[66:67]
	s_nop 0
	v_pk_add_f32 v[66:67], v[76:77], v[66:67]
	s_nop 0
	v_pk_add_f32 v[66:67], v[78:79], v[66:67]
	s_nop 0
	v_pk_add_f32 v[66:67], v[80:81], v[66:67]
	s_nop 0
	v_pk_add_f32 v[168:169], v[66:67], v[66:67] op_sel:[0,1] op_sel_hi:[1,0]
	v_sub_f32_e32 v66, v200, v176
	v_mul_f32_e32 v66, 0x3e0293ee, v66
	v_exp_f32_e32 v66, v66
	v_mov_b32_e32 v201, v168
	s_nop 1
	v_permlane32_swap_b32_e32 v168, v201
	v_cndmask_b32_e64 v169, v66, 1.0, vcc
	v_cmp_gt_f32_e32 vcc, 1.0, v169
	s_cbranch_vccz .LBB0_1887
	s_and_saveexec_b64 s[28:29], s[2:3]
	ds_write_b32 v191, v169 offset:128
	s_or_b64 exec, exec, s[28:29]
	s_waitcnt lgkmcnt(0)
	s_nop 15
	s_nop 7
	ds_read2_b32 v[66:67], v189 offset0:32 offset1:33
	ds_read2_b32 v[68:69], v189 offset0:34 offset1:35
	ds_read2_b32 v[70:71], v189 offset0:40 offset1:41
	ds_read2_b32 v[72:73], v189 offset0:42 offset1:43
	s_waitcnt lgkmcnt(0)
	v_pk_mul_f32 v[2:3], v[66:67], v[2:3]
	v_pk_mul_f32 v[18:19], v[66:67], v[18:19]
	v_pk_mul_f32 v[34:35], v[66:67], v[34:35]
	v_pk_mul_f32 v[50:51], v[66:67], v[50:51]
	v_pk_mul_f32 v[4:5], v[4:5], v[68:69]
	v_pk_mul_f32 v[20:21], v[20:21], v[68:69]
	v_pk_mul_f32 v[36:37], v[36:37], v[68:69]
	v_pk_mul_f32 v[52:53], v[52:53], v[68:69]
	v_pk_mul_f32 v[6:7], v[6:7], v[70:71]
	v_pk_mul_f32 v[22:23], v[22:23], v[70:71]
	v_pk_mul_f32 v[38:39], v[38:39], v[70:71]
	v_pk_mul_f32 v[54:55], v[54:55], v[70:71]
	v_pk_mul_f32 v[8:9], v[8:9], v[72:73]
	v_pk_mul_f32 v[24:25], v[24:25], v[72:73]
	v_pk_mul_f32 v[40:41], v[40:41], v[72:73]
	ds_read2_b32 v[66:67], v189 offset0:48 offset1:49
	v_pk_mul_f32 v[56:57], v[56:57], v[72:73]
	ds_read2_b32 v[68:69], v189 offset0:50 offset1:51
	ds_read2_b32 v[70:71], v189 offset0:56 offset1:57
	ds_read2_b32 v[72:73], v189 offset0:58 offset1:59
	s_waitcnt lgkmcnt(0)
	v_pk_mul_f32 v[10:11], v[10:11], v[66:67]
	v_pk_mul_f32 v[26:27], v[26:27], v[66:67]
	v_pk_mul_f32 v[42:43], v[42:43], v[66:67]
	v_pk_mul_f32 v[58:59], v[58:59], v[66:67]
	v_pk_mul_f32 v[12:13], v[12:13], v[68:69]
	v_pk_mul_f32 v[28:29], v[28:29], v[68:69]
	v_pk_mul_f32 v[44:45], v[44:45], v[68:69]
	v_pk_mul_f32 v[60:61], v[60:61], v[68:69]
	v_pk_mul_f32 v[14:15], v[14:15], v[70:71]
	v_pk_mul_f32 v[30:31], v[30:31], v[70:71]
	v_pk_mul_f32 v[46:47], v[46:47], v[70:71]
	v_pk_mul_f32 v[62:63], v[62:63], v[70:71]
	v_pk_mul_f32 v[16:17], v[16:17], v[72:73]
	v_pk_mul_f32 v[32:33], v[32:33], v[72:73]
	v_pk_mul_f32 v[48:49], v[48:49], v[72:73]
	v_pk_mul_f32 v[64:65], v[64:65], v[72:73]
.LBB0_1887:
	s_waitcnt vmcnt(1)
	s_add_i32 s49, s31, 0xc000
	s_barrier
	v_lshl_add_u64 v[66:67], v[138:139], 0, s[12:13]
	s_mov_b32 m0, s49
	v_exp_f32_e32 v170, v102
	global_load_lds_dwordx4 v[66:67], off
	v_exp_f32_e32 v171, v103
	v_exp_f32_e32 v172, v104
	v_exp_f32_e32 v173, v105
	v_exp_f32_e32 v176, v106
	v_exp_f32_e32 v177, v107
	v_exp_f32_e32 v178, v108
	v_exp_f32_e32 v179, v109
	v_exp_f32_e32 v110, v110
	v_exp_f32_e32 v111, v111
	v_exp_f32_e32 v112, v112
	v_exp_f32_e32 v113, v113
	ds_read_b128 v[86:89], v198 offset:32768
	ds_read_b128 v[82:85], v197 offset:32768
	ds_read_b128 v[90:93], v197 offset:36864
	ds_read_b128 v[94:97], v198 offset:36864
	v_mov_b32_e32 v102, 0
	v_mov_b32_e32 v106, 0
	s_waitcnt lgkmcnt(0)
	v_mfma_f32_32x32x64_f8f6f4 v[66:81], v[82:89], v[154:161], 0
	ds_read_b128 v[82:85], v195 offset:32768
	ds_read_b128 v[86:89], v196 offset:32768
	v_exp_f32_e32 v114, v114
	v_exp_f32_e32 v115, v115
	v_exp_f32_e32 v116, v116
	v_exp_f32_e32 v117, v117
	v_mfma_f32_32x32x64_f8f6f4 v[130:145], v[90:97], v[154:161], 0
	ds_read_b128 v[90:93], v195 offset:36864
	ds_read_b128 v[94:97], v196 offset:36864
	v_exp_f32_e32 v118, v118
	v_exp_f32_e32 v119, v119
	v_exp_f32_e32 v120, v120
	v_exp_f32_e32 v121, v121
	s_waitcnt lgkmcnt(0)
	v_mfma_f32_32x32x64_f8f6f4 v[66:81], v[82:89], v[146:153], v[66:81]
	v_mov_b32_e32 v103, 0
	v_exp_f32_e32 v122, v122
	v_exp_f32_e32 v123, v123
	v_exp_f32_e32 v124, v124
	v_exp_f32_e32 v125, v125
	v_mfma_f32_32x32x64_f8f6f4 v[130:145], v[90:97], v[146:153], v[130:145]
	ds_read_b64_tr_b8 v[82:83], v188 offset:0
	ds_read_b64_tr_b8 v[84:85], v188 offset:0x800
	ds_read_b64_tr_b8 v[86:87], v188 offset:0x1000
	v_mov_b32_e32 v107, 0
	v_exp_f32_e32 v126, v126
	v_exp_f32_e32 v127, v127
	v_mov_b32_e32 v104, 0
	v_mov_b32_e32 v108, 0
	v_mov_b32_e32 v105, 0
	v_mov_b32_e32 v109, 0
	ds_read_b64_tr_b8 v[88:89], v188 offset:0x1800
	v_cvt_pk_fp8_f32 v102, v98, v99
	v_exp_f32_e32 v128, v128
	v_exp_f32_e32 v129, v129
	v_cvt_pk_fp8_f32 v106, v114, v115
	v_cvt_pk_fp8_f32 v103, v170, v171
	v_cvt_pk_fp8_f32 v107, v118, v119
	v_cvt_pk_fp8_f32 v104, v176, v177
	v_cvt_pk_fp8_f32 v108, v122, v123
	v_cvt_pk_fp8_f32 v105, v110, v111
	v_cvt_pk_fp8_f32 v109, v126, v127
	ds_read_b64_tr_b8 v[90:91], v187 offset:0
	ds_read_b64_tr_b8 v[92:93], v187 offset:0x800
	ds_read_b64_tr_b8 v[94:95], v187 offset:0x1000
	ds_read_b64_tr_b8 v[96:97], v187 offset:0x1800
	v_cvt_pk_fp8_f32 v102, v100, v101 op_sel:[0,0,1]
	v_cvt_pk_fp8_f32 v106, v116, v117 op_sel:[0,0,1]
	v_cvt_pk_fp8_f32 v103, v172, v173 op_sel:[0,0,1]
	v_cvt_pk_fp8_f32 v107, v120, v121 op_sel:[0,0,1]
	v_cvt_pk_fp8_f32 v104, v178, v179 op_sel:[0,0,1]
	v_cvt_pk_fp8_f32 v108, v124, v125 op_sel:[0,0,1]
	v_cvt_pk_fp8_f32 v105, v112, v113 op_sel:[0,0,1]
	v_cvt_pk_fp8_f32 v109, v128, v129 op_sel:[0,0,1]
	s_waitcnt lgkmcnt(4)
	s_mov_b32 m0, s47
	v_mfma_f32_32x32x64_f8f6f4 v[2:17], v[102:109], v[82:89], v[2:17]
	ds_read_b64_tr_b8 v[204:205], v186 offset:0
	ds_read_b64_tr_b8 v[206:207], v186 offset:0x800
	ds_read_b64_tr_b8 v[208:209], v186 offset:0x1000
	ds_read_b64_tr_b8 v[210:211], v186 offset:0x1800
	s_waitcnt lgkmcnt(4)
	s_nop 0
	v_max_f32_e32 v82, v67, v67
	v_max_f32_e32 v83, v66, v66
	v_max_f32_e32 v82, v83, v82
	v_max3_f32 v82, v82, v68, v69
	v_max3_f32 v82, v82, v70, v71
	v_max3_f32 v82, v82, v72, v73
	v_max3_f32 v82, v82, v74, v75
	v_max3_f32 v82, v82, v76, v77
	v_max3_f32 v82, v82, v78, v79
	v_max3_f32 v82, v82, v80, v81
	v_max3_f32 v82, v82, v130, v131
	v_max3_f32 v82, v82, v132, v133
	v_max3_f32 v82, v82, v134, v135
	v_max3_f32 v82, v82, v136, v137
	v_max3_f32 v82, v82, v138, v139
	v_max3_f32 v82, v82, v140, v141
	v_max3_f32 v82, v82, v142, v143
	v_max3_f32 v82, v82, v144, v145
	v_mov_b32_e32 v83, v82
	s_nop 1
	v_permlane32_swap_b32_e32 v82, v83
	v_max_f32_e32 v83, v83, v83
	v_max_f32_e32 v82, v82, v82
	v_max_f32_e32 v82, v82, v83
	v_sub_f32_e32 v83, v82, v202
	v_cmp_ge_f32_e32 vcc, s38, v83
	s_cmp_eq_u64 vcc, exec
	v_max_f32_e32 v83, v202, v202
	v_max_f32_e32 v203, v83, v82
	s_cselect_b64 vcc, -1, 0
	v_cndmask_b32_e32 v200, v203, v202, vcc
	v_fma_f32 v212, v200, s39, 4.0
	v_mfma_f32_32x32x64_f8f6f4 v[18:33], v[102:109], v[90:97], v[18:33]
	v_pk_add_f32 v[98:99], v[98:99], v[100:101]
	v_pk_fma_f32 v[82:83], v[66:67], s[6:7], v[212:213] op_sel_hi:[1,0,0]
	v_pk_fma_f32 v[66:67], v[130:131], s[6:7], v[212:213] op_sel_hi:[1,0,0]
	ds_read_b64_tr_b8 v[130:131], v185 offset:0
	v_pk_fma_f32 v[84:85], v[68:69], s[6:7], v[212:213] op_sel_hi:[1,0,0]
	v_pk_fma_f32 v[68:69], v[132:133], s[6:7], v[212:213] op_sel_hi:[1,0,0]
	ds_read_b64_tr_b8 v[132:133], v185 offset:0x800
	v_pk_fma_f32 v[86:87], v[70:71], s[6:7], v[212:213] op_sel_hi:[1,0,0]
	v_pk_fma_f32 v[70:71], v[134:135], s[6:7], v[212:213] op_sel_hi:[1,0,0]
	ds_read_b64_tr_b8 v[134:135], v185 offset:0x1000
	v_pk_fma_f32 v[96:97], v[80:81], s[6:7], v[212:213] op_sel_hi:[1,0,0]
	v_pk_fma_f32 v[94:95], v[78:79], s[6:7], v[212:213] op_sel_hi:[1,0,0]
	v_pk_fma_f32 v[92:93], v[76:77], s[6:7], v[212:213] op_sel_hi:[1,0,0]
	v_pk_fma_f32 v[90:91], v[74:75], s[6:7], v[212:213] op_sel_hi:[1,0,0]
	v_pk_fma_f32 v[88:89], v[72:73], s[6:7], v[212:213] op_sel_hi:[1,0,0]
	v_pk_fma_f32 v[80:81], v[144:145], s[6:7], v[212:213] op_sel_hi:[1,0,0]
	v_pk_fma_f32 v[78:79], v[142:143], s[6:7], v[212:213] op_sel_hi:[1,0,0]
	v_pk_fma_f32 v[76:77], v[140:141], s[6:7], v[212:213] op_sel_hi:[1,0,0]
	v_pk_fma_f32 v[74:75], v[138:139], s[6:7], v[212:213] op_sel_hi:[1,0,0]
	v_pk_fma_f32 v[72:73], v[136:137], s[6:7], v[212:213] op_sel_hi:[1,0,0]
	ds_read_b64_tr_b8 v[136:137], v185 offset:0x1800
	s_waitcnt lgkmcnt(4)
	v_pk_add_f32 v[98:99], v[98:99], v[170:171]
	v_mfma_f32_32x32x64_f8f6f4 v[34:49], v[102:109], v[204:211], v[34:49]
	s_waitcnt lgkmcnt(0)
	s_nop 0
	v_exp_f32_e32 v82, v82
	v_exp_f32_e32 v83, v83
	v_exp_f32_e32 v84, v84
	v_exp_f32_e32 v85, v85
	v_mfma_f32_32x32x64_f8f6f4 v[50:65], v[102:109], v[130:137], v[50:65]
	s_barrier
	v_lshl_add_u64 v[102:103], v[174:175], 0, s[14:15]
	global_load_lds_dwordx4 v[102:103], off
	v_pk_add_f32 v[98:99], v[172:173], v[98:99]
	s_nop 0
	v_pk_add_f32 v[98:99], v[176:177], v[98:99]
	s_nop 0
	v_pk_add_f32 v[98:99], v[178:179], v[98:99]
	s_nop 0
	v_pk_add_f32 v[98:99], v[110:111], v[98:99]
	s_nop 0
	v_pk_add_f32 v[98:99], v[112:113], v[98:99]
	s_nop 0
	v_pk_add_f32 v[98:99], v[98:99], v[114:115]
	s_nop 0
	v_pk_add_f32 v[98:99], v[116:117], v[98:99]
	s_nop 0
	v_pk_add_f32 v[98:99], v[118:119], v[98:99]
	s_nop 0
	v_pk_add_f32 v[98:99], v[120:121], v[98:99]
	s_nop 0
	v_pk_add_f32 v[98:99], v[122:123], v[98:99]
	s_nop 0
	v_pk_add_f32 v[98:99], v[124:125], v[98:99]
	s_nop 0
	v_pk_add_f32 v[98:99], v[126:127], v[98:99]
	s_nop 0
	v_pk_add_f32 v[98:99], v[128:129], v[98:99]
	s_nop 0
	v_pk_add_f32 v[98:99], v[98:99], v[98:99] op_sel:[0,1] op_sel_hi:[1,0]
	s_nop 0
	v_sub_f32_e32 v99, v202, v203
	v_mul_f32_e32 v99, 0x3e0293ee, v99
	v_exp_f32_e32 v100, v99
	v_mov_b32_e32 v99, v98
	s_nop 1
	v_permlane32_swap_b32_e32 v98, v99
	v_cndmask_b32_e64 v174, v100, 1.0, vcc
	v_cmp_gt_f32_e32 vcc, 1.0, v174
	s_cbranch_vccz .LBB0_1891
	s_and_saveexec_b64 s[28:29], s[2:3]
	ds_write_b32 v191, v174 offset:128
	s_or_b64 exec, exec, s[28:29]
	s_waitcnt lgkmcnt(0)
	s_nop 15
	s_nop 7
	ds_read2_b32 v[100:101], v189 offset0:32 offset1:33
	ds_read2_b32 v[102:103], v189 offset0:34 offset1:35
	ds_read2_b32 v[104:105], v189 offset0:40 offset1:41
	ds_read2_b32 v[106:107], v189 offset0:42 offset1:43
	s_waitcnt lgkmcnt(0)
	v_pk_mul_f32 v[2:3], v[100:101], v[2:3]
	v_pk_mul_f32 v[18:19], v[100:101], v[18:19]
	v_pk_mul_f32 v[34:35], v[100:101], v[34:35]
	v_pk_mul_f32 v[50:51], v[100:101], v[50:51]
	v_pk_mul_f32 v[4:5], v[4:5], v[102:103]
	v_pk_mul_f32 v[20:21], v[20:21], v[102:103]
	v_pk_mul_f32 v[36:37], v[36:37], v[102:103]
	v_pk_mul_f32 v[52:53], v[52:53], v[102:103]
	v_pk_mul_f32 v[6:7], v[6:7], v[104:105]
	v_pk_mul_f32 v[22:23], v[22:23], v[104:105]
	v_pk_mul_f32 v[38:39], v[38:39], v[104:105]
	v_pk_mul_f32 v[54:55], v[54:55], v[104:105]
	v_pk_mul_f32 v[8:9], v[8:9], v[106:107]
	v_pk_mul_f32 v[24:25], v[24:25], v[106:107]
	v_pk_mul_f32 v[40:41], v[40:41], v[106:107]
	ds_read2_b32 v[100:101], v189 offset0:48 offset1:49
	v_pk_mul_f32 v[56:57], v[56:57], v[106:107]
	ds_read2_b32 v[102:103], v189 offset0:50 offset1:51
	ds_read2_b32 v[104:105], v189 offset0:56 offset1:57
	ds_read2_b32 v[106:107], v189 offset0:58 offset1:59
	s_waitcnt lgkmcnt(0)
	v_pk_mul_f32 v[10:11], v[10:11], v[100:101]
	v_pk_mul_f32 v[26:27], v[26:27], v[100:101]
	v_pk_mul_f32 v[42:43], v[42:43], v[100:101]
	v_pk_mul_f32 v[58:59], v[58:59], v[100:101]
	v_pk_mul_f32 v[12:13], v[12:13], v[102:103]
	v_pk_mul_f32 v[28:29], v[28:29], v[102:103]
	v_pk_mul_f32 v[44:45], v[44:45], v[102:103]
	v_pk_mul_f32 v[60:61], v[60:61], v[102:103]
	v_pk_mul_f32 v[14:15], v[14:15], v[104:105]
	v_pk_mul_f32 v[30:31], v[30:31], v[104:105]
	v_pk_mul_f32 v[46:47], v[46:47], v[104:105]
	v_pk_mul_f32 v[62:63], v[62:63], v[104:105]
	v_pk_mul_f32 v[16:17], v[16:17], v[106:107]
	v_pk_mul_f32 v[32:33], v[32:33], v[106:107]
	v_pk_mul_f32 v[48:49], v[48:49], v[106:107]
	v_pk_mul_f32 v[64:65], v[64:65], v[106:107]

.LBB0_1893:
	ds_read_b128 v[90:93], v198 offset:49152
	ds_read_b128 v[86:89], v197 offset:49152
	ds_read_b128 v[130:133], v197 offset:53248
	ds_read_b128 v[134:137], v198 offset:53248
	v_pk_add_f32 v[94:95], v[82:83], v[84:85]
	s_waitcnt lgkmcnt(0)
	v_mfma_f32_32x32x64_f8f6f4 v[114:129], v[86:93], v[154:161], 0
	s_nop 0
	v_exp_f32_e32 v66, v66
	v_exp_f32_e32 v67, v67
	v_exp_f32_e32 v68, v68
	v_exp_f32_e32 v69, v69
	ds_read_b128 v[86:89], v195 offset:49152
	ds_read_b128 v[90:93], v196 offset:49152
	v_mfma_f32_32x32x64_f8f6f4 v[98:113], v[130:137], v[154:161], 0
	ds_read_b128 v[130:133], v195 offset:53248
	ds_read_b128 v[134:137], v196 offset:53248
	v_exp_f32_e32 v70, v70
	v_exp_f32_e32 v71, v71
	v_exp_f32_e32 v72, v72
	v_exp_f32_e32 v73, v73
	v_pk_add_f32 v[94:95], v[94:95], v[172:173]
	s_waitcnt lgkmcnt(0)
	v_mfma_f32_32x32x64_f8f6f4 v[114:129], v[86:93], v[146:153], v[114:129]
	v_pk_add_f32 v[94:95], v[94:95], v[170:171]
	v_exp_f32_e32 v74, v74
	v_exp_f32_e32 v75, v75
	v_exp_f32_e32 v76, v76
	v_exp_f32_e32 v77, v77
	v_pk_add_f32 v[86:87], v[94:95], v[168:169]
	v_mfma_f32_32x32x64_f8f6f4 v[98:113], v[130:137], v[146:153], v[98:113]
	v_mov_b32_e32 v134, v163
	v_pk_add_f32 v[86:87], v[86:87], v[140:141]
	v_cvt_pk_fp8_f32 v134, v66, v67
	v_pk_add_f32 v[86:87], v[86:87], v[144:145]
	v_mov_b32_e32 v135, v163
	v_exp_f32_e32 v78, v78
	v_exp_f32_e32 v79, v79
	v_pk_add_f32 v[86:87], v[86:87], v[142:143]
	v_cvt_pk_fp8_f32 v135, v70, v71
	v_pk_add_f32 v[86:87], v[86:87], v[66:67]
	v_mov_b32_e32 v136, v163
	ds_read_b64_tr_b8 v[66:67], v194 offset:0
	v_pk_add_f32 v[86:87], v[68:69], v[86:87]
	v_cvt_pk_fp8_f32 v134, v68, v69 op_sel:[0,0,1]
	v_cvt_pk_fp8_f32 v136, v74, v75
	ds_read_b64_tr_b8 v[68:69], v194 offset:0x800
	v_pk_add_f32 v[86:87], v[70:71], v[86:87]
	v_mov_b32_e32 v137, v163
	ds_read_b64_tr_b8 v[70:71], v194 offset:0x1000
	v_exp_f32_e32 v80, v80
	v_exp_f32_e32 v81, v81
	v_pk_add_f32 v[86:87], v[72:73], v[86:87]
	v_mov_b32_e32 v130, v163
	v_mov_b32_e32 v131, v163
	v_cvt_pk_fp8_f32 v135, v72, v73 op_sel:[0,0,1]
	v_mov_b32_e32 v132, v163
	v_mov_b32_e32 v133, v163
	v_cvt_pk_fp8_f32 v137, v78, v79
	ds_read_b64_tr_b8 v[72:73], v194 offset:0x1800
	v_pk_add_f32 v[86:87], v[74:75], v[86:87]
	v_cvt_pk_fp8_f32 v130, v82, v83
	v_cvt_pk_fp8_f32 v131, v172, v173
	v_cvt_pk_fp8_f32 v132, v168, v169
	v_cvt_pk_fp8_f32 v133, v144, v145
	ds_read_b64_tr_b8 v[74:75], v193 offset:0
	v_pk_add_f32 v[86:87], v[76:77], v[86:87]
	v_cvt_pk_fp8_f32 v136, v76, v77 op_sel:[0,0,1]
	ds_read_b64_tr_b8 v[76:77], v193 offset:0x800
	v_pk_add_f32 v[86:87], v[78:79], v[86:87]
	ds_read_b64_tr_b8 v[78:79], v193 offset:0x1000
	v_cvt_pk_fp8_f32 v137, v80, v81 op_sel:[0,0,1]
	v_pk_add_f32 v[86:87], v[80:81], v[86:87]
	ds_read_b64_tr_b8 v[80:81], v193 offset:0x1800
	v_cvt_pk_fp8_f32 v130, v84, v85 op_sel:[0,0,1]
	v_cvt_pk_fp8_f32 v131, v170, v171 op_sel:[0,0,1]
	v_cvt_pk_fp8_f32 v132, v140, v141 op_sel:[0,0,1]
	v_cvt_pk_fp8_f32 v133, v142, v143 op_sel:[0,0,1]
	s_waitcnt lgkmcnt(4)
	v_pk_add_f32 v[138:139], v[86:87], v[86:87] op_sel:[0,1] op_sel_hi:[1,0]
	v_mfma_f32_32x32x64_f8f6f4 v[2:17], v[130:137], v[66:73], v[2:17]
	ds_read_b64_tr_b8 v[140:141], v192 offset:0
	ds_read_b64_tr_b8 v[142:143], v192 offset:0x800
	ds_read_b64_tr_b8 v[144:145], v192 offset:0x1000
	ds_read_b64_tr_b8 v[146:147], v192 offset:0x1800
	s_waitcnt lgkmcnt(4)
	s_nop 0
	v_max_f32_e32 v66, v115, v115
	v_max_f32_e32 v67, v114, v114
	v_max_f32_e32 v66, v67, v66
	v_max3_f32 v66, v66, v116, v117
	v_max3_f32 v66, v66, v118, v119
	v_max3_f32 v66, v66, v120, v121
	v_max3_f32 v66, v66, v122, v123
	v_max3_f32 v66, v66, v124, v125
	v_max3_f32 v66, v66, v126, v127
	v_max3_f32 v66, v66, v128, v129
	v_max3_f32 v66, v66, v98, v99
	v_max3_f32 v66, v66, v100, v101
	v_max3_f32 v66, v66, v102, v103
	v_max3_f32 v66, v66, v104, v105
	v_max3_f32 v66, v66, v106, v107
	v_max3_f32 v66, v66, v108, v109
	v_max3_f32 v66, v66, v110, v111
	v_max3_f32 v66, v66, v112, v113
	v_mov_b32_e32 v67, v66
	s_nop 1
	v_permlane32_swap_b32_e32 v66, v67
	v_max_f32_e32 v67, v67, v67
	v_max_f32_e32 v66, v66, v66
	v_max_f32_e32 v66, v66, v67
	v_sub_f32_e32 v67, v66, v200
	v_cmp_ge_f32_e32 vcc, s38, v67
	s_cmp_eq_u64 vcc, exec
	v_max_f32_e32 v67, v200, v200
	v_max_f32_e32 v66, v67, v66
	s_cselect_b64 vcc, -1, 0
	v_sub_f32_e32 v67, v200, v66
	v_cndmask_b32_e32 v66, v66, v200, vcc
	v_mul_f32_e32 v83, 0x3e0293ee, v67
	v_fma_f32 v82, v66, s39, 4.0
	v_mfma_f32_32x32x64_f8f6f4 v[18:33], v[130:137], v[74:81], v[18:33]
	v_mov_b32_e32 v139, v138
	v_pk_fma_f32 v[84:85], v[100:101], s[6:7], v[82:83] op_sel_hi:[1,0,0]
	ds_read_b64_tr_b8 v[100:101], v190 offset:0
	v_pk_fma_f32 v[66:67], v[114:115], s[6:7], v[82:83] op_sel_hi:[1,0,0]
	v_exp_f32_e32 v114, v83
	v_pk_fma_f32 v[86:87], v[102:103], s[6:7], v[82:83] op_sel_hi:[1,0,0]
	ds_read_b64_tr_b8 v[102:103], v190 offset:0x800
	v_pk_fma_f32 v[88:89], v[104:105], s[6:7], v[82:83] op_sel_hi:[1,0,0]
	ds_read_b64_tr_b8 v[104:105], v190 offset:0x1000
	v_pk_fma_f32 v[80:81], v[128:129], s[6:7], v[82:83] op_sel_hi:[1,0,0]
	v_pk_fma_f32 v[78:79], v[126:127], s[6:7], v[82:83] op_sel_hi:[1,0,0]
	v_pk_fma_f32 v[76:77], v[124:125], s[6:7], v[82:83] op_sel_hi:[1,0,0]
	v_pk_fma_f32 v[74:75], v[122:123], s[6:7], v[82:83] op_sel_hi:[1,0,0]
	v_pk_fma_f32 v[72:73], v[120:121], s[6:7], v[82:83] op_sel_hi:[1,0,0]
	v_pk_fma_f32 v[70:71], v[118:119], s[6:7], v[82:83] op_sel_hi:[1,0,0]
	v_pk_fma_f32 v[68:69], v[116:117], s[6:7], v[82:83] op_sel_hi:[1,0,0]
	v_pk_fma_f32 v[96:97], v[112:113], s[6:7], v[82:83] op_sel_hi:[1,0,0]
	v_pk_fma_f32 v[94:95], v[110:111], s[6:7], v[82:83] op_sel_hi:[1,0,0]
	v_pk_fma_f32 v[92:93], v[108:109], s[6:7], v[82:83] op_sel_hi:[1,0,0]
	v_pk_fma_f32 v[90:91], v[106:107], s[6:7], v[82:83] op_sel_hi:[1,0,0]
	v_pk_fma_f32 v[82:83], v[98:99], s[6:7], v[82:83] op_sel_hi:[1,0,0]
	ds_read_b64_tr_b8 v[106:107], v190 offset:0x1800
	s_waitcnt lgkmcnt(4)
	v_cndmask_b32_e64 v98, v114, 1.0, vcc
	v_mfma_f32_32x32x64_f8f6f4 v[34:49], v[130:137], v[140:147], v[34:49]
	s_waitcnt lgkmcnt(0)
	v_permlane32_swap_b32_e32 v138, v139
	v_exp_f32_e32 v66, v66
	v_exp_f32_e32 v67, v67
	v_exp_f32_e32 v68, v68
	v_exp_f32_e32 v69, v69
	v_cmp_gt_f32_e32 vcc, 1.0, v98
	v_mfma_f32_32x32x64_f8f6f4 v[50:65], v[130:137], v[100:107], v[50:65]
	s_cbranch_vccz .LBB0_1897
	s_and_saveexec_b64 s[28:29], s[2:3]
	ds_write_b32 v191, v98 offset:128
	s_or_b64 exec, exec, s[28:29]
	s_waitcnt lgkmcnt(0)
	s_nop 15
	s_nop 7
	ds_read2_b32 v[100:101], v189 offset0:32 offset1:33
	ds_read2_b32 v[102:103], v189 offset0:34 offset1:35
	ds_read2_b32 v[104:105], v189 offset0:40 offset1:41
	ds_read2_b32 v[106:107], v189 offset0:42 offset1:43
	s_waitcnt lgkmcnt(0)
	v_pk_mul_f32 v[2:3], v[100:101], v[2:3]
	v_pk_mul_f32 v[18:19], v[100:101], v[18:19]
	v_pk_mul_f32 v[34:35], v[100:101], v[34:35]
	v_pk_mul_f32 v[50:51], v[100:101], v[50:51]
	v_pk_mul_f32 v[4:5], v[4:5], v[102:103]
	v_pk_mul_f32 v[20:21], v[20:21], v[102:103]
	v_pk_mul_f32 v[36:37], v[36:37], v[102:103]
	v_pk_mul_f32 v[52:53], v[52:53], v[102:103]
	v_pk_mul_f32 v[6:7], v[6:7], v[104:105]
	v_pk_mul_f32 v[22:23], v[22:23], v[104:105]
	v_pk_mul_f32 v[38:39], v[38:39], v[104:105]
	v_pk_mul_f32 v[54:55], v[54:55], v[104:105]
	v_pk_mul_f32 v[8:9], v[8:9], v[106:107]
	v_pk_mul_f32 v[24:25], v[24:25], v[106:107]
	v_pk_mul_f32 v[40:41], v[40:41], v[106:107]
	ds_read2_b32 v[100:101], v189 offset0:48 offset1:49
	v_pk_mul_f32 v[56:57], v[56:57], v[106:107]
	ds_read2_b32 v[102:103], v189 offset0:50 offset1:51
	ds_read2_b32 v[104:105], v189 offset0:56 offset1:57
	ds_read2_b32 v[106:107], v189 offset0:58 offset1:59
	s_waitcnt lgkmcnt(0)
	v_pk_mul_f32 v[10:11], v[10:11], v[100:101]
	v_pk_mul_f32 v[26:27], v[26:27], v[100:101]
	v_pk_mul_f32 v[42:43], v[42:43], v[100:101]
	v_pk_mul_f32 v[58:59], v[58:59], v[100:101]
	v_pk_mul_f32 v[12:13], v[12:13], v[102:103]
	v_pk_mul_f32 v[28:29], v[28:29], v[102:103]
	v_pk_mul_f32 v[44:45], v[44:45], v[102:103]
	v_pk_mul_f32 v[60:61], v[60:61], v[102:103]
	v_pk_mul_f32 v[14:15], v[14:15], v[104:105]
	v_pk_mul_f32 v[30:31], v[30:31], v[104:105]
	v_pk_mul_f32 v[46:47], v[46:47], v[104:105]
	v_pk_mul_f32 v[62:63], v[62:63], v[104:105]
	v_pk_mul_f32 v[16:17], v[16:17], v[106:107]
	v_pk_mul_f32 v[32:33], v[32:33], v[106:107]
	v_pk_mul_f32 v[48:49], v[48:49], v[106:107]
	v_pk_mul_f32 v[64:65], v[64:65], v[106:107]

.LBB0_1899:
	v_exp_f32_e32 v99, v70
	v_add_f32_e32 v70, 0, v66
	v_exp_f32_e32 v71, v71
	v_add_f32_e32 v70, v67, v70
	v_exp_f32_e32 v100, v72
	v_add_f32_e32 v70, v68, v70
	v_exp_f32_e32 v101, v73
	v_add_f32_e32 v70, v69, v70
	v_exp_f32_e32 v102, v74
	v_add_f32_e32 v70, v99, v70
	v_exp_f32_e32 v75, v75
	v_add_f32_e32 v70, v71, v70
	v_exp_f32_e32 v103, v76
	v_add_f32_e32 v70, v100, v70
	v_exp_f32_e32 v104, v77
	v_add_f32_e32 v70, v101, v70
	v_exp_f32_e32 v105, v78
	v_add_f32_e32 v70, v102, v70
	v_exp_f32_e32 v79, v79
	v_add_f32_e32 v70, v75, v70
	v_exp_f32_e32 v80, v80
	v_add_f32_e32 v70, v103, v70
	v_exp_f32_e32 v81, v81
	v_add_f32_e32 v70, v104, v70
	v_exp_f32_e32 v73, v82
	v_add_f32_e32 v70, v105, v70
	v_exp_f32_e32 v74, v83
	v_add_f32_e32 v70, v79, v70
	v_exp_f32_e32 v78, v84
	v_add_f32_e32 v70, v80, v70
	v_exp_f32_e32 v82, v85
	v_add_f32_e32 v70, v81, v70
	v_exp_f32_e32 v83, v86
	v_add_f32_e32 v70, v73, v70
	v_exp_f32_e32 v84, v87
	v_add_f32_e32 v70, v74, v70
	v_exp_f32_e32 v85, v88
	v_add_f32_e32 v70, v78, v70
	v_exp_f32_e32 v86, v89
	v_add_f32_e32 v70, v82, v70
	v_exp_f32_e32 v87, v90
	v_add_f32_e32 v70, v83, v70
	v_exp_f32_e32 v88, v91
	v_add_f32_e32 v70, v84, v70
	v_exp_f32_e32 v89, v92
	v_add_f32_e32 v70, v85, v70
	v_exp_f32_e32 v90, v93
	v_add_f32_e32 v70, v86, v70
	v_exp_f32_e32 v91, v94
	v_add_f32_e32 v70, v87, v70
	v_mov_b32_e32 v76, v163
	v_exp_f32_e32 v92, v95
	v_add_f32_e32 v70, v88, v70
	v_cvt_pk_fp8_f32 v76, v73, v74
	v_exp_f32_e32 v93, v96
	v_add_f32_e32 v70, v89, v70
	v_exp_f32_e32 v94, v97
	v_add_f32_e32 v70, v90, v70
	v_mov_b32_e32 v74, v163
	v_add_f32_e32 v70, v91, v70
	v_cvt_pk_fp8_f32 v74, v102, v75
	v_mov_b32_e32 v75, v163
	v_add_f32_e32 v70, v92, v70
	v_mov_b32_e32 v72, v163
	v_mov_b32_e32 v73, v163
	v_mov_b32_e32 v77, v163
	v_cvt_pk_fp8_f32 v76, v78, v82 op_sel:[0,0,1]
	v_mov_b32_e32 v78, v163
	v_cvt_pk_fp8_f32 v75, v105, v79
	v_mov_b32_e32 v79, v163
	v_add_f32_e32 v70, v93, v70
	v_cvt_pk_fp8_f32 v72, v66, v67
	v_cvt_pk_fp8_f32 v73, v99, v71
	v_cvt_pk_fp8_f32 v77, v83, v84
	v_cvt_pk_fp8_f32 v78, v87, v88
	v_cvt_pk_fp8_f32 v79, v91, v92
	v_add_f32_e32 v70, v94, v70
	v_mov_b32_e32 v66, v70
	s_nop 1
	v_permlane32_swap_b32_e32 v70, v66
	v_cvt_pk_fp8_f32 v72, v68, v69 op_sel:[0,0,1]
	v_cvt_pk_fp8_f32 v73, v100, v101 op_sel:[0,0,1]
	v_cvt_pk_fp8_f32 v77, v85, v86 op_sel:[0,0,1]
	v_cvt_pk_fp8_f32 v74, v103, v104 op_sel:[0,0,1]
	v_cvt_pk_fp8_f32 v78, v89, v90 op_sel:[0,0,1]
	v_cvt_pk_fp8_f32 v75, v80, v81 op_sel:[0,0,1]
	v_cvt_pk_fp8_f32 v79, v93, v94 op_sel:[0,0,1]
	ds_read_b64_tr_b8 v[80:81], v188 offset:0
	ds_read_b64_tr_b8 v[82:83], v188 offset:0x800
	ds_read_b64_tr_b8 v[84:85], v188 offset:0x1000
	ds_read_b64_tr_b8 v[86:87], v188 offset:0x1800
	s_waitcnt lgkmcnt(0)
	s_nop 0
	v_mfma_f32_32x32x64_f8f6f4 v[2:17], v[72:79], v[80:87], v[2:17]
	ds_read_b64_tr_b8 v[80:81], v187 offset:0
	ds_read_b64_tr_b8 v[82:83], v187 offset:0x800
	ds_read_b64_tr_b8 v[84:85], v187 offset:0x1000
	ds_read_b64_tr_b8 v[86:87], v187 offset:0x1800
	s_waitcnt lgkmcnt(0)
	s_nop 0
	v_mfma_f32_32x32x64_f8f6f4 v[18:33], v[72:79], v[80:87], v[18:33]
	ds_read_b64_tr_b8 v[80:81], v186 offset:0
	ds_read_b64_tr_b8 v[82:83], v186 offset:0x800
	ds_read_b64_tr_b8 v[84:85], v186 offset:0x1000
	ds_read_b64_tr_b8 v[86:87], v186 offset:0x1800
	s_waitcnt lgkmcnt(0)
	s_nop 0
	v_mfma_f32_32x32x64_f8f6f4 v[34:49], v[72:79], v[80:87], v[34:49]
	ds_read_b64_tr_b8 v[80:81], v185 offset:0
	ds_read_b64_tr_b8 v[82:83], v185 offset:0x800
	ds_read_b64_tr_b8 v[84:85], v185 offset:0x1000
	ds_read_b64_tr_b8 v[86:87], v185 offset:0x1800
	s_waitcnt lgkmcnt(0)
	s_nop 0
	v_mfma_f32_32x32x64_f8f6f4 v[50:65], v[72:79], v[80:87], v[50:65]
	s_nop 0
	s_nop 15
	s_nop 7
	s_nop 0
	v_and_b32_e32 v67, 31, v181
	v_cmp_gt_u32_e32 vcc, 32, v181
	s_and_saveexec_b64 s[2:3], vcc
	s_cbranch_execz .LBB0_1868
	v_add_f32_e32 v68, v138, v139
	v_fmac_f32_e32 v68, v162, v174
	v_add_f32_e32 v66, v70, v66
	v_fmac_f32_e32 v66, v68, v98
	v_lshl_add_u32 v68, v67, 2, s30
	ds_write_b32 v68, v66
	s_branch .LBB0_1868

.LBB0_1913:
	v_lshrrev_b32_e32 v5, 3, v37
	v_and_b32_e32 v54, 4, v5
	v_and_or_b32 v5, s17, 32, v36
	v_med3_i32 v6, v5, 8, 56
	v_sub_u32_e32 v133, v6, v54
	v_xad_u32 v198, v5, 63, v54
	v_and_b32_e32 v5, 8, v37
	v_bfe_u32 v6, v37, 1, 2
	v_or3_b32 v5, v6, v5, v54
	v_lshlrev_b32_e32 v6, 3, v37
	v_bfe_u32 v55, v37, 1, 3
	v_lshlrev_b32_e32 v5, 7, v5
	v_and_b32_e32 v6, 8, v6
	v_and_b32_e32 v56, 1, v4
	v_add3_u32 v57, v6, s67, v5
	v_bitop3_b32 v4, v4, v55, 1 bitop3:0x6c
	v_lshlrev_b32_e32 v46, 3, v36
	s_lshl_b32 s1, s14, 2
	s_ashr_i32 s33, s15, 7
	v_lshl_add_u32 v200, v4, 4, v57
	v_bitop3_b32 v4, v46, v2, s18 bitop3:0x6c
	v_lshl_add_u32 v47, v36, 7, s67
	s_add_i32 s7, s33, s1
	s_waitcnt lgkmcnt(0)
	v_add_u32_e32 v203, v47, v4
	v_or_b32_e32 v4, 16, v2
	v_med3_i32 v7, s7, 4, 28
	s_barrier
	v_bitop3_b32 v4, v46, v4, s18 bitop3:0x6c
	v_readfirstlane_b32 s74, v7
	v_add_u32_e32 v204, v47, v4
	ds_read_b128 v[4:7], v203 offset:32768
	ds_read_b128 v[38:41], v203 offset:36864
	ds_read_b128 v[8:11], v204 offset:32768
	ds_read_b128 v[42:45], v204 offset:36864
	v_bitop3_b32 v12, v56, v55, 2 bitop3:0x36
	v_lshl_add_u32 v202, v12, 4, v57
	v_bitop3_b32 v12, v56, v55, 4 bitop3:0x36
	v_lshl_add_u32 v199, v12, 4, v57
	s_waitcnt vmcnt(0) lgkmcnt(0)
	v_mfma_f32_32x32x64_f8f6f4 v[20:35], v[4:11], v[172:179], 0
	v_mfma_f32_32x32x64_f8f6f4 v[4:19], v[38:45], v[172:179], 0
	v_or_b32_e32 v38, 64, v2
	v_bitop3_b32 v38, v46, v38, s18 bitop3:0x6c
	v_or_b32_e32 v2, 0x50, v2
	v_add_u32_e32 v205, v47, v38
	v_bitop3_b32 v2, v46, v2, s18 bitop3:0x6c
	v_add_u32_e32 v206, v47, v2
	ds_read_b128 v[38:41], v205 offset:32768
	ds_read_b128 v[46:49], v205 offset:36864
	ds_read_b128 v[42:45], v206 offset:32768
	ds_read_b128 v[50:53], v206 offset:36864
	v_bitop3_b32 v2, v56, v55, 6 bitop3:0x36
	s_waitcnt lgkmcnt(1)
	v_mfma_f32_32x32x64_f8f6f4 v[20:35], v[38:45], v[164:171], v[20:35]
	s_waitcnt lgkmcnt(0)
	v_mfma_f32_32x32x64_f8f6f4 v[4:19], v[46:53], v[164:171], v[4:19]
	v_lshl_add_u32 v201, v2, 4, v57
	v_and_b32_e32 v189, 63, v37
	s_nop 15
	s_nop 7
	v_writelane_b32 v252, s17, 24
	v_max_f32_e32 v2, v21, v21
	v_max_f32_e32 v37, v20, v20
	v_max_f32_e32 v2, v37, v2
	v_max3_f32 v2, v2, v22, v23
	v_max3_f32 v2, v2, v24, v25
	v_max3_f32 v2, v2, v26, v27
	v_max3_f32 v2, v2, v28, v29
	v_max3_f32 v2, v2, v30, v31
	v_max3_f32 v2, v2, v32, v33
	v_max3_f32 v2, v2, v34, v35
	v_max3_f32 v2, v2, v4, v5
	v_writelane_b32 v252, s7, 25
	s_and_b32 s7, s16, 7
	v_max3_f32 v2, v2, v6, v7
	s_add_i32 s93, s74, -4
	s_lshl_b32 s70, s7, 2
	s_add_i32 s1, s1, -4
	v_max3_f32 v2, v2, v8, v9
	s_cmp_eq_u32 s14, 0
	v_max3_f32 v2, v2, v10, v11
	s_cselect_b64 s[8:9], -1, 0
	v_max3_f32 v2, v2, v12, v13
	v_writelane_b32 v252, s16, 23
	s_and_b64 s[16:17], s[8:9], exec
	v_max3_f32 v2, v2, v14, v15
	s_cselect_b32 s1, 0, s1
	s_cmp_eq_u32 s14, 7
	v_max3_f32 v2, v2, v16, v17
	s_cselect_b64 s[16:17], -1, 0
	v_max3_f32 v2, v2, v18, v19
	s_or_b64 s[8:9], s[8:9], s[16:17]
	v_mov_b32_e32 v37, v2
	s_and_b64 s[8:9], s[8:9], exec
	s_nop 0
	v_permlane32_swap_b32_e32 v2, v37
	s_cselect_b32 s78, 12, 16
	s_lshl_b32 s79, s1, 6
	v_max_f32_e32 v37, v37, v37
	v_max_f32_e32 v2, v2, v2
	s_add_i32 s79, s79, s6
	s_and_b32 s6, s15, 0x3fffffc0
	v_max_f32_e32 v2, v2, v37
	s_lshl_b32 s6, s6, 2
	v_add_f32_e32 v37, 0x7149f2ca, v2
	s_add_i32 s71, s71, s6
	v_cmp_ge_f32_e32 vcc, s92, v37
	s_cmp_eq_u64 vcc, exec
	v_max_f32_e32 v2, 0xf149f2ca, v2
	s_cselect_b64 vcc, -1, 0
	v_cndmask_b32_e32 v196, v2, v188, vcc
	s_mov_b32 s6, 0xbe0293ee
	s_add_u32 s2, s12, s2
	v_sub_f32_e32 v38, 0xf149f2ca, v2
	v_fma_f32 v2, v196, s6, 4.0
	s_addc_u32 s3, s13, s3
	s_add_i32 s76, s67, s10
	v_pk_fma_f32 v[100:101], v[4:5], s[80:81], v[2:3] op_sel_hi:[1,0,0]
	v_lshl_add_u64 v[4:5], s[2:3], 0, v[180:181]
	s_mov_b64 s[2:3], 0x420000
	s_add_i32 s95, s76, 0x4000
	v_lshl_add_u64 v[4:5], v[4:5], 0, s[2:3]
	s_mov_b32 m0, s95
	v_fmamk_f32 v20, v20, 0x3e0293ee, v2
	global_load_lds_dwordx4 v[4:5], off
	v_fmamk_f32 v21, v21, 0x3e0293ee, v2
	v_fmamk_f32 v22, v22, 0x3e0293ee, v2
	v_fmamk_f32 v23, v23, 0x3e0293ee, v2
	v_fmamk_f32 v24, v24, 0x3e0293ee, v2
	v_fmamk_f32 v25, v25, 0x3e0293ee, v2
	v_fmamk_f32 v26, v26, 0x3e0293ee, v2
	v_fmamk_f32 v27, v27, 0x3e0293ee, v2
	v_fmamk_f32 v28, v28, 0x3e0293ee, v2
	v_fmamk_f32 v29, v29, 0x3e0293ee, v2
	v_fmamk_f32 v30, v30, 0x3e0293ee, v2
	v_fmamk_f32 v31, v31, 0x3e0293ee, v2
	v_fmamk_f32 v32, v32, 0x3e0293ee, v2
	v_fmamk_f32 v33, v33, 0x3e0293ee, v2
	v_fmamk_f32 v34, v34, 0x3e0293ee, v2
	v_mov_b32_e32 v37, v2
	v_pk_fma_f32 v[114:115], v[18:19], s[80:81], v[2:3] op_sel_hi:[1,0,0]
	v_pk_fma_f32 v[112:113], v[16:17], s[80:81], v[2:3] op_sel_hi:[1,0,0]
	v_pk_fma_f32 v[110:111], v[14:15], s[80:81], v[2:3] op_sel_hi:[1,0,0]
	v_pk_fma_f32 v[108:109], v[12:13], s[80:81], v[2:3] op_sel_hi:[1,0,0]
	v_pk_fma_f32 v[106:107], v[10:11], s[80:81], v[2:3] op_sel_hi:[1,0,0]
	v_pk_fma_f32 v[104:105], v[8:9], s[80:81], v[2:3] op_sel_hi:[1,0,0]
	v_pk_fma_f32 v[102:103], v[6:7], s[80:81], v[2:3] op_sel_hi:[1,0,0]
	v_subrev_co_u32_e64 v2, s[68:69], 9, v133
	v_subrev_u32_e32 v7, 28, v133
	v_cmp_gt_u32_e64 s[36:37], 16, v2
	v_subrev_u32_e32 v2, 41, v133
	v_cmp_gt_u32_e64 s[54:55], 16, v7
	v_add_u32_e32 v7, -1, v133
	v_cmp_gt_u32_e64 s[34:35], 16, v2
	v_subrev_u32_e32 v2, 42, v133
	v_cmp_gt_u32_e64 s[52:53], 16, v7
	v_subrev_u32_e32 v7, 33, v133
	v_cmp_gt_u32_e64 s[28:29], 16, v2
	v_subrev_u32_e32 v2, 43, v133
	v_cmp_gt_u32_e64 s[50:51], 16, v7
	v_add_u32_e32 v7, -2, v133
	v_cmp_gt_u32_e64 s[24:25], 16, v2
	v_subrev_u32_e32 v2, 44, v133
	v_mul_f32_e32 v38, 0x3e0293ee, v38
	v_cmp_gt_u32_e64 s[48:49], 16, v7
	v_subrev_u32_e32 v7, 34, v133
	v_cmp_gt_u32_e64 s[20:21], 16, v2
	v_subrev_u32_e32 v2, 17, v133
	v_exp_f32_e32 v38, v38
	v_cmp_gt_u32_e64 s[46:47], 16, v7
	v_add_u32_e32 v7, -3, v133
	v_cmp_gt_u32_e64 s[18:19], 16, v2
	v_subrev_u32_e32 v2, 18, v133
	v_cmp_gt_u32_e64 s[44:45], 16, v7
	v_subrev_u32_e32 v7, 35, v133
	v_cmp_gt_u32_e64 s[14:15], 16, v2
	v_subrev_u32_e32 v2, 19, v133
	v_fmac_f32_e32 v37, 0x3e0293ee, v35
	v_subrev_u32_e32 v4, 25, v133
	v_subrev_u32_e32 v5, 26, v133
	v_subrev_u32_e32 v6, 27, v133
	v_cmp_gt_u32_e64 s[42:43], 16, v7
	v_add_u32_e32 v7, -4, v133
	v_cmp_gt_u32_e64 s[8:9], 16, v2
	v_subrev_u32_e32 v2, 20, v133
	v_exp_f32_e32 v116, v20
	v_exp_f32_e32 v117, v21
	v_exp_f32_e32 v118, v22
	v_exp_f32_e32 v119, v23
	v_exp_f32_e32 v120, v24
	v_exp_f32_e32 v121, v25
	v_exp_f32_e32 v122, v26
	v_exp_f32_e32 v123, v27
	v_exp_f32_e32 v124, v28
	v_exp_f32_e32 v125, v29
	v_exp_f32_e32 v126, v30
	v_exp_f32_e32 v127, v31
	v_exp_f32_e32 v128, v32
	v_exp_f32_e32 v129, v33
	v_exp_f32_e32 v130, v34
	v_exp_f32_e32 v131, v37
	s_waitcnt vmcnt(1)
	v_cmp_gt_u32_e64 s[66:67], 16, v4
	v_subrev_co_u32_e64 v4, s[64:65], 10, v133
	v_cmp_gt_u32_e64 s[62:63], 16, v5
	v_subrev_co_u32_e64 v5, s[60:61], 11, v133
	v_cmp_gt_u32_e64 s[58:59], 16, v6
	v_subrev_co_u32_e64 v6, s[56:57], 12, v133
	v_cmp_gt_u32_e64 s[40:41], 16, v7
	v_subrev_u32_e32 v7, 36, v133
	v_lshl_add_u64 v[184:185], s[4:5], 0, v[182:183]
	v_cmp_gt_u32_e64 s[4:5], 16, v2
	v_mov_b32_e32 v16, v3
	v_mov_b32_e32 v17, v3
	v_cndmask_b32_e64 v132, v38, 1.0, vcc
	s_barrier
	v_lshl_add_u32 v195, v36, 2, s71
	v_cmp_gt_u32_e64 s[38:39], 16, v7
	v_cmp_gt_u32_e64 s[30:31], 16, v4
	v_cmp_gt_u32_e64 s[26:27], 16, v5
	v_cmp_gt_u32_e64 s[22:23], 16, v6
	v_writelane_b32 v252, s4, 28
	v_lshl_add_u32 v194, v54, 2, s71
	v_mov_b32_e32 v2, v3
	v_mov_b32_e32 v4, v3
	v_mov_b32_e32 v5, v3
	v_mov_b32_e32 v6, v3
	v_mov_b32_e32 v7, v3
	v_mov_b32_e32 v8, v3
	v_mov_b32_e32 v9, v3
	v_mov_b32_e32 v10, v3
	v_mov_b32_e32 v11, v3
	v_mov_b32_e32 v12, v3
	v_mov_b32_e32 v13, v3
	v_mov_b32_e32 v14, v3
	v_mov_b32_e32 v15, v3
	v_mov_b64_e32 v[66:67], v[16:17]
	v_mov_b64_e32 v[50:51], v[16:17]
	v_mov_b64_e32 v[34:35], v[16:17]
	v_writelane_b32 v252, s5, 29
	s_sub_i32 s4, s1, s33
	v_mov_b64_e32 v[64:65], v[14:15]
	v_mov_b64_e32 v[62:63], v[12:13]
	v_mov_b64_e32 v[60:61], v[10:11]
	v_mov_b64_e32 v[58:59], v[8:9]
	v_mov_b64_e32 v[56:57], v[6:7]
	v_mov_b64_e32 v[54:55], v[4:5]
	v_mov_b64_e32 v[52:53], v[2:3]
	v_mov_b64_e32 v[48:49], v[14:15]
	v_mov_b64_e32 v[46:47], v[12:13]
	v_mov_b64_e32 v[44:45], v[10:11]
	v_mov_b64_e32 v[42:43], v[8:9]
	v_mov_b64_e32 v[40:41], v[6:7]
	v_mov_b64_e32 v[38:39], v[4:5]
	v_mov_b64_e32 v[36:37], v[2:3]
	v_mov_b64_e32 v[32:33], v[14:15]
	v_mov_b64_e32 v[30:31], v[12:13]
	v_mov_b64_e32 v[28:29], v[10:11]
	v_mov_b64_e32 v[26:27], v[8:9]
	v_mov_b64_e32 v[24:25], v[6:7]
	v_mov_b64_e32 v[22:23], v[4:5]
	v_mov_b64_e32 v[20:21], v[2:3]
	v_mov_b64_e32 v[18:19], v[16:17]
	s_mov_b32 s75, 2
	s_add_i32 s74, s74, 4
	v_cmp_gt_u32_e64 s[2:3], 32, v189
	v_cmp_lt_u32_e64 s[16:17], 48, v133
	v_cmp_lt_u32_e64 s[10:11], 49, v133
	v_cmp_lt_u32_e64 s[6:7], 50, v133
	v_lshl_add_u64 v[186:187], s[12:13], 0, v[180:181]
	v_add_u32_e32 v193, 0x4000, v200
	v_add_u32_e32 v192, 0x4000, v202
	v_add_u32_e32 v191, 0x4000, v199
	v_add_u32_e32 v190, 0x4000, v201
	v_lshl_add_u32 v207, v198, 2, s77
	s_sub_i32 s33, s4, s70
	v_mov_b32_e32 v197, 0
	s_movk_i32 s77, 0x80
	v_mov_b64_e32 v[16:17], v[14:15]
	v_mov_b64_e32 v[14:15], v[12:13]
	v_mov_b64_e32 v[12:13], v[10:11]
	v_mov_b64_e32 v[10:11], v[8:9]
	v_mov_b64_e32 v[8:9], v[6:7]
	v_mov_b64_e32 v[6:7], v[4:5]
	v_mov_b64_e32 v[4:5], v[2:3]
	v_cmp_lt_u32_e64 s[12:13], 51, v133
	v_writelane_b32 v252, s71, 30
	s_branch .LBB0_1916

.LBB0_1916:
	s_cmp_gt_u32 s75, 3
	s_cselect_b64 s[84:85], -1, 0
	s_add_i32 s4, s77, 0xffffff00
	s_cmp_lt_u32 s75, 4
	s_cselect_b64 s[72:73], -1, 0
	s_and_b64 s[70:71], s[72:73], exec
	s_cselect_b32 s5, s0, s79
	s_cselect_b32 s4, s77, s4
	s_ashr_i32 s71, s5, 31
	s_add_u32 s70, s4, s5
	s_addc_u32 s71, 0, s71
	s_lshl_b64 s[86:87], s[70:71], 11
	s_add_i32 s94, s76, 0x8000
	v_lshl_add_u64 v[134:135], v[184:185], 0, s[86:87]
	s_mov_b32 m0, s94
	s_add_i32 s82, s75, -1
	global_load_lds_dwordx4 v[134:135], off
	s_cmp_gt_u32 s82, 3
	s_cselect_b64 s[90:91], -1, 0
	s_cmp_lt_u32 s82, 4
	s_cselect_b64 s[70:71], -1, 0
	s_add_i32 s81, s1, s75
	s_add_i32 s4, s81, -5
	s_cmp_ge_i32 s4, s93
	s_cselect_b64 s[88:89], -1, 0
	s_cmp_lt_i32 s4, s74
	s_cselect_b64 vcc, -1, 0
	s_and_b64 s[88:89], s[88:89], vcc
	s_or_b64 vcc, s[70:71], s[88:89]
	v_cndmask_b32_e64 v2, 0, 1, vcc
	v_cmp_ne_u32_e64 s[70:71], 1, v2
	s_andn2_b64 vcc, exec, vcc
	s_cbranch_vccnz .LBB0_1918
	ds_read_b128 v[68:71], v203 offset:49152
	ds_read_b128 v[134:137], v203 offset:53248
	ds_read_b128 v[72:75], v204 offset:49152
	ds_read_b128 v[138:141], v204 offset:53248
	s_waitcnt lgkmcnt(0)
	v_mfma_f32_32x32x64_f8f6f4 v[84:99], v[68:75], v[172:179], 0
	v_mfma_f32_32x32x64_f8f6f4 v[68:83], v[134:141], v[172:179], 0
	ds_read_b128 v[134:137], v205 offset:49152
	ds_read_b128 v[142:145], v205 offset:53248
	ds_read_b128 v[138:141], v206 offset:49152
	ds_read_b128 v[146:149], v206 offset:53248
	s_waitcnt lgkmcnt(0)
	v_mfma_f32_32x32x64_f8f6f4 v[84:99], v[134:141], v[164:171], v[84:99]
	v_mfma_f32_32x32x64_f8f6f4 v[68:83], v[142:149], v[164:171], v[68:83]
	s_nop 0
	s_nop 15
	s_nop 7
.LBB0_1918:
	s_cmp_lt_u32 s82, 5
	s_cselect_b64 vcc, -1, 0
	s_add_i32 s4, s81, -6
	s_cmp_ge_i32 s4, s93
	s_cselect_b64 s[96:97], -1, 0
	s_cmp_lt_i32 s4, s74
	s_cselect_b64 s[4:5], -1, 0
	s_and_b64 s[4:5], s[96:97], s[4:5]
	s_or_b64 s[4:5], vcc, s[4:5]
	s_andn2_b64 vcc, exec, s[4:5]
	s_cbranch_vccnz .LBB0_1920
	v_add_f32_e32 v2, 0, v116
	v_add_f32_e32 v2, v117, v2
	v_add_f32_e32 v2, v118, v2
	v_add_f32_e32 v2, v119, v2
	v_add_f32_e32 v2, v120, v2
	v_add_f32_e32 v2, v121, v2
	v_add_f32_e32 v2, v122, v2
	v_add_f32_e32 v2, v123, v2
	v_add_f32_e32 v2, v124, v2
	v_add_f32_e32 v2, v125, v2
	v_add_f32_e32 v2, v126, v2
	v_add_f32_e32 v2, v127, v2
	v_exp_f32_e32 v100, v100
	v_add_f32_e32 v2, v128, v2
	v_exp_f32_e32 v101, v101
	v_add_f32_e32 v2, v129, v2
	v_exp_f32_e32 v102, v102
	v_add_f32_e32 v2, v130, v2
	v_exp_f32_e32 v103, v103
	v_add_f32_e32 v2, v131, v2
	v_exp_f32_e32 v104, v104
	v_add_f32_e32 v2, v100, v2
	v_exp_f32_e32 v105, v105
	v_add_f32_e32 v2, v101, v2
	v_exp_f32_e32 v106, v106
	v_add_f32_e32 v2, v102, v2
	v_exp_f32_e32 v107, v107
	v_add_f32_e32 v2, v103, v2
	v_exp_f32_e32 v108, v108
	v_add_f32_e32 v2, v104, v2
	v_exp_f32_e32 v109, v109
	v_add_f32_e32 v2, v105, v2
	v_exp_f32_e32 v110, v110
	v_add_f32_e32 v2, v106, v2
	v_exp_f32_e32 v111, v111
	v_add_f32_e32 v2, v107, v2
	v_exp_f32_e32 v112, v112
	v_add_f32_e32 v2, v108, v2
	v_exp_f32_e32 v113, v113
	v_add_f32_e32 v2, v109, v2
	v_exp_f32_e32 v114, v114
	v_add_f32_e32 v2, v110, v2
	v_exp_f32_e32 v115, v115
	v_add_f32_e32 v2, v111, v2
	v_add_f32_e32 v2, v112, v2
	v_add_f32_e32 v2, v113, v2
	v_add_f32_e32 v2, v114, v2
	v_add_f32_e32 v2, v115, v2
	v_mov_b32_e32 v133, v2
	s_nop 1
	v_permlane32_swap_b32_e32 v2, v133
	v_add_f32_e32 v2, v2, v133
	v_fmac_f32_e32 v2, v197, v132
	v_mov_b32_e32 v132, 0
	v_mov_b32_e32 v136, 0
	v_mov_b32_e32 v133, 0
	v_mov_b32_e32 v137, 0
	v_mov_b32_e32 v134, 0
	v_mov_b32_e32 v138, 0
	v_mov_b32_e32 v135, 0
	v_mov_b32_e32 v139, 0
	v_cvt_pk_fp8_f32 v132, v116, v117
	v_cvt_pk_fp8_f32 v136, v100, v101
	v_cvt_pk_fp8_f32 v133, v120, v121
	v_cvt_pk_fp8_f32 v137, v104, v105
	v_cvt_pk_fp8_f32 v134, v124, v125
	v_cvt_pk_fp8_f32 v138, v108, v109
	v_cvt_pk_fp8_f32 v135, v128, v129
	v_cvt_pk_fp8_f32 v139, v112, v113
	v_cvt_pk_fp8_f32 v132, v118, v119 op_sel:[0,0,1]
	v_cvt_pk_fp8_f32 v136, v102, v103 op_sel:[0,0,1]
	v_cvt_pk_fp8_f32 v133, v122, v123 op_sel:[0,0,1]
	v_cvt_pk_fp8_f32 v137, v106, v107 op_sel:[0,0,1]
	v_cvt_pk_fp8_f32 v134, v126, v127 op_sel:[0,0,1]
	v_cvt_pk_fp8_f32 v138, v110, v111 op_sel:[0,0,1]
	v_cvt_pk_fp8_f32 v135, v130, v131 op_sel:[0,0,1]
	v_cvt_pk_fp8_f32 v139, v114, v115 op_sel:[0,0,1]
	ds_read_b64_tr_b8 v[140:141], v200 offset:0
	ds_read_b64_tr_b8 v[142:143], v200 offset:0x800
	ds_read_b64_tr_b8 v[144:145], v200 offset:0x1000
	ds_read_b64_tr_b8 v[146:147], v200 offset:0x1800
	s_waitcnt lgkmcnt(0)
	s_nop 0
	v_mfma_f32_32x32x64_f8f6f4 v[52:67], v[132:139], v[140:147], v[52:67]
	ds_read_b64_tr_b8 v[140:141], v202 offset:0
	ds_read_b64_tr_b8 v[142:143], v202 offset:0x800
	ds_read_b64_tr_b8 v[144:145], v202 offset:0x1000
	ds_read_b64_tr_b8 v[146:147], v202 offset:0x1800
	s_waitcnt lgkmcnt(0)
	s_nop 0
	v_mfma_f32_32x32x64_f8f6f4 v[36:51], v[132:139], v[140:147], v[36:51]
	ds_read_b64_tr_b8 v[140:141], v199 offset:0
	ds_read_b64_tr_b8 v[142:143], v199 offset:0x800
	ds_read_b64_tr_b8 v[144:145], v199 offset:0x1000
	ds_read_b64_tr_b8 v[146:147], v199 offset:0x1800
	s_waitcnt lgkmcnt(0)
	s_nop 0
	v_mfma_f32_32x32x64_f8f6f4 v[20:35], v[132:139], v[140:147], v[20:35]
	ds_read_b64_tr_b8 v[140:141], v201 offset:0
	ds_read_b64_tr_b8 v[142:143], v201 offset:0x800
	ds_read_b64_tr_b8 v[144:145], v201 offset:0x1000
	ds_read_b64_tr_b8 v[146:147], v201 offset:0x1800
	s_waitcnt lgkmcnt(0)
	s_nop 0
	v_mfma_f32_32x32x64_f8f6f4 v[4:19], v[132:139], v[140:147], v[4:19]
	v_mov_b32_e32 v197, v2
	s_nop 15
	s_nop 7

.LBB0_1992:
	s_add_i32 s4, s82, 2
	s_add_i32 s83, s82, -2
	s_cmp_lt_u32 s82, 2
	s_cselect_b32 s4, s4, s83
	s_cselect_b32 s5, s0, s79
	s_ashr_i32 s82, s5, 31
	s_lshl_b32 s4, s4, 6
	s_add_u32 s4, s4, s5
	s_addc_u32 s5, 0, s82
	s_waitcnt vmcnt(1)
	s_lshl_b64 s[86:87], s[4:5], 11
	s_add_i32 s90, s76, 0xc000
	s_barrier
	v_lshl_add_u64 v[132:133], v[184:185], 0, s[86:87]
	s_mov_b32 m0, s90
	s_add_i32 s81, s81, -4
	global_load_lds_dwordx4 v[132:133], off
	s_cmp_ge_i32 s81, s93
	s_cselect_b64 s[4:5], -1, 0
	s_cmp_lt_i32 s81, s74
	s_cselect_b64 s[88:89], -1, 0
	s_and_b64 s[88:89], s[4:5], s[88:89]
	s_or_b64 s[4:5], s[72:73], s[88:89]
	v_cndmask_b32_e64 v132, 0, 1, s[4:5]
	v_cmp_ne_u32_e64 s[72:73], 1, v132
	s_andn2_b64 vcc, exec, s[4:5]
	s_cbranch_vccnz .LBB0_1995
	ds_read_b128 v[100:103], v203 offset:32768
	ds_read_b128 v[132:135], v203 offset:36864
	ds_read_b128 v[104:107], v204 offset:32768
	ds_read_b128 v[136:139], v204 offset:36864
	s_waitcnt lgkmcnt(0)
	v_mfma_f32_32x32x64_f8f6f4 v[116:131], v[100:107], v[172:179], 0
	v_mfma_f32_32x32x64_f8f6f4 v[100:115], v[132:139], v[172:179], 0
	ds_read_b128 v[132:135], v205 offset:32768
	ds_read_b128 v[140:143], v205 offset:36864
	ds_read_b128 v[136:139], v206 offset:32768
	ds_read_b128 v[144:147], v206 offset:36864
	s_waitcnt lgkmcnt(0)
	v_mfma_f32_32x32x64_f8f6f4 v[116:131], v[132:139], v[164:171], v[116:131]
	v_mfma_f32_32x32x64_f8f6f4 v[100:115], v[140:147], v[164:171], v[100:115]
	s_nop 0
	s_nop 15
	s_nop 7
	s_and_b64 vcc, exec, s[70:71]
	s_cbranch_vccz .LBB0_1996

.LBB0_1996:
	v_add_f32_e32 v132, 0, v84
	v_add_f32_e32 v132, v85, v132
	v_add_f32_e32 v132, v86, v132
	v_add_f32_e32 v132, v87, v132
	v_add_f32_e32 v132, v88, v132
	v_add_f32_e32 v132, v89, v132
	v_add_f32_e32 v132, v90, v132
	v_add_f32_e32 v132, v91, v132
	v_add_f32_e32 v132, v92, v132
	v_add_f32_e32 v132, v93, v132
	v_add_f32_e32 v132, v94, v132
	v_add_f32_e32 v132, v95, v132
	v_exp_f32_e32 v68, v68
	v_add_f32_e32 v132, v96, v132
	v_exp_f32_e32 v69, v69
	v_add_f32_e32 v132, v97, v132
	v_exp_f32_e32 v70, v70
	v_add_f32_e32 v132, v98, v132
	v_exp_f32_e32 v71, v71
	v_add_f32_e32 v132, v99, v132
	v_exp_f32_e32 v72, v72
	v_add_f32_e32 v132, v68, v132
	v_exp_f32_e32 v73, v73
	v_add_f32_e32 v132, v69, v132
	v_exp_f32_e32 v74, v74
	v_add_f32_e32 v132, v70, v132
	v_exp_f32_e32 v75, v75
	v_add_f32_e32 v132, v71, v132
	v_exp_f32_e32 v76, v76
	v_add_f32_e32 v132, v72, v132
	v_exp_f32_e32 v77, v77
	v_add_f32_e32 v132, v73, v132
	v_exp_f32_e32 v78, v78
	v_add_f32_e32 v132, v74, v132
	v_exp_f32_e32 v79, v79
	v_add_f32_e32 v132, v75, v132
	v_exp_f32_e32 v80, v80
	v_add_f32_e32 v132, v76, v132
	v_exp_f32_e32 v81, v81
	v_add_f32_e32 v132, v77, v132
	v_exp_f32_e32 v82, v82
	v_add_f32_e32 v132, v78, v132
	v_exp_f32_e32 v83, v83
	v_add_f32_e32 v132, v79, v132
	v_add_f32_e32 v132, v80, v132
	v_add_f32_e32 v132, v81, v132
	v_add_f32_e32 v132, v82, v132
	v_add_f32_e32 v132, v83, v132
	v_mov_b32_e32 v133, v132
	s_nop 1
	v_permlane32_swap_b32_e32 v132, v133
	v_add_f32_e32 v148, v132, v133
	v_mov_b32_e32 v132, 0
	v_mov_b32_e32 v136, 0
	v_mov_b32_e32 v133, 0
	v_mov_b32_e32 v137, 0
	v_mov_b32_e32 v134, 0
	v_mov_b32_e32 v138, 0
	v_mov_b32_e32 v135, 0
	v_mov_b32_e32 v139, 0
	v_cvt_pk_fp8_f32 v132, v84, v85
	v_cvt_pk_fp8_f32 v136, v68, v69
	v_cvt_pk_fp8_f32 v133, v88, v89
	v_cvt_pk_fp8_f32 v137, v72, v73
	v_cvt_pk_fp8_f32 v134, v92, v93
	v_cvt_pk_fp8_f32 v138, v76, v77
	v_cvt_pk_fp8_f32 v135, v96, v97
	v_cvt_pk_fp8_f32 v139, v80, v81
	v_fmac_f32_e32 v148, v197, v2
	v_cvt_pk_fp8_f32 v132, v86, v87 op_sel:[0,0,1]
	v_cvt_pk_fp8_f32 v136, v70, v71 op_sel:[0,0,1]
	v_cvt_pk_fp8_f32 v133, v90, v91 op_sel:[0,0,1]
	v_cvt_pk_fp8_f32 v137, v74, v75 op_sel:[0,0,1]
	v_cvt_pk_fp8_f32 v134, v94, v95 op_sel:[0,0,1]
	v_cvt_pk_fp8_f32 v138, v78, v79 op_sel:[0,0,1]
	v_cvt_pk_fp8_f32 v135, v98, v99 op_sel:[0,0,1]
	v_cvt_pk_fp8_f32 v139, v82, v83 op_sel:[0,0,1]
	ds_read_b64_tr_b8 v[140:141], v193 offset:0
	ds_read_b64_tr_b8 v[142:143], v193 offset:0x800
	ds_read_b64_tr_b8 v[144:145], v193 offset:0x1000
	ds_read_b64_tr_b8 v[146:147], v193 offset:0x1800
	s_waitcnt lgkmcnt(0)
	s_nop 0
	v_mfma_f32_32x32x64_f8f6f4 v[52:67], v[132:139], v[140:147], v[52:67]
	ds_read_b64_tr_b8 v[140:141], v192 offset:0
	ds_read_b64_tr_b8 v[142:143], v192 offset:0x800
	ds_read_b64_tr_b8 v[144:145], v192 offset:0x1000
	ds_read_b64_tr_b8 v[146:147], v192 offset:0x1800
	s_waitcnt lgkmcnt(0)
	s_nop 0
	v_mfma_f32_32x32x64_f8f6f4 v[36:51], v[132:139], v[140:147], v[36:51]
	ds_read_b64_tr_b8 v[140:141], v191 offset:0
	ds_read_b64_tr_b8 v[142:143], v191 offset:0x800
	ds_read_b64_tr_b8 v[144:145], v191 offset:0x1000
	ds_read_b64_tr_b8 v[146:147], v191 offset:0x1800
	s_waitcnt lgkmcnt(0)
	s_nop 0
	v_mfma_f32_32x32x64_f8f6f4 v[20:35], v[132:139], v[140:147], v[20:35]
	ds_read_b64_tr_b8 v[140:141], v190 offset:0
	ds_read_b64_tr_b8 v[142:143], v190 offset:0x800
	ds_read_b64_tr_b8 v[144:145], v190 offset:0x1000
	ds_read_b64_tr_b8 v[146:147], v190 offset:0x1800
	s_waitcnt lgkmcnt(0)
	s_nop 0
	v_mfma_f32_32x32x64_f8f6f4 v[4:19], v[132:139], v[140:147], v[4:19]
	v_mov_b32_e32 v197, v148
	s_nop 15
	s_nop 7
	s_and_b64 vcc, exec, s[72:73]
	v_mov_b32_e32 v132, 1.0
	s_cbranch_vccnz .LBB0_2064

.LBB0_2067:
	s_add_i32 s70, s1, s78
	s_add_i32 s33, s70, -5
	s_cmp_ge_i32 s33, s93
	s_cselect_b64 s[0:1], -1, 0
	s_cmp_lt_i32 s33, s74
	s_cselect_b64 s[72:73], -1, 0
	s_and_b64 s[0:1], s[0:1], s[72:73]
	s_and_b64 vcc, exec, s[0:1]
	s_cbranch_vccz .LBB0_2069
	ds_read_b128 v[68:71], v203 offset:49152
	ds_read_b128 v[134:137], v203 offset:53248
	ds_read_b128 v[72:75], v204 offset:49152
	ds_read_b128 v[138:141], v204 offset:53248
	s_waitcnt lgkmcnt(0)
	v_mfma_f32_32x32x64_f8f6f4 v[84:99], v[68:75], v[172:179], 0
	v_mfma_f32_32x32x64_f8f6f4 v[68:83], v[134:141], v[172:179], 0
	ds_read_b128 v[134:137], v205 offset:49152
	ds_read_b128 v[142:145], v205 offset:53248
	ds_read_b128 v[138:141], v206 offset:49152
	ds_read_b128 v[146:149], v206 offset:53248
	s_waitcnt lgkmcnt(0)
	v_mfma_f32_32x32x64_f8f6f4 v[84:99], v[134:141], v[164:171], v[84:99]
	v_mfma_f32_32x32x64_f8f6f4 v[68:83], v[142:149], v[164:171], v[68:83]
	s_nop 0
	s_nop 15
	s_nop 7
.LBB0_2069:
	s_add_i32 s70, s70, -6
	s_cmp_ge_i32 s70, s93
	s_cselect_b64 s[4:5], -1, 0
	s_cmp_lt_i32 s70, s74
	s_cselect_b64 s[70:71], -1, 0
	s_and_b64 s[4:5], s[4:5], s[70:71]
	s_andn2_b64 vcc, exec, s[4:5]
	v_readlane_b32 s87, v252, 7
	v_readlane_b32 s88, v252, 8
	v_readlane_b32 s72, v252, 19
	v_readlane_b32 s73, v252, 26
	v_readlane_b32 s77, v252, 14
	s_cbranch_vccnz .LBB0_2071
	v_exp_f32_e32 v2, v100
	v_add_f32_e32 v100, 0, v116
	v_add_f32_e32 v100, v117, v100
	v_add_f32_e32 v100, v118, v100
	v_add_f32_e32 v100, v119, v100
	v_add_f32_e32 v100, v120, v100
	v_add_f32_e32 v100, v121, v100
	v_add_f32_e32 v100, v122, v100
	v_add_f32_e32 v100, v123, v100
	v_add_f32_e32 v100, v124, v100
	v_add_f32_e32 v100, v125, v100
	v_add_f32_e32 v100, v126, v100
	v_add_f32_e32 v100, v127, v100
	v_add_f32_e32 v100, v128, v100
	v_exp_f32_e32 v101, v101
	v_add_f32_e32 v100, v129, v100
	v_exp_f32_e32 v102, v102
	v_add_f32_e32 v100, v130, v100
	v_exp_f32_e32 v103, v103
	v_add_f32_e32 v100, v131, v100
	v_exp_f32_e32 v133, v104
	v_add_f32_e32 v100, v2, v100
	v_exp_f32_e32 v134, v105
	v_add_f32_e32 v100, v101, v100
	v_exp_f32_e32 v106, v106
	v_add_f32_e32 v100, v102, v100
	v_exp_f32_e32 v107, v107
	v_add_f32_e32 v100, v103, v100
	v_exp_f32_e32 v108, v108
	v_add_f32_e32 v100, v133, v100
	v_exp_f32_e32 v109, v109
	v_add_f32_e32 v100, v134, v100
	v_exp_f32_e32 v110, v110
	v_add_f32_e32 v100, v106, v100
	v_exp_f32_e32 v111, v111
	v_add_f32_e32 v100, v107, v100
	v_exp_f32_e32 v112, v112
	v_add_f32_e32 v100, v108, v100
	v_exp_f32_e32 v113, v113
	v_add_f32_e32 v100, v109, v100
	v_exp_f32_e32 v114, v114
	v_add_f32_e32 v100, v110, v100
	v_mov_b32_e32 v104, v3
	v_mov_b32_e32 v105, v3
	v_exp_f32_e32 v115, v115
	v_add_f32_e32 v100, v111, v100
	v_cvt_pk_fp8_f32 v104, v2, v101
	v_cvt_pk_fp8_f32 v105, v133, v134
	v_add_f32_e32 v100, v112, v100
	v_add_f32_e32 v100, v113, v100
	v_add_f32_e32 v100, v114, v100
	v_add_f32_e32 v135, v115, v100
	v_mov_b32_e32 v100, v3
	v_mov_b32_e32 v101, v3
	v_cvt_pk_fp8_f32 v104, v102, v103 op_sel:[0,0,1]
	v_cvt_pk_fp8_f32 v105, v106, v107 op_sel:[0,0,1]
	v_mov_b32_e32 v102, v3
	v_mov_b32_e32 v106, v3
	v_mov_b32_e32 v103, v3
	v_mov_b32_e32 v107, v3
	v_cvt_pk_fp8_f32 v100, v116, v117
	v_cvt_pk_fp8_f32 v101, v120, v121
	v_cvt_pk_fp8_f32 v102, v124, v125
	v_cvt_pk_fp8_f32 v106, v108, v109
	v_cvt_pk_fp8_f32 v103, v128, v129
	v_cvt_pk_fp8_f32 v107, v112, v113
	v_mov_b32_e32 v136, v135
	s_nop 1
	v_permlane32_swap_b32_e32 v135, v136
	v_add_f32_e32 v2, v135, v136
	v_cvt_pk_fp8_f32 v100, v118, v119 op_sel:[0,0,1]
	v_cvt_pk_fp8_f32 v101, v122, v123 op_sel:[0,0,1]
	v_cvt_pk_fp8_f32 v102, v126, v127 op_sel:[0,0,1]
	v_cvt_pk_fp8_f32 v106, v110, v111 op_sel:[0,0,1]
	v_cvt_pk_fp8_f32 v103, v130, v131 op_sel:[0,0,1]
	v_cvt_pk_fp8_f32 v107, v114, v115 op_sel:[0,0,1]
	v_fmac_f32_e32 v2, v197, v132
	ds_read_b64_tr_b8 v[108:109], v200 offset:0
	ds_read_b64_tr_b8 v[110:111], v200 offset:0x800
	ds_read_b64_tr_b8 v[112:113], v200 offset:0x1000
	ds_read_b64_tr_b8 v[114:115], v200 offset:0x1800
	s_waitcnt lgkmcnt(0)
	s_nop 0
	v_mfma_f32_32x32x64_f8f6f4 v[52:67], v[100:107], v[108:115], v[52:67]
	ds_read_b64_tr_b8 v[108:109], v202 offset:0
	ds_read_b64_tr_b8 v[110:111], v202 offset:0x800
	ds_read_b64_tr_b8 v[112:113], v202 offset:0x1000
	ds_read_b64_tr_b8 v[114:115], v202 offset:0x1800
	s_waitcnt lgkmcnt(0)
	s_nop 0
	v_mfma_f32_32x32x64_f8f6f4 v[36:51], v[100:107], v[108:115], v[36:51]
	ds_read_b64_tr_b8 v[108:109], v199 offset:0
	ds_read_b64_tr_b8 v[110:111], v199 offset:0x800
	ds_read_b64_tr_b8 v[112:113], v199 offset:0x1000
	ds_read_b64_tr_b8 v[114:115], v199 offset:0x1800
	s_waitcnt lgkmcnt(0)
	s_nop 0
	v_mfma_f32_32x32x64_f8f6f4 v[20:35], v[100:107], v[108:115], v[20:35]
	ds_read_b64_tr_b8 v[108:109], v201 offset:0
	ds_read_b64_tr_b8 v[110:111], v201 offset:0x800
	ds_read_b64_tr_b8 v[112:113], v201 offset:0x1000
	ds_read_b64_tr_b8 v[114:115], v201 offset:0x1800
	s_waitcnt lgkmcnt(0)
	s_nop 0
	v_mfma_f32_32x32x64_f8f6f4 v[4:19], v[100:107], v[108:115], v[4:19]
	v_mov_b32_e32 v197, v2
	s_nop 15
	s_nop 7

.LBB0_2143:
	s_and_b64 vcc, exec, s[70:71]
	s_cbranch_vccnz .LBB0_2145
	v_exp_f32_e32 v100, v68
	v_add_f32_e32 v68, 0, v84
	v_add_f32_e32 v68, v85, v68
	v_add_f32_e32 v68, v86, v68
	v_add_f32_e32 v68, v87, v68
	v_add_f32_e32 v68, v88, v68
	v_add_f32_e32 v68, v89, v68
	v_add_f32_e32 v68, v90, v68
	v_add_f32_e32 v68, v91, v68
	v_add_f32_e32 v68, v92, v68
	v_add_f32_e32 v68, v93, v68
	v_add_f32_e32 v68, v94, v68
	v_add_f32_e32 v68, v95, v68
	v_add_f32_e32 v68, v96, v68
	v_exp_f32_e32 v69, v69
	v_add_f32_e32 v68, v97, v68
	v_exp_f32_e32 v70, v70
	v_add_f32_e32 v68, v98, v68
	v_exp_f32_e32 v71, v71
	v_add_f32_e32 v68, v99, v68
	v_exp_f32_e32 v101, v72
	v_add_f32_e32 v68, v100, v68
	v_exp_f32_e32 v102, v73
	v_add_f32_e32 v68, v69, v68
	v_exp_f32_e32 v74, v74
	v_add_f32_e32 v68, v70, v68
	v_exp_f32_e32 v75, v75
	v_add_f32_e32 v68, v71, v68
	v_exp_f32_e32 v76, v76
	v_add_f32_e32 v68, v101, v68
	v_exp_f32_e32 v77, v77
	v_add_f32_e32 v68, v102, v68
	v_exp_f32_e32 v78, v78
	v_add_f32_e32 v68, v74, v68
	v_exp_f32_e32 v79, v79
	v_add_f32_e32 v68, v75, v68
	v_exp_f32_e32 v80, v80
	v_add_f32_e32 v68, v76, v68
	v_exp_f32_e32 v81, v81
	v_add_f32_e32 v68, v77, v68
	v_exp_f32_e32 v82, v82
	v_add_f32_e32 v68, v78, v68
	v_mov_b32_e32 v72, v3
	v_mov_b32_e32 v73, v3
	v_exp_f32_e32 v83, v83
	v_add_f32_e32 v68, v79, v68
	v_cvt_pk_fp8_f32 v72, v100, v69
	v_cvt_pk_fp8_f32 v73, v101, v102
	v_add_f32_e32 v68, v80, v68
	v_add_f32_e32 v68, v81, v68
	v_add_f32_e32 v68, v82, v68
	v_add_f32_e32 v103, v83, v68
	v_mov_b32_e32 v68, v3
	v_mov_b32_e32 v69, v3
	v_cvt_pk_fp8_f32 v72, v70, v71 op_sel:[0,0,1]
	v_cvt_pk_fp8_f32 v73, v74, v75 op_sel:[0,0,1]
	v_mov_b32_e32 v70, v3
	v_mov_b32_e32 v74, v3
	v_mov_b32_e32 v71, v3
	v_mov_b32_e32 v75, v3
	v_cvt_pk_fp8_f32 v68, v84, v85
	v_cvt_pk_fp8_f32 v69, v88, v89
	v_cvt_pk_fp8_f32 v70, v92, v93
	v_cvt_pk_fp8_f32 v74, v76, v77
	v_cvt_pk_fp8_f32 v71, v96, v97
	v_cvt_pk_fp8_f32 v75, v80, v81
	v_mov_b32_e32 v104, v103
	s_nop 1
	v_permlane32_swap_b32_e32 v103, v104
	v_add_f32_e32 v84, v103, v104
	v_cvt_pk_fp8_f32 v68, v86, v87 op_sel:[0,0,1]
	v_cvt_pk_fp8_f32 v69, v90, v91 op_sel:[0,0,1]
	v_cvt_pk_fp8_f32 v70, v94, v95 op_sel:[0,0,1]
	v_cvt_pk_fp8_f32 v74, v78, v79 op_sel:[0,0,1]
	v_cvt_pk_fp8_f32 v71, v98, v99 op_sel:[0,0,1]
	v_cvt_pk_fp8_f32 v75, v82, v83 op_sel:[0,0,1]
	v_fmac_f32_e32 v84, v197, v2
	ds_read_b64_tr_b8 v[76:77], v193 offset:0
	ds_read_b64_tr_b8 v[78:79], v193 offset:0x800
	ds_read_b64_tr_b8 v[80:81], v193 offset:0x1000
	ds_read_b64_tr_b8 v[82:83], v193 offset:0x1800
	s_waitcnt lgkmcnt(0)
	s_nop 0
	v_mfma_f32_32x32x64_f8f6f4 v[52:67], v[68:75], v[76:83], v[52:67]
	ds_read_b64_tr_b8 v[76:77], v192 offset:0
	ds_read_b64_tr_b8 v[78:79], v192 offset:0x800
	ds_read_b64_tr_b8 v[80:81], v192 offset:0x1000
	ds_read_b64_tr_b8 v[82:83], v192 offset:0x1800
	s_waitcnt lgkmcnt(0)
	s_nop 0
	v_mfma_f32_32x32x64_f8f6f4 v[36:51], v[68:75], v[76:83], v[36:51]
	ds_read_b64_tr_b8 v[76:77], v191 offset:0
	ds_read_b64_tr_b8 v[78:79], v191 offset:0x800
	ds_read_b64_tr_b8 v[80:81], v191 offset:0x1000
	ds_read_b64_tr_b8 v[82:83], v191 offset:0x1800
	s_waitcnt lgkmcnt(0)
	s_nop 0
	v_mfma_f32_32x32x64_f8f6f4 v[20:35], v[68:75], v[76:83], v[20:35]
	ds_read_b64_tr_b8 v[76:77], v190 offset:0
	ds_read_b64_tr_b8 v[78:79], v190 offset:0x800
	ds_read_b64_tr_b8 v[80:81], v190 offset:0x1000
	ds_read_b64_tr_b8 v[82:83], v190 offset:0x1800
	s_waitcnt lgkmcnt(0)
	s_nop 0
	v_mfma_f32_32x32x64_f8f6f4 v[4:19], v[68:75], v[76:83], v[4:19]
	v_mov_b32_e32 v197, v84
	s_nop 15
	s_nop 7

.LBB0_2224:
	s_waitcnt lgkmcnt(0)
	s_barrier
	s_setprio 1
	s_waitcnt lgkmcnt(0)
	v_mfma_f32_16x16x128_f8f6f4 v[126:129], v[26:33], v[58:65], v[126:129]
	v_mfma_f32_16x16x128_f8f6f4 v[122:125], v[18:25], v[58:65], v[122:125]
	v_mfma_f32_16x16x128_f8f6f4 v[110:113], v[26:33], v[50:57], v[110:113]
	v_mfma_f32_16x16x128_f8f6f4 v[106:109], v[18:25], v[50:57], v[106:109]
	v_mfma_f32_16x16x128_f8f6f4 v[94:97], v[26:33], v[42:49], v[94:97]
	v_mfma_f32_16x16x128_f8f6f4 v[90:93], v[18:25], v[42:49], v[90:93]
	v_mfma_f32_16x16x128_f8f6f4 v[78:81], v[26:33], v[34:41], v[78:81]
	v_mfma_f32_16x16x128_f8f6f4 v[74:77], v[18:25], v[34:41], v[74:77]
	s_setprio 0
	s_setprio 1
	v_mfma_f32_16x16x128_f8f6f4 v[118:121], v[10:17], v[58:65], v[118:121]
	v_mfma_f32_16x16x128_f8f6f4 v[114:117], v[2:9], v[58:65], v[114:117]
	v_mfma_f32_16x16x128_f8f6f4 v[102:105], v[10:17], v[50:57], v[102:105]
	v_mfma_f32_16x16x128_f8f6f4 v[98:101], v[2:9], v[50:57], v[98:101]
	v_mfma_f32_16x16x128_f8f6f4 v[86:89], v[10:17], v[42:49], v[86:89]
	v_mfma_f32_16x16x128_f8f6f4 v[82:85], v[2:9], v[42:49], v[82:85]
	v_mfma_f32_16x16x128_f8f6f4 v[70:73], v[10:17], v[34:41], v[70:73]
	v_mfma_f32_16x16x128_f8f6f4 v[66:69], v[2:9], v[34:41], v[66:69]
	s_setprio 0
	s_barrier
	v_add_u32_e32 v14, s48, v222
	v_add_u32_e32 v30, s53, v222
	ds_read_b128 v[2:5], v14
	ds_read_b128 v[6:9], v14 offset:1024
	ds_read_b128 v[10:13], v14 offset:2048
	ds_read_b128 v[14:17], v14 offset:3072
	ds_read_b128 v[18:21], v30
	ds_read_b128 v[22:25], v30 offset:1024
	ds_read_b128 v[26:29], v30 offset:2048
	ds_read_b128 v[30:33], v30 offset:3072
	s_add_u32 s28, s28, 0x530000
	s_addc_u32 s29, s29, 0
	s_mov_b32 m0, s42
	v_lshl_add_u64 v[228:229], s[28:29], 0, v[194:195]
	ds_read_b128 v[34:37], v226 offset:32768
	ds_read_b128 v[38:41], v226 offset:33792
	ds_read_b128 v[42:45], v226 offset:34816
	ds_read_b128 v[46:49], v226 offset:35840
	ds_read_b128 v[50:53], v226 offset:36864
	ds_read_b128 v[54:57], v226 offset:37888
	ds_read_b128 v[58:61], v226 offset:38912
	ds_read_b128 v[62:65], v226 offset:39936
	global_load_lds_dwordx4 v[228:229], off
	v_lshl_add_u64 v[228:229], s[28:29], 0, v[198:199]
	s_mov_b32 m0, s43
	s_nop 0
	global_load_lds_dwordx4 v[228:229], off
	s_waitcnt vmcnt(8)
	s_waitcnt lgkmcnt(0)
	s_barrier
	s_setprio 1
	s_waitcnt lgkmcnt(0)
	v_mfma_f32_16x16x128_f8f6f4 v[190:193], v[2:9], v[34:41], v[190:193]
	v_mfma_f32_16x16x128_f8f6f4 v[186:189], v[10:17], v[34:41], v[186:189]
	v_mfma_f32_16x16x128_f8f6f4 v[174:177], v[2:9], v[42:49], v[174:177]
	v_mfma_f32_16x16x128_f8f6f4 v[170:173], v[10:17], v[42:49], v[170:173]
	v_mfma_f32_16x16x128_f8f6f4 v[158:161], v[2:9], v[50:57], v[158:161]
	v_mfma_f32_16x16x128_f8f6f4 v[154:157], v[10:17], v[50:57], v[154:157]
	v_mfma_f32_16x16x128_f8f6f4 v[142:145], v[2:9], v[58:65], v[142:145]
	v_mfma_f32_16x16x128_f8f6f4 v[138:141], v[10:17], v[58:65], v[138:141]
	s_setprio 0
	s_setprio 1
	v_mfma_f32_16x16x128_f8f6f4 v[182:185], v[18:25], v[34:41], v[182:185]
	v_mfma_f32_16x16x128_f8f6f4 v[178:181], v[26:33], v[34:41], v[178:181]
	v_mfma_f32_16x16x128_f8f6f4 v[166:169], v[18:25], v[42:49], v[166:169]
	v_mfma_f32_16x16x128_f8f6f4 v[162:165], v[26:33], v[42:49], v[162:165]
	v_mfma_f32_16x16x128_f8f6f4 v[150:153], v[18:25], v[50:57], v[150:153]
	v_mfma_f32_16x16x128_f8f6f4 v[146:149], v[26:33], v[50:57], v[146:149]
	v_mfma_f32_16x16x128_f8f6f4 v[134:137], v[18:25], v[58:65], v[134:137]
	v_mfma_f32_16x16x128_f8f6f4 v[130:133], v[26:33], v[58:65], v[130:133]
	s_setprio 0
	s_barrier
	s_mov_b32 m0, s49
	v_lshl_add_u64 v[214:215], v[214:215], 0, s[14:15]
	s_add_u32 s26, s26, 0x40080
	ds_read_b128 v[34:37], v226 offset:49152
	ds_read_b128 v[38:41], v226 offset:50176
	ds_read_b128 v[42:45], v226 offset:51200
	ds_read_b128 v[46:49], v226 offset:52224
	ds_read_b128 v[50:53], v226 offset:53248
	ds_read_b128 v[54:57], v226 offset:54272
	ds_read_b128 v[58:61], v226 offset:55296
	ds_read_b128 v[62:65], v226 offset:56320
	global_load_lds_dwordx4 v[214:215], off
	v_lshl_add_u64 v[214:215], v[216:217], 0, s[14:15]
	s_mov_b32 m0, s50
	s_addc_u32 s27, s27, 0
	global_load_lds_dwordx4 v[214:215], off
	v_lshl_add_u64 v[214:215], s[26:27], 0, v[196:197]
	s_mov_b32 m0, s54
	s_nop 0
	global_load_lds_dwordx4 v[214:215], off
	v_lshl_add_u64 v[214:215], s[26:27], 0, v[200:201]
	s_mov_b32 m0, s55
	s_nop 0
	global_load_lds_dwordx4 v[214:215], off
	v_lshl_add_u64 v[214:215], v[218:219], 0, s[16:17]
	s_mov_b32 m0, s51
	s_nop 0
	global_load_lds_dwordx4 v[214:215], off
	v_lshl_add_u64 v[214:215], v[220:221], 0, s[16:17]
	s_mov_b32 m0, s52
	s_nop 0
	global_load_lds_dwordx4 v[214:215], off
	s_waitcnt vmcnt(8)
	s_waitcnt lgkmcnt(0)
	s_barrier
	s_setprio 1
	s_waitcnt lgkmcnt(0)
	v_mfma_f32_16x16x128_f8f6f4 v[126:129], v[2:9], v[34:41], v[126:129]
	v_mfma_f32_16x16x128_f8f6f4 v[122:125], v[10:17], v[34:41], v[122:125]
	v_mfma_f32_16x16x128_f8f6f4 v[110:113], v[2:9], v[42:49], v[110:113]
	v_mfma_f32_16x16x128_f8f6f4 v[106:109], v[10:17], v[42:49], v[106:109]
	v_mfma_f32_16x16x128_f8f6f4 v[94:97], v[2:9], v[50:57], v[94:97]
	v_mfma_f32_16x16x128_f8f6f4 v[90:93], v[10:17], v[50:57], v[90:93]
	v_mfma_f32_16x16x128_f8f6f4 v[78:81], v[2:9], v[58:65], v[78:81]
	v_mfma_f32_16x16x128_f8f6f4 v[74:77], v[10:17], v[58:65], v[74:77]
	s_setprio 0
	s_setprio 1
	v_mfma_f32_16x16x128_f8f6f4 v[118:121], v[18:25], v[34:41], v[118:121]
	v_mfma_f32_16x16x128_f8f6f4 v[114:117], v[26:33], v[34:41], v[114:117]
	v_mfma_f32_16x16x128_f8f6f4 v[102:105], v[18:25], v[42:49], v[102:105]
	v_mfma_f32_16x16x128_f8f6f4 v[98:101], v[26:33], v[42:49], v[98:101]
	v_mfma_f32_16x16x128_f8f6f4 v[86:89], v[18:25], v[50:57], v[86:89]
	v_mfma_f32_16x16x128_f8f6f4 v[82:85], v[26:33], v[50:57], v[82:85]
	v_mfma_f32_16x16x128_f8f6f4 v[70:73], v[18:25], v[58:65], v[70:73]
	v_mfma_f32_16x16x128_f8f6f4 v[66:69], v[26:33], v[58:65], v[66:69]
	s_setprio 0
	s_barrier
	s_add_i32 s69, s69, 2
	s_add_u32 s6, s6, 0x200
	s_addc_u32 s7, s7, 0
	s_add_u32 s67, s67, 0x100
	s_addc_u32 s68, s68, 0
	s_cmp_gt_u32 s69, 13
	s_cbranch_scc1 .LBB0_2232

.LBB0_2228:
	s_add_u32 s26, s4, s6
	s_addc_u32 s27, s5, s7
	s_add_u32 s26, s26, 0x200
	s_addc_u32 s27, s27, 0
	s_waitcnt lgkmcnt(0)
	s_cmpk_eq_i32 s6, 0xe00
	s_cselect_b32 s29, s23, s27
	s_cselect_b32 s28, s22, s26
	s_cselect_b32 s27, s65, s68
	s_cselect_b32 s26, s66, s67
	s_barrier
	s_setprio 1
	s_waitcnt lgkmcnt(0)
	v_mfma_f32_16x16x128_f8f6f4 v[190:193], v[26:33], v[58:65], v[190:193]
	v_mfma_f32_16x16x128_f8f6f4 v[186:189], v[18:25], v[58:65], v[186:189]
	v_mfma_f32_16x16x128_f8f6f4 v[174:177], v[26:33], v[50:57], v[174:177]
	v_mfma_f32_16x16x128_f8f6f4 v[170:173], v[18:25], v[50:57], v[170:173]
	v_mfma_f32_16x16x128_f8f6f4 v[158:161], v[26:33], v[42:49], v[158:161]
	v_mfma_f32_16x16x128_f8f6f4 v[154:157], v[18:25], v[42:49], v[154:157]
	v_mfma_f32_16x16x128_f8f6f4 v[142:145], v[26:33], v[34:41], v[142:145]
	v_mfma_f32_16x16x128_f8f6f4 v[138:141], v[18:25], v[34:41], v[138:141]
	s_setprio 0
	s_setprio 1
	v_mfma_f32_16x16x128_f8f6f4 v[182:185], v[10:17], v[58:65], v[182:185]
	v_mfma_f32_16x16x128_f8f6f4 v[178:181], v[2:9], v[58:65], v[178:181]
	v_mfma_f32_16x16x128_f8f6f4 v[166:169], v[10:17], v[50:57], v[166:169]
	v_mfma_f32_16x16x128_f8f6f4 v[162:165], v[2:9], v[50:57], v[162:165]
	v_mfma_f32_16x16x128_f8f6f4 v[150:153], v[10:17], v[42:49], v[150:153]
	v_mfma_f32_16x16x128_f8f6f4 v[146:149], v[2:9], v[42:49], v[146:149]
	v_mfma_f32_16x16x128_f8f6f4 v[134:137], v[10:17], v[34:41], v[134:137]
	v_mfma_f32_16x16x128_f8f6f4 v[130:133], v[2:9], v[34:41], v[130:133]
	s_setprio 0
	s_barrier
	s_mov_b32 m0, s36
	v_lshl_add_u64 v[214:215], s[26:27], 0, v[196:197]
	s_add_u32 s70, s26, 0x40000
	ds_read_b128 v[58:61], v226 offset:16384
	ds_read_b128 v[62:65], v226 offset:17408
	ds_read_b128 v[50:53], v226 offset:18432
	ds_read_b128 v[54:57], v226 offset:19456
	ds_read_b128 v[42:45], v226 offset:20480
	ds_read_b128 v[46:49], v226 offset:21504
	ds_read_b128 v[34:37], v226 offset:22528
	ds_read_b128 v[38:41], v226 offset:23552
	global_load_lds_dwordx4 v[214:215], off
	v_lshl_add_u64 v[216:217], s[26:27], 0, v[200:201]
	s_mov_b32 m0, s37
	s_addc_u32 s71, s27, 0
	global_load_lds_dwordx4 v[216:217], off
	v_lshl_add_u64 v[218:219], s[70:71], 0, v[196:197]
	s_mov_b32 m0, s38
	v_lshl_add_u64 v[220:221], s[28:29], 0, v[198:199]
	global_load_lds_dwordx4 v[218:219], off
	v_lshl_add_u64 v[218:219], s[70:71], 0, v[200:201]
	s_mov_b32 m0, s39
	s_andn2_b64 vcc, exec, s[30:31]
	global_load_lds_dwordx4 v[218:219], off
	v_lshl_add_u64 v[218:219], s[28:29], 0, v[194:195]
	s_mov_b32 m0, s40
	s_nop 0
	global_load_lds_dwordx4 v[218:219], off
	s_mov_b32 m0, s41
	s_nop 0
	global_load_lds_dwordx4 v[220:221], off
	s_cbranch_vccnz .LBB0_2231
	s_waitcnt vmcnt(24)
	s_cbranch_execnz .LBB0_2224
	s_branch .LBB0_2223

.LBB0_2409:
	s_waitcnt lgkmcnt(0)
	s_barrier
	s_setprio 1
	s_waitcnt lgkmcnt(0)
	v_mfma_f32_16x16x128_f8f6f4 v[126:129], v[26:33], v[58:65], v[126:129]
	v_mfma_f32_16x16x128_f8f6f4 v[122:125], v[18:25], v[58:65], v[122:125]
	v_mfma_f32_16x16x128_f8f6f4 v[114:117], v[26:33], v[50:57], v[114:117]
	v_mfma_f32_16x16x128_f8f6f4 v[106:109], v[18:25], v[50:57], v[106:109]
	v_mfma_f32_16x16x128_f8f6f4 v[98:101], v[26:33], v[42:49], v[98:101]
	v_mfma_f32_16x16x128_f8f6f4 v[90:93], v[18:25], v[42:49], v[90:93]
	v_mfma_f32_16x16x128_f8f6f4 v[82:85], v[26:33], v[34:41], v[82:85]
	v_mfma_f32_16x16x128_f8f6f4 v[74:77], v[18:25], v[34:41], v[74:77]
	s_setprio 0
	s_setprio 1
	v_mfma_f32_16x16x128_f8f6f4 v[118:121], v[10:17], v[58:65], v[118:121]
	v_mfma_f32_16x16x128_f8f6f4 v[110:113], v[2:9], v[58:65], v[110:113]
	v_mfma_f32_16x16x128_f8f6f4 v[102:105], v[10:17], v[50:57], v[102:105]
	v_mfma_f32_16x16x128_f8f6f4 v[94:97], v[2:9], v[50:57], v[94:97]
	v_mfma_f32_16x16x128_f8f6f4 v[86:89], v[10:17], v[42:49], v[86:89]
	v_mfma_f32_16x16x128_f8f6f4 v[78:81], v[2:9], v[42:49], v[78:81]
	v_mfma_f32_16x16x128_f8f6f4 v[70:73], v[10:17], v[34:41], v[70:73]
	v_mfma_f32_16x16x128_f8f6f4 v[66:69], v[2:9], v[34:41], v[66:69]
	s_setprio 0
	s_barrier
	v_add_u32_e32 v14, s57, v222
	v_add_u32_e32 v30, s62, v222
	ds_read_b128 v[2:5], v14
	ds_read_b128 v[6:9], v14 offset:1024
	ds_read_b128 v[10:13], v14 offset:2048
	ds_read_b128 v[14:17], v14 offset:3072
	ds_read_b128 v[18:21], v30
	ds_read_b128 v[22:25], v30 offset:1024
	ds_read_b128 v[26:29], v30 offset:2048
	ds_read_b128 v[30:33], v30 offset:3072
	s_add_u32 s40, s40, 0x40000
	s_addc_u32 s41, s41, 0
	s_mov_b32 m0, s55
	v_lshl_add_u64 v[228:229], s[40:41], 0, v[194:195]
	ds_read_b128 v[34:37], v226 offset:32768
	ds_read_b128 v[38:41], v226 offset:33792
	ds_read_b128 v[42:45], v226 offset:34816
	ds_read_b128 v[46:49], v226 offset:35840
	ds_read_b128 v[50:53], v226 offset:36864
	ds_read_b128 v[54:57], v226 offset:37888
	ds_read_b128 v[58:61], v226 offset:38912
	ds_read_b128 v[62:65], v226 offset:39936
	global_load_lds_dwordx4 v[228:229], off
	v_lshl_add_u64 v[228:229], s[40:41], 0, v[198:199]
	s_mov_b32 m0, s56
	s_nop 0
	global_load_lds_dwordx4 v[228:229], off
	s_waitcnt vmcnt(8)
	s_waitcnt lgkmcnt(0)
	s_barrier
	s_setprio 1
	s_waitcnt lgkmcnt(0)
	v_mfma_f32_16x16x128_f8f6f4 v[190:193], v[2:9], v[34:41], v[190:193]
	v_mfma_f32_16x16x128_f8f6f4 v[186:189], v[10:17], v[34:41], v[186:189]
	v_mfma_f32_16x16x128_f8f6f4 v[178:181], v[2:9], v[42:49], v[178:181]
	v_mfma_f32_16x16x128_f8f6f4 v[170:173], v[10:17], v[42:49], v[170:173]
	v_mfma_f32_16x16x128_f8f6f4 v[162:165], v[2:9], v[50:57], v[162:165]
	v_mfma_f32_16x16x128_f8f6f4 v[154:157], v[10:17], v[50:57], v[154:157]
	v_mfma_f32_16x16x128_f8f6f4 v[146:149], v[2:9], v[58:65], v[146:149]
	v_mfma_f32_16x16x128_f8f6f4 v[138:141], v[10:17], v[58:65], v[138:141]
	s_setprio 0
	s_setprio 1
	v_mfma_f32_16x16x128_f8f6f4 v[182:185], v[18:25], v[34:41], v[182:185]
	v_mfma_f32_16x16x128_f8f6f4 v[174:177], v[26:33], v[34:41], v[174:177]
	v_mfma_f32_16x16x128_f8f6f4 v[166:169], v[18:25], v[42:49], v[166:169]
	v_mfma_f32_16x16x128_f8f6f4 v[158:161], v[26:33], v[42:49], v[158:161]
	v_mfma_f32_16x16x128_f8f6f4 v[150:153], v[18:25], v[50:57], v[150:153]
	v_mfma_f32_16x16x128_f8f6f4 v[142:145], v[26:33], v[50:57], v[142:145]
	v_mfma_f32_16x16x128_f8f6f4 v[134:137], v[18:25], v[58:65], v[134:137]
	v_mfma_f32_16x16x128_f8f6f4 v[130:133], v[26:33], v[58:65], v[130:133]
	s_setprio 0
	s_barrier
	s_mov_b32 m0, s58
	v_lshl_add_u64 v[214:215], v[214:215], 0, s[6:7]
	s_add_u32 s38, s38, 0x40080
	ds_read_b128 v[34:37], v226 offset:49152
	ds_read_b128 v[38:41], v226 offset:50176
	ds_read_b128 v[42:45], v226 offset:51200
	ds_read_b128 v[46:49], v226 offset:52224
	ds_read_b128 v[50:53], v226 offset:53248
	ds_read_b128 v[54:57], v226 offset:54272
	ds_read_b128 v[58:61], v226 offset:55296
	ds_read_b128 v[62:65], v226 offset:56320
	global_load_lds_dwordx4 v[214:215], off
	v_lshl_add_u64 v[214:215], v[216:217], 0, s[6:7]
	s_mov_b32 m0, s59
	s_addc_u32 s39, s39, 0
	global_load_lds_dwordx4 v[214:215], off
	v_lshl_add_u64 v[214:215], s[38:39], 0, v[196:197]
	s_mov_b32 m0, s63
	s_nop 0
	global_load_lds_dwordx4 v[214:215], off
	v_lshl_add_u64 v[214:215], s[38:39], 0, v[200:201]
	s_mov_b32 m0, s64
	s_nop 0
	global_load_lds_dwordx4 v[214:215], off
	v_lshl_add_u64 v[214:215], v[218:219], 0, s[6:7]
	s_mov_b32 m0, s60
	s_nop 0
	global_load_lds_dwordx4 v[214:215], off
	v_lshl_add_u64 v[214:215], v[220:221], 0, s[6:7]
	s_mov_b32 m0, s61
	s_nop 0
	global_load_lds_dwordx4 v[214:215], off
	s_waitcnt vmcnt(8)
	s_waitcnt lgkmcnt(0)
	s_barrier
	s_setprio 1
	s_waitcnt lgkmcnt(0)
	v_mfma_f32_16x16x128_f8f6f4 v[126:129], v[2:9], v[34:41], v[126:129]
	v_mfma_f32_16x16x128_f8f6f4 v[122:125], v[10:17], v[34:41], v[122:125]
	v_mfma_f32_16x16x128_f8f6f4 v[114:117], v[2:9], v[42:49], v[114:117]
	v_mfma_f32_16x16x128_f8f6f4 v[106:109], v[10:17], v[42:49], v[106:109]
	v_mfma_f32_16x16x128_f8f6f4 v[98:101], v[2:9], v[50:57], v[98:101]
	v_mfma_f32_16x16x128_f8f6f4 v[90:93], v[10:17], v[50:57], v[90:93]
	v_mfma_f32_16x16x128_f8f6f4 v[82:85], v[2:9], v[58:65], v[82:85]
	v_mfma_f32_16x16x128_f8f6f4 v[74:77], v[10:17], v[58:65], v[74:77]
	s_setprio 0
	s_setprio 1
	v_mfma_f32_16x16x128_f8f6f4 v[118:121], v[18:25], v[34:41], v[118:121]
	v_mfma_f32_16x16x128_f8f6f4 v[110:113], v[26:33], v[34:41], v[110:113]
	v_mfma_f32_16x16x128_f8f6f4 v[102:105], v[18:25], v[42:49], v[102:105]
	v_mfma_f32_16x16x128_f8f6f4 v[94:97], v[26:33], v[42:49], v[94:97]
	v_mfma_f32_16x16x128_f8f6f4 v[86:89], v[18:25], v[50:57], v[86:89]
	v_mfma_f32_16x16x128_f8f6f4 v[78:81], v[26:33], v[50:57], v[78:81]
	v_mfma_f32_16x16x128_f8f6f4 v[70:73], v[18:25], v[58:65], v[70:73]
	v_mfma_f32_16x16x128_f8f6f4 v[66:69], v[26:33], v[58:65], v[66:69]
	s_setprio 0
	s_barrier
	s_add_i32 s76, s76, 2
	s_add_u32 s36, s36, 0x100
	s_addc_u32 s37, s37, 0
	s_cmp_gt_u32 s76, 13
	s_cbranch_scc1 .LBB0_2417

.LBB0_2413:
	s_add_u32 s38, s30, s36
	s_addc_u32 s39, s31, s37
	s_add_u32 s38, s38, 0x100
	s_addc_u32 s39, s39, 0
	s_add_u32 s77, s74, s36
	s_addc_u32 s78, s75, s37
	s_waitcnt lgkmcnt(0)
	s_cmpk_eq_i32 s36, 0x700
	s_cselect_b32 s41, s21, s39
	s_cselect_b32 s40, s72, s38
	s_cselect_b32 s39, s23, s78
	s_cselect_b32 s38, s73, s77
	s_barrier
	s_setprio 1
	s_waitcnt lgkmcnt(0)
	v_mfma_f32_16x16x128_f8f6f4 v[190:193], v[26:33], v[58:65], v[190:193]
	v_mfma_f32_16x16x128_f8f6f4 v[186:189], v[18:25], v[58:65], v[186:189]
	v_mfma_f32_16x16x128_f8f6f4 v[178:181], v[26:33], v[50:57], v[178:181]
	v_mfma_f32_16x16x128_f8f6f4 v[170:173], v[18:25], v[50:57], v[170:173]
	v_mfma_f32_16x16x128_f8f6f4 v[162:165], v[26:33], v[42:49], v[162:165]
	v_mfma_f32_16x16x128_f8f6f4 v[154:157], v[18:25], v[42:49], v[154:157]
	v_mfma_f32_16x16x128_f8f6f4 v[146:149], v[26:33], v[34:41], v[146:149]
	v_mfma_f32_16x16x128_f8f6f4 v[138:141], v[18:25], v[34:41], v[138:141]
	s_setprio 0
	s_setprio 1
	v_mfma_f32_16x16x128_f8f6f4 v[182:185], v[10:17], v[58:65], v[182:185]
	v_mfma_f32_16x16x128_f8f6f4 v[174:177], v[2:9], v[58:65], v[174:177]
	v_mfma_f32_16x16x128_f8f6f4 v[166:169], v[10:17], v[50:57], v[166:169]
	v_mfma_f32_16x16x128_f8f6f4 v[158:161], v[2:9], v[50:57], v[158:161]
	v_mfma_f32_16x16x128_f8f6f4 v[150:153], v[10:17], v[42:49], v[150:153]
	v_mfma_f32_16x16x128_f8f6f4 v[142:145], v[2:9], v[42:49], v[142:145]
	v_mfma_f32_16x16x128_f8f6f4 v[134:137], v[10:17], v[34:41], v[134:137]
	v_mfma_f32_16x16x128_f8f6f4 v[130:133], v[2:9], v[34:41], v[130:133]
	s_setprio 0
	s_barrier
	s_mov_b32 m0, s29
	v_lshl_add_u64 v[214:215], s[38:39], 0, v[196:197]
	s_add_u32 s78, s38, 0x40000
	ds_read_b128 v[58:61], v226 offset:16384
	ds_read_b128 v[62:65], v226 offset:17408
	ds_read_b128 v[50:53], v226 offset:18432
	ds_read_b128 v[54:57], v226 offset:19456
	ds_read_b128 v[42:45], v226 offset:20480
	ds_read_b128 v[46:49], v226 offset:21504
	ds_read_b128 v[34:37], v226 offset:22528
	ds_read_b128 v[38:41], v226 offset:23552
	global_load_lds_dwordx4 v[214:215], off
	v_lshl_add_u64 v[216:217], s[38:39], 0, v[200:201]
	s_mov_b32 m0, s50
	s_addc_u32 s79, s39, 0
	global_load_lds_dwordx4 v[216:217], off
	v_lshl_add_u64 v[218:219], s[78:79], 0, v[196:197]
	s_mov_b32 m0, s51
	v_lshl_add_u64 v[220:221], s[40:41], 0, v[198:199]
	global_load_lds_dwordx4 v[218:219], off
	v_lshl_add_u64 v[218:219], s[78:79], 0, v[200:201]
	s_mov_b32 m0, s52
	s_andn2_b64 vcc, exec, s[42:43]
	global_load_lds_dwordx4 v[218:219], off
	v_lshl_add_u64 v[218:219], s[40:41], 0, v[194:195]
	s_mov_b32 m0, s53
	s_nop 0
	global_load_lds_dwordx4 v[218:219], off
	s_mov_b32 m0, s54
	s_nop 0
	global_load_lds_dwordx4 v[220:221], off
	s_cbranch_vccnz .LBB0_2416
	s_waitcnt vmcnt(24)
	s_cbranch_execnz .LBB0_2409
	s_branch .LBB0_2408
